# t45 with the priority toggles and redundant wait removed from inside all GEMM K-loops (same bytes parked as nops after each loop's back-edge, loop heads unmoved)
# baseline (speedup 1.0000x reference)
;     __host__ __device__ bool next(int i, Unit& u) const { if (i != 0 || r < 0 || r >= 148) return false; if (r < 116) { u.pm = r % 29; u.pn = 47 + r / 29; } else { u.pm = 32; u.pn = 19 + (r - 116); } u.ko = 0; return true; }
;     __host__ __device__ bool next(int i, Unit& u) const { const int L = i * G + (G - 1 - c); if (L >= nN * S) return false; u.pm = pm; u.pn = L % nN; u.ko = (L / nN) * ksub; return true; }
; #define PG8_STAGE(bufoff, gbase, voff) do { _Pragma("unroll") for (int _i = 0; _i < 2; ++_i) \
;         __builtin_amdgcn_global_load_lds((const unsigned*)((const char*)(gbase) + (voff)[_i]), (PG8_LAS unsigned*)(lds + (bufoff) + ldsw + _i * 8192), 16, 0, 0); } while (0)
; #define PG8_LDA(dst, b, h) do { _Pragma("unroll") for (int m = 0; m < 4; ++m) _Pragma("unroll") for (int k = 0; k < 2; ++k) dst[m][k] = *(const PG8_LAS bf16x8*)(lds + PG8_SA(b, h) + aoff + m * 2048 + k * 1024); } while (0)
; #define PG8_BAR __builtin_amdgcn_s_barrier()
; template <class Epi, class Sched, bool ALIGN_EPI = false, bool SP2 = false>
; __device__ __forceinline__ void gemm_phase(PG8_LAS unsigned char* lds, const Gemm g, const Sched& S, const Epi& E) {
;     ...
;         const bool has_next = S.next(ui + 1, nxt);
;         const char* nA = has_next ? (const char*)g.A + (size_t)nxt.pm * tstep + (size_t)nxt.ko * 2 : cA; const char* nB = has_next ? (const char*)g.Bt + (size_t)nxt.pn * tstep + (size_t)nxt.ko * 2 : cB;
;         for (int t = 0; t < nt; t += 2) {
;             const bool last = (t == nt - 2);
;             const char* a1 = cA + (size_t)(t + 1) * kstep;
;             const char* a2 = last ? nA : cA + (size_t)(t + 2) * kstep; const char* b2 = last ? nB : cB + (size_t)(t + 2) * kstep;
;             const char* a3 = a2 + kstep; const char* b3 = b2 + kstep;
;             if (last && has_next) S.a_ready(nxt);
;             if constexpr (SP2) {
;             PG8_LDB(B0, 0, 0); PG8_LDB(B1, 0, 1); PG8_SCHED; PG8_LDA(At, 0, 0); PG8_STAGE(PG8_SA(1, 1), a1 + hstep, voffA);
;             PG8_WAIT_V(8); PG8_WAIT_L(0); PG8_BAR; PG8_MMA(0, 0, At, B0); PG8_MMA(0, 1, At, B1); PG8_BAR; PG8_SCHED;
;             PG8_LDA(At, 0, 1); PG8_STAGE(PG8_SB(0, 0), b2, voffB); PG8_STAGE(PG8_SB(0, 1), b2 + hstep, voffB); PG8_STAGE(PG8_SA(0, 0), a2, voffA);
;             PG8_WAIT_V(8); PG8_WAIT_L(0); PG8_BAR; PG8_MMA(1, 0, At, B0); PG8_MMA(1, 1, At, B1); PG8_BAR; PG8_SCHED;
.LBB0_239:
	s_add_u32 s48, s12, 0xfff80080
	s_addc_u32 s49, s13, -1
	s_cmp_eq_u32 s47, 28
	s_cselect_b32 s51, s1, s49
	s_cselect_b32 s50, s2, s48
	s_cselect_b32 s49, s3, s37
	s_cselect_b32 s48, s15, s35
	s_add_i32 s65, 0, 0x10000
	v_add_u32_e32 v0, s65, v185
	s_add_i32 s68, 0, 0x14000
	ds_read_b128 v[132:135], v0
	ds_read_b128 v[136:139], v0 offset:1024
	ds_read_b128 v[140:143], v0 offset:2048
	ds_read_b128 v[144:147], v0 offset:3072
	v_add_u32_e32 v0, s68, v185
	ds_read_b128 v[148:151], v0
	ds_read_b128 v[152:155], v0 offset:1024
	ds_read_b128 v[172:175], v0 offset:2048
	ds_read_b128 v[176:179], v0 offset:3072
	v_lshl_add_u64 v[228:229], s[12:13], 0, v[168:169]
	s_add_i32 m0, s53, 0xc000
	ds_read_b128 v[180:183], v190
	ds_read_b128 v[192:195], v190 offset:1024
	ds_read_b128 v[196:199], v190 offset:2048
	ds_read_b128 v[200:203], v190 offset:3072
	ds_read_b128 v[204:207], v190 offset:4096
	ds_read_b128 v[208:211], v190 offset:5120
	ds_read_b128 v[220:223], v190 offset:6144
	ds_read_b128 v[224:227], v190 offset:7168
	global_load_lds_dwordx4 v[228:229], off
	v_lshl_add_u64 v[228:229], s[12:13], 0, v[170:171]
	s_add_i32 m0, s53, 0xe000
	s_nop 0
	global_load_lds_dwordx4 v[228:229], off
	s_waitcnt vmcnt(8)
	s_waitcnt lgkmcnt(0)
	s_barrier
	v_mfma_f32_16x16x32_bf16 v[128:131], v[132:135], v[180:183], v[128:131]
	v_mfma_f32_16x16x32_bf16 v[124:127], v[140:143], v[180:183], v[124:127]
	v_mfma_f32_16x16x32_bf16 v[112:115], v[132:135], v[196:199], v[112:115]
	v_mfma_f32_16x16x32_bf16 v[108:111], v[140:143], v[196:199], v[108:111]
	v_mfma_f32_16x16x32_bf16 v[96:99], v[132:135], v[204:207], v[96:99]
	v_mfma_f32_16x16x32_bf16 v[92:95], v[140:143], v[204:207], v[92:95]
	v_mfma_f32_16x16x32_bf16 v[80:83], v[132:135], v[220:223], v[80:83]
	v_mfma_f32_16x16x32_bf16 v[76:79], v[140:143], v[220:223], v[76:79]
	v_mfma_f32_16x16x32_bf16 v[128:131], v[136:139], v[192:195], v[128:131]
	v_mfma_f32_16x16x32_bf16 v[124:127], v[144:147], v[192:195], v[124:127]
	v_mfma_f32_16x16x32_bf16 v[112:115], v[136:139], v[200:203], v[112:115]
	v_mfma_f32_16x16x32_bf16 v[108:111], v[144:147], v[200:203], v[108:111]
	v_mfma_f32_16x16x32_bf16 v[96:99], v[136:139], v[208:211], v[96:99]
	v_mfma_f32_16x16x32_bf16 v[92:95], v[144:147], v[208:211], v[92:95]
	v_mfma_f32_16x16x32_bf16 v[80:83], v[136:139], v[224:227], v[80:83]
	v_mfma_f32_16x16x32_bf16 v[76:79], v[144:147], v[224:227], v[76:79]
	v_mfma_f32_16x16x32_bf16 v[120:123], v[148:151], v[180:183], v[120:123]
	v_mfma_f32_16x16x32_bf16 v[116:119], v[172:175], v[180:183], v[116:119]
	v_mfma_f32_16x16x32_bf16 v[104:107], v[148:151], v[196:199], v[104:107]
	v_mfma_f32_16x16x32_bf16 v[100:103], v[172:175], v[196:199], v[100:103]
	v_mfma_f32_16x16x32_bf16 v[88:91], v[148:151], v[204:207], v[88:91]
	v_mfma_f32_16x16x32_bf16 v[84:87], v[172:175], v[204:207], v[84:87]
	v_mfma_f32_16x16x32_bf16 v[72:75], v[148:151], v[220:223], v[72:75]
	v_mfma_f32_16x16x32_bf16 v[68:71], v[172:175], v[220:223], v[68:71]
	v_mfma_f32_16x16x32_bf16 v[120:123], v[152:155], v[192:195], v[120:123]
	v_mfma_f32_16x16x32_bf16 v[116:119], v[176:179], v[192:195], v[116:119]
	v_mfma_f32_16x16x32_bf16 v[104:107], v[152:155], v[200:203], v[104:107]
	v_mfma_f32_16x16x32_bf16 v[100:103], v[176:179], v[200:203], v[100:103]
	v_mfma_f32_16x16x32_bf16 v[88:91], v[152:155], v[208:211], v[88:91]
	v_mfma_f32_16x16x32_bf16 v[84:87], v[176:179], v[208:211], v[84:87]
	v_mfma_f32_16x16x32_bf16 v[72:75], v[152:155], v[224:227], v[72:75]
	v_mfma_f32_16x16x32_bf16 v[68:71], v[176:179], v[224:227], v[68:71]
	s_barrier
	s_add_i32 s65, s65, s52
	v_lshl_add_u64 v[228:229], s[48:49], 0, v[158:159]
	s_mov_b32 m0, s65
	ds_read_b128 v[180:183], v190 offset:16384
	ds_read_b128 v[192:195], v190 offset:17408
	ds_read_b128 v[196:199], v190 offset:18432
	ds_read_b128 v[200:203], v190 offset:19456
	ds_read_b128 v[204:207], v190 offset:20480
	ds_read_b128 v[208:211], v190 offset:21504
	ds_read_b128 v[220:223], v190 offset:22528
	ds_read_b128 v[224:227], v190 offset:23552
	global_load_lds_dwordx4 v[228:229], off
	s_add_i32 m0, s65, 0x2000
	s_add_u32 s66, s48, 0x80000
	v_lshl_add_u64 v[230:231], s[48:49], 0, v[162:163]
	s_addc_u32 s67, s49, 0
	s_add_i32 s65, s68, s52
	global_load_lds_dwordx4 v[230:231], off
	v_lshl_add_u64 v[232:233], s[66:67], 0, v[158:159]
	s_mov_b32 m0, s65
	v_lshl_add_u64 v[234:235], s[50:51], 0, v[160:161]
	global_load_lds_dwordx4 v[232:233], off
	v_lshl_add_u64 v[232:233], s[66:67], 0, v[162:163]
	s_add_i32 m0, s65, 0x2000
	s_nop 0
	global_load_lds_dwordx4 v[232:233], off
	v_lshl_add_u64 v[232:233], s[50:51], 0, v[156:157]
	s_mov_b32 m0, s53
	s_nop 0
	global_load_lds_dwordx4 v[232:233], off
	s_mov_b32 m0, s54
	s_nop 0
	global_load_lds_dwordx4 v[234:235], off
	s_waitcnt vmcnt(8)
	s_waitcnt lgkmcnt(0)
	s_barrier
; #define PG8_STAGE(bufoff, gbase, voff) do { _Pragma("unroll") for (int _i = 0; _i < 2; ++_i) \
;         __builtin_amdgcn_global_load_lds((const unsigned*)((const char*)(gbase) + (voff)[_i]), (PG8_LAS unsigned*)(lds + (bufoff) + ldsw + _i * 8192), 16, 0, 0); } while (0)
; #define PG8_LDA(dst, b, h) do { _Pragma("unroll") for (int m = 0; m < 4; ++m) _Pragma("unroll") for (int k = 0; k < 2; ++k) dst[m][k] = *(const PG8_LAS bf16x8*)(lds + PG8_SA(b, h) + aoff + m * 2048 + k * 1024); } while (0)
; #define PG8_LDB(dst, b, h) do { _Pragma("unroll") for (int n = 0; n < 2; ++n) _Pragma("unroll") for (int k = 0; k < 2; ++k) dst[n][k] = *(const PG8_LAS bf16x8*)(lds + PG8_SB(b, h) + boff + n * 2048 + k * 1024); } while (0)
; #define PG8_MMA(ai, bj, At, Bt) do { __builtin_amdgcn_s_setprio(1); _Pragma("unroll") for (int m = 0; m < 4; ++m) _Pragma("unroll") for (int n = 0; n < 2; ++n) _Pragma("unroll") for (int k = 0; k < 2; ++k) \
;         acc[ai][bj][m][n] = __builtin_amdgcn_mfma_f32_16x16x32_bf16(Bt[n][k], At[m][k], acc[ai][bj][m][n], 0, 0, 0); __builtin_amdgcn_s_setprio(0); } while (0)
; #define PG8_WAIT_V(n) asm volatile("s_waitcnt vmcnt(" #n ")" ::: "memory")
; #define PG8_WAIT_L(n) asm volatile("s_waitcnt lgkmcnt(" #n ")" ::: "memory")
; #define PG8_BAR __builtin_amdgcn_s_barrier()
; #define PG8_SCHED __builtin_amdgcn_sched_barrier(0)
; template <class Epi, class Sched, bool ALIGN_EPI = false, bool SP2 = false>
; __device__ __forceinline__ void gemm_phase(PG8_LAS unsigned char* lds, const Gemm g, const Sched& S, const Epi& E) {
;     ...
;             PG8_WAIT_V(8); PG8_WAIT_L(0); PG8_BAR; PG8_MMA(1, 0, At, B0); PG8_MMA(1, 1, At, B1); PG8_BAR; PG8_SCHED;
;             PG8_LDB(B0, 1, 0); PG8_LDB(B1, 1, 1); PG8_SCHED; PG8_LDA(At, 1, 0); PG8_STAGE(PG8_SA(0, 1), a2 + hstep, voffA);
;             PG8_WAIT_V(8); PG8_WAIT_L(0); PG8_BAR; PG8_MMA(0, 0, At, B0); PG8_MMA(0, 1, At, B1); PG8_BAR; PG8_SCHED;
	v_mfma_f32_16x16x32_bf16 v[62:65], v[132:135], v[180:183], v[62:65]
	v_mfma_f32_16x16x32_bf16 v[58:61], v[140:143], v[180:183], v[58:61]
	v_mfma_f32_16x16x32_bf16 v[46:49], v[132:135], v[196:199], v[46:49]
	v_mfma_f32_16x16x32_bf16 v[42:45], v[140:143], v[196:199], v[42:45]
	v_mfma_f32_16x16x32_bf16 v[30:33], v[132:135], v[204:207], v[30:33]
	v_mfma_f32_16x16x32_bf16 v[26:29], v[140:143], v[204:207], v[26:29]
	v_mfma_f32_16x16x32_bf16 v[14:17], v[132:135], v[220:223], v[14:17]
	v_mfma_f32_16x16x32_bf16 v[10:13], v[140:143], v[220:223], v[10:13]
	v_mfma_f32_16x16x32_bf16 v[62:65], v[136:139], v[192:195], v[62:65]
	v_mfma_f32_16x16x32_bf16 v[58:61], v[144:147], v[192:195], v[58:61]
	v_mfma_f32_16x16x32_bf16 v[46:49], v[136:139], v[200:203], v[46:49]
	v_mfma_f32_16x16x32_bf16 v[42:45], v[144:147], v[200:203], v[42:45]
	v_mfma_f32_16x16x32_bf16 v[30:33], v[136:139], v[208:211], v[30:33]
	v_mfma_f32_16x16x32_bf16 v[26:29], v[144:147], v[208:211], v[26:29]
	v_mfma_f32_16x16x32_bf16 v[14:17], v[136:139], v[224:227], v[14:17]
	v_mfma_f32_16x16x32_bf16 v[10:13], v[144:147], v[224:227], v[10:13]
	v_mfma_f32_16x16x32_bf16 v[54:57], v[148:151], v[180:183], v[54:57]
	v_mfma_f32_16x16x32_bf16 v[50:53], v[172:175], v[180:183], v[50:53]
	v_mfma_f32_16x16x32_bf16 v[38:41], v[148:151], v[196:199], v[38:41]
	v_mfma_f32_16x16x32_bf16 v[34:37], v[172:175], v[196:199], v[34:37]
	v_mfma_f32_16x16x32_bf16 v[22:25], v[148:151], v[204:207], v[22:25]
	v_mfma_f32_16x16x32_bf16 v[18:21], v[172:175], v[204:207], v[18:21]
	v_mfma_f32_16x16x32_bf16 v[6:9], v[148:151], v[220:223], v[6:9]
	v_mfma_f32_16x16x32_bf16 v[2:5], v[172:175], v[220:223], v[2:5]
	v_mfma_f32_16x16x32_bf16 v[54:57], v[152:155], v[192:195], v[54:57]
	v_mfma_f32_16x16x32_bf16 v[50:53], v[176:179], v[192:195], v[50:53]
	v_mfma_f32_16x16x32_bf16 v[38:41], v[152:155], v[200:203], v[38:41]
	v_mfma_f32_16x16x32_bf16 v[34:37], v[176:179], v[200:203], v[34:37]
	v_mfma_f32_16x16x32_bf16 v[22:25], v[152:155], v[208:211], v[22:25]
	v_mfma_f32_16x16x32_bf16 v[18:21], v[176:179], v[208:211], v[18:21]
	v_mfma_f32_16x16x32_bf16 v[6:9], v[152:155], v[224:227], v[6:9]
	v_mfma_f32_16x16x32_bf16 v[2:5], v[176:179], v[224:227], v[2:5]
	s_barrier
	s_add_i32 s65, 0, 0x18000
	v_add_u32_e32 v0, s65, v185
	s_add_i32 s66, 0, 0x1c000
	ds_read_b128 v[132:135], v0
	ds_read_b128 v[136:139], v0 offset:1024
	ds_read_b128 v[140:143], v0 offset:2048
	ds_read_b128 v[144:147], v0 offset:3072
	v_add_u32_e32 v0, s66, v185
	ds_read_b128 v[148:151], v0
	ds_read_b128 v[152:155], v0 offset:1024
	ds_read_b128 v[172:175], v0 offset:2048
	ds_read_b128 v[176:179], v0 offset:3072
	s_add_u32 s50, s50, 0x80000
	s_addc_u32 s51, s51, 0
	s_mov_b32 m0, s55
	v_lshl_add_u64 v[246:247], s[50:51], 0, v[156:157]
	ds_read_b128 v[180:183], v190 offset:32768
	ds_read_b128 v[192:195], v190 offset:33792
	ds_read_b128 v[196:199], v190 offset:34816
	ds_read_b128 v[200:203], v190 offset:35840
	ds_read_b128 v[204:207], v190 offset:36864
	ds_read_b128 v[208:211], v190 offset:37888
	ds_read_b128 v[220:223], v190 offset:38912
	ds_read_b128 v[224:227], v190 offset:39936
	global_load_lds_dwordx4 v[246:247], off
	v_lshl_add_u64 v[246:247], s[50:51], 0, v[160:161]
	s_mov_b32 m0, s56
	s_nop 0
	global_load_lds_dwordx4 v[246:247], off
	s_waitcnt vmcnt(8)
	s_waitcnt lgkmcnt(0)
	s_barrier
	v_mfma_f32_16x16x32_bf16 v[128:131], v[132:135], v[180:183], v[128:131]
	v_mfma_f32_16x16x32_bf16 v[124:127], v[140:143], v[180:183], v[124:127]
	v_mfma_f32_16x16x32_bf16 v[112:115], v[132:135], v[196:199], v[112:115]
	v_mfma_f32_16x16x32_bf16 v[108:111], v[140:143], v[196:199], v[108:111]
	v_mfma_f32_16x16x32_bf16 v[96:99], v[132:135], v[204:207], v[96:99]
	v_mfma_f32_16x16x32_bf16 v[92:95], v[140:143], v[204:207], v[92:95]
	v_mfma_f32_16x16x32_bf16 v[80:83], v[132:135], v[220:223], v[80:83]
	v_mfma_f32_16x16x32_bf16 v[76:79], v[140:143], v[220:223], v[76:79]
	v_mfma_f32_16x16x32_bf16 v[128:131], v[136:139], v[192:195], v[128:131]
	v_mfma_f32_16x16x32_bf16 v[124:127], v[144:147], v[192:195], v[124:127]
	v_mfma_f32_16x16x32_bf16 v[112:115], v[136:139], v[200:203], v[112:115]
	v_mfma_f32_16x16x32_bf16 v[108:111], v[144:147], v[200:203], v[108:111]
	v_mfma_f32_16x16x32_bf16 v[96:99], v[136:139], v[208:211], v[96:99]
	v_mfma_f32_16x16x32_bf16 v[92:95], v[144:147], v[208:211], v[92:95]
	v_mfma_f32_16x16x32_bf16 v[80:83], v[136:139], v[224:227], v[80:83]
	v_mfma_f32_16x16x32_bf16 v[76:79], v[144:147], v[224:227], v[76:79]
	v_mfma_f32_16x16x32_bf16 v[120:123], v[148:151], v[180:183], v[120:123]
	v_mfma_f32_16x16x32_bf16 v[116:119], v[172:175], v[180:183], v[116:119]
	v_mfma_f32_16x16x32_bf16 v[104:107], v[148:151], v[196:199], v[104:107]
	v_mfma_f32_16x16x32_bf16 v[100:103], v[172:175], v[196:199], v[100:103]
	v_mfma_f32_16x16x32_bf16 v[88:91], v[148:151], v[204:207], v[88:91]
	v_mfma_f32_16x16x32_bf16 v[84:87], v[172:175], v[204:207], v[84:87]
	v_mfma_f32_16x16x32_bf16 v[72:75], v[148:151], v[220:223], v[72:75]
	v_mfma_f32_16x16x32_bf16 v[68:71], v[172:175], v[220:223], v[68:71]
	v_mfma_f32_16x16x32_bf16 v[120:123], v[152:155], v[192:195], v[120:123]
	v_mfma_f32_16x16x32_bf16 v[116:119], v[176:179], v[192:195], v[116:119]
	v_mfma_f32_16x16x32_bf16 v[104:107], v[152:155], v[200:203], v[104:107]
	v_mfma_f32_16x16x32_bf16 v[100:103], v[176:179], v[200:203], v[100:103]
	v_mfma_f32_16x16x32_bf16 v[88:91], v[152:155], v[208:211], v[88:91]
	v_mfma_f32_16x16x32_bf16 v[84:87], v[176:179], v[208:211], v[84:87]
	v_mfma_f32_16x16x32_bf16 v[72:75], v[152:155], v[224:227], v[72:75]
	v_mfma_f32_16x16x32_bf16 v[68:71], v[176:179], v[224:227], v[68:71]
	s_barrier
; #define PG8_STAGE(bufoff, gbase, voff) do { _Pragma("unroll") for (int _i = 0; _i < 2; ++_i) \
;         __builtin_amdgcn_global_load_lds((const unsigned*)((const char*)(gbase) + (voff)[_i]), (PG8_LAS unsigned*)(lds + (bufoff) + ldsw + _i * 8192), 16, 0, 0); } while (0)
; #define PG8_LDA(dst, b, h) do { _Pragma("unroll") for (int m = 0; m < 4; ++m) _Pragma("unroll") for (int k = 0; k < 2; ++k) dst[m][k] = *(const PG8_LAS bf16x8*)(lds + PG8_SA(b, h) + aoff + m * 2048 + k * 1024); } while (0)
; #define PG8_MMA(ai, bj, At, Bt) do { __builtin_amdgcn_s_setprio(1); _Pragma("unroll") for (int m = 0; m < 4; ++m) _Pragma("unroll") for (int n = 0; n < 2; ++n) _Pragma("unroll") for (int k = 0; k < 2; ++k) \
;         acc[ai][bj][m][n] = __builtin_amdgcn_mfma_f32_16x16x32_bf16(Bt[n][k], At[m][k], acc[ai][bj][m][n], 0, 0, 0); __builtin_amdgcn_s_setprio(0); } while (0)
; #define PG8_WAIT_V(n) asm volatile("s_waitcnt vmcnt(" #n ")" ::: "memory")
; #define PG8_WAIT_L(n) asm volatile("s_waitcnt lgkmcnt(" #n ")" ::: "memory")
; #define PG8_BAR __builtin_amdgcn_s_barrier()
; #define PG8_SCHED __builtin_amdgcn_sched_barrier(0)
; template <class Epi, class Sched, bool ALIGN_EPI = false, bool SP2 = false>
; __device__ __forceinline__ void gemm_phase(PG8_LAS unsigned char* lds, const Gemm g, const Sched& S, const Epi& E) {
;     ...
;             PG8_LDA(At, 1, 1); PG8_STAGE(PG8_SB(1, 0), b3, voffB); PG8_STAGE(PG8_SB(1, 1), b3 + hstep, voffB); PG8_STAGE(PG8_SA(1, 0), a3, voffA);
;             PG8_WAIT_V(8); PG8_WAIT_L(0); PG8_BAR; PG8_MMA(1, 0, At, B0); PG8_MMA(1, 1, At, B1); PG8_BAR; PG8_SCHED;
	s_add_i32 s50, s65, s52
	v_lshl_add_u64 v[228:229], v[228:229], 0, s[88:89]
	s_mov_b32 m0, s50
	ds_read_b128 v[180:183], v190 offset:49152
	ds_read_b128 v[192:195], v190 offset:50176
	ds_read_b128 v[196:199], v190 offset:51200
	ds_read_b128 v[200:203], v190 offset:52224
	ds_read_b128 v[204:207], v190 offset:53248
	ds_read_b128 v[208:211], v190 offset:54272
	ds_read_b128 v[220:223], v190 offset:55296
	ds_read_b128 v[224:227], v190 offset:56320
	global_load_lds_dwordx4 v[228:229], off
	s_add_i32 m0, s50, 0x2000
	s_add_u32 s48, s48, 0x80080
	v_lshl_add_u64 v[228:229], v[230:231], 0, s[88:89]
	s_addc_u32 s49, s49, 0
	s_add_i32 s50, s66, s52
	global_load_lds_dwordx4 v[228:229], off
	v_lshl_add_u64 v[228:229], s[48:49], 0, v[158:159]
	s_mov_b32 m0, s50
	s_nop 0
	global_load_lds_dwordx4 v[228:229], off
	v_lshl_add_u64 v[228:229], s[48:49], 0, v[162:163]
	s_add_i32 m0, s50, 0x2000
	s_nop 0
	global_load_lds_dwordx4 v[228:229], off
	v_lshl_add_u64 v[228:229], v[232:233], 0, s[88:89]
	s_mov_b32 m0, s58
	s_nop 0
	global_load_lds_dwordx4 v[228:229], off
	v_lshl_add_u64 v[228:229], v[234:235], 0, s[88:89]
	s_mov_b32 m0, s59
	s_nop 0
	global_load_lds_dwordx4 v[228:229], off
	s_waitcnt vmcnt(8)
	s_waitcnt lgkmcnt(0)
	s_barrier
	v_mfma_f32_16x16x32_bf16 v[62:65], v[132:135], v[180:183], v[62:65]
	v_mfma_f32_16x16x32_bf16 v[58:61], v[140:143], v[180:183], v[58:61]
	v_mfma_f32_16x16x32_bf16 v[46:49], v[132:135], v[196:199], v[46:49]
	v_mfma_f32_16x16x32_bf16 v[42:45], v[140:143], v[196:199], v[42:45]
	v_mfma_f32_16x16x32_bf16 v[30:33], v[132:135], v[204:207], v[30:33]
	v_mfma_f32_16x16x32_bf16 v[26:29], v[140:143], v[204:207], v[26:29]
	v_mfma_f32_16x16x32_bf16 v[14:17], v[132:135], v[220:223], v[14:17]
	v_mfma_f32_16x16x32_bf16 v[10:13], v[140:143], v[220:223], v[10:13]
	v_mfma_f32_16x16x32_bf16 v[62:65], v[136:139], v[192:195], v[62:65]
	v_mfma_f32_16x16x32_bf16 v[58:61], v[144:147], v[192:195], v[58:61]
	v_mfma_f32_16x16x32_bf16 v[46:49], v[136:139], v[200:203], v[46:49]
	v_mfma_f32_16x16x32_bf16 v[42:45], v[144:147], v[200:203], v[42:45]
	v_mfma_f32_16x16x32_bf16 v[30:33], v[136:139], v[208:211], v[30:33]
	v_mfma_f32_16x16x32_bf16 v[26:29], v[144:147], v[208:211], v[26:29]
	v_mfma_f32_16x16x32_bf16 v[14:17], v[136:139], v[224:227], v[14:17]
	v_mfma_f32_16x16x32_bf16 v[10:13], v[144:147], v[224:227], v[10:13]
	v_mfma_f32_16x16x32_bf16 v[54:57], v[148:151], v[180:183], v[54:57]
	v_mfma_f32_16x16x32_bf16 v[50:53], v[172:175], v[180:183], v[50:53]
	v_mfma_f32_16x16x32_bf16 v[38:41], v[148:151], v[196:199], v[38:41]
	v_mfma_f32_16x16x32_bf16 v[34:37], v[172:175], v[196:199], v[34:37]
	v_mfma_f32_16x16x32_bf16 v[22:25], v[148:151], v[204:207], v[22:25]
	v_mfma_f32_16x16x32_bf16 v[18:21], v[172:175], v[204:207], v[18:21]
	v_mfma_f32_16x16x32_bf16 v[6:9], v[148:151], v[220:223], v[6:9]
	v_mfma_f32_16x16x32_bf16 v[2:5], v[172:175], v[220:223], v[2:5]
	v_mfma_f32_16x16x32_bf16 v[54:57], v[152:155], v[192:195], v[54:57]
	v_mfma_f32_16x16x32_bf16 v[50:53], v[176:179], v[192:195], v[50:53]
	v_mfma_f32_16x16x32_bf16 v[38:41], v[152:155], v[200:203], v[38:41]
	v_mfma_f32_16x16x32_bf16 v[34:37], v[176:179], v[200:203], v[34:37]
	v_mfma_f32_16x16x32_bf16 v[22:25], v[152:155], v[208:211], v[22:25]
	v_mfma_f32_16x16x32_bf16 v[18:21], v[176:179], v[208:211], v[18:21]
	v_mfma_f32_16x16x32_bf16 v[6:9], v[152:155], v[224:227], v[6:9]
	v_mfma_f32_16x16x32_bf16 v[2:5], v[176:179], v[224:227], v[2:5]
	s_barrier
	s_add_i32 s47, s47, 2
	s_add_u32 s12, s12, 0x100
	s_addc_u32 s13, s13, 0
	s_add_u32 s35, s35, 0x100
	s_addc_u32 s37, s37, 0
	s_cmp_gt_u32 s47, 29
	s_cbranch_scc0 .LBB0_239
	s_nop 0
	s_nop 0
	s_nop 0
	s_nop 0
	s_nop 0
	s_nop 0
	s_nop 0
	s_nop 0
	s_nop 0
	s_nop 0
	s_nop 0
	s_nop 0
	s_nop 0
	s_nop 0
	s_nop 0
	s_nop 0
	s_nop 0
	s_nop 0
	s_nop 0
	s_nop 0
	s_and_b64 vcc, exec, s[30:31]
	s_cbranch_vccz .LBB0_242
	s_barrier

;     __host__ __device__ bool next(int i, Unit& u) const { if (i != 0 || r < 0 || r >= 148) return false; if (r < 116) { u.pm = r % 29; u.pn = 47 + r / 29; } else { u.pm = 32; u.pn = 19 + (r - 116); } u.ko = 0; return true; }
;     __host__ __device__ bool next(int i, Unit& u) const { const int L = i * G + (G - 1 - c); if (L >= nN * S) return false; u.pm = pm; u.pn = L % nN; u.ko = (L / nN) * ksub; return true; }
; #define PG8_STAGE(bufoff, gbase, voff) do { _Pragma("unroll") for (int _i = 0; _i < 2; ++_i) \
;         __builtin_amdgcn_global_load_lds((const unsigned*)((const char*)(gbase) + (voff)[_i]), (PG8_LAS unsigned*)(lds + (bufoff) + ldsw + _i * 8192), 16, 0, 0); } while (0)
; #define PG8_LDA(dst, b, h) do { _Pragma("unroll") for (int m = 0; m < 4; ++m) _Pragma("unroll") for (int k = 0; k < 2; ++k) dst[m][k] = *(const PG8_LAS bf16x8*)(lds + PG8_SA(b, h) + aoff + m * 2048 + k * 1024); } while (0)
; #define PG8_BAR __builtin_amdgcn_s_barrier()
; template <class Epi, class Sched, bool ALIGN_EPI = false, bool SP2 = false>
; __device__ __forceinline__ void gemm_phase(PG8_LAS unsigned char* lds, const Gemm g, const Sched& S, const Epi& E) {
;     ...
;         const bool has_next = S.next(ui + 1, nxt);
;         const char* nA = has_next ? (const char*)g.A + (size_t)nxt.pm * tstep + (size_t)nxt.ko * 2 : cA; const char* nB = has_next ? (const char*)g.Bt + (size_t)nxt.pn * tstep + (size_t)nxt.ko * 2 : cB;
;         for (int t = 0; t < nt; t += 2) {
;             const bool last = (t == nt - 2);
;             const char* a1 = cA + (size_t)(t + 1) * kstep;
;             const char* a2 = last ? nA : cA + (size_t)(t + 2) * kstep; const char* b2 = last ? nB : cB + (size_t)(t + 2) * kstep;
;             const char* a3 = a2 + kstep; const char* b3 = b2 + kstep;
;             if (last && has_next) S.a_ready(nxt);
;             if constexpr (SP2) {
;             PG8_LDB(B0, 0, 0); PG8_LDB(B1, 0, 1); PG8_SCHED; PG8_LDA(At, 0, 0); PG8_STAGE(PG8_SA(1, 1), a1 + hstep, voffA);
;             PG8_WAIT_V(8); PG8_WAIT_L(0); PG8_BAR; PG8_MMA(0, 0, At, B0); PG8_MMA(0, 1, At, B1); PG8_BAR; PG8_SCHED;
;             PG8_LDA(At, 0, 1); PG8_STAGE(PG8_SB(0, 0), b2, voffB); PG8_STAGE(PG8_SB(0, 1), b2 + hstep, voffB); PG8_STAGE(PG8_SA(0, 0), a2, voffA);
;             PG8_WAIT_V(8); PG8_WAIT_L(0); PG8_BAR; PG8_MMA(1, 0, At, B0); PG8_MMA(1, 1, At, B1); PG8_BAR; PG8_SCHED;
.LBB0_398:
	s_lshl_b32 s54, s43, 7
	s_add_u32 s55, s30, s54
	s_addc_u32 s56, s31, 0
	s_add_u32 s57, s55, 0x100
	s_addc_u32 s58, s56, 0
	s_and_b64 s[52:53], s[12:13], exec
	s_cselect_b32 s53, s58, s1
	s_cselect_b32 s52, s57, s2
	s_add_u32 s54, s34, s54
	s_addc_u32 s57, s35, 0
	s_add_u32 s54, s54, 0x100
	s_addc_u32 s57, s57, 0
	s_and_b64 s[12:13], s[12:13], exec
	s_cselect_b32 s13, s57, s3
	s_cselect_b32 s12, s54, s41
	s_add_i32 s57, 0, 0x10000
	v_add_u32_e32 v0, s57, v181
	s_add_i32 s58, 0, 0x14000
	ds_read_b128 v[132:135], v0
	ds_read_b128 v[136:139], v0 offset:1024
	ds_read_b128 v[140:143], v0 offset:2048
	ds_read_b128 v[144:147], v0 offset:3072
	v_add_u32_e32 v0, s58, v181
	ds_read_b128 v[148:151], v0
	ds_read_b128 v[152:155], v0 offset:1024
	ds_read_b128 v[168:171], v0 offset:2048
	ds_read_b128 v[172:175], v0 offset:3072
	s_add_u32 s54, s55, 0x80080
	s_addc_u32 s55, s56, 0
	v_lshl_add_u64 v[224:225], s[54:55], 0, v[156:157]
	s_add_i32 m0, s29, 0xc000
	ds_read_b128 v[176:179], v187
	ds_read_b128 v[188:191], v187 offset:1024
	ds_read_b128 v[192:195], v187 offset:2048
	ds_read_b128 v[196:199], v187 offset:3072
	ds_read_b128 v[200:203], v187 offset:4096
	ds_read_b128 v[204:207], v187 offset:5120
	ds_read_b128 v[208:211], v187 offset:6144
	ds_read_b128 v[220:223], v187 offset:7168
	global_load_lds_dwordx4 v[224:225], off
	v_lshl_add_u64 v[224:225], s[54:55], 0, v[160:161]
	s_add_i32 m0, s29, 0xe000
	s_nop 0
	global_load_lds_dwordx4 v[224:225], off
	s_waitcnt vmcnt(8)
	s_waitcnt lgkmcnt(0)
	s_barrier
	v_mfma_f32_16x16x32_bf16 v[128:131], v[132:135], v[176:179], v[128:131]
	v_mfma_f32_16x16x32_bf16 v[124:127], v[140:143], v[176:179], v[124:127]
	v_mfma_f32_16x16x32_bf16 v[120:123], v[132:135], v[192:195], v[120:123]
	v_mfma_f32_16x16x32_bf16 v[116:119], v[140:143], v[192:195], v[116:119]
	v_mfma_f32_16x16x32_bf16 v[112:115], v[132:135], v[200:203], v[112:115]
	v_mfma_f32_16x16x32_bf16 v[108:111], v[140:143], v[200:203], v[108:111]
	v_mfma_f32_16x16x32_bf16 v[104:107], v[132:135], v[208:211], v[104:107]
	v_mfma_f32_16x16x32_bf16 v[100:103], v[140:143], v[208:211], v[100:103]
	v_mfma_f32_16x16x32_bf16 v[128:131], v[136:139], v[188:191], v[128:131]
	v_mfma_f32_16x16x32_bf16 v[124:127], v[144:147], v[188:191], v[124:127]
	v_mfma_f32_16x16x32_bf16 v[120:123], v[136:139], v[196:199], v[120:123]
	v_mfma_f32_16x16x32_bf16 v[116:119], v[144:147], v[196:199], v[116:119]
	v_mfma_f32_16x16x32_bf16 v[112:115], v[136:139], v[204:207], v[112:115]
	v_mfma_f32_16x16x32_bf16 v[108:111], v[144:147], v[204:207], v[108:111]
	v_mfma_f32_16x16x32_bf16 v[104:107], v[136:139], v[220:223], v[104:107]
	v_mfma_f32_16x16x32_bf16 v[100:103], v[144:147], v[220:223], v[100:103]
	v_mfma_f32_16x16x32_bf16 v[96:99], v[148:151], v[176:179], v[96:99]
	v_mfma_f32_16x16x32_bf16 v[92:95], v[168:171], v[176:179], v[92:95]
	v_mfma_f32_16x16x32_bf16 v[88:91], v[148:151], v[192:195], v[88:91]
	v_mfma_f32_16x16x32_bf16 v[84:87], v[168:171], v[192:195], v[84:87]
	v_mfma_f32_16x16x32_bf16 v[80:83], v[148:151], v[200:203], v[80:83]
	v_mfma_f32_16x16x32_bf16 v[76:79], v[168:171], v[200:203], v[76:79]
	v_mfma_f32_16x16x32_bf16 v[72:75], v[148:151], v[208:211], v[72:75]
	v_mfma_f32_16x16x32_bf16 v[68:71], v[168:171], v[208:211], v[68:71]
	v_mfma_f32_16x16x32_bf16 v[96:99], v[152:155], v[188:191], v[96:99]
	v_mfma_f32_16x16x32_bf16 v[92:95], v[172:175], v[188:191], v[92:95]
	v_mfma_f32_16x16x32_bf16 v[88:91], v[152:155], v[196:199], v[88:91]
	v_mfma_f32_16x16x32_bf16 v[84:87], v[172:175], v[196:199], v[84:87]
	v_mfma_f32_16x16x32_bf16 v[80:83], v[152:155], v[204:207], v[80:83]
	v_mfma_f32_16x16x32_bf16 v[76:79], v[172:175], v[204:207], v[76:79]
	v_mfma_f32_16x16x32_bf16 v[72:75], v[152:155], v[220:223], v[72:75]
	v_mfma_f32_16x16x32_bf16 v[68:71], v[172:175], v[220:223], v[68:71]
	s_barrier
	s_add_i32 s54, s57, s15
	v_lshl_add_u64 v[224:225], s[12:13], 0, v[158:159]
	s_mov_b32 m0, s54
	ds_read_b128 v[176:179], v187 offset:16384
	ds_read_b128 v[188:191], v187 offset:17408
	ds_read_b128 v[192:195], v187 offset:18432
	ds_read_b128 v[196:199], v187 offset:19456
	ds_read_b128 v[200:203], v187 offset:20480
	ds_read_b128 v[204:207], v187 offset:21504
	ds_read_b128 v[208:211], v187 offset:22528
	ds_read_b128 v[220:223], v187 offset:23552
	global_load_lds_dwordx4 v[224:225], off
	s_add_i32 m0, s54, 0x2000
	s_add_u32 s54, s12, 0x80000
	v_lshl_add_u64 v[226:227], s[12:13], 0, v[162:163]
	s_addc_u32 s55, s13, 0
	s_add_i32 s56, s58, s15
	global_load_lds_dwordx4 v[226:227], off
	v_lshl_add_u64 v[228:229], s[54:55], 0, v[158:159]
	s_mov_b32 m0, s56
	v_lshl_add_u64 v[230:231], s[52:53], 0, v[160:161]
	global_load_lds_dwordx4 v[228:229], off
	v_lshl_add_u64 v[228:229], s[54:55], 0, v[162:163]
	s_add_i32 m0, s56, 0x2000
	s_nop 0
	global_load_lds_dwordx4 v[228:229], off
	v_lshl_add_u64 v[228:229], s[52:53], 0, v[156:157]
	s_mov_b32 m0, s29
	s_nop 0
	global_load_lds_dwordx4 v[228:229], off
	s_mov_b32 m0, s65
	s_nop 0
	global_load_lds_dwordx4 v[230:231], off
	s_waitcnt vmcnt(8)
	s_waitcnt lgkmcnt(0)
	s_barrier
; #define PG8_STAGE(bufoff, gbase, voff) do { _Pragma("unroll") for (int _i = 0; _i < 2; ++_i) \
;         __builtin_amdgcn_global_load_lds((const unsigned*)((const char*)(gbase) + (voff)[_i]), (PG8_LAS unsigned*)(lds + (bufoff) + ldsw + _i * 8192), 16, 0, 0); } while (0)
; #define PG8_LDA(dst, b, h) do { _Pragma("unroll") for (int m = 0; m < 4; ++m) _Pragma("unroll") for (int k = 0; k < 2; ++k) dst[m][k] = *(const PG8_LAS bf16x8*)(lds + PG8_SA(b, h) + aoff + m * 2048 + k * 1024); } while (0)
; #define PG8_LDB(dst, b, h) do { _Pragma("unroll") for (int n = 0; n < 2; ++n) _Pragma("unroll") for (int k = 0; k < 2; ++k) dst[n][k] = *(const PG8_LAS bf16x8*)(lds + PG8_SB(b, h) + boff + n * 2048 + k * 1024); } while (0)
; #define PG8_MMA(ai, bj, At, Bt) do { __builtin_amdgcn_s_setprio(1); _Pragma("unroll") for (int m = 0; m < 4; ++m) _Pragma("unroll") for (int n = 0; n < 2; ++n) _Pragma("unroll") for (int k = 0; k < 2; ++k) \
;         acc[ai][bj][m][n] = __builtin_amdgcn_mfma_f32_16x16x32_bf16(Bt[n][k], At[m][k], acc[ai][bj][m][n], 0, 0, 0); __builtin_amdgcn_s_setprio(0); } while (0)
; #define PG8_WAIT_V(n) asm volatile("s_waitcnt vmcnt(" #n ")" ::: "memory")
; #define PG8_WAIT_L(n) asm volatile("s_waitcnt lgkmcnt(" #n ")" ::: "memory")
; #define PG8_BAR __builtin_amdgcn_s_barrier()
; #define PG8_SCHED __builtin_amdgcn_sched_barrier(0)
; template <class Epi, class Sched, bool ALIGN_EPI = false, bool SP2 = false>
; __device__ __forceinline__ void gemm_phase(PG8_LAS unsigned char* lds, const Gemm g, const Sched& S, const Epi& E) {
;     ...
;             PG8_WAIT_V(8); PG8_WAIT_L(0); PG8_BAR; PG8_MMA(1, 0, At, B0); PG8_MMA(1, 1, At, B1); PG8_BAR; PG8_SCHED;
;             PG8_LDB(B0, 1, 0); PG8_LDB(B1, 1, 1); PG8_SCHED; PG8_LDA(At, 1, 0); PG8_STAGE(PG8_SA(0, 1), a2 + hstep, voffA);
;             PG8_WAIT_V(8); PG8_WAIT_L(0); PG8_BAR; PG8_MMA(0, 0, At, B0); PG8_MMA(0, 1, At, B1); PG8_BAR; PG8_SCHED;
	v_mfma_f32_16x16x32_bf16 v[62:65], v[132:135], v[176:179], v[62:65]
	v_mfma_f32_16x16x32_bf16 v[58:61], v[140:143], v[176:179], v[58:61]
	v_mfma_f32_16x16x32_bf16 v[54:57], v[132:135], v[192:195], v[54:57]
	v_mfma_f32_16x16x32_bf16 v[50:53], v[140:143], v[192:195], v[50:53]
	v_mfma_f32_16x16x32_bf16 v[46:49], v[132:135], v[200:203], v[46:49]
	v_mfma_f32_16x16x32_bf16 v[42:45], v[140:143], v[200:203], v[42:45]
	v_mfma_f32_16x16x32_bf16 v[38:41], v[132:135], v[208:211], v[38:41]
	v_mfma_f32_16x16x32_bf16 v[34:37], v[140:143], v[208:211], v[34:37]
	v_mfma_f32_16x16x32_bf16 v[62:65], v[136:139], v[188:191], v[62:65]
	v_mfma_f32_16x16x32_bf16 v[58:61], v[144:147], v[188:191], v[58:61]
	v_mfma_f32_16x16x32_bf16 v[54:57], v[136:139], v[196:199], v[54:57]
	v_mfma_f32_16x16x32_bf16 v[50:53], v[144:147], v[196:199], v[50:53]
	v_mfma_f32_16x16x32_bf16 v[46:49], v[136:139], v[204:207], v[46:49]
	v_mfma_f32_16x16x32_bf16 v[42:45], v[144:147], v[204:207], v[42:45]
	v_mfma_f32_16x16x32_bf16 v[38:41], v[136:139], v[220:223], v[38:41]
	v_mfma_f32_16x16x32_bf16 v[34:37], v[144:147], v[220:223], v[34:37]
	v_mfma_f32_16x16x32_bf16 v[30:33], v[148:151], v[176:179], v[30:33]
	v_mfma_f32_16x16x32_bf16 v[26:29], v[168:171], v[176:179], v[26:29]
	v_mfma_f32_16x16x32_bf16 v[22:25], v[148:151], v[192:195], v[22:25]
	v_mfma_f32_16x16x32_bf16 v[18:21], v[168:171], v[192:195], v[18:21]
	v_mfma_f32_16x16x32_bf16 v[14:17], v[148:151], v[200:203], v[14:17]
	v_mfma_f32_16x16x32_bf16 v[10:13], v[168:171], v[200:203], v[10:13]
	v_mfma_f32_16x16x32_bf16 v[6:9], v[148:151], v[208:211], v[6:9]
	v_mfma_f32_16x16x32_bf16 v[2:5], v[168:171], v[208:211], v[2:5]
	v_mfma_f32_16x16x32_bf16 v[30:33], v[152:155], v[188:191], v[30:33]
	v_mfma_f32_16x16x32_bf16 v[26:29], v[172:175], v[188:191], v[26:29]
	v_mfma_f32_16x16x32_bf16 v[22:25], v[152:155], v[196:199], v[22:25]
	v_mfma_f32_16x16x32_bf16 v[18:21], v[172:175], v[196:199], v[18:21]
	v_mfma_f32_16x16x32_bf16 v[14:17], v[152:155], v[204:207], v[14:17]
	v_mfma_f32_16x16x32_bf16 v[10:13], v[172:175], v[204:207], v[10:13]
	v_mfma_f32_16x16x32_bf16 v[6:9], v[152:155], v[220:223], v[6:9]
	v_mfma_f32_16x16x32_bf16 v[2:5], v[172:175], v[220:223], v[2:5]
	s_barrier
	s_add_i32 s54, 0, 0x18000
	v_add_u32_e32 v0, s54, v181
	s_add_i32 s55, 0, 0x1c000
	ds_read_b128 v[132:135], v0
	ds_read_b128 v[136:139], v0 offset:1024
	ds_read_b128 v[140:143], v0 offset:2048
	ds_read_b128 v[144:147], v0 offset:3072
	v_add_u32_e32 v0, s55, v181
	ds_read_b128 v[148:151], v0
	ds_read_b128 v[152:155], v0 offset:1024
	ds_read_b128 v[168:171], v0 offset:2048
	ds_read_b128 v[172:175], v0 offset:3072
	s_add_u32 s52, s52, 0x80000
	s_addc_u32 s53, s53, 0
	s_mov_b32 m0, s66
	v_lshl_add_u64 v[232:233], s[52:53], 0, v[156:157]
	ds_read_b128 v[176:179], v187 offset:32768
	ds_read_b128 v[188:191], v187 offset:33792
	ds_read_b128 v[192:195], v187 offset:34816
	ds_read_b128 v[196:199], v187 offset:35840
	ds_read_b128 v[200:203], v187 offset:36864
	ds_read_b128 v[204:207], v187 offset:37888
	ds_read_b128 v[208:211], v187 offset:38912
	ds_read_b128 v[220:223], v187 offset:39936
	global_load_lds_dwordx4 v[232:233], off
	v_lshl_add_u64 v[232:233], s[52:53], 0, v[160:161]
	s_mov_b32 m0, s67
	s_nop 0
	global_load_lds_dwordx4 v[232:233], off
	s_waitcnt vmcnt(8)
	s_waitcnt lgkmcnt(0)
	s_barrier
	v_mfma_f32_16x16x32_bf16 v[128:131], v[132:135], v[176:179], v[128:131]
	v_mfma_f32_16x16x32_bf16 v[124:127], v[140:143], v[176:179], v[124:127]
	v_mfma_f32_16x16x32_bf16 v[120:123], v[132:135], v[192:195], v[120:123]
	v_mfma_f32_16x16x32_bf16 v[116:119], v[140:143], v[192:195], v[116:119]
	v_mfma_f32_16x16x32_bf16 v[112:115], v[132:135], v[200:203], v[112:115]
	v_mfma_f32_16x16x32_bf16 v[108:111], v[140:143], v[200:203], v[108:111]
	v_mfma_f32_16x16x32_bf16 v[104:107], v[132:135], v[208:211], v[104:107]
	v_mfma_f32_16x16x32_bf16 v[100:103], v[140:143], v[208:211], v[100:103]
	v_mfma_f32_16x16x32_bf16 v[128:131], v[136:139], v[188:191], v[128:131]
	v_mfma_f32_16x16x32_bf16 v[124:127], v[144:147], v[188:191], v[124:127]
	v_mfma_f32_16x16x32_bf16 v[120:123], v[136:139], v[196:199], v[120:123]
	v_mfma_f32_16x16x32_bf16 v[116:119], v[144:147], v[196:199], v[116:119]
	v_mfma_f32_16x16x32_bf16 v[112:115], v[136:139], v[204:207], v[112:115]
	v_mfma_f32_16x16x32_bf16 v[108:111], v[144:147], v[204:207], v[108:111]
	v_mfma_f32_16x16x32_bf16 v[104:107], v[136:139], v[220:223], v[104:107]
	v_mfma_f32_16x16x32_bf16 v[100:103], v[144:147], v[220:223], v[100:103]
	v_mfma_f32_16x16x32_bf16 v[96:99], v[148:151], v[176:179], v[96:99]
	v_mfma_f32_16x16x32_bf16 v[92:95], v[168:171], v[176:179], v[92:95]
	v_mfma_f32_16x16x32_bf16 v[88:91], v[148:151], v[192:195], v[88:91]
	v_mfma_f32_16x16x32_bf16 v[84:87], v[168:171], v[192:195], v[84:87]
	v_mfma_f32_16x16x32_bf16 v[80:83], v[148:151], v[200:203], v[80:83]
	v_mfma_f32_16x16x32_bf16 v[76:79], v[168:171], v[200:203], v[76:79]
	v_mfma_f32_16x16x32_bf16 v[72:75], v[148:151], v[208:211], v[72:75]
	v_mfma_f32_16x16x32_bf16 v[68:71], v[168:171], v[208:211], v[68:71]
	v_mfma_f32_16x16x32_bf16 v[96:99], v[152:155], v[188:191], v[96:99]
	v_mfma_f32_16x16x32_bf16 v[92:95], v[172:175], v[188:191], v[92:95]
	v_mfma_f32_16x16x32_bf16 v[88:91], v[152:155], v[196:199], v[88:91]
	v_mfma_f32_16x16x32_bf16 v[84:87], v[172:175], v[196:199], v[84:87]
	v_mfma_f32_16x16x32_bf16 v[80:83], v[152:155], v[204:207], v[80:83]
	v_mfma_f32_16x16x32_bf16 v[76:79], v[172:175], v[204:207], v[76:79]
	v_mfma_f32_16x16x32_bf16 v[72:75], v[152:155], v[220:223], v[72:75]
	v_mfma_f32_16x16x32_bf16 v[68:71], v[172:175], v[220:223], v[68:71]
	s_barrier
; #define PG8_STAGE(bufoff, gbase, voff) do { _Pragma("unroll") for (int _i = 0; _i < 2; ++_i) \
;         __builtin_amdgcn_global_load_lds((const unsigned*)((const char*)(gbase) + (voff)[_i]), (PG8_LAS unsigned*)(lds + (bufoff) + ldsw + _i * 8192), 16, 0, 0); } while (0)
; #define PG8_LDA(dst, b, h) do { _Pragma("unroll") for (int m = 0; m < 4; ++m) _Pragma("unroll") for (int k = 0; k < 2; ++k) dst[m][k] = *(const PG8_LAS bf16x8*)(lds + PG8_SA(b, h) + aoff + m * 2048 + k * 1024); } while (0)
; #define PG8_MMA(ai, bj, At, Bt) do { __builtin_amdgcn_s_setprio(1); _Pragma("unroll") for (int m = 0; m < 4; ++m) _Pragma("unroll") for (int n = 0; n < 2; ++n) _Pragma("unroll") for (int k = 0; k < 2; ++k) \
;         acc[ai][bj][m][n] = __builtin_amdgcn_mfma_f32_16x16x32_bf16(Bt[n][k], At[m][k], acc[ai][bj][m][n], 0, 0, 0); __builtin_amdgcn_s_setprio(0); } while (0)
; #define PG8_WAIT_V(n) asm volatile("s_waitcnt vmcnt(" #n ")" ::: "memory")
; #define PG8_WAIT_L(n) asm volatile("s_waitcnt lgkmcnt(" #n ")" ::: "memory")
; #define PG8_BAR __builtin_amdgcn_s_barrier()
; #define PG8_SCHED __builtin_amdgcn_sched_barrier(0)
; template <class Epi, class Sched, bool ALIGN_EPI = false, bool SP2 = false>
; __device__ __forceinline__ void gemm_phase(PG8_LAS unsigned char* lds, const Gemm g, const Sched& S, const Epi& E) {
;     ...
;             PG8_LDA(At, 1, 1); PG8_STAGE(PG8_SB(1, 0), b3, voffB); PG8_STAGE(PG8_SB(1, 1), b3 + hstep, voffB); PG8_STAGE(PG8_SA(1, 0), a3, voffA);
;             PG8_WAIT_V(8); PG8_WAIT_L(0); PG8_BAR; PG8_MMA(1, 0, At, B0); PG8_MMA(1, 1, At, B1); PG8_BAR; PG8_SCHED;
	s_add_i32 s52, s54, s15
	v_lshl_add_u64 v[224:225], v[224:225], 0, s[88:89]
	s_mov_b32 m0, s52
	ds_read_b128 v[176:179], v187 offset:49152
	ds_read_b128 v[188:191], v187 offset:50176
	ds_read_b128 v[192:195], v187 offset:51200
	ds_read_b128 v[196:199], v187 offset:52224
	ds_read_b128 v[200:203], v187 offset:53248
	ds_read_b128 v[204:207], v187 offset:54272
	ds_read_b128 v[208:211], v187 offset:55296
	ds_read_b128 v[220:223], v187 offset:56320
	global_load_lds_dwordx4 v[224:225], off
	s_add_i32 m0, s52, 0x2000
	s_add_u32 s12, s12, 0x80080
	v_lshl_add_u64 v[224:225], v[226:227], 0, s[88:89]
	s_addc_u32 s13, s13, 0
	s_add_i32 s52, s55, s15
	global_load_lds_dwordx4 v[224:225], off
	v_lshl_add_u64 v[224:225], s[12:13], 0, v[158:159]
	s_mov_b32 m0, s52
	s_nop 0
	global_load_lds_dwordx4 v[224:225], off
	v_lshl_add_u64 v[224:225], s[12:13], 0, v[162:163]
	s_add_i32 m0, s52, 0x2000
	s_nop 0
	global_load_lds_dwordx4 v[224:225], off
	v_lshl_add_u64 v[224:225], v[228:229], 0, s[88:89]
	s_mov_b32 m0, s69
	s_nop 0
	global_load_lds_dwordx4 v[224:225], off
	v_lshl_add_u64 v[224:225], v[230:231], 0, s[88:89]
	s_mov_b32 m0, s70
	s_nop 0
	global_load_lds_dwordx4 v[224:225], off
	s_waitcnt vmcnt(8)
	s_waitcnt lgkmcnt(0)
	s_barrier
	v_mfma_f32_16x16x32_bf16 v[62:65], v[132:135], v[176:179], v[62:65]
	v_mfma_f32_16x16x32_bf16 v[58:61], v[140:143], v[176:179], v[58:61]
	v_mfma_f32_16x16x32_bf16 v[54:57], v[132:135], v[192:195], v[54:57]
	v_mfma_f32_16x16x32_bf16 v[50:53], v[140:143], v[192:195], v[50:53]
	v_mfma_f32_16x16x32_bf16 v[46:49], v[132:135], v[200:203], v[46:49]
	v_mfma_f32_16x16x32_bf16 v[42:45], v[140:143], v[200:203], v[42:45]
	v_mfma_f32_16x16x32_bf16 v[38:41], v[132:135], v[208:211], v[38:41]
	v_mfma_f32_16x16x32_bf16 v[34:37], v[140:143], v[208:211], v[34:37]
	v_mfma_f32_16x16x32_bf16 v[62:65], v[136:139], v[188:191], v[62:65]
	v_mfma_f32_16x16x32_bf16 v[58:61], v[144:147], v[188:191], v[58:61]
	v_mfma_f32_16x16x32_bf16 v[54:57], v[136:139], v[196:199], v[54:57]
	v_mfma_f32_16x16x32_bf16 v[50:53], v[144:147], v[196:199], v[50:53]
	v_mfma_f32_16x16x32_bf16 v[46:49], v[136:139], v[204:207], v[46:49]
	v_mfma_f32_16x16x32_bf16 v[42:45], v[144:147], v[204:207], v[42:45]
	v_mfma_f32_16x16x32_bf16 v[38:41], v[136:139], v[220:223], v[38:41]
	v_mfma_f32_16x16x32_bf16 v[34:37], v[144:147], v[220:223], v[34:37]
	v_mfma_f32_16x16x32_bf16 v[30:33], v[148:151], v[176:179], v[30:33]
	v_mfma_f32_16x16x32_bf16 v[26:29], v[168:171], v[176:179], v[26:29]
	v_mfma_f32_16x16x32_bf16 v[22:25], v[148:151], v[192:195], v[22:25]
	v_mfma_f32_16x16x32_bf16 v[18:21], v[168:171], v[192:195], v[18:21]
	v_mfma_f32_16x16x32_bf16 v[14:17], v[148:151], v[200:203], v[14:17]
	v_mfma_f32_16x16x32_bf16 v[10:13], v[168:171], v[200:203], v[10:13]
	v_mfma_f32_16x16x32_bf16 v[6:9], v[148:151], v[208:211], v[6:9]
	v_mfma_f32_16x16x32_bf16 v[2:5], v[168:171], v[208:211], v[2:5]
	v_mfma_f32_16x16x32_bf16 v[30:33], v[152:155], v[188:191], v[30:33]
	v_mfma_f32_16x16x32_bf16 v[26:29], v[172:175], v[188:191], v[26:29]
	v_mfma_f32_16x16x32_bf16 v[22:25], v[152:155], v[196:199], v[22:25]
	v_mfma_f32_16x16x32_bf16 v[18:21], v[172:175], v[196:199], v[18:21]
	v_mfma_f32_16x16x32_bf16 v[14:17], v[152:155], v[204:207], v[14:17]
	v_mfma_f32_16x16x32_bf16 v[10:13], v[172:175], v[204:207], v[10:13]
	v_mfma_f32_16x16x32_bf16 v[6:9], v[152:155], v[220:223], v[6:9]
	v_mfma_f32_16x16x32_bf16 v[2:5], v[172:175], v[220:223], v[2:5]
	s_barrier
	s_add_i32 s12, s43, 2
	s_cmp_gt_u32 s43, 29
	s_cbranch_scc1 .LBB0_400
	s_mov_b32 s43, s12
	s_branch .LBB0_384
	s_nop 0
	s_nop 0
	s_nop 0
	s_nop 0
	s_nop 0
	s_nop 0
	s_nop 0
	s_nop 0
	s_nop 0
	s_nop 0
	s_nop 0
	s_nop 0
	s_nop 0
	s_nop 0
	s_nop 0
	s_nop 0
	s_nop 0
	s_nop 0
	s_nop 0
	s_nop 0

;     __host__ __device__ bool next(int i, Unit& u) const { if (i != 0 || r < 0 || r >= 148) return false; if (r < 116) { u.pm = r % 29; u.pn = 47 + r / 29; } else { u.pm = 32; u.pn = 19 + (r - 116); } u.ko = 0; return true; }
;     __host__ __device__ bool next(int i, Unit& u) const { const int L = i * G + (G - 1 - c); if (L >= nN * S) return false; u.pm = pm; u.pn = L % nN; u.ko = (L / nN) * ksub; return true; }
; #define PG8_STAGE(bufoff, gbase, voff) do { _Pragma("unroll") for (int _i = 0; _i < 2; ++_i) \
;         __builtin_amdgcn_global_load_lds((const unsigned*)((const char*)(gbase) + (voff)[_i]), (PG8_LAS unsigned*)(lds + (bufoff) + ldsw + _i * 8192), 16, 0, 0); } while (0)
; #define PG8_LDA(dst, b, h) do { _Pragma("unroll") for (int m = 0; m < 4; ++m) _Pragma("unroll") for (int k = 0; k < 2; ++k) dst[m][k] = *(const PG8_LAS bf16x8*)(lds + PG8_SA(b, h) + aoff + m * 2048 + k * 1024); } while (0)
; #define PG8_BAR __builtin_amdgcn_s_barrier()
; template <class Epi, class Sched, bool ALIGN_EPI = false, bool SP2 = false>
; __device__ __forceinline__ void gemm_phase(PG8_LAS unsigned char* lds, const Gemm g, const Sched& S, const Epi& E) {
;     ...
;         const bool has_next = S.next(ui + 1, nxt);
;         const char* nA = has_next ? (const char*)g.A + (size_t)nxt.pm * tstep + (size_t)nxt.ko * 2 : cA; const char* nB = has_next ? (const char*)g.Bt + (size_t)nxt.pn * tstep + (size_t)nxt.ko * 2 : cB;
;         for (int t = 0; t < nt; t += 2) {
;             const bool last = (t == nt - 2);
;             const char* a1 = cA + (size_t)(t + 1) * kstep;
;             const char* a2 = last ? nA : cA + (size_t)(t + 2) * kstep; const char* b2 = last ? nB : cB + (size_t)(t + 2) * kstep;
;             const char* a3 = a2 + kstep; const char* b3 = b2 + kstep;
;             if (last && has_next) S.a_ready(nxt);
;             if constexpr (SP2) {
;             PG8_LDB(B0, 0, 0); PG8_LDB(B1, 0, 1); PG8_SCHED; PG8_LDA(At, 0, 0); PG8_STAGE(PG8_SA(1, 1), a1 + hstep, voffA);
;             PG8_WAIT_V(8); PG8_WAIT_L(0); PG8_BAR; PG8_MMA(0, 0, At, B0); PG8_MMA(0, 1, At, B1); PG8_BAR; PG8_SCHED;
;             PG8_LDA(At, 0, 1); PG8_STAGE(PG8_SB(0, 0), b2, voffB); PG8_STAGE(PG8_SB(0, 1), b2 + hstep, voffB); PG8_STAGE(PG8_SA(0, 0), a2, voffA);
;             PG8_WAIT_V(8); PG8_WAIT_L(0); PG8_BAR; PG8_MMA(1, 0, At, B0); PG8_MMA(1, 1, At, B1); PG8_BAR; PG8_SCHED;
.LBB0_702:
	s_add_u32 s14, s26, s12
	s_addc_u32 s15, s27, s13
	s_add_u32 s14, s14, 0x5800100
	s_addc_u32 s15, s15, 0
	s_add_u32 s31, s28, s12
	s_addc_u32 s34, s29, s13
	s_add_i32 s35, 0, 0x10000
	s_cmpk_eq_i32 s12, 0xf00
	s_cselect_b32 s17, s9, s15
	s_cselect_b32 s16, s8, s14
	v_add_u32_e32 v89, s35, v87
	s_cselect_b32 s15, s7, s34
	s_cselect_b32 s14, s6, s31
	s_add_i32 s31, 0, 0x14000
	ds_read_b128 v[148:151], v89
	ds_read_b128 v[152:155], v89 offset:1024
	ds_read_b128 v[156:159], v89 offset:2048
	ds_read_b128 v[160:163], v89 offset:3072
	v_add_u32_e32 v89, s31, v87
	ds_read_b128 v[166:169], v89
	ds_read_b128 v[170:173], v89 offset:1024
	ds_read_b128 v[174:177], v89 offset:2048
	ds_read_b128 v[178:181], v89 offset:3072
	v_lshl_add_u64 v[90:91], v[74:75], 0, s[12:13]
	s_add_i32 m0, s20, 0xc000
	ds_read_b128 v[182:185], v88
	ds_read_b128 v[186:189], v88 offset:1024
	ds_read_b128 v[190:193], v88 offset:2048
	ds_read_b128 v[194:197], v88 offset:3072
	ds_read_b128 v[200:203], v88 offset:4096
	ds_read_b128 v[204:207], v88 offset:5120
	ds_read_b128 v[208:211], v88 offset:6144
	ds_read_b128 v[220:223], v88 offset:7168
	global_load_lds_dwordx4 v[90:91], off
	v_lshl_add_u64 v[90:91], v[84:85], 0, s[12:13]
	s_add_i32 m0, s20, 0xe000
	s_nop 0
	global_load_lds_dwordx4 v[90:91], off
	s_waitcnt vmcnt(8)
	s_waitcnt lgkmcnt(0)
	s_barrier
	v_mfma_f32_16x16x32_bf16 v[144:147], v[148:151], v[182:185], v[144:147]
	v_mfma_f32_16x16x32_bf16 v[140:143], v[156:159], v[182:185], v[140:143]
	v_mfma_f32_16x16x32_bf16 v[128:131], v[148:151], v[190:193], v[128:131]
	v_mfma_f32_16x16x32_bf16 v[124:127], v[156:159], v[190:193], v[124:127]
	v_mfma_f32_16x16x32_bf16 v[112:115], v[148:151], v[200:203], v[112:115]
	v_mfma_f32_16x16x32_bf16 v[108:111], v[156:159], v[200:203], v[108:111]
	v_mfma_f32_16x16x32_bf16 v[96:99], v[148:151], v[208:211], v[96:99]
	v_mfma_f32_16x16x32_bf16 v[90:93], v[156:159], v[208:211], v[92:95]
	v_mfma_f32_16x16x32_bf16 v[144:147], v[152:155], v[186:189], v[144:147]
	v_mfma_f32_16x16x32_bf16 v[140:143], v[160:163], v[186:189], v[140:143]
	v_mfma_f32_16x16x32_bf16 v[128:131], v[152:155], v[194:197], v[128:131]
	v_mfma_f32_16x16x32_bf16 v[124:127], v[160:163], v[194:197], v[124:127]
	v_mfma_f32_16x16x32_bf16 v[112:115], v[152:155], v[204:207], v[112:115]
	v_mfma_f32_16x16x32_bf16 v[108:111], v[160:163], v[204:207], v[108:111]
	v_mfma_f32_16x16x32_bf16 v[96:99], v[152:155], v[220:223], v[96:99]
	v_mfma_f32_16x16x32_bf16 v[90:93], v[160:163], v[220:223], v[90:93]
	v_mfma_f32_16x16x32_bf16 v[136:139], v[166:169], v[182:185], v[136:139]
	v_mfma_f32_16x16x32_bf16 v[132:135], v[174:177], v[182:185], v[132:135]
	v_mfma_f32_16x16x32_bf16 v[120:123], v[166:169], v[190:193], v[120:123]
	v_mfma_f32_16x16x32_bf16 v[116:119], v[174:177], v[190:193], v[116:119]
	v_mfma_f32_16x16x32_bf16 v[104:107], v[166:169], v[200:203], v[104:107]
	v_mfma_f32_16x16x32_bf16 v[100:103], v[174:177], v[200:203], v[100:103]
	v_mfma_f32_16x16x32_bf16 v[80:83], v[166:169], v[208:211], v[80:83]
	v_mfma_f32_16x16x32_bf16 v[76:79], v[174:177], v[208:211], v[76:79]
	v_mfma_f32_16x16x32_bf16 v[136:139], v[170:173], v[186:189], v[136:139]
	v_mfma_f32_16x16x32_bf16 v[132:135], v[178:181], v[186:189], v[132:135]
	v_mfma_f32_16x16x32_bf16 v[120:123], v[170:173], v[194:197], v[120:123]
	v_mfma_f32_16x16x32_bf16 v[116:119], v[178:181], v[194:197], v[116:119]
	v_mfma_f32_16x16x32_bf16 v[104:107], v[170:173], v[204:207], v[104:107]
	v_mfma_f32_16x16x32_bf16 v[100:103], v[178:181], v[204:207], v[100:103]
	v_mfma_f32_16x16x32_bf16 v[80:83], v[170:173], v[220:223], v[80:83]
	v_mfma_f32_16x16x32_bf16 v[76:79], v[178:181], v[220:223], v[76:79]
	s_barrier
	s_add_i32 s34, s35, s18
	v_lshl_add_u64 v[224:225], s[14:15], 0, v[66:67]
	s_mov_b32 m0, s34
	ds_read_b128 v[182:185], v88 offset:16384
	ds_read_b128 v[186:189], v88 offset:17408
	ds_read_b128 v[190:193], v88 offset:18432
	ds_read_b128 v[194:197], v88 offset:19456
	ds_read_b128 v[200:203], v88 offset:20480
	ds_read_b128 v[204:207], v88 offset:21504
	ds_read_b128 v[208:211], v88 offset:22528
	ds_read_b128 v[220:223], v88 offset:23552
	global_load_lds_dwordx4 v[224:225], off
	s_add_i32 m0, s34, 0x2000
	s_add_u32 s34, s14, 0x80000
	v_lshl_add_u64 v[226:227], s[14:15], 0, v[72:73]
	s_addc_u32 s35, s15, 0
	s_add_i32 s31, s31, s18
	global_load_lds_dwordx4 v[226:227], off
	v_lshl_add_u64 v[94:95], s[34:35], 0, v[66:67]
	s_mov_b32 m0, s31
	v_lshl_add_u64 v[228:229], s[16:17], 0, v[68:69]
	global_load_lds_dwordx4 v[94:95], off
	v_lshl_add_u64 v[94:95], s[34:35], 0, v[72:73]
	s_add_i32 m0, s31, 0x2000
	v_lshl_add_u64 v[230:231], s[16:17], 0, v[70:71]
	global_load_lds_dwordx4 v[94:95], off
	s_mov_b32 m0, s20
	s_nop 0
	global_load_lds_dwordx4 v[228:229], off
	s_mov_b32 m0, s3
	s_nop 0
	global_load_lds_dwordx4 v[230:231], off
	s_waitcnt vmcnt(8)
	s_waitcnt lgkmcnt(0)
	s_barrier
; #define PG8_STAGE(bufoff, gbase, voff) do { _Pragma("unroll") for (int _i = 0; _i < 2; ++_i) \
;         __builtin_amdgcn_global_load_lds((const unsigned*)((const char*)(gbase) + (voff)[_i]), (PG8_LAS unsigned*)(lds + (bufoff) + ldsw + _i * 8192), 16, 0, 0); } while (0)
; #define PG8_LDA(dst, b, h) do { _Pragma("unroll") for (int m = 0; m < 4; ++m) _Pragma("unroll") for (int k = 0; k < 2; ++k) dst[m][k] = *(const PG8_LAS bf16x8*)(lds + PG8_SA(b, h) + aoff + m * 2048 + k * 1024); } while (0)
; #define PG8_LDB(dst, b, h) do { _Pragma("unroll") for (int n = 0; n < 2; ++n) _Pragma("unroll") for (int k = 0; k < 2; ++k) dst[n][k] = *(const PG8_LAS bf16x8*)(lds + PG8_SB(b, h) + boff + n * 2048 + k * 1024); } while (0)
; #define PG8_MMA(ai, bj, At, Bt) do { __builtin_amdgcn_s_setprio(1); _Pragma("unroll") for (int m = 0; m < 4; ++m) _Pragma("unroll") for (int n = 0; n < 2; ++n) _Pragma("unroll") for (int k = 0; k < 2; ++k) \
;         acc[ai][bj][m][n] = __builtin_amdgcn_mfma_f32_16x16x32_bf16(Bt[n][k], At[m][k], acc[ai][bj][m][n], 0, 0, 0); __builtin_amdgcn_s_setprio(0); } while (0)
; #define PG8_WAIT_V(n) asm volatile("s_waitcnt vmcnt(" #n ")" ::: "memory")
; #define PG8_WAIT_L(n) asm volatile("s_waitcnt lgkmcnt(" #n ")" ::: "memory")
; #define PG8_BAR __builtin_amdgcn_s_barrier()
; #define PG8_SCHED __builtin_amdgcn_sched_barrier(0)
; template <class Epi, class Sched, bool ALIGN_EPI = false, bool SP2 = false>
; __device__ __forceinline__ void gemm_phase(PG8_LAS unsigned char* lds, const Gemm g, const Sched& S, const Epi& E) {
;     ...
;             PG8_WAIT_V(8); PG8_WAIT_L(0); PG8_BAR; PG8_MMA(1, 0, At, B0); PG8_MMA(1, 1, At, B1); PG8_BAR; PG8_SCHED;
;             PG8_LDB(B0, 1, 0); PG8_LDB(B1, 1, 1); PG8_SCHED; PG8_LDA(At, 1, 0); PG8_STAGE(PG8_SA(0, 1), a2 + hstep, voffA);
;             PG8_WAIT_V(8); PG8_WAIT_L(0); PG8_BAR; PG8_MMA(0, 0, At, B0); PG8_MMA(0, 1, At, B1); PG8_BAR; PG8_SCHED;
	v_mfma_f32_16x16x32_bf16 v[62:65], v[148:151], v[182:185], v[62:65]
	v_mfma_f32_16x16x32_bf16 v[58:61], v[156:159], v[182:185], v[58:61]
	v_mfma_f32_16x16x32_bf16 v[46:49], v[148:151], v[190:193], v[46:49]
	v_mfma_f32_16x16x32_bf16 v[42:45], v[156:159], v[190:193], v[42:45]
	v_mfma_f32_16x16x32_bf16 v[30:33], v[148:151], v[200:203], v[30:33]
	v_mfma_f32_16x16x32_bf16 v[26:29], v[156:159], v[200:203], v[26:29]
	v_mfma_f32_16x16x32_bf16 v[14:17], v[148:151], v[208:211], v[14:17]
	v_mfma_f32_16x16x32_bf16 v[10:13], v[156:159], v[208:211], v[10:13]
	v_mfma_f32_16x16x32_bf16 v[62:65], v[152:155], v[186:189], v[62:65]
	v_mfma_f32_16x16x32_bf16 v[58:61], v[160:163], v[186:189], v[58:61]
	v_mfma_f32_16x16x32_bf16 v[46:49], v[152:155], v[194:197], v[46:49]
	v_mfma_f32_16x16x32_bf16 v[42:45], v[160:163], v[194:197], v[42:45]
	v_mfma_f32_16x16x32_bf16 v[30:33], v[152:155], v[204:207], v[30:33]
	v_mfma_f32_16x16x32_bf16 v[26:29], v[160:163], v[204:207], v[26:29]
	v_mfma_f32_16x16x32_bf16 v[14:17], v[152:155], v[220:223], v[14:17]
	v_mfma_f32_16x16x32_bf16 v[10:13], v[160:163], v[220:223], v[10:13]
	v_mfma_f32_16x16x32_bf16 v[54:57], v[166:169], v[182:185], v[54:57]
	v_mfma_f32_16x16x32_bf16 v[50:53], v[174:177], v[182:185], v[50:53]
	v_mfma_f32_16x16x32_bf16 v[38:41], v[166:169], v[190:193], v[38:41]
	v_mfma_f32_16x16x32_bf16 v[34:37], v[174:177], v[190:193], v[34:37]
	v_mfma_f32_16x16x32_bf16 v[22:25], v[166:169], v[200:203], v[22:25]
	v_mfma_f32_16x16x32_bf16 v[18:21], v[174:177], v[200:203], v[18:21]
	v_mfma_f32_16x16x32_bf16 v[6:9], v[166:169], v[208:211], v[6:9]
	v_mfma_f32_16x16x32_bf16 v[2:5], v[174:177], v[208:211], v[2:5]
	v_mfma_f32_16x16x32_bf16 v[54:57], v[170:173], v[186:189], v[54:57]
	v_mfma_f32_16x16x32_bf16 v[50:53], v[178:181], v[186:189], v[50:53]
	v_mfma_f32_16x16x32_bf16 v[38:41], v[170:173], v[194:197], v[38:41]
	v_mfma_f32_16x16x32_bf16 v[34:37], v[178:181], v[194:197], v[34:37]
	v_mfma_f32_16x16x32_bf16 v[22:25], v[170:173], v[204:207], v[22:25]
	v_mfma_f32_16x16x32_bf16 v[18:21], v[178:181], v[204:207], v[18:21]
	v_mfma_f32_16x16x32_bf16 v[6:9], v[170:173], v[220:223], v[6:9]
	v_mfma_f32_16x16x32_bf16 v[2:5], v[178:181], v[220:223], v[2:5]
	s_barrier
	s_add_i32 s31, 0, 0x18000
	v_add_u32_e32 v89, s31, v87
	s_add_i32 s34, 0, 0x1c000
	ds_read_b128 v[148:151], v89
	ds_read_b128 v[152:155], v89 offset:1024
	ds_read_b128 v[156:159], v89 offset:2048
	ds_read_b128 v[160:163], v89 offset:3072
	v_add_u32_e32 v89, s34, v87
	ds_read_b128 v[166:169], v89
	ds_read_b128 v[170:173], v89 offset:1024
	ds_read_b128 v[174:177], v89 offset:2048
	ds_read_b128 v[178:181], v89 offset:3072
	s_add_u32 s16, s16, 0x80000
	s_addc_u32 s17, s17, 0
	s_mov_b32 m0, s21
	v_lshl_add_u64 v[94:95], s[16:17], 0, v[68:69]
	ds_read_b128 v[182:185], v88 offset:32768
	ds_read_b128 v[186:189], v88 offset:33792
	ds_read_b128 v[190:193], v88 offset:34816
	ds_read_b128 v[194:197], v88 offset:35840
	ds_read_b128 v[200:203], v88 offset:36864
	ds_read_b128 v[204:207], v88 offset:37888
	ds_read_b128 v[208:211], v88 offset:38912
	ds_read_b128 v[220:223], v88 offset:39936
	global_load_lds_dwordx4 v[94:95], off
	v_lshl_add_u64 v[94:95], s[16:17], 0, v[70:71]
	s_mov_b32 m0, s22
	s_nop 0
	global_load_lds_dwordx4 v[94:95], off
	s_waitcnt vmcnt(8)
	s_waitcnt lgkmcnt(0)
	s_barrier
	v_mfma_f32_16x16x32_bf16 v[144:147], v[148:151], v[182:185], v[144:147]
	v_mfma_f32_16x16x32_bf16 v[140:143], v[156:159], v[182:185], v[140:143]
	v_mfma_f32_16x16x32_bf16 v[128:131], v[148:151], v[190:193], v[128:131]
	v_mfma_f32_16x16x32_bf16 v[124:127], v[156:159], v[190:193], v[124:127]
	v_mfma_f32_16x16x32_bf16 v[112:115], v[148:151], v[200:203], v[112:115]
	v_mfma_f32_16x16x32_bf16 v[108:111], v[156:159], v[200:203], v[108:111]
	v_mfma_f32_16x16x32_bf16 v[94:97], v[148:151], v[208:211], v[96:99]
	v_mfma_f32_16x16x32_bf16 v[90:93], v[156:159], v[208:211], v[90:93]
	v_mfma_f32_16x16x32_bf16 v[144:147], v[152:155], v[186:189], v[144:147]
	v_mfma_f32_16x16x32_bf16 v[140:143], v[160:163], v[186:189], v[140:143]
	v_mfma_f32_16x16x32_bf16 v[128:131], v[152:155], v[194:197], v[128:131]
	v_mfma_f32_16x16x32_bf16 v[124:127], v[160:163], v[194:197], v[124:127]
	v_mfma_f32_16x16x32_bf16 v[112:115], v[152:155], v[204:207], v[112:115]
	v_mfma_f32_16x16x32_bf16 v[108:111], v[160:163], v[204:207], v[108:111]
	v_mfma_f32_16x16x32_bf16 v[96:99], v[152:155], v[220:223], v[94:97]
	v_mfma_f32_16x16x32_bf16 v[92:95], v[160:163], v[220:223], v[90:93]
	v_mfma_f32_16x16x32_bf16 v[136:139], v[166:169], v[182:185], v[136:139]
	v_mfma_f32_16x16x32_bf16 v[132:135], v[174:177], v[182:185], v[132:135]
	v_mfma_f32_16x16x32_bf16 v[120:123], v[166:169], v[190:193], v[120:123]
	v_mfma_f32_16x16x32_bf16 v[116:119], v[174:177], v[190:193], v[116:119]
	v_mfma_f32_16x16x32_bf16 v[104:107], v[166:169], v[200:203], v[104:107]
	v_mfma_f32_16x16x32_bf16 v[100:103], v[174:177], v[200:203], v[100:103]
	v_mfma_f32_16x16x32_bf16 v[80:83], v[166:169], v[208:211], v[80:83]
	v_mfma_f32_16x16x32_bf16 v[76:79], v[174:177], v[208:211], v[76:79]
	v_mfma_f32_16x16x32_bf16 v[136:139], v[170:173], v[186:189], v[136:139]
	v_mfma_f32_16x16x32_bf16 v[132:135], v[178:181], v[186:189], v[132:135]
	v_mfma_f32_16x16x32_bf16 v[120:123], v[170:173], v[194:197], v[120:123]
	v_mfma_f32_16x16x32_bf16 v[116:119], v[178:181], v[194:197], v[116:119]
	v_mfma_f32_16x16x32_bf16 v[104:107], v[170:173], v[204:207], v[104:107]
	v_mfma_f32_16x16x32_bf16 v[100:103], v[178:181], v[204:207], v[100:103]
	v_mfma_f32_16x16x32_bf16 v[80:83], v[170:173], v[220:223], v[80:83]
	v_mfma_f32_16x16x32_bf16 v[76:79], v[178:181], v[220:223], v[76:79]
	s_barrier
; #define PG8_STAGE(bufoff, gbase, voff) do { _Pragma("unroll") for (int _i = 0; _i < 2; ++_i) \
;         __builtin_amdgcn_global_load_lds((const unsigned*)((const char*)(gbase) + (voff)[_i]), (PG8_LAS unsigned*)(lds + (bufoff) + ldsw + _i * 8192), 16, 0, 0); } while (0)
; #define PG8_LDA(dst, b, h) do { _Pragma("unroll") for (int m = 0; m < 4; ++m) _Pragma("unroll") for (int k = 0; k < 2; ++k) dst[m][k] = *(const PG8_LAS bf16x8*)(lds + PG8_SA(b, h) + aoff + m * 2048 + k * 1024); } while (0)
; #define PG8_MMA(ai, bj, At, Bt) do { __builtin_amdgcn_s_setprio(1); _Pragma("unroll") for (int m = 0; m < 4; ++m) _Pragma("unroll") for (int n = 0; n < 2; ++n) _Pragma("unroll") for (int k = 0; k < 2; ++k) \
;         acc[ai][bj][m][n] = __builtin_amdgcn_mfma_f32_16x16x32_bf16(Bt[n][k], At[m][k], acc[ai][bj][m][n], 0, 0, 0); __builtin_amdgcn_s_setprio(0); } while (0)
; #define PG8_WAIT_V(n) asm volatile("s_waitcnt vmcnt(" #n ")" ::: "memory")
; #define PG8_WAIT_L(n) asm volatile("s_waitcnt lgkmcnt(" #n ")" ::: "memory")
; #define PG8_BAR __builtin_amdgcn_s_barrier()
; #define PG8_SCHED __builtin_amdgcn_sched_barrier(0)
; template <class Epi, class Sched, bool ALIGN_EPI = false, bool SP2 = false>
; __device__ __forceinline__ void gemm_phase(PG8_LAS unsigned char* lds, const Gemm g, const Sched& S, const Epi& E) {
;     ...
;             PG8_LDA(At, 1, 1); PG8_STAGE(PG8_SB(1, 0), b3, voffB); PG8_STAGE(PG8_SB(1, 1), b3 + hstep, voffB); PG8_STAGE(PG8_SA(1, 0), a3, voffA);
;             PG8_WAIT_V(8); PG8_WAIT_L(0); PG8_BAR; PG8_MMA(1, 0, At, B0); PG8_MMA(1, 1, At, B1); PG8_BAR; PG8_SCHED;
	s_add_i32 s16, s31, s18
	v_lshl_add_u64 v[90:91], v[224:225], 0, s[88:89]
	s_mov_b32 m0, s16
	ds_read_b128 v[182:185], v88 offset:49152
	ds_read_b128 v[186:189], v88 offset:50176
	ds_read_b128 v[190:193], v88 offset:51200
	ds_read_b128 v[194:197], v88 offset:52224
	ds_read_b128 v[200:203], v88 offset:53248
	ds_read_b128 v[204:207], v88 offset:54272
	ds_read_b128 v[208:211], v88 offset:55296
	ds_read_b128 v[220:223], v88 offset:56320
	global_load_lds_dwordx4 v[90:91], off
	s_add_i32 m0, s16, 0x2000
	s_add_u32 s14, s14, 0x80080
	v_lshl_add_u64 v[90:91], v[226:227], 0, s[88:89]
	s_addc_u32 s15, s15, 0
	s_add_i32 s16, s34, s18
	global_load_lds_dwordx4 v[90:91], off
	v_lshl_add_u64 v[90:91], s[14:15], 0, v[66:67]
	s_mov_b32 m0, s16
	s_nop 0
	global_load_lds_dwordx4 v[90:91], off
	v_lshl_add_u64 v[90:91], s[14:15], 0, v[72:73]
	s_add_i32 m0, s16, 0x2000
	s_nop 0
	global_load_lds_dwordx4 v[90:91], off
	v_lshl_add_u64 v[90:91], v[228:229], 0, s[88:89]
	s_mov_b32 m0, s24
	s_nop 0
	global_load_lds_dwordx4 v[90:91], off
	v_lshl_add_u64 v[90:91], v[230:231], 0, s[88:89]
	s_mov_b32 m0, s25
	s_nop 0
	global_load_lds_dwordx4 v[90:91], off
	s_waitcnt vmcnt(8)
	s_waitcnt lgkmcnt(0)
	s_barrier
	v_mfma_f32_16x16x32_bf16 v[62:65], v[148:151], v[182:185], v[62:65]
	v_mfma_f32_16x16x32_bf16 v[58:61], v[156:159], v[182:185], v[58:61]
	v_mfma_f32_16x16x32_bf16 v[46:49], v[148:151], v[190:193], v[46:49]
	v_mfma_f32_16x16x32_bf16 v[42:45], v[156:159], v[190:193], v[42:45]
	v_mfma_f32_16x16x32_bf16 v[30:33], v[148:151], v[200:203], v[30:33]
	v_mfma_f32_16x16x32_bf16 v[26:29], v[156:159], v[200:203], v[26:29]
	v_mfma_f32_16x16x32_bf16 v[14:17], v[148:151], v[208:211], v[14:17]
	v_mfma_f32_16x16x32_bf16 v[10:13], v[156:159], v[208:211], v[10:13]
	v_mfma_f32_16x16x32_bf16 v[62:65], v[152:155], v[186:189], v[62:65]
	v_mfma_f32_16x16x32_bf16 v[58:61], v[160:163], v[186:189], v[58:61]
	v_mfma_f32_16x16x32_bf16 v[46:49], v[152:155], v[194:197], v[46:49]
	v_mfma_f32_16x16x32_bf16 v[42:45], v[160:163], v[194:197], v[42:45]
	v_mfma_f32_16x16x32_bf16 v[30:33], v[152:155], v[204:207], v[30:33]
	v_mfma_f32_16x16x32_bf16 v[26:29], v[160:163], v[204:207], v[26:29]
	v_mfma_f32_16x16x32_bf16 v[14:17], v[152:155], v[220:223], v[14:17]
	v_mfma_f32_16x16x32_bf16 v[10:13], v[160:163], v[220:223], v[10:13]
	v_mfma_f32_16x16x32_bf16 v[54:57], v[166:169], v[182:185], v[54:57]
	v_mfma_f32_16x16x32_bf16 v[50:53], v[174:177], v[182:185], v[50:53]
	v_mfma_f32_16x16x32_bf16 v[38:41], v[166:169], v[190:193], v[38:41]
	v_mfma_f32_16x16x32_bf16 v[34:37], v[174:177], v[190:193], v[34:37]
	v_mfma_f32_16x16x32_bf16 v[22:25], v[166:169], v[200:203], v[22:25]
	v_mfma_f32_16x16x32_bf16 v[18:21], v[174:177], v[200:203], v[18:21]
	v_mfma_f32_16x16x32_bf16 v[6:9], v[166:169], v[208:211], v[6:9]
	v_mfma_f32_16x16x32_bf16 v[2:5], v[174:177], v[208:211], v[2:5]
	v_mfma_f32_16x16x32_bf16 v[54:57], v[170:173], v[186:189], v[54:57]
	v_mfma_f32_16x16x32_bf16 v[50:53], v[178:181], v[186:189], v[50:53]
	v_mfma_f32_16x16x32_bf16 v[38:41], v[170:173], v[194:197], v[38:41]
	v_mfma_f32_16x16x32_bf16 v[34:37], v[178:181], v[194:197], v[34:37]
	v_mfma_f32_16x16x32_bf16 v[22:25], v[170:173], v[204:207], v[22:25]
	v_mfma_f32_16x16x32_bf16 v[18:21], v[178:181], v[204:207], v[18:21]
	v_mfma_f32_16x16x32_bf16 v[6:9], v[170:173], v[220:223], v[6:9]
	v_mfma_f32_16x16x32_bf16 v[2:5], v[178:181], v[220:223], v[2:5]
	s_barrier
	s_add_i32 s30, s30, 2
	s_add_u32 s12, s12, 0x100
	s_addc_u32 s13, s13, 0
	s_cmp_gt_u32 s30, 29
	s_cbranch_scc0 .LBB0_702
	s_nop 0
	s_nop 0
	s_nop 0
	s_nop 0
	s_nop 0
	s_nop 0
	s_nop 0
	s_nop 0
	s_nop 0
	s_nop 0
	s_nop 0
	s_nop 0
	s_nop 0
	s_nop 0
	s_nop 0
	s_nop 0
	s_nop 0
	s_nop 0
	s_nop 0
	s_nop 0
	s_cmpk_lt_u32 s1, 0x100
	s_cbranch_scc0 .LBB0_705
	s_barrier

;     __host__ __device__ bool next(int i, Unit& u) const { if (i != 0 || r < 0 || r >= 148) return false; if (r < 116) { u.pm = r % 29; u.pn = 47 + r / 29; } else { u.pm = 32; u.pn = 19 + (r - 116); } u.ko = 0; return true; }
;     __host__ __device__ bool next(int i, Unit& u) const { const int L = i * G + (G - 1 - c); if (L >= nN * S) return false; u.pm = pm; u.pn = L % nN; u.ko = (L / nN) * ksub; return true; }
; #define PG8_STAGE(bufoff, gbase, voff) do { _Pragma("unroll") for (int _i = 0; _i < 2; ++_i) \
;         __builtin_amdgcn_global_load_lds((const unsigned*)((const char*)(gbase) + (voff)[_i]), (PG8_LAS unsigned*)(lds + (bufoff) + ldsw + _i * 8192), 16, 0, 0); } while (0)
; #define PG8_LDA(dst, b, h) do { _Pragma("unroll") for (int m = 0; m < 4; ++m) _Pragma("unroll") for (int k = 0; k < 2; ++k) dst[m][k] = *(const PG8_LAS bf16x8*)(lds + PG8_SA(b, h) + aoff + m * 2048 + k * 1024); } while (0)
; #define PG8_BAR __builtin_amdgcn_s_barrier()
; template <class Epi, class Sched, bool ALIGN_EPI = false, bool SP2 = false>
; __device__ __forceinline__ void gemm_phase(PG8_LAS unsigned char* lds, const Gemm g, const Sched& S, const Epi& E) {
;     ...
;         const bool has_next = S.next(ui + 1, nxt);
;         const char* nA = has_next ? (const char*)g.A + (size_t)nxt.pm * tstep + (size_t)nxt.ko * 2 : cA; const char* nB = has_next ? (const char*)g.Bt + (size_t)nxt.pn * tstep + (size_t)nxt.ko * 2 : cB;
;         for (int t = 0; t < nt; t += 2) {
;             const bool last = (t == nt - 2);
;             const char* a1 = cA + (size_t)(t + 1) * kstep;
;             const char* a2 = last ? nA : cA + (size_t)(t + 2) * kstep; const char* b2 = last ? nB : cB + (size_t)(t + 2) * kstep;
;             const char* a3 = a2 + kstep; const char* b3 = b2 + kstep;
;             if (last && has_next) S.a_ready(nxt);
;             if constexpr (SP2) {
;             PG8_LDB(B0, 0, 0); PG8_LDB(B1, 0, 1); PG8_SCHED; PG8_LDA(At, 0, 0); PG8_STAGE(PG8_SA(1, 1), a1 + hstep, voffA);
;             PG8_WAIT_V(8); PG8_WAIT_L(0); PG8_BAR; PG8_MMA(0, 0, At, B0); PG8_MMA(0, 1, At, B1); PG8_BAR; PG8_SCHED;
;             PG8_LDA(At, 0, 1); PG8_STAGE(PG8_SB(0, 0), b2, voffB); PG8_STAGE(PG8_SB(0, 1), b2 + hstep, voffB); PG8_STAGE(PG8_SA(0, 0), a2, voffA);
;             PG8_WAIT_V(8); PG8_WAIT_L(0); PG8_BAR; PG8_MMA(1, 0, At, B0); PG8_MMA(1, 1, At, B1); PG8_BAR; PG8_SCHED;
.LBB0_782:
	s_add_u32 s1, s26, 0xfff80080
	s_addc_u32 s2, s27, -1
	s_add_i32 s3, 0, 0x10000
	s_cmpk_eq_i32 s28, 0x1e00
	s_cselect_b32 s35, s21, s2
	s_cselect_b32 s34, s50, s1
	v_add_u32_e32 v66, s3, v206
	s_cselect_b32 s31, s19, s53
	s_cselect_b32 s30, s51, s52
	s_add_i32 s1, 0, 0x14000
	ds_read_b128 v[152:155], v66
	ds_read_b128 v[156:159], v66 offset:1024
	ds_read_b128 v[160:163], v66 offset:2048
	ds_read_b128 v[164:167], v66 offset:3072
	v_add_u32_e32 v66, s1, v206
	ds_read_b128 v[168:171], v66
	ds_read_b128 v[172:175], v66 offset:1024
	ds_read_b128 v[176:179], v66 offset:2048
	ds_read_b128 v[180:183], v66 offset:3072
	v_lshl_add_u64 v[68:69], s[26:27], 0, v[142:143]
	s_add_i32 m0, s43, 0xc000
	ds_read_b128 v[184:187], v208
	ds_read_b128 v[188:191], v208 offset:1024
	ds_read_b128 v[192:195], v208 offset:2048
	ds_read_b128 v[196:199], v208 offset:3072
	ds_read_b128 v[200:203], v208 offset:4096
	ds_read_b128 v[220:223], v208 offset:5120
	ds_read_b128 v[224:227], v208 offset:6144
	ds_read_b128 v[228:231], v208 offset:7168
	global_load_lds_dwordx4 v[68:69], off
	v_lshl_add_u64 v[68:69], s[26:27], 0, v[144:145]
	s_add_i32 m0, s43, 0xe000
	s_nop 0
	global_load_lds_dwordx4 v[68:69], off
	s_waitcnt vmcnt(8)
	s_waitcnt lgkmcnt(0)
	s_barrier
	v_mfma_f32_16x16x32_bf16 v[130:133], v[152:155], v[184:187], v[130:133]
	v_mfma_f32_16x16x32_bf16 v[126:129], v[160:163], v[184:187], v[126:129]
	v_mfma_f32_16x16x32_bf16 v[114:117], v[152:155], v[192:195], v[114:117]
	v_mfma_f32_16x16x32_bf16 v[110:113], v[160:163], v[192:195], v[110:113]
	v_mfma_f32_16x16x32_bf16 v[98:101], v[152:155], v[200:203], v[98:101]
	v_mfma_f32_16x16x32_bf16 v[94:97], v[160:163], v[200:203], v[94:97]
	v_mfma_f32_16x16x32_bf16 v[82:85], v[152:155], v[224:227], v[82:85]
	v_mfma_f32_16x16x32_bf16 v[78:81], v[160:163], v[224:227], v[78:81]
	v_mfma_f32_16x16x32_bf16 v[130:133], v[156:159], v[188:191], v[130:133]
	v_mfma_f32_16x16x32_bf16 v[126:129], v[164:167], v[188:191], v[126:129]
	v_mfma_f32_16x16x32_bf16 v[114:117], v[156:159], v[196:199], v[114:117]
	v_mfma_f32_16x16x32_bf16 v[110:113], v[164:167], v[196:199], v[110:113]
	v_mfma_f32_16x16x32_bf16 v[98:101], v[156:159], v[220:223], v[98:101]
	v_mfma_f32_16x16x32_bf16 v[94:97], v[164:167], v[220:223], v[94:97]
	v_mfma_f32_16x16x32_bf16 v[82:85], v[156:159], v[228:231], v[82:85]
	v_mfma_f32_16x16x32_bf16 v[78:81], v[164:167], v[228:231], v[78:81]
	v_mfma_f32_16x16x32_bf16 v[122:125], v[168:171], v[184:187], v[122:125]
	v_mfma_f32_16x16x32_bf16 v[118:121], v[176:179], v[184:187], v[118:121]
	v_mfma_f32_16x16x32_bf16 v[106:109], v[168:171], v[192:195], v[106:109]
	v_mfma_f32_16x16x32_bf16 v[102:105], v[176:179], v[192:195], v[102:105]
	v_mfma_f32_16x16x32_bf16 v[90:93], v[168:171], v[200:203], v[90:93]
	v_mfma_f32_16x16x32_bf16 v[86:89], v[176:179], v[200:203], v[86:89]
	v_mfma_f32_16x16x32_bf16 v[74:77], v[168:171], v[224:227], v[74:77]
	v_mfma_f32_16x16x32_bf16 v[68:71], v[176:179], v[224:227], v[70:73]
	v_mfma_f32_16x16x32_bf16 v[122:125], v[172:175], v[188:191], v[122:125]
	v_mfma_f32_16x16x32_bf16 v[118:121], v[180:183], v[188:191], v[118:121]
	v_mfma_f32_16x16x32_bf16 v[106:109], v[172:175], v[196:199], v[106:109]
	v_mfma_f32_16x16x32_bf16 v[102:105], v[180:183], v[196:199], v[102:105]
	v_mfma_f32_16x16x32_bf16 v[90:93], v[172:175], v[220:223], v[90:93]
	v_mfma_f32_16x16x32_bf16 v[86:89], v[180:183], v[220:223], v[86:89]
	v_mfma_f32_16x16x32_bf16 v[74:77], v[172:175], v[228:231], v[74:77]
	v_mfma_f32_16x16x32_bf16 v[68:71], v[180:183], v[228:231], v[68:71]
	s_barrier
	s_add_i32 s2, s3, s42
	v_lshl_add_u64 v[204:205], s[30:31], 0, v[138:139]
	s_mov_b32 m0, s2
	ds_read_b128 v[184:187], v208 offset:16384
	ds_read_b128 v[188:191], v208 offset:17408
	ds_read_b128 v[192:195], v208 offset:18432
	ds_read_b128 v[196:199], v208 offset:19456
	ds_read_b128 v[200:203], v208 offset:20480
	ds_read_b128 v[220:223], v208 offset:21504
	ds_read_b128 v[224:227], v208 offset:22528
	ds_read_b128 v[228:231], v208 offset:23552
	global_load_lds_dwordx4 v[204:205], off
	s_add_i32 m0, s2, 0x2000
	s_add_u32 s2, s30, 0x80000
	v_lshl_add_u64 v[210:211], s[30:31], 0, v[134:135]
	s_addc_u32 s3, s31, 0
	s_add_i32 s1, s1, s42
	global_load_lds_dwordx4 v[210:211], off
	v_lshl_add_u64 v[72:73], s[2:3], 0, v[138:139]
	s_mov_b32 m0, s1
	v_lshl_add_u64 v[232:233], s[34:35], 0, v[140:141]
	global_load_lds_dwordx4 v[72:73], off
	v_lshl_add_u64 v[72:73], s[2:3], 0, v[134:135]
	s_add_i32 m0, s1, 0x2000
	v_lshl_add_u64 v[234:235], s[34:35], 0, v[136:137]
	global_load_lds_dwordx4 v[72:73], off
	s_mov_b32 m0, s43
	s_nop 0
	global_load_lds_dwordx4 v[232:233], off
	s_mov_b32 m0, s44
	s_nop 0
	global_load_lds_dwordx4 v[234:235], off
	s_waitcnt vmcnt(8)
	s_waitcnt lgkmcnt(0)
	s_barrier
; #define PG8_STAGE(bufoff, gbase, voff) do { _Pragma("unroll") for (int _i = 0; _i < 2; ++_i) \
;         __builtin_amdgcn_global_load_lds((const unsigned*)((const char*)(gbase) + (voff)[_i]), (PG8_LAS unsigned*)(lds + (bufoff) + ldsw + _i * 8192), 16, 0, 0); } while (0)
; #define PG8_LDA(dst, b, h) do { _Pragma("unroll") for (int m = 0; m < 4; ++m) _Pragma("unroll") for (int k = 0; k < 2; ++k) dst[m][k] = *(const PG8_LAS bf16x8*)(lds + PG8_SA(b, h) + aoff + m * 2048 + k * 1024); } while (0)
; #define PG8_LDB(dst, b, h) do { _Pragma("unroll") for (int n = 0; n < 2; ++n) _Pragma("unroll") for (int k = 0; k < 2; ++k) dst[n][k] = *(const PG8_LAS bf16x8*)(lds + PG8_SB(b, h) + boff + n * 2048 + k * 1024); } while (0)
; #define PG8_MMA(ai, bj, At, Bt) do { __builtin_amdgcn_s_setprio(1); _Pragma("unroll") for (int m = 0; m < 4; ++m) _Pragma("unroll") for (int n = 0; n < 2; ++n) _Pragma("unroll") for (int k = 0; k < 2; ++k) \
;         acc[ai][bj][m][n] = __builtin_amdgcn_mfma_f32_16x16x32_bf16(Bt[n][k], At[m][k], acc[ai][bj][m][n], 0, 0, 0); __builtin_amdgcn_s_setprio(0); } while (0)
; #define PG8_WAIT_V(n) asm volatile("s_waitcnt vmcnt(" #n ")" ::: "memory")
; #define PG8_WAIT_L(n) asm volatile("s_waitcnt lgkmcnt(" #n ")" ::: "memory")
; #define PG8_BAR __builtin_amdgcn_s_barrier()
; #define PG8_SCHED __builtin_amdgcn_sched_barrier(0)
; template <class Epi, class Sched, bool ALIGN_EPI = false, bool SP2 = false>
; __device__ __forceinline__ void gemm_phase(PG8_LAS unsigned char* lds, const Gemm g, const Sched& S, const Epi& E) {
;     ...
;             PG8_WAIT_V(8); PG8_WAIT_L(0); PG8_BAR; PG8_MMA(1, 0, At, B0); PG8_MMA(1, 1, At, B1); PG8_BAR; PG8_SCHED;
;             PG8_LDB(B0, 1, 0); PG8_LDB(B1, 1, 1); PG8_SCHED; PG8_LDA(At, 1, 0); PG8_STAGE(PG8_SA(0, 1), a2 + hstep, voffA);
;             PG8_WAIT_V(8); PG8_WAIT_L(0); PG8_BAR; PG8_MMA(0, 0, At, B0); PG8_MMA(0, 1, At, B1); PG8_BAR; PG8_SCHED;
	v_mfma_f32_16x16x32_bf16 v[62:65], v[152:155], v[184:187], v[62:65]
	v_mfma_f32_16x16x32_bf16 v[58:61], v[160:163], v[184:187], v[58:61]
	v_mfma_f32_16x16x32_bf16 v[46:49], v[152:155], v[192:195], v[46:49]
	v_mfma_f32_16x16x32_bf16 v[42:45], v[160:163], v[192:195], v[42:45]
	v_mfma_f32_16x16x32_bf16 v[30:33], v[152:155], v[200:203], v[30:33]
	v_mfma_f32_16x16x32_bf16 v[26:29], v[160:163], v[200:203], v[26:29]
	v_mfma_f32_16x16x32_bf16 v[14:17], v[152:155], v[224:227], v[14:17]
	v_mfma_f32_16x16x32_bf16 v[10:13], v[160:163], v[224:227], v[10:13]
	v_mfma_f32_16x16x32_bf16 v[62:65], v[156:159], v[188:191], v[62:65]
	v_mfma_f32_16x16x32_bf16 v[58:61], v[164:167], v[188:191], v[58:61]
	v_mfma_f32_16x16x32_bf16 v[46:49], v[156:159], v[196:199], v[46:49]
	v_mfma_f32_16x16x32_bf16 v[42:45], v[164:167], v[196:199], v[42:45]
	v_mfma_f32_16x16x32_bf16 v[30:33], v[156:159], v[220:223], v[30:33]
	v_mfma_f32_16x16x32_bf16 v[26:29], v[164:167], v[220:223], v[26:29]
	v_mfma_f32_16x16x32_bf16 v[14:17], v[156:159], v[228:231], v[14:17]
	v_mfma_f32_16x16x32_bf16 v[10:13], v[164:167], v[228:231], v[10:13]
	v_mfma_f32_16x16x32_bf16 v[54:57], v[168:171], v[184:187], v[54:57]
	v_mfma_f32_16x16x32_bf16 v[50:53], v[176:179], v[184:187], v[50:53]
	v_mfma_f32_16x16x32_bf16 v[38:41], v[168:171], v[192:195], v[38:41]
	v_mfma_f32_16x16x32_bf16 v[34:37], v[176:179], v[192:195], v[34:37]
	v_mfma_f32_16x16x32_bf16 v[22:25], v[168:171], v[200:203], v[22:25]
	v_mfma_f32_16x16x32_bf16 v[18:21], v[176:179], v[200:203], v[18:21]
	v_mfma_f32_16x16x32_bf16 v[6:9], v[168:171], v[224:227], v[6:9]
	v_mfma_f32_16x16x32_bf16 v[2:5], v[176:179], v[224:227], v[2:5]
	v_mfma_f32_16x16x32_bf16 v[54:57], v[172:175], v[188:191], v[54:57]
	v_mfma_f32_16x16x32_bf16 v[50:53], v[180:183], v[188:191], v[50:53]
	v_mfma_f32_16x16x32_bf16 v[38:41], v[172:175], v[196:199], v[38:41]
	v_mfma_f32_16x16x32_bf16 v[34:37], v[180:183], v[196:199], v[34:37]
	v_mfma_f32_16x16x32_bf16 v[22:25], v[172:175], v[220:223], v[22:25]
	v_mfma_f32_16x16x32_bf16 v[18:21], v[180:183], v[220:223], v[18:21]
	v_mfma_f32_16x16x32_bf16 v[6:9], v[172:175], v[228:231], v[6:9]
	v_mfma_f32_16x16x32_bf16 v[2:5], v[180:183], v[228:231], v[2:5]
	s_barrier
	s_add_i32 s1, 0, 0x18000
	v_add_u32_e32 v66, s1, v206
	s_add_i32 s55, 0, 0x1c000
	ds_read_b128 v[152:155], v66
	ds_read_b128 v[156:159], v66 offset:1024
	ds_read_b128 v[160:163], v66 offset:2048
	ds_read_b128 v[164:167], v66 offset:3072
	v_add_u32_e32 v66, s55, v206
	ds_read_b128 v[168:171], v66
	ds_read_b128 v[172:175], v66 offset:1024
	ds_read_b128 v[176:179], v66 offset:2048
	ds_read_b128 v[180:183], v66 offset:3072
	s_add_u32 s2, s34, 0x80000
	s_addc_u32 s3, s35, 0
	s_mov_b32 m0, s45
	v_lshl_add_u64 v[72:73], s[2:3], 0, v[140:141]
	ds_read_b128 v[184:187], v208 offset:32768
	ds_read_b128 v[188:191], v208 offset:33792
	ds_read_b128 v[192:195], v208 offset:34816
	ds_read_b128 v[196:199], v208 offset:35840
	ds_read_b128 v[200:203], v208 offset:36864
	ds_read_b128 v[220:223], v208 offset:37888
	ds_read_b128 v[224:227], v208 offset:38912
	ds_read_b128 v[228:231], v208 offset:39936
	global_load_lds_dwordx4 v[72:73], off
	v_lshl_add_u64 v[72:73], s[2:3], 0, v[136:137]
	s_mov_b32 m0, s46
	s_nop 0
	global_load_lds_dwordx4 v[72:73], off
	s_waitcnt vmcnt(8)
	s_waitcnt lgkmcnt(0)
	s_barrier
	v_mfma_f32_16x16x32_bf16 v[130:133], v[152:155], v[184:187], v[130:133]
	v_mfma_f32_16x16x32_bf16 v[126:129], v[160:163], v[184:187], v[126:129]
	v_mfma_f32_16x16x32_bf16 v[114:117], v[152:155], v[192:195], v[114:117]
	v_mfma_f32_16x16x32_bf16 v[110:113], v[160:163], v[192:195], v[110:113]
	v_mfma_f32_16x16x32_bf16 v[98:101], v[152:155], v[200:203], v[98:101]
	v_mfma_f32_16x16x32_bf16 v[94:97], v[160:163], v[200:203], v[94:97]
	v_mfma_f32_16x16x32_bf16 v[82:85], v[152:155], v[224:227], v[82:85]
	v_mfma_f32_16x16x32_bf16 v[78:81], v[160:163], v[224:227], v[78:81]
	v_mfma_f32_16x16x32_bf16 v[130:133], v[156:159], v[188:191], v[130:133]
	v_mfma_f32_16x16x32_bf16 v[126:129], v[164:167], v[188:191], v[126:129]
	v_mfma_f32_16x16x32_bf16 v[114:117], v[156:159], v[196:199], v[114:117]
	v_mfma_f32_16x16x32_bf16 v[110:113], v[164:167], v[196:199], v[110:113]
	v_mfma_f32_16x16x32_bf16 v[98:101], v[156:159], v[220:223], v[98:101]
	v_mfma_f32_16x16x32_bf16 v[94:97], v[164:167], v[220:223], v[94:97]
	v_mfma_f32_16x16x32_bf16 v[82:85], v[156:159], v[228:231], v[82:85]
	v_mfma_f32_16x16x32_bf16 v[78:81], v[164:167], v[228:231], v[78:81]
	v_mfma_f32_16x16x32_bf16 v[122:125], v[168:171], v[184:187], v[122:125]
	v_mfma_f32_16x16x32_bf16 v[118:121], v[176:179], v[184:187], v[118:121]
	v_mfma_f32_16x16x32_bf16 v[106:109], v[168:171], v[192:195], v[106:109]
	v_mfma_f32_16x16x32_bf16 v[102:105], v[176:179], v[192:195], v[102:105]
	v_mfma_f32_16x16x32_bf16 v[90:93], v[168:171], v[200:203], v[90:93]
	v_mfma_f32_16x16x32_bf16 v[86:89], v[176:179], v[200:203], v[86:89]
	v_mfma_f32_16x16x32_bf16 v[72:75], v[168:171], v[224:227], v[74:77]
	v_mfma_f32_16x16x32_bf16 v[68:71], v[176:179], v[224:227], v[68:71]
	v_mfma_f32_16x16x32_bf16 v[122:125], v[172:175], v[188:191], v[122:125]
	v_mfma_f32_16x16x32_bf16 v[118:121], v[180:183], v[188:191], v[118:121]
	v_mfma_f32_16x16x32_bf16 v[106:109], v[172:175], v[196:199], v[106:109]
	v_mfma_f32_16x16x32_bf16 v[102:105], v[180:183], v[196:199], v[102:105]
	v_mfma_f32_16x16x32_bf16 v[90:93], v[172:175], v[220:223], v[90:93]
	v_mfma_f32_16x16x32_bf16 v[86:89], v[180:183], v[220:223], v[86:89]
	v_mfma_f32_16x16x32_bf16 v[74:77], v[172:175], v[228:231], v[72:75]
	v_mfma_f32_16x16x32_bf16 v[70:73], v[180:183], v[228:231], v[68:71]
	s_barrier
; #define PG8_WAIT_V(n) asm volatile("s_waitcnt vmcnt(" #n ")" ::: "memory")
; #define PG8_BAR __builtin_amdgcn_s_barrier()
;     __device__ __forceinline__ void mid(f32x4 (&acc)[2][2][4][2], const Unit& u, int seg, int wr, int wc, int fr, int fq) const {
;     ...
;         int row0 = u.pm * BM + wr * 64 + fr; asm volatile("" : "+v"(row0));
;         const int col0 = u.pn * BM + wc * 32 + 8 * fq;
;         u32x2v ga[2][4][2], gb[2][4][2];
; #pragma unroll
;         for (int ai = 0; ai < 2; ++ai)
; #pragma unroll
; template <class Epi, class Sched, bool ALIGN_EPI = false, bool SP2 = false>
; __device__ __forceinline__ void gemm_phase(PG8_LAS unsigned char* lds, const Gemm g, const Sched& S, const Epi& E) {
;     ...
;             PG8_LDA(At, 1, 1); PG8_STAGE(PG8_SB(1, 0), b3, voffB); PG8_STAGE(PG8_SB(1, 1), b3 + hstep, voffB); PG8_STAGE(PG8_SA(1, 0), a3, voffA);
;             PG8_WAIT_V(8); PG8_WAIT_L(0); PG8_BAR; PG8_MMA(1, 0, At, B0); PG8_MMA(1, 1, At, B1); PG8_BAR; PG8_SCHED;
;             } else {
;             PG8_LDB(B0, 0, 0); PG8_SCHED; PG8_LDA(At, 0, 0); PG8_STAGE(PG8_SA(1, 1), a1 + hstep, voffA);
;             PG8_WAIT_L(8); PG8_BAR; PG8_WAIT_L(0); PG8_MMA(0, 0, At, B0); PG8_BAR; PG8_SCHED;
;             PG8_LDB(B1, 0, 1); PG8_STAGE(PG8_SB(0, 0), b2, voffB);
;             PG8_BAR; PG8_WAIT_L(0); PG8_MMA(0, 1, At, B1); PG8_BAR;
;             PG8_LDA(At, 0, 1); PG8_STAGE(PG8_SA(0, 0), a2, voffA);
;             PG8_BAR; PG8_WAIT_L(0); PG8_MMA(1, 0, At, B0); PG8_BAR; PG8_SCHED;
;             PG8_STAGE(PG8_SB(0, 1), b2 + hstep, voffB);
;             PG8_WAIT_V(6); PG8_BAR; PG8_MMA(1, 1, At, B1); PG8_BAR;
;             PG8_LDB(B0, 1, 0); PG8_SCHED; PG8_LDA(At, 1, 0); PG8_STAGE(PG8_SA(0, 1), a2 + hstep, voffA);
;             PG8_WAIT_L(8); PG8_BAR; PG8_WAIT_L(0); PG8_MMA(0, 0, At, B0); PG8_BAR; PG8_SCHED;
;             PG8_LDB(B1, 1, 1); PG8_STAGE(PG8_SB(1, 0), b3, voffB);
;             PG8_BAR; PG8_WAIT_L(0); PG8_MMA(0, 1, At, B1); PG8_BAR;
;             PG8_LDA(At, 1, 1); PG8_STAGE(PG8_SA(1, 0), a3, voffA);
;             PG8_BAR; PG8_WAIT_L(0); PG8_MMA(1, 0, At, B0); PG8_BAR; PG8_SCHED;
;             PG8_STAGE(PG8_SB(1, 1), b3 + hstep, voffB);
;             PG8_WAIT_V(6); PG8_BAR; PG8_MMA(1, 1, At, B1); PG8_BAR;
;             }
;             if constexpr (Epi::HAS_MID) { if ((((t + 2) & 7) == 0) && ((t + 2) < nt)) E.mid(acc, cur, ((t + 2) >> 3) - 1, wr, wc, fr, fq); }
	s_add_i32 s1, s1, s42
	v_lshl_add_u64 v[68:69], v[204:205], 0, s[88:89]
	s_mov_b32 m0, s1
	ds_read_b128 v[184:187], v208 offset:49152
	ds_read_b128 v[188:191], v208 offset:50176
	ds_read_b128 v[192:195], v208 offset:51200
	ds_read_b128 v[196:199], v208 offset:52224
	ds_read_b128 v[200:203], v208 offset:53248
	ds_read_b128 v[220:223], v208 offset:54272
	ds_read_b128 v[224:227], v208 offset:55296
	ds_read_b128 v[228:231], v208 offset:56320
	global_load_lds_dwordx4 v[68:69], off
	s_add_i32 m0, s1, 0x2000
	s_add_u32 s2, s30, 0x80080
	v_lshl_add_u64 v[68:69], v[210:211], 0, s[88:89]
	s_addc_u32 s3, s31, 0
	s_add_i32 s1, s55, s42
	global_load_lds_dwordx4 v[68:69], off
	v_lshl_add_u64 v[68:69], s[2:3], 0, v[138:139]
	s_mov_b32 m0, s1
	s_nop 0
	global_load_lds_dwordx4 v[68:69], off
	v_lshl_add_u64 v[68:69], s[2:3], 0, v[134:135]
	s_add_i32 m0, s1, 0x2000
	s_nop 0
	global_load_lds_dwordx4 v[68:69], off
	v_lshl_add_u64 v[68:69], v[232:233], 0, s[88:89]
	s_mov_b32 m0, s47
	s_nop 0
	global_load_lds_dwordx4 v[68:69], off
	v_lshl_add_u64 v[68:69], v[234:235], 0, s[88:89]
	s_mov_b32 m0, s48
	s_nop 0
	global_load_lds_dwordx4 v[68:69], off
	s_waitcnt vmcnt(8)
	s_waitcnt lgkmcnt(0)
	s_barrier
	v_mfma_f32_16x16x32_bf16 v[62:65], v[152:155], v[184:187], v[62:65]
	v_mfma_f32_16x16x32_bf16 v[58:61], v[160:163], v[184:187], v[58:61]
	v_mfma_f32_16x16x32_bf16 v[46:49], v[152:155], v[192:195], v[46:49]
	v_mfma_f32_16x16x32_bf16 v[42:45], v[160:163], v[192:195], v[42:45]
	v_mfma_f32_16x16x32_bf16 v[30:33], v[152:155], v[200:203], v[30:33]
	v_mfma_f32_16x16x32_bf16 v[26:29], v[160:163], v[200:203], v[26:29]
	v_mfma_f32_16x16x32_bf16 v[14:17], v[152:155], v[224:227], v[14:17]
	v_mfma_f32_16x16x32_bf16 v[10:13], v[160:163], v[224:227], v[10:13]
	v_mfma_f32_16x16x32_bf16 v[62:65], v[156:159], v[188:191], v[62:65]
	v_mfma_f32_16x16x32_bf16 v[58:61], v[164:167], v[188:191], v[58:61]
	v_mfma_f32_16x16x32_bf16 v[46:49], v[156:159], v[196:199], v[46:49]
	v_mfma_f32_16x16x32_bf16 v[42:45], v[164:167], v[196:199], v[42:45]
	v_mfma_f32_16x16x32_bf16 v[30:33], v[156:159], v[220:223], v[30:33]
	v_mfma_f32_16x16x32_bf16 v[26:29], v[164:167], v[220:223], v[26:29]
	v_mfma_f32_16x16x32_bf16 v[14:17], v[156:159], v[228:231], v[14:17]
	v_mfma_f32_16x16x32_bf16 v[10:13], v[164:167], v[228:231], v[10:13]
	v_mfma_f32_16x16x32_bf16 v[54:57], v[168:171], v[184:187], v[54:57]
	v_mfma_f32_16x16x32_bf16 v[50:53], v[176:179], v[184:187], v[50:53]
	v_mfma_f32_16x16x32_bf16 v[38:41], v[168:171], v[192:195], v[38:41]
	v_mfma_f32_16x16x32_bf16 v[34:37], v[176:179], v[192:195], v[34:37]
	v_mfma_f32_16x16x32_bf16 v[22:25], v[168:171], v[200:203], v[22:25]
	v_mfma_f32_16x16x32_bf16 v[18:21], v[176:179], v[200:203], v[18:21]
	v_mfma_f32_16x16x32_bf16 v[6:9], v[168:171], v[224:227], v[6:9]
	v_mfma_f32_16x16x32_bf16 v[2:5], v[176:179], v[224:227], v[2:5]
	v_mfma_f32_16x16x32_bf16 v[54:57], v[172:175], v[188:191], v[54:57]
	v_mfma_f32_16x16x32_bf16 v[50:53], v[180:183], v[188:191], v[50:53]
	v_mfma_f32_16x16x32_bf16 v[38:41], v[172:175], v[196:199], v[38:41]
	v_mfma_f32_16x16x32_bf16 v[34:37], v[180:183], v[196:199], v[34:37]
	v_mfma_f32_16x16x32_bf16 v[22:25], v[172:175], v[220:223], v[22:25]
	v_mfma_f32_16x16x32_bf16 v[18:21], v[180:183], v[220:223], v[18:21]
	v_mfma_f32_16x16x32_bf16 v[6:9], v[172:175], v[228:231], v[6:9]
	v_mfma_f32_16x16x32_bf16 v[2:5], v[180:183], v[228:231], v[2:5]
	s_barrier
	s_mov_b32 s1, s54
	s_add_i32 s54, s54, 2
	s_and_b32 s2, s54, 6
	s_cmp_eq_u32 s2, 0
	s_cselect_b64 s[2:3], -1, 0
	s_cmp_gt_u32 s1, 29
	s_cselect_b64 s[30:31], -1, 0
	s_cmp_lt_u32 s1, 30
	s_cselect_b64 s[34:35], -1, 0
	s_and_b64 s[2:3], s[2:3], s[34:35]
	s_andn2_b64 vcc, exec, s[2:3]
	s_cbranch_vccnz .LBB0_781
	s_nop 0
	s_nop 0
	s_nop 0
	s_nop 0
	s_nop 0
	s_nop 0
	s_nop 0
	s_nop 0
	s_nop 0
	s_nop 0
	s_nop 0
	s_nop 0
	s_nop 0
	s_nop 0
	s_nop 0
	s_nop 0
	s_nop 0
	s_nop 0
	s_nop 0
	s_nop 0
	v_mov_b32_e32 v68, v148
	s_nop 0
	v_ashrrev_i32_e32 v69, 31, v68
	v_lshlrev_b64 v[68:69], 13, v[68:69]
	v_lshl_add_u64 v[68:69], s[28:29], 0, v[68:69]
	v_lshl_add_u64 v[68:69], v[150:151], 0, v[68:69]
	v_add_co_u32_e32 v152, vcc, 0xcbff000, v68
	s_nop 1
	v_addc_co_u32_e32 v153, vcc, 0, v69, vcc
	v_add_co_u32_e32 v154, vcc, 0xcc00000, v68
	s_nop 1
	v_addc_co_u32_e32 v155, vcc, 0, v69, vcc
	global_load_dwordx2 v[210:211], v[152:153], off offset:2560
	global_load_dwordx2 v[220:221], v[154:155], off offset:512
	global_load_dwordx2 v[222:223], v[154:155], off offset:640
	global_load_dwordx2 v[224:225], v[152:153], off offset:2688
	v_add_co_u32_e32 v152, vcc, 0xcc1f000, v68
	s_nop 1
	v_addc_co_u32_e32 v153, vcc, 0, v69, vcc
	v_add_co_u32_e32 v154, vcc, 0xcc20000, v68
	s_nop 0
	s_nop 0
	v_addc_co_u32_e32 v155, vcc, 0, v69, vcc
	global_load_dwordx2 v[202:203], v[152:153], off offset:2560
	global_load_dwordx2 v[204:205], v[154:155], off offset:512
	global_load_dwordx2 v[200:201], v[154:155], off offset:640
	global_load_dwordx2 v[198:199], v[152:153], off offset:2688
	v_add_co_u32_e32 v152, vcc, 0xcc3f000, v68
	s_nop 0
	s_nop 0
	v_addc_co_u32_e32 v153, vcc, 0, v69, vcc
	v_add_co_u32_e32 v154, vcc, 0xcc40000, v68
	s_nop 0
	s_nop 0
	v_addc_co_u32_e32 v155, vcc, 0, v69, vcc
	global_load_dwordx2 v[194:195], v[152:153], off offset:2560
	global_load_dwordx2 v[196:197], v[154:155], off offset:512
	global_load_dwordx2 v[192:193], v[154:155], off offset:640
	global_load_dwordx2 v[190:191], v[152:153], off offset:2688
	v_add_co_u32_e32 v152, vcc, 0xcc5f000, v68
	s_nop 0
	s_nop 0
	v_addc_co_u32_e32 v153, vcc, 0, v69, vcc
	v_add_co_u32_e32 v154, vcc, 0xcc60000, v68
	s_nop 1
	v_addc_co_u32_e32 v155, vcc, 0, v69, vcc
; __device__ __forceinline__ float gate_v(unsigned q) { return (float)q; }
;     __device__ __forceinline__ void mid(f32x4 (&acc)[2][2][4][2], const Unit& u, int seg, int wr, int wc, int fr, int fq) const {
;     ...
;             for (int m = 0; m < 4; ++m) { const unsigned char* rowp = G + (size_t)(row0 + ai * HALF + m * 16) * 8192 + col0 + seg * 2048;
; #pragma unroll
;                 for (int bj = 0; bj < 2; ++bj) { ga[ai][m][bj] = *(const u32x2v*)(rowp + bj * HALF); gb[ai][m][bj] = *(const u32x2v*)(rowp + 2048 + bj * HALF); } }
; #pragma unroll
;         for (int ai = 0; ai < 2; ++ai)
; #pragma unroll
;             for (int m = 0; m < 4; ++m)
; #pragma unroll
;                 for (int bj = 0; bj < 2; ++bj)
; #pragma unroll
;                     for (int e = 0; e < 8; ++e) { const unsigned a = (ga[ai][m][bj][e >> 2] >> (8 * (e & 3))) & 255u, b = (gb[ai][m][bj][e >> 2] >> (8 * (e & 3))) & 255u;
;                         acc[ai][bj][m][e >> 2][e & 3] *= gate_v(a) * __builtin_amdgcn_rcpf(gate_v(b)); }
	global_load_dwordx2 v[186:187], v[152:153], off offset:2560
	global_load_dwordx2 v[188:189], v[154:155], off offset:512
	global_load_dwordx2 v[184:185], v[154:155], off offset:640
	global_load_dwordx2 v[182:183], v[152:153], off offset:2688
	v_add_co_u32_e32 v152, vcc, 0xccff000, v68
	s_nop 1
	v_addc_co_u32_e32 v153, vcc, 0, v69, vcc
	v_add_co_u32_e32 v154, vcc, 0xcd00000, v68
	s_nop 1
	v_addc_co_u32_e32 v155, vcc, 0, v69, vcc
	global_load_dwordx2 v[178:179], v[152:153], off offset:2560
	global_load_dwordx2 v[180:181], v[154:155], off offset:512
	global_load_dwordx2 v[176:177], v[154:155], off offset:640
	global_load_dwordx2 v[174:175], v[152:153], off offset:2688
	v_add_co_u32_e32 v152, vcc, 0xcd1f000, v68
	s_nop 1
	v_addc_co_u32_e32 v153, vcc, 0, v69, vcc
	v_add_co_u32_e32 v154, vcc, 0xcd20000, v68
	s_nop 1
	v_addc_co_u32_e32 v155, vcc, 0, v69, vcc
	global_load_dwordx2 v[170:171], v[152:153], off offset:2560
	global_load_dwordx2 v[172:173], v[154:155], off offset:512
	global_load_dwordx2 v[168:169], v[154:155], off offset:640
	global_load_dwordx2 v[166:167], v[152:153], off offset:2688
	v_add_co_u32_e32 v152, vcc, 0xcd3f000, v68
	s_nop 1
	v_addc_co_u32_e32 v153, vcc, 0, v69, vcc
	v_add_co_u32_e32 v154, vcc, 0xcd40000, v68
	s_nop 1
	v_addc_co_u32_e32 v155, vcc, 0, v69, vcc
	v_add_co_u32_e32 v226, vcc, 0xcd5f000, v68
	global_load_dwordx2 v[162:163], v[152:153], off offset:2560
	global_load_dwordx2 v[164:165], v[154:155], off offset:512
	global_load_dwordx2 v[160:161], v[154:155], off offset:640
	global_load_dwordx2 v[158:159], v[152:153], off offset:2688
	v_addc_co_u32_e32 v227, vcc, 0, v69, vcc
	v_add_co_u32_e32 v68, vcc, 0xcd60000, v68
	s_nop 1
	v_addc_co_u32_e32 v69, vcc, 0, v69, vcc
	global_load_dwordx2 v[154:155], v[226:227], off offset:2560
	global_load_dwordx2 v[156:157], v[68:69], off offset:512
	global_load_dwordx2 v[152:153], v[68:69], off offset:640
	s_nop 0
	global_load_dwordx2 v[68:69], v[226:227], off offset:2688
	s_waitcnt vmcnt(28)
	v_cvt_f32_ubyte1_e32 v233, v210
	v_cvt_f32_ubyte0_e32 v66, v220
	v_cvt_f32_ubyte0_e32 v232, v210
	v_cvt_f32_ubyte3_e32 v231, v210
	v_cvt_f32_ubyte2_e32 v230, v210
	v_rcp_iflag_f32_e32 v226, v66
	v_cvt_f32_ubyte1_e32 v66, v220
	v_rcp_iflag_f32_e32 v227, v66
	v_cvt_f32_ubyte2_e32 v66, v220
	v_rcp_iflag_f32_e32 v228, v66
	v_cvt_f32_ubyte3_e32 v66, v220
	v_rcp_iflag_f32_e32 v229, v66
	v_pk_mul_f32 v[226:227], v[226:227], v[232:233]
	v_cvt_f32_ubyte0_e32 v66, v221
	v_pk_mul_f32 v[130:131], v[130:131], v[226:227]
	v_rcp_iflag_f32_e32 v226, v66
	v_cvt_f32_ubyte1_e32 v66, v221
	v_rcp_iflag_f32_e32 v227, v66
	v_cvt_f32_ubyte2_e32 v66, v221
	v_pk_mul_f32 v[228:229], v[228:229], v[230:231]
	v_rcp_iflag_f32_e32 v220, v66
	v_cvt_f32_ubyte3_e32 v66, v221
	v_cvt_f32_ubyte1_e32 v231, v211
	v_cvt_f32_ubyte0_e32 v230, v211
	v_pk_mul_f32 v[132:133], v[132:133], v[228:229]
	v_rcp_iflag_f32_e32 v221, v66
	v_cvt_f32_ubyte3_e32 v229, v211
	v_cvt_f32_ubyte2_e32 v228, v211
	v_pk_mul_f32 v[210:211], v[226:227], v[230:231]
	v_cvt_f32_ubyte0_e32 v66, v222
	v_pk_mul_f32 v[126:127], v[126:127], v[210:211]
	v_rcp_iflag_f32_e32 v210, v66
	v_cvt_f32_ubyte1_e32 v66, v222
	v_rcp_iflag_f32_e32 v211, v66
	v_pk_mul_f32 v[220:221], v[220:221], v[228:229]
	v_cvt_f32_ubyte2_e32 v66, v222
	v_pk_mul_f32 v[128:129], v[128:129], v[220:221]
	v_rcp_iflag_f32_e32 v220, v66
	v_cvt_f32_ubyte3_e32 v66, v222
	v_cvt_f32_ubyte1_e32 v229, v224
	v_cvt_f32_ubyte0_e32 v228, v224
	v_rcp_iflag_f32_e32 v221, v66
	v_pk_mul_f32 v[210:211], v[210:211], v[228:229]
	v_cvt_f32_ubyte0_e32 v66, v223
	v_pk_mul_f32 v[122:123], v[122:123], v[210:211]
	v_rcp_iflag_f32_e32 v210, v66
	v_cvt_f32_ubyte1_e32 v66, v223
	v_rcp_iflag_f32_e32 v211, v66
	v_cvt_f32_ubyte3_e32 v227, v224
	v_cvt_f32_ubyte2_e32 v226, v224
	v_pk_mul_f32 v[220:221], v[220:221], v[226:227]
	v_cvt_f32_ubyte2_e32 v66, v223
	v_pk_mul_f32 v[124:125], v[124:125], v[220:221]
	v_rcp_iflag_f32_e32 v220, v66
	v_cvt_f32_ubyte3_e32 v66, v223
	v_cvt_f32_ubyte1_e32 v227, v225
	v_cvt_f32_ubyte0_e32 v226, v225
	v_rcp_iflag_f32_e32 v221, v66
	v_pk_mul_f32 v[210:211], v[210:211], v[226:227]
	s_waitcnt vmcnt(26)
	v_cvt_f32_ubyte0_e32 v66, v204
	v_pk_mul_f32 v[118:119], v[118:119], v[210:211]
	v_rcp_iflag_f32_e32 v210, v66
	v_cvt_f32_ubyte1_e32 v66, v204
	v_rcp_iflag_f32_e32 v211, v66
	v_cvt_f32_ubyte3_e32 v223, v225
	v_cvt_f32_ubyte2_e32 v222, v225
	v_pk_mul_f32 v[220:221], v[220:221], v[222:223]
	v_cvt_f32_ubyte2_e32 v66, v204
	v_pk_mul_f32 v[120:121], v[120:121], v[220:221]
	v_rcp_iflag_f32_e32 v220, v66
	v_cvt_f32_ubyte3_e32 v66, v204
	v_cvt_f32_ubyte1_e32 v225, v202
	v_cvt_f32_ubyte0_e32 v224, v202
	v_rcp_iflag_f32_e32 v221, v66
	v_pk_mul_f32 v[210:211], v[210:211], v[224:225]
	v_cvt_f32_ubyte0_e32 v66, v205
	v_pk_mul_f32 v[114:115], v[114:115], v[210:211]
	v_rcp_iflag_f32_e32 v210, v66
	v_cvt_f32_ubyte1_e32 v66, v205
	v_rcp_iflag_f32_e32 v211, v66
	v_cvt_f32_ubyte3_e32 v223, v202
	v_cvt_f32_ubyte2_e32 v222, v202
	v_cvt_f32_ubyte2_e32 v66, v205
	v_pk_mul_f32 v[220:221], v[220:221], v[222:223]
	v_rcp_iflag_f32_e32 v204, v66
	v_cvt_f32_ubyte3_e32 v66, v205
	v_cvt_f32_ubyte1_e32 v223, v203
	v_cvt_f32_ubyte0_e32 v222, v203
	v_pk_mul_f32 v[116:117], v[116:117], v[220:221]
	v_rcp_iflag_f32_e32 v205, v66
	v_cvt_f32_ubyte3_e32 v221, v203
	v_cvt_f32_ubyte2_e32 v220, v203
	v_pk_mul_f32 v[202:203], v[210:211], v[222:223]
	s_waitcnt vmcnt(25)
	v_cvt_f32_ubyte0_e32 v66, v200
	v_pk_mul_f32 v[110:111], v[110:111], v[202:203]
	v_rcp_iflag_f32_e32 v202, v66
	v_cvt_f32_ubyte1_e32 v66, v200
	v_rcp_iflag_f32_e32 v203, v66
	v_pk_mul_f32 v[204:205], v[204:205], v[220:221]
	v_cvt_f32_ubyte2_e32 v66, v200
	v_pk_mul_f32 v[112:113], v[112:113], v[204:205]
	v_rcp_iflag_f32_e32 v204, v66
	v_cvt_f32_ubyte3_e32 v66, v200
	s_waitcnt vmcnt(24)
; __device__ __forceinline__ float gate_v(unsigned q) { return (float)q; }
;     __device__ __forceinline__ void mid(f32x4 (&acc)[2][2][4][2], const Unit& u, int seg, int wr, int wc, int fr, int fq) const {
;     ...
;         for (int ai = 0; ai < 2; ++ai)
; #pragma unroll
;             for (int m = 0; m < 4; ++m)
; #pragma unroll
;                 for (int bj = 0; bj < 2; ++bj)
; #pragma unroll
;                     for (int e = 0; e < 8; ++e) { const unsigned a = (ga[ai][m][bj][e >> 2] >> (8 * (e & 3))) & 255u, b = (gb[ai][m][bj][e >> 2] >> (8 * (e & 3))) & 255u;
;                         acc[ai][bj][m][e >> 2][e & 3] *= gate_v(a) * __builtin_amdgcn_rcpf(gate_v(b)); }
	v_cvt_f32_ubyte1_e32 v221, v198
	v_cvt_f32_ubyte0_e32 v220, v198
	v_rcp_iflag_f32_e32 v205, v66
	v_pk_mul_f32 v[202:203], v[202:203], v[220:221]
	v_cvt_f32_ubyte0_e32 v66, v201
	v_pk_mul_f32 v[106:107], v[106:107], v[202:203]
	v_rcp_iflag_f32_e32 v202, v66
	v_cvt_f32_ubyte1_e32 v66, v201
	v_rcp_iflag_f32_e32 v203, v66
	v_cvt_f32_ubyte3_e32 v211, v198
	v_cvt_f32_ubyte2_e32 v210, v198
	v_cvt_f32_ubyte2_e32 v66, v201
	v_pk_mul_f32 v[204:205], v[204:205], v[210:211]
	v_rcp_iflag_f32_e32 v200, v66
	v_cvt_f32_ubyte3_e32 v66, v201
	v_cvt_f32_ubyte1_e32 v211, v199
	v_cvt_f32_ubyte0_e32 v210, v199
	v_pk_mul_f32 v[108:109], v[108:109], v[204:205]
	v_rcp_iflag_f32_e32 v201, v66
	v_cvt_f32_ubyte3_e32 v205, v199
	v_cvt_f32_ubyte2_e32 v204, v199
	v_pk_mul_f32 v[198:199], v[202:203], v[210:211]
	s_waitcnt vmcnt(22)
	v_cvt_f32_ubyte0_e32 v66, v196
	v_pk_mul_f32 v[102:103], v[102:103], v[198:199]
	v_rcp_iflag_f32_e32 v198, v66
	v_cvt_f32_ubyte1_e32 v66, v196
	v_rcp_iflag_f32_e32 v199, v66
	v_pk_mul_f32 v[200:201], v[200:201], v[204:205]
	v_cvt_f32_ubyte2_e32 v66, v196
	v_pk_mul_f32 v[104:105], v[104:105], v[200:201]
	v_rcp_iflag_f32_e32 v200, v66
	v_cvt_f32_ubyte3_e32 v66, v196
	v_cvt_f32_ubyte1_e32 v205, v194
	v_cvt_f32_ubyte0_e32 v204, v194
	v_rcp_iflag_f32_e32 v201, v66
	v_pk_mul_f32 v[198:199], v[198:199], v[204:205]
	v_cvt_f32_ubyte0_e32 v66, v197
	v_pk_mul_f32 v[98:99], v[98:99], v[198:199]
	v_rcp_iflag_f32_e32 v198, v66
	v_cvt_f32_ubyte1_e32 v66, v197
	v_rcp_iflag_f32_e32 v199, v66
	v_cvt_f32_ubyte3_e32 v203, v194
	v_cvt_f32_ubyte2_e32 v202, v194
	v_cvt_f32_ubyte2_e32 v66, v197
	v_pk_mul_f32 v[200:201], v[200:201], v[202:203]
	v_rcp_iflag_f32_e32 v196, v66
	v_cvt_f32_ubyte3_e32 v66, v197
	v_cvt_f32_ubyte1_e32 v203, v195
	v_cvt_f32_ubyte0_e32 v202, v195
	v_pk_mul_f32 v[100:101], v[100:101], v[200:201]
	v_rcp_iflag_f32_e32 v197, v66
	v_cvt_f32_ubyte3_e32 v201, v195
	v_cvt_f32_ubyte2_e32 v200, v195
	v_pk_mul_f32 v[194:195], v[198:199], v[202:203]
	s_waitcnt vmcnt(21)
	v_cvt_f32_ubyte0_e32 v66, v192
	v_pk_mul_f32 v[94:95], v[94:95], v[194:195]
	v_rcp_iflag_f32_e32 v194, v66
	v_cvt_f32_ubyte1_e32 v66, v192
	v_rcp_iflag_f32_e32 v195, v66
	v_pk_mul_f32 v[196:197], v[196:197], v[200:201]
	v_cvt_f32_ubyte2_e32 v66, v192
	v_pk_mul_f32 v[96:97], v[96:97], v[196:197]
	v_rcp_iflag_f32_e32 v196, v66
	v_cvt_f32_ubyte3_e32 v66, v192
	s_waitcnt vmcnt(20)
	v_cvt_f32_ubyte1_e32 v201, v190
	v_cvt_f32_ubyte0_e32 v200, v190
	v_rcp_iflag_f32_e32 v197, v66
	v_pk_mul_f32 v[194:195], v[194:195], v[200:201]
	v_cvt_f32_ubyte0_e32 v66, v193
	v_pk_mul_f32 v[90:91], v[90:91], v[194:195]
	v_rcp_iflag_f32_e32 v194, v66
	v_cvt_f32_ubyte1_e32 v66, v193
	v_rcp_iflag_f32_e32 v195, v66
	v_cvt_f32_ubyte3_e32 v199, v190
	v_cvt_f32_ubyte2_e32 v198, v190
	v_cvt_f32_ubyte2_e32 v66, v193
	v_pk_mul_f32 v[196:197], v[196:197], v[198:199]
	v_rcp_iflag_f32_e32 v192, v66
	v_cvt_f32_ubyte3_e32 v66, v193
	v_cvt_f32_ubyte1_e32 v199, v191
	v_cvt_f32_ubyte0_e32 v198, v191
	v_pk_mul_f32 v[92:93], v[92:93], v[196:197]
	v_rcp_iflag_f32_e32 v193, v66
	v_cvt_f32_ubyte3_e32 v197, v191
	v_cvt_f32_ubyte2_e32 v196, v191
	v_pk_mul_f32 v[190:191], v[194:195], v[198:199]
	s_waitcnt vmcnt(18)
	v_cvt_f32_ubyte0_e32 v66, v188
	v_pk_mul_f32 v[86:87], v[86:87], v[190:191]
	v_rcp_iflag_f32_e32 v190, v66
	v_cvt_f32_ubyte1_e32 v66, v188
	v_rcp_iflag_f32_e32 v191, v66
	v_pk_mul_f32 v[192:193], v[192:193], v[196:197]
	v_cvt_f32_ubyte2_e32 v66, v188
	v_pk_mul_f32 v[88:89], v[88:89], v[192:193]
	v_rcp_iflag_f32_e32 v192, v66
	v_cvt_f32_ubyte3_e32 v66, v188
	v_cvt_f32_ubyte1_e32 v197, v186
	v_cvt_f32_ubyte0_e32 v196, v186
	v_rcp_iflag_f32_e32 v193, v66
	v_pk_mul_f32 v[190:191], v[190:191], v[196:197]
	v_cvt_f32_ubyte0_e32 v66, v189
	v_pk_mul_f32 v[82:83], v[82:83], v[190:191]
	v_rcp_iflag_f32_e32 v190, v66
	v_cvt_f32_ubyte1_e32 v66, v189
	v_rcp_iflag_f32_e32 v191, v66
	v_cvt_f32_ubyte3_e32 v195, v186
	v_cvt_f32_ubyte2_e32 v194, v186
	v_cvt_f32_ubyte2_e32 v66, v189
	v_pk_mul_f32 v[192:193], v[192:193], v[194:195]
	v_rcp_iflag_f32_e32 v188, v66
	v_cvt_f32_ubyte3_e32 v66, v189
	v_cvt_f32_ubyte1_e32 v195, v187
	v_cvt_f32_ubyte0_e32 v194, v187
	v_pk_mul_f32 v[84:85], v[84:85], v[192:193]
	v_rcp_iflag_f32_e32 v189, v66
	v_cvt_f32_ubyte3_e32 v193, v187
	v_cvt_f32_ubyte2_e32 v192, v187
	v_pk_mul_f32 v[186:187], v[190:191], v[194:195]
	s_waitcnt vmcnt(17)
	v_cvt_f32_ubyte0_e32 v66, v184
	v_pk_mul_f32 v[78:79], v[78:79], v[186:187]
	v_rcp_iflag_f32_e32 v186, v66
	v_cvt_f32_ubyte1_e32 v66, v184
	v_rcp_iflag_f32_e32 v187, v66
	v_pk_mul_f32 v[188:189], v[188:189], v[192:193]
	v_cvt_f32_ubyte2_e32 v66, v184
	v_pk_mul_f32 v[80:81], v[80:81], v[188:189]
	v_rcp_iflag_f32_e32 v188, v66
	v_cvt_f32_ubyte3_e32 v66, v184
	s_waitcnt vmcnt(16)
	v_cvt_f32_ubyte1_e32 v193, v182
	v_cvt_f32_ubyte0_e32 v192, v182
	v_rcp_iflag_f32_e32 v189, v66
	v_pk_mul_f32 v[186:187], v[186:187], v[192:193]
	v_cvt_f32_ubyte0_e32 v66, v185
	v_pk_mul_f32 v[74:75], v[74:75], v[186:187]
	v_rcp_iflag_f32_e32 v186, v66
	v_cvt_f32_ubyte1_e32 v66, v185
	v_rcp_iflag_f32_e32 v187, v66
	v_cvt_f32_ubyte3_e32 v191, v182
	v_cvt_f32_ubyte2_e32 v190, v182
	v_cvt_f32_ubyte2_e32 v66, v185
	v_pk_mul_f32 v[188:189], v[188:189], v[190:191]
	v_rcp_iflag_f32_e32 v184, v66
	v_cvt_f32_ubyte3_e32 v66, v185
	v_cvt_f32_ubyte1_e32 v191, v183
	v_cvt_f32_ubyte0_e32 v190, v183
	v_pk_mul_f32 v[76:77], v[76:77], v[188:189]
	v_rcp_iflag_f32_e32 v185, v66
	v_cvt_f32_ubyte3_e32 v189, v183
	v_cvt_f32_ubyte2_e32 v188, v183
	v_pk_mul_f32 v[182:183], v[186:187], v[190:191]
	s_waitcnt vmcnt(14)
; __device__ __forceinline__ float gate_v(unsigned q) { return (float)q; }
;     __device__ __forceinline__ void mid(f32x4 (&acc)[2][2][4][2], const Unit& u, int seg, int wr, int wc, int fr, int fq) const {
;     ...
;         for (int ai = 0; ai < 2; ++ai)
; #pragma unroll
;             for (int m = 0; m < 4; ++m)
; #pragma unroll
;                 for (int bj = 0; bj < 2; ++bj)
; #pragma unroll
;                     for (int e = 0; e < 8; ++e) { const unsigned a = (ga[ai][m][bj][e >> 2] >> (8 * (e & 3))) & 255u, b = (gb[ai][m][bj][e >> 2] >> (8 * (e & 3))) & 255u;
;                         acc[ai][bj][m][e >> 2][e & 3] *= gate_v(a) * __builtin_amdgcn_rcpf(gate_v(b)); }
	v_cvt_f32_ubyte0_e32 v66, v180
	v_pk_mul_f32 v[70:71], v[70:71], v[182:183]
	v_rcp_iflag_f32_e32 v182, v66
	v_cvt_f32_ubyte1_e32 v66, v180
	v_rcp_iflag_f32_e32 v183, v66
	v_pk_mul_f32 v[184:185], v[184:185], v[188:189]
	v_cvt_f32_ubyte2_e32 v66, v180
	v_pk_mul_f32 v[72:73], v[72:73], v[184:185]
	v_rcp_iflag_f32_e32 v184, v66
	v_cvt_f32_ubyte3_e32 v66, v180
	v_cvt_f32_ubyte1_e32 v189, v178
	v_cvt_f32_ubyte0_e32 v188, v178
	v_rcp_iflag_f32_e32 v185, v66
	v_pk_mul_f32 v[182:183], v[182:183], v[188:189]
	v_cvt_f32_ubyte0_e32 v66, v181
	v_pk_mul_f32 v[62:63], v[62:63], v[182:183]
	v_rcp_iflag_f32_e32 v182, v66
	v_cvt_f32_ubyte1_e32 v66, v181
	v_rcp_iflag_f32_e32 v183, v66
	v_cvt_f32_ubyte3_e32 v187, v178
	v_cvt_f32_ubyte2_e32 v186, v178
	v_cvt_f32_ubyte2_e32 v66, v181
	v_pk_mul_f32 v[184:185], v[184:185], v[186:187]
	v_rcp_iflag_f32_e32 v180, v66
	v_cvt_f32_ubyte3_e32 v66, v181
	v_cvt_f32_ubyte1_e32 v187, v179
	v_cvt_f32_ubyte0_e32 v186, v179
	v_pk_mul_f32 v[64:65], v[64:65], v[184:185]
	v_rcp_iflag_f32_e32 v181, v66
	v_cvt_f32_ubyte3_e32 v185, v179
	v_cvt_f32_ubyte2_e32 v184, v179
	v_pk_mul_f32 v[178:179], v[182:183], v[186:187]
	s_waitcnt vmcnt(13)
	v_cvt_f32_ubyte0_e32 v66, v176
	v_pk_mul_f32 v[58:59], v[58:59], v[178:179]
	v_rcp_iflag_f32_e32 v178, v66
	v_cvt_f32_ubyte1_e32 v66, v176
	v_rcp_iflag_f32_e32 v179, v66
	v_pk_mul_f32 v[180:181], v[180:181], v[184:185]
	v_cvt_f32_ubyte2_e32 v66, v176
	v_pk_mul_f32 v[60:61], v[60:61], v[180:181]
	v_rcp_iflag_f32_e32 v180, v66
	v_cvt_f32_ubyte3_e32 v66, v176
	s_waitcnt vmcnt(12)
	v_cvt_f32_ubyte1_e32 v185, v174
	v_cvt_f32_ubyte0_e32 v184, v174
	v_rcp_iflag_f32_e32 v181, v66
	v_pk_mul_f32 v[178:179], v[178:179], v[184:185]
	v_cvt_f32_ubyte0_e32 v66, v177
	v_pk_mul_f32 v[54:55], v[54:55], v[178:179]
	v_rcp_iflag_f32_e32 v178, v66
	v_cvt_f32_ubyte1_e32 v66, v177
	v_rcp_iflag_f32_e32 v179, v66
	v_cvt_f32_ubyte3_e32 v183, v174
	v_cvt_f32_ubyte2_e32 v182, v174
	v_cvt_f32_ubyte2_e32 v66, v177
	v_pk_mul_f32 v[180:181], v[180:181], v[182:183]
	v_rcp_iflag_f32_e32 v176, v66
	v_cvt_f32_ubyte3_e32 v66, v177
	v_cvt_f32_ubyte1_e32 v183, v175
	v_cvt_f32_ubyte0_e32 v182, v175
	v_pk_mul_f32 v[56:57], v[56:57], v[180:181]
	v_rcp_iflag_f32_e32 v177, v66
	v_cvt_f32_ubyte3_e32 v181, v175
	v_cvt_f32_ubyte2_e32 v180, v175
	v_pk_mul_f32 v[174:175], v[178:179], v[182:183]
	s_waitcnt vmcnt(10)
	v_cvt_f32_ubyte0_e32 v66, v172
	v_pk_mul_f32 v[50:51], v[50:51], v[174:175]
	v_rcp_iflag_f32_e32 v174, v66
	v_cvt_f32_ubyte1_e32 v66, v172
	v_rcp_iflag_f32_e32 v175, v66
	v_pk_mul_f32 v[176:177], v[176:177], v[180:181]
	v_cvt_f32_ubyte2_e32 v66, v172
	v_pk_mul_f32 v[52:53], v[52:53], v[176:177]
	v_rcp_iflag_f32_e32 v176, v66
	v_cvt_f32_ubyte3_e32 v66, v172
	v_cvt_f32_ubyte1_e32 v181, v170
	v_cvt_f32_ubyte0_e32 v180, v170
	v_rcp_iflag_f32_e32 v177, v66
	v_pk_mul_f32 v[174:175], v[174:175], v[180:181]
	v_cvt_f32_ubyte0_e32 v66, v173
	v_pk_mul_f32 v[46:47], v[46:47], v[174:175]
	v_rcp_iflag_f32_e32 v174, v66
	v_cvt_f32_ubyte1_e32 v66, v173
	v_rcp_iflag_f32_e32 v175, v66
	v_cvt_f32_ubyte3_e32 v179, v170
	v_cvt_f32_ubyte2_e32 v178, v170
	v_cvt_f32_ubyte2_e32 v66, v173
	v_pk_mul_f32 v[176:177], v[176:177], v[178:179]
	v_rcp_iflag_f32_e32 v172, v66
	v_cvt_f32_ubyte3_e32 v66, v173
	v_cvt_f32_ubyte1_e32 v179, v171
	v_cvt_f32_ubyte0_e32 v178, v171
	v_pk_mul_f32 v[48:49], v[48:49], v[176:177]
	v_rcp_iflag_f32_e32 v173, v66
	v_cvt_f32_ubyte3_e32 v177, v171
	v_cvt_f32_ubyte2_e32 v176, v171
	v_pk_mul_f32 v[170:171], v[174:175], v[178:179]
	s_waitcnt vmcnt(9)
	v_cvt_f32_ubyte0_e32 v66, v168
	v_pk_mul_f32 v[42:43], v[42:43], v[170:171]
	v_rcp_iflag_f32_e32 v170, v66
	v_cvt_f32_ubyte1_e32 v66, v168
	v_rcp_iflag_f32_e32 v171, v66
	v_pk_mul_f32 v[172:173], v[172:173], v[176:177]
	v_cvt_f32_ubyte2_e32 v66, v168
	v_pk_mul_f32 v[44:45], v[44:45], v[172:173]
	v_rcp_iflag_f32_e32 v172, v66
	v_cvt_f32_ubyte3_e32 v66, v168
	s_waitcnt vmcnt(8)
	v_cvt_f32_ubyte1_e32 v177, v166
	v_cvt_f32_ubyte0_e32 v176, v166
	v_rcp_iflag_f32_e32 v173, v66
	v_pk_mul_f32 v[170:171], v[170:171], v[176:177]
	v_cvt_f32_ubyte0_e32 v66, v169
	v_pk_mul_f32 v[38:39], v[38:39], v[170:171]
	v_rcp_iflag_f32_e32 v170, v66
	v_cvt_f32_ubyte1_e32 v66, v169
	v_rcp_iflag_f32_e32 v171, v66
	v_cvt_f32_ubyte3_e32 v175, v166
	v_cvt_f32_ubyte2_e32 v174, v166
	v_cvt_f32_ubyte2_e32 v66, v169
	v_pk_mul_f32 v[172:173], v[172:173], v[174:175]
	v_rcp_iflag_f32_e32 v168, v66
	v_cvt_f32_ubyte3_e32 v66, v169
	v_cvt_f32_ubyte1_e32 v175, v167
	v_cvt_f32_ubyte0_e32 v174, v167
	v_pk_mul_f32 v[40:41], v[40:41], v[172:173]
	v_rcp_iflag_f32_e32 v169, v66
	v_cvt_f32_ubyte3_e32 v173, v167
	v_cvt_f32_ubyte2_e32 v172, v167
	v_pk_mul_f32 v[166:167], v[170:171], v[174:175]
	s_waitcnt vmcnt(6)
; __device__ __forceinline__ float gate_v(unsigned q) { return (float)q; }
;     __device__ __forceinline__ void mid(f32x4 (&acc)[2][2][4][2], const Unit& u, int seg, int wr, int wc, int fr, int fq) const {
;     ...
;         for (int ai = 0; ai < 2; ++ai)
; #pragma unroll
;             for (int m = 0; m < 4; ++m)
; #pragma unroll
;                 for (int bj = 0; bj < 2; ++bj)
; #pragma unroll
;                     for (int e = 0; e < 8; ++e) { const unsigned a = (ga[ai][m][bj][e >> 2] >> (8 * (e & 3))) & 255u, b = (gb[ai][m][bj][e >> 2] >> (8 * (e & 3))) & 255u;
;                         acc[ai][bj][m][e >> 2][e & 3] *= gate_v(a) * __builtin_amdgcn_rcpf(gate_v(b)); }
;         asm volatile("" ::: "memory");
	v_cvt_f32_ubyte0_e32 v66, v164
	v_pk_mul_f32 v[34:35], v[34:35], v[166:167]
	v_rcp_iflag_f32_e32 v166, v66
	v_cvt_f32_ubyte1_e32 v66, v164
	v_rcp_iflag_f32_e32 v167, v66
	v_pk_mul_f32 v[168:169], v[168:169], v[172:173]
	v_cvt_f32_ubyte2_e32 v66, v164
	v_pk_mul_f32 v[36:37], v[36:37], v[168:169]
	v_rcp_iflag_f32_e32 v168, v66
	v_cvt_f32_ubyte3_e32 v66, v164
	v_cvt_f32_ubyte1_e32 v173, v162
	v_cvt_f32_ubyte0_e32 v172, v162
	v_rcp_iflag_f32_e32 v169, v66
	v_pk_mul_f32 v[166:167], v[166:167], v[172:173]
	v_cvt_f32_ubyte0_e32 v66, v165
	v_pk_mul_f32 v[30:31], v[30:31], v[166:167]
	v_rcp_iflag_f32_e32 v166, v66
	v_cvt_f32_ubyte1_e32 v66, v165
	v_rcp_iflag_f32_e32 v167, v66
	v_cvt_f32_ubyte3_e32 v171, v162
	v_cvt_f32_ubyte2_e32 v170, v162
	v_cvt_f32_ubyte2_e32 v66, v165
	v_pk_mul_f32 v[168:169], v[168:169], v[170:171]
	v_rcp_iflag_f32_e32 v164, v66
	v_cvt_f32_ubyte3_e32 v66, v165
	v_cvt_f32_ubyte1_e32 v171, v163
	v_cvt_f32_ubyte0_e32 v170, v163
	v_pk_mul_f32 v[32:33], v[32:33], v[168:169]
	v_rcp_iflag_f32_e32 v165, v66
	v_cvt_f32_ubyte3_e32 v169, v163
	v_cvt_f32_ubyte2_e32 v168, v163
	v_pk_mul_f32 v[162:163], v[166:167], v[170:171]
	s_waitcnt vmcnt(5)
	v_cvt_f32_ubyte0_e32 v66, v160
	v_pk_mul_f32 v[26:27], v[26:27], v[162:163]
	v_rcp_iflag_f32_e32 v162, v66
	v_cvt_f32_ubyte1_e32 v66, v160
	v_rcp_iflag_f32_e32 v163, v66
	v_pk_mul_f32 v[164:165], v[164:165], v[168:169]
	v_cvt_f32_ubyte2_e32 v66, v160
	v_pk_mul_f32 v[28:29], v[28:29], v[164:165]
	v_rcp_iflag_f32_e32 v164, v66
	v_cvt_f32_ubyte3_e32 v66, v160
	s_waitcnt vmcnt(4)
	v_cvt_f32_ubyte1_e32 v169, v158
	v_cvt_f32_ubyte0_e32 v168, v158
	v_rcp_iflag_f32_e32 v165, v66
	v_pk_mul_f32 v[162:163], v[162:163], v[168:169]
	v_cvt_f32_ubyte0_e32 v66, v161
	v_pk_mul_f32 v[22:23], v[22:23], v[162:163]
	v_rcp_iflag_f32_e32 v162, v66
	v_cvt_f32_ubyte1_e32 v66, v161
	v_rcp_iflag_f32_e32 v163, v66
	v_cvt_f32_ubyte3_e32 v167, v158
	v_cvt_f32_ubyte2_e32 v166, v158
	v_cvt_f32_ubyte2_e32 v66, v161
	v_pk_mul_f32 v[164:165], v[164:165], v[166:167]
	v_rcp_iflag_f32_e32 v160, v66
	v_cvt_f32_ubyte3_e32 v66, v161
	v_cvt_f32_ubyte1_e32 v167, v159
	v_cvt_f32_ubyte0_e32 v166, v159
	v_pk_mul_f32 v[24:25], v[24:25], v[164:165]
	v_rcp_iflag_f32_e32 v161, v66
	v_cvt_f32_ubyte3_e32 v165, v159
	v_cvt_f32_ubyte2_e32 v164, v159
	v_pk_mul_f32 v[158:159], v[162:163], v[166:167]
	s_waitcnt vmcnt(2)
	v_cvt_f32_ubyte0_e32 v66, v156
	v_pk_mul_f32 v[18:19], v[18:19], v[158:159]
	v_rcp_iflag_f32_e32 v158, v66
	v_cvt_f32_ubyte1_e32 v66, v156
	v_rcp_iflag_f32_e32 v159, v66
	v_pk_mul_f32 v[160:161], v[160:161], v[164:165]
	v_cvt_f32_ubyte2_e32 v66, v156
	v_pk_mul_f32 v[20:21], v[20:21], v[160:161]
	v_rcp_iflag_f32_e32 v160, v66
	v_cvt_f32_ubyte3_e32 v66, v156
	v_cvt_f32_ubyte1_e32 v165, v154
	v_cvt_f32_ubyte0_e32 v164, v154
	v_rcp_iflag_f32_e32 v161, v66
	v_pk_mul_f32 v[158:159], v[158:159], v[164:165]
	v_cvt_f32_ubyte0_e32 v66, v157
	v_pk_mul_f32 v[14:15], v[14:15], v[158:159]
	v_rcp_iflag_f32_e32 v158, v66
	v_cvt_f32_ubyte1_e32 v66, v157
	v_rcp_iflag_f32_e32 v159, v66
	v_cvt_f32_ubyte3_e32 v163, v154
	v_cvt_f32_ubyte2_e32 v162, v154
	v_cvt_f32_ubyte2_e32 v66, v157
	v_pk_mul_f32 v[160:161], v[160:161], v[162:163]
	v_rcp_iflag_f32_e32 v156, v66
	v_cvt_f32_ubyte3_e32 v66, v157
	v_cvt_f32_ubyte1_e32 v163, v155
	v_cvt_f32_ubyte0_e32 v162, v155
	v_pk_mul_f32 v[16:17], v[16:17], v[160:161]
	v_rcp_iflag_f32_e32 v157, v66
	v_cvt_f32_ubyte3_e32 v161, v155
	v_cvt_f32_ubyte2_e32 v160, v155
	v_pk_mul_f32 v[154:155], v[158:159], v[162:163]
	s_waitcnt vmcnt(1)
	v_cvt_f32_ubyte0_e32 v66, v152
	v_pk_mul_f32 v[10:11], v[10:11], v[154:155]
	v_rcp_iflag_f32_e32 v154, v66
	v_cvt_f32_ubyte1_e32 v66, v152
	v_rcp_iflag_f32_e32 v155, v66
	v_pk_mul_f32 v[156:157], v[156:157], v[160:161]
	v_cvt_f32_ubyte2_e32 v66, v152
	v_pk_mul_f32 v[12:13], v[12:13], v[156:157]
	v_rcp_iflag_f32_e32 v156, v66
	v_cvt_f32_ubyte3_e32 v66, v152
	s_waitcnt vmcnt(0)
	v_cvt_f32_ubyte1_e32 v161, v68
	v_cvt_f32_ubyte0_e32 v160, v68
	v_rcp_iflag_f32_e32 v157, v66
	v_pk_mul_f32 v[154:155], v[154:155], v[160:161]
	v_cvt_f32_ubyte0_e32 v66, v153
	v_pk_mul_f32 v[6:7], v[6:7], v[154:155]
	v_rcp_iflag_f32_e32 v154, v66
	v_cvt_f32_ubyte1_e32 v66, v153
	v_rcp_iflag_f32_e32 v155, v66
	v_cvt_f32_ubyte2_e32 v66, v153
	v_rcp_iflag_f32_e32 v152, v66
	v_cvt_f32_ubyte3_e32 v66, v153
	v_rcp_iflag_f32_e32 v153, v66
	v_cvt_f32_ubyte3_e32 v159, v68
	v_cvt_f32_ubyte2_e32 v158, v68
	v_pk_mul_f32 v[156:157], v[156:157], v[158:159]
	v_cvt_f32_ubyte1_e32 v159, v69
	v_pk_mul_f32 v[8:9], v[8:9], v[156:157]
	v_cvt_f32_ubyte3_e32 v157, v69
	v_cvt_f32_ubyte2_e32 v156, v69
	v_cvt_f32_ubyte0_e32 v158, v69
	v_pk_mul_f32 v[68:69], v[154:155], v[158:159]
	v_pk_mul_f32 v[152:153], v[152:153], v[156:157]
	v_pk_mul_f32 v[2:3], v[2:3], v[68:69]
	v_pk_mul_f32 v[4:5], v[4:5], v[152:153]
	s_branch .LBB0_781

;     __host__ __device__ bool next(int i, Unit& u) const { if (i != 0 || r < 0 || r >= 148) return false; if (r < 116) { u.pm = r % 29; u.pn = 47 + r / 29; } else { u.pm = 32; u.pn = 19 + (r - 116); } u.ko = 0; return true; }
;     __host__ __device__ bool next(int i, Unit& u) const { const int L = i * G + (G - 1 - c); if (L >= nN * S) return false; u.pm = pm; u.pn = L % nN; u.ko = (L / nN) * ksub; return true; }
; #define PG8_STAGE(bufoff, gbase, voff) do { _Pragma("unroll") for (int _i = 0; _i < 2; ++_i) \
;         __builtin_amdgcn_global_load_lds((const unsigned*)((const char*)(gbase) + (voff)[_i]), (PG8_LAS unsigned*)(lds + (bufoff) + ldsw + _i * 8192), 16, 0, 0); } while (0)
; #define PG8_LDA(dst, b, h) do { _Pragma("unroll") for (int m = 0; m < 4; ++m) _Pragma("unroll") for (int k = 0; k < 2; ++k) dst[m][k] = *(const PG8_LAS bf16x8*)(lds + PG8_SA(b, h) + aoff + m * 2048 + k * 1024); } while (0)
; #define PG8_BAR __builtin_amdgcn_s_barrier()
; template <class Epi, class Sched, bool ALIGN_EPI = false, bool SP2 = false>
; __device__ __forceinline__ void gemm_phase(PG8_LAS unsigned char* lds, const Gemm g, const Sched& S, const Epi& E) {
;     ...
;         const bool has_next = S.next(ui + 1, nxt);
;         const char* nA = has_next ? (const char*)g.A + (size_t)nxt.pm * tstep + (size_t)nxt.ko * 2 : cA; const char* nB = has_next ? (const char*)g.Bt + (size_t)nxt.pn * tstep + (size_t)nxt.ko * 2 : cB;
;         for (int t = 0; t < nt; t += 2) {
;             const bool last = (t == nt - 2);
;             const char* a1 = cA + (size_t)(t + 1) * kstep;
;             const char* a2 = last ? nA : cA + (size_t)(t + 2) * kstep; const char* b2 = last ? nB : cB + (size_t)(t + 2) * kstep;
;             const char* a3 = a2 + kstep; const char* b3 = b2 + kstep;
;             if (last && has_next) S.a_ready(nxt);
;             if constexpr (SP2) {
;             PG8_LDB(B0, 0, 0); PG8_LDB(B1, 0, 1); PG8_SCHED; PG8_LDA(At, 0, 0); PG8_STAGE(PG8_SA(1, 1), a1 + hstep, voffA);
;             PG8_WAIT_V(8); PG8_WAIT_L(0); PG8_BAR; PG8_MMA(0, 0, At, B0); PG8_MMA(0, 1, At, B1); PG8_BAR; PG8_SCHED;
;             PG8_LDA(At, 0, 1); PG8_STAGE(PG8_SB(0, 0), b2, voffB); PG8_STAGE(PG8_SB(0, 1), b2 + hstep, voffB); PG8_STAGE(PG8_SA(0, 0), a2, voffA);
;             PG8_WAIT_V(8); PG8_WAIT_L(0); PG8_BAR; PG8_MMA(1, 0, At, B0); PG8_MMA(1, 1, At, B1); PG8_BAR; PG8_SCHED;
.LBB0_802:
	s_add_u32 s22, s20, 0x100
	s_addc_u32 s23, s21, 0
	s_cmp_eq_u32 s43, 4
	s_cselect_b32 s27, s19, s23
	s_cselect_b32 s26, s18, s22
	s_cselect_b32 s25, s17, s15
	s_cselect_b32 s24, s16, s13
	s_add_i32 s44, 0, 0x10000
	s_add_i32 s45, 0, 0x14000
	v_add_u32_e32 v168, s44, v0
	v_add_u32_e32 v184, s45, v0
	ds_read_b128 v[156:159], v168
	ds_read_b128 v[160:163], v168 offset:1024
	ds_read_b128 v[164:167], v168 offset:2048
	ds_read_b128 v[168:171], v168 offset:3072
	ds_read_b128 v[172:175], v184
	ds_read_b128 v[176:179], v184 offset:1024
	ds_read_b128 v[180:183], v184 offset:2048
	ds_read_b128 v[184:187], v184 offset:3072
	v_lshl_add_u64 v[228:229], s[20:21], 0, v[150:151]
	s_add_i32 m0, s30, 0xc000
	ds_read_b128 v[188:191], v155
	ds_read_b128 v[192:195], v155 offset:1024
	ds_read_b128 v[196:199], v155 offset:2048
	ds_read_b128 v[200:203], v155 offset:3072
	ds_read_b128 v[204:207], v155 offset:4096
	ds_read_b128 v[208:211], v155 offset:5120
	ds_read_b128 v[220:223], v155 offset:6144
	ds_read_b128 v[224:227], v155 offset:7168
	global_load_lds_dwordx4 v[228:229], off
	v_lshl_add_u64 v[228:229], s[20:21], 0, v[152:153]
	s_add_i32 m0, s30, 0xe000
	s_nop 0
	global_load_lds_dwordx4 v[228:229], off
	s_waitcnt vmcnt(8)
	s_waitcnt lgkmcnt(0)
	s_barrier
	v_mfma_f32_16x16x32_bf16 v[128:131], v[156:159], v[188:191], v[128:131]
	v_mfma_f32_16x16x32_bf16 v[124:127], v[164:167], v[188:191], v[124:127]
	v_mfma_f32_16x16x32_bf16 v[120:123], v[156:159], v[196:199], v[120:123]
	v_mfma_f32_16x16x32_bf16 v[116:119], v[164:167], v[196:199], v[116:119]
	v_mfma_f32_16x16x32_bf16 v[112:115], v[156:159], v[204:207], v[112:115]
	v_mfma_f32_16x16x32_bf16 v[108:111], v[164:167], v[204:207], v[108:111]
	v_mfma_f32_16x16x32_bf16 v[100:103], v[156:159], v[220:223], v[100:103]
	v_mfma_f32_16x16x32_bf16 v[92:95], v[164:167], v[220:223], v[92:95]
	v_mfma_f32_16x16x32_bf16 v[128:131], v[160:163], v[192:195], v[128:131]
	v_mfma_f32_16x16x32_bf16 v[124:127], v[168:171], v[192:195], v[124:127]
	v_mfma_f32_16x16x32_bf16 v[120:123], v[160:163], v[200:203], v[120:123]
	v_mfma_f32_16x16x32_bf16 v[116:119], v[168:171], v[200:203], v[116:119]
	v_mfma_f32_16x16x32_bf16 v[112:115], v[160:163], v[208:211], v[112:115]
	v_mfma_f32_16x16x32_bf16 v[108:111], v[168:171], v[208:211], v[108:111]
	v_mfma_f32_16x16x32_bf16 v[100:103], v[160:163], v[224:227], v[100:103]
	v_mfma_f32_16x16x32_bf16 v[92:95], v[168:171], v[224:227], v[92:95]
	v_mfma_f32_16x16x32_bf16 v[104:107], v[172:175], v[188:191], v[104:107]
	v_mfma_f32_16x16x32_bf16 v[96:99], v[180:183], v[188:191], v[96:99]
	v_mfma_f32_16x16x32_bf16 v[88:91], v[172:175], v[196:199], v[88:91]
	v_mfma_f32_16x16x32_bf16 v[84:87], v[180:183], v[196:199], v[84:87]
	v_mfma_f32_16x16x32_bf16 v[80:83], v[172:175], v[204:207], v[80:83]
	v_mfma_f32_16x16x32_bf16 v[76:79], v[180:183], v[204:207], v[76:79]
	v_mfma_f32_16x16x32_bf16 v[72:75], v[172:175], v[220:223], v[72:75]
	v_mfma_f32_16x16x32_bf16 v[68:71], v[180:183], v[220:223], v[68:71]
	v_mfma_f32_16x16x32_bf16 v[104:107], v[176:179], v[192:195], v[104:107]
	v_mfma_f32_16x16x32_bf16 v[96:99], v[184:187], v[192:195], v[96:99]
	v_mfma_f32_16x16x32_bf16 v[88:91], v[176:179], v[200:203], v[88:91]
	v_mfma_f32_16x16x32_bf16 v[84:87], v[184:187], v[200:203], v[84:87]
	v_mfma_f32_16x16x32_bf16 v[80:83], v[176:179], v[208:211], v[80:83]
	v_mfma_f32_16x16x32_bf16 v[76:79], v[184:187], v[208:211], v[76:79]
	v_mfma_f32_16x16x32_bf16 v[72:75], v[176:179], v[224:227], v[72:75]
	v_mfma_f32_16x16x32_bf16 v[68:71], v[184:187], v[224:227], v[68:71]
	s_barrier
	s_add_i32 s20, s44, s1
	v_lshl_add_u64 v[228:229], s[24:25], 0, v[66:67]
	s_mov_b32 m0, s20
	ds_read_b128 v[188:191], v155 offset:16384
	ds_read_b128 v[192:195], v155 offset:17408
	ds_read_b128 v[196:199], v155 offset:18432
	ds_read_b128 v[200:203], v155 offset:19456
	ds_read_b128 v[204:207], v155 offset:20480
	ds_read_b128 v[208:211], v155 offset:21504
	ds_read_b128 v[220:223], v155 offset:22528
	ds_read_b128 v[224:227], v155 offset:23552
	global_load_lds_dwordx4 v[228:229], off
	s_add_i32 m0, s20, 0x2000
	s_add_u32 s20, s24, 0x80000
	v_lshl_add_u64 v[230:231], s[24:25], 0, v[132:133]
	s_addc_u32 s21, s25, 0
	s_add_i32 s44, s45, s1
	global_load_lds_dwordx4 v[230:231], off
	v_lshl_add_u64 v[232:233], s[20:21], 0, v[66:67]
	s_mov_b32 m0, s44
	v_lshl_add_u64 v[234:235], s[26:27], 0, v[132:133]
	global_load_lds_dwordx4 v[232:233], off
	v_lshl_add_u64 v[232:233], s[20:21], 0, v[132:133]
	s_add_i32 m0, s44, 0x2000
	s_nop 0
	global_load_lds_dwordx4 v[232:233], off
	v_lshl_add_u64 v[232:233], s[26:27], 0, v[66:67]
	s_mov_b32 m0, s30
	s_nop 0
	global_load_lds_dwordx4 v[232:233], off
	s_mov_b32 m0, s31
	s_nop 0
	global_load_lds_dwordx4 v[234:235], off
	s_waitcnt vmcnt(8)
	s_waitcnt lgkmcnt(0)
	s_barrier
; #define PG8_STAGE(bufoff, gbase, voff) do { _Pragma("unroll") for (int _i = 0; _i < 2; ++_i) \
;         __builtin_amdgcn_global_load_lds((const unsigned*)((const char*)(gbase) + (voff)[_i]), (PG8_LAS unsigned*)(lds + (bufoff) + ldsw + _i * 8192), 16, 0, 0); } while (0)
; #define PG8_LDA(dst, b, h) do { _Pragma("unroll") for (int m = 0; m < 4; ++m) _Pragma("unroll") for (int k = 0; k < 2; ++k) dst[m][k] = *(const PG8_LAS bf16x8*)(lds + PG8_SA(b, h) + aoff + m * 2048 + k * 1024); } while (0)
; #define PG8_LDB(dst, b, h) do { _Pragma("unroll") for (int n = 0; n < 2; ++n) _Pragma("unroll") for (int k = 0; k < 2; ++k) dst[n][k] = *(const PG8_LAS bf16x8*)(lds + PG8_SB(b, h) + boff + n * 2048 + k * 1024); } while (0)
; #define PG8_MMA(ai, bj, At, Bt) do { __builtin_amdgcn_s_setprio(1); _Pragma("unroll") for (int m = 0; m < 4; ++m) _Pragma("unroll") for (int n = 0; n < 2; ++n) _Pragma("unroll") for (int k = 0; k < 2; ++k) \
;         acc[ai][bj][m][n] = __builtin_amdgcn_mfma_f32_16x16x32_bf16(Bt[n][k], At[m][k], acc[ai][bj][m][n], 0, 0, 0); __builtin_amdgcn_s_setprio(0); } while (0)
; #define PG8_WAIT_V(n) asm volatile("s_waitcnt vmcnt(" #n ")" ::: "memory")
; #define PG8_WAIT_L(n) asm volatile("s_waitcnt lgkmcnt(" #n ")" ::: "memory")
; #define PG8_BAR __builtin_amdgcn_s_barrier()
; #define PG8_SCHED __builtin_amdgcn_sched_barrier(0)
; template <class Epi, class Sched, bool ALIGN_EPI = false, bool SP2 = false>
; __device__ __forceinline__ void gemm_phase(PG8_LAS unsigned char* lds, const Gemm g, const Sched& S, const Epi& E) {
;     ...
;             PG8_WAIT_V(8); PG8_WAIT_L(0); PG8_BAR; PG8_MMA(1, 0, At, B0); PG8_MMA(1, 1, At, B1); PG8_BAR; PG8_SCHED;
;             PG8_LDB(B0, 1, 0); PG8_LDB(B1, 1, 1); PG8_SCHED; PG8_LDA(At, 1, 0); PG8_STAGE(PG8_SA(0, 1), a2 + hstep, voffA);
;             PG8_WAIT_V(8); PG8_WAIT_L(0); PG8_BAR; PG8_MMA(0, 0, At, B0); PG8_MMA(0, 1, At, B1); PG8_BAR; PG8_SCHED;
	v_mfma_f32_16x16x32_bf16 v[62:65], v[156:159], v[188:191], v[62:65]
	v_mfma_f32_16x16x32_bf16 v[58:61], v[164:167], v[188:191], v[58:61]
	v_mfma_f32_16x16x32_bf16 v[54:57], v[156:159], v[196:199], v[54:57]
	v_mfma_f32_16x16x32_bf16 v[50:53], v[164:167], v[196:199], v[50:53]
	v_mfma_f32_16x16x32_bf16 v[46:49], v[156:159], v[204:207], v[46:49]
	v_mfma_f32_16x16x32_bf16 v[42:45], v[164:167], v[204:207], v[42:45]
	v_mfma_f32_16x16x32_bf16 v[34:37], v[156:159], v[220:223], v[34:37]
	v_mfma_f32_16x16x32_bf16 v[26:29], v[164:167], v[220:223], v[26:29]
	v_mfma_f32_16x16x32_bf16 v[62:65], v[160:163], v[192:195], v[62:65]
	v_mfma_f32_16x16x32_bf16 v[58:61], v[168:171], v[192:195], v[58:61]
	v_mfma_f32_16x16x32_bf16 v[54:57], v[160:163], v[200:203], v[54:57]
	v_mfma_f32_16x16x32_bf16 v[50:53], v[168:171], v[200:203], v[50:53]
	v_mfma_f32_16x16x32_bf16 v[46:49], v[160:163], v[208:211], v[46:49]
	v_mfma_f32_16x16x32_bf16 v[42:45], v[168:171], v[208:211], v[42:45]
	v_mfma_f32_16x16x32_bf16 v[34:37], v[160:163], v[224:227], v[34:37]
	v_mfma_f32_16x16x32_bf16 v[26:29], v[168:171], v[224:227], v[26:29]
	v_mfma_f32_16x16x32_bf16 v[38:41], v[172:175], v[188:191], v[38:41]
	v_mfma_f32_16x16x32_bf16 v[30:33], v[180:183], v[188:191], v[30:33]
	v_mfma_f32_16x16x32_bf16 v[22:25], v[172:175], v[196:199], v[22:25]
	v_mfma_f32_16x16x32_bf16 v[18:21], v[180:183], v[196:199], v[18:21]
	v_mfma_f32_16x16x32_bf16 v[14:17], v[172:175], v[204:207], v[14:17]
	v_mfma_f32_16x16x32_bf16 v[10:13], v[180:183], v[204:207], v[10:13]
	v_mfma_f32_16x16x32_bf16 v[6:9], v[172:175], v[220:223], v[6:9]
	v_mfma_f32_16x16x32_bf16 v[2:5], v[180:183], v[220:223], v[2:5]
	v_mfma_f32_16x16x32_bf16 v[38:41], v[176:179], v[192:195], v[38:41]
	v_mfma_f32_16x16x32_bf16 v[30:33], v[184:187], v[192:195], v[30:33]
	v_mfma_f32_16x16x32_bf16 v[22:25], v[176:179], v[200:203], v[22:25]
	v_mfma_f32_16x16x32_bf16 v[18:21], v[184:187], v[200:203], v[18:21]
	v_mfma_f32_16x16x32_bf16 v[14:17], v[176:179], v[208:211], v[14:17]
	v_mfma_f32_16x16x32_bf16 v[10:13], v[184:187], v[208:211], v[10:13]
	v_mfma_f32_16x16x32_bf16 v[6:9], v[176:179], v[224:227], v[6:9]
	v_mfma_f32_16x16x32_bf16 v[2:5], v[184:187], v[224:227], v[2:5]
	s_barrier
	s_add_i32 s44, 0, 0x18000
	s_add_i32 s45, 0, 0x1c000
	v_add_u32_e32 v168, s44, v0
	v_add_u32_e32 v184, s45, v0
	ds_read_b128 v[156:159], v168
	ds_read_b128 v[160:163], v168 offset:1024
	ds_read_b128 v[164:167], v168 offset:2048
	ds_read_b128 v[168:171], v168 offset:3072
	ds_read_b128 v[172:175], v184
	ds_read_b128 v[176:179], v184 offset:1024
	ds_read_b128 v[180:183], v184 offset:2048
	ds_read_b128 v[184:187], v184 offset:3072
	s_add_u32 s20, s26, 0x80000
	s_addc_u32 s21, s27, 0
	s_mov_b32 m0, s34
	v_lshl_add_u64 v[246:247], s[20:21], 0, v[66:67]
	ds_read_b128 v[188:191], v155 offset:32768
	ds_read_b128 v[192:195], v155 offset:33792
	ds_read_b128 v[196:199], v155 offset:34816
	ds_read_b128 v[200:203], v155 offset:35840
	ds_read_b128 v[204:207], v155 offset:36864
	ds_read_b128 v[208:211], v155 offset:37888
	ds_read_b128 v[220:223], v155 offset:38912
	ds_read_b128 v[224:227], v155 offset:39936
	global_load_lds_dwordx4 v[246:247], off
	v_lshl_add_u64 v[246:247], s[20:21], 0, v[132:133]
	s_mov_b32 m0, s35
	s_nop 0
	global_load_lds_dwordx4 v[246:247], off
	s_waitcnt vmcnt(8)
	s_waitcnt lgkmcnt(0)
	s_barrier
	v_mfma_f32_16x16x32_bf16 v[128:131], v[156:159], v[188:191], v[128:131]
	v_mfma_f32_16x16x32_bf16 v[124:127], v[164:167], v[188:191], v[124:127]
	v_mfma_f32_16x16x32_bf16 v[120:123], v[156:159], v[196:199], v[120:123]
	v_mfma_f32_16x16x32_bf16 v[116:119], v[164:167], v[196:199], v[116:119]
	v_mfma_f32_16x16x32_bf16 v[112:115], v[156:159], v[204:207], v[112:115]
	v_mfma_f32_16x16x32_bf16 v[108:111], v[164:167], v[204:207], v[108:111]
	v_mfma_f32_16x16x32_bf16 v[100:103], v[156:159], v[220:223], v[100:103]
	v_mfma_f32_16x16x32_bf16 v[92:95], v[164:167], v[220:223], v[92:95]
	v_mfma_f32_16x16x32_bf16 v[128:131], v[160:163], v[192:195], v[128:131]
	v_mfma_f32_16x16x32_bf16 v[124:127], v[168:171], v[192:195], v[124:127]
	v_mfma_f32_16x16x32_bf16 v[120:123], v[160:163], v[200:203], v[120:123]
	v_mfma_f32_16x16x32_bf16 v[116:119], v[168:171], v[200:203], v[116:119]
	v_mfma_f32_16x16x32_bf16 v[112:115], v[160:163], v[208:211], v[112:115]
	v_mfma_f32_16x16x32_bf16 v[108:111], v[168:171], v[208:211], v[108:111]
	v_mfma_f32_16x16x32_bf16 v[100:103], v[160:163], v[224:227], v[100:103]
	v_mfma_f32_16x16x32_bf16 v[92:95], v[168:171], v[224:227], v[92:95]
	v_mfma_f32_16x16x32_bf16 v[104:107], v[172:175], v[188:191], v[104:107]
	v_mfma_f32_16x16x32_bf16 v[96:99], v[180:183], v[188:191], v[96:99]
	v_mfma_f32_16x16x32_bf16 v[88:91], v[172:175], v[196:199], v[88:91]
	v_mfma_f32_16x16x32_bf16 v[84:87], v[180:183], v[196:199], v[84:87]
	v_mfma_f32_16x16x32_bf16 v[80:83], v[172:175], v[204:207], v[80:83]
	v_mfma_f32_16x16x32_bf16 v[76:79], v[180:183], v[204:207], v[76:79]
	v_mfma_f32_16x16x32_bf16 v[72:75], v[172:175], v[220:223], v[72:75]
	v_mfma_f32_16x16x32_bf16 v[68:71], v[180:183], v[220:223], v[68:71]
	v_mfma_f32_16x16x32_bf16 v[104:107], v[176:179], v[192:195], v[104:107]
	v_mfma_f32_16x16x32_bf16 v[96:99], v[184:187], v[192:195], v[96:99]
	v_mfma_f32_16x16x32_bf16 v[88:91], v[176:179], v[200:203], v[88:91]
	v_mfma_f32_16x16x32_bf16 v[84:87], v[184:187], v[200:203], v[84:87]
	v_mfma_f32_16x16x32_bf16 v[80:83], v[176:179], v[208:211], v[80:83]
	v_mfma_f32_16x16x32_bf16 v[76:79], v[184:187], v[208:211], v[76:79]
	v_mfma_f32_16x16x32_bf16 v[72:75], v[176:179], v[224:227], v[72:75]
	v_mfma_f32_16x16x32_bf16 v[68:71], v[184:187], v[224:227], v[68:71]
	s_barrier
; #define PG8_STAGE(bufoff, gbase, voff) do { _Pragma("unroll") for (int _i = 0; _i < 2; ++_i) \
;         __builtin_amdgcn_global_load_lds((const unsigned*)((const char*)(gbase) + (voff)[_i]), (PG8_LAS unsigned*)(lds + (bufoff) + ldsw + _i * 8192), 16, 0, 0); } while (0)
; #define PG8_LDA(dst, b, h) do { _Pragma("unroll") for (int m = 0; m < 4; ++m) _Pragma("unroll") for (int k = 0; k < 2; ++k) dst[m][k] = *(const PG8_LAS bf16x8*)(lds + PG8_SA(b, h) + aoff + m * 2048 + k * 1024); } while (0)
; #define PG8_MMA(ai, bj, At, Bt) do { __builtin_amdgcn_s_setprio(1); _Pragma("unroll") for (int m = 0; m < 4; ++m) _Pragma("unroll") for (int n = 0; n < 2; ++n) _Pragma("unroll") for (int k = 0; k < 2; ++k) \
;         acc[ai][bj][m][n] = __builtin_amdgcn_mfma_f32_16x16x32_bf16(Bt[n][k], At[m][k], acc[ai][bj][m][n], 0, 0, 0); __builtin_amdgcn_s_setprio(0); } while (0)
; #define PG8_WAIT_V(n) asm volatile("s_waitcnt vmcnt(" #n ")" ::: "memory")
; #define PG8_WAIT_L(n) asm volatile("s_waitcnt lgkmcnt(" #n ")" ::: "memory")
; #define PG8_BAR __builtin_amdgcn_s_barrier()
; #define PG8_SCHED __builtin_amdgcn_sched_barrier(0)
; template <class Epi, class Sched, bool ALIGN_EPI = false, bool SP2 = false>
; __device__ __forceinline__ void gemm_phase(PG8_LAS unsigned char* lds, const Gemm g, const Sched& S, const Epi& E) {
;     ...
;             PG8_LDA(At, 1, 1); PG8_STAGE(PG8_SB(1, 0), b3, voffB); PG8_STAGE(PG8_SB(1, 1), b3 + hstep, voffB); PG8_STAGE(PG8_SA(1, 0), a3, voffA);
;             PG8_WAIT_V(8); PG8_WAIT_L(0); PG8_BAR; PG8_MMA(1, 0, At, B0); PG8_MMA(1, 1, At, B1); PG8_BAR; PG8_SCHED;
	s_add_i32 s20, s44, s1
	v_lshl_add_u64 v[228:229], v[228:229], 0, s[88:89]
	s_mov_b32 m0, s20
	ds_read_b128 v[188:191], v155 offset:49152
	ds_read_b128 v[192:195], v155 offset:50176
	ds_read_b128 v[196:199], v155 offset:51200
	ds_read_b128 v[200:203], v155 offset:52224
	ds_read_b128 v[204:207], v155 offset:53248
	ds_read_b128 v[208:211], v155 offset:54272
	ds_read_b128 v[220:223], v155 offset:55296
	ds_read_b128 v[224:227], v155 offset:56320
	global_load_lds_dwordx4 v[228:229], off
	s_add_i32 m0, s20, 0x2000
	s_add_u32 s20, s24, 0x80080
	v_lshl_add_u64 v[228:229], v[230:231], 0, s[88:89]
	s_addc_u32 s21, s25, 0
	s_add_i32 s24, s45, s1
	global_load_lds_dwordx4 v[228:229], off
	v_lshl_add_u64 v[228:229], s[20:21], 0, v[66:67]
	s_mov_b32 m0, s24
	s_nop 0
	global_load_lds_dwordx4 v[228:229], off
	v_lshl_add_u64 v[228:229], s[20:21], 0, v[132:133]
	s_add_i32 m0, s24, 0x2000
	s_nop 0
	global_load_lds_dwordx4 v[228:229], off
	v_lshl_add_u64 v[228:229], v[232:233], 0, s[88:89]
	s_mov_b32 m0, s40
	s_nop 0
	global_load_lds_dwordx4 v[228:229], off
	v_lshl_add_u64 v[228:229], v[234:235], 0, s[88:89]
	s_mov_b32 m0, s41
	s_nop 0
	global_load_lds_dwordx4 v[228:229], off
	s_waitcnt vmcnt(8)
	s_waitcnt lgkmcnt(0)
	s_barrier
	v_mfma_f32_16x16x32_bf16 v[62:65], v[156:159], v[188:191], v[62:65]
	v_mfma_f32_16x16x32_bf16 v[58:61], v[164:167], v[188:191], v[58:61]
	v_mfma_f32_16x16x32_bf16 v[54:57], v[156:159], v[196:199], v[54:57]
	v_mfma_f32_16x16x32_bf16 v[50:53], v[164:167], v[196:199], v[50:53]
	v_mfma_f32_16x16x32_bf16 v[46:49], v[156:159], v[204:207], v[46:49]
	v_mfma_f32_16x16x32_bf16 v[42:45], v[164:167], v[204:207], v[42:45]
	v_mfma_f32_16x16x32_bf16 v[34:37], v[156:159], v[220:223], v[34:37]
	v_mfma_f32_16x16x32_bf16 v[26:29], v[164:167], v[220:223], v[26:29]
	v_mfma_f32_16x16x32_bf16 v[62:65], v[160:163], v[192:195], v[62:65]
	v_mfma_f32_16x16x32_bf16 v[58:61], v[168:171], v[192:195], v[58:61]
	v_mfma_f32_16x16x32_bf16 v[54:57], v[160:163], v[200:203], v[54:57]
	v_mfma_f32_16x16x32_bf16 v[50:53], v[168:171], v[200:203], v[50:53]
	v_mfma_f32_16x16x32_bf16 v[46:49], v[160:163], v[208:211], v[46:49]
	v_mfma_f32_16x16x32_bf16 v[42:45], v[168:171], v[208:211], v[42:45]
	v_mfma_f32_16x16x32_bf16 v[34:37], v[160:163], v[224:227], v[34:37]
	v_mfma_f32_16x16x32_bf16 v[26:29], v[168:171], v[224:227], v[26:29]
	v_mfma_f32_16x16x32_bf16 v[38:41], v[172:175], v[188:191], v[38:41]
	v_mfma_f32_16x16x32_bf16 v[30:33], v[180:183], v[188:191], v[30:33]
	v_mfma_f32_16x16x32_bf16 v[22:25], v[172:175], v[196:199], v[22:25]
	v_mfma_f32_16x16x32_bf16 v[18:21], v[180:183], v[196:199], v[18:21]
	v_mfma_f32_16x16x32_bf16 v[14:17], v[172:175], v[204:207], v[14:17]
	v_mfma_f32_16x16x32_bf16 v[10:13], v[180:183], v[204:207], v[10:13]
	v_mfma_f32_16x16x32_bf16 v[6:9], v[172:175], v[220:223], v[6:9]
	v_mfma_f32_16x16x32_bf16 v[2:5], v[180:183], v[220:223], v[2:5]
	v_mfma_f32_16x16x32_bf16 v[38:41], v[176:179], v[192:195], v[38:41]
	v_mfma_f32_16x16x32_bf16 v[30:33], v[184:187], v[192:195], v[30:33]
	v_mfma_f32_16x16x32_bf16 v[22:25], v[176:179], v[200:203], v[22:25]
	v_mfma_f32_16x16x32_bf16 v[18:21], v[184:187], v[200:203], v[18:21]
	v_mfma_f32_16x16x32_bf16 v[14:17], v[176:179], v[208:211], v[14:17]
	v_mfma_f32_16x16x32_bf16 v[10:13], v[184:187], v[208:211], v[10:13]
	v_mfma_f32_16x16x32_bf16 v[6:9], v[176:179], v[224:227], v[6:9]
	v_mfma_f32_16x16x32_bf16 v[2:5], v[184:187], v[224:227], v[2:5]
	s_barrier
	s_add_i32 s43, s43, 2
	s_add_u32 s13, s13, 0x100
	s_addc_u32 s15, s15, 0
	s_cmp_gt_u32 s43, 5
	s_mov_b64 s[20:21], s[22:23]
	s_cbranch_scc0 .LBB0_802
	s_nop 0
	s_nop 0
	s_nop 0
	s_nop 0
	s_nop 0
	s_nop 0
	s_nop 0
	s_nop 0
	s_nop 0
	s_nop 0
	s_nop 0
	s_nop 0
	s_nop 0
	s_nop 0
	s_nop 0
	s_nop 0
	s_nop 0
	s_nop 0
	s_nop 0
	s_nop 0
	s_and_b64 vcc, exec, s[8:9]
	s_cbranch_vccz .LBB0_805
	s_barrier

;     __host__ __device__ bool next(int i, Unit& u) const { if (i != 0 || r < 0 || r >= 148) return false; if (r < 116) { u.pm = r % 29; u.pn = 47 + r / 29; } else { u.pm = 32; u.pn = 19 + (r - 116); } u.ko = 0; return true; }
;     __host__ __device__ bool next(int i, Unit& u) const { const int L = i * G + (G - 1 - c); if (L >= nN * S) return false; u.pm = pm; u.pn = L % nN; u.ko = (L / nN) * ksub; return true; }
; #define PG8_STAGE(bufoff, gbase, voff) do { _Pragma("unroll") for (int _i = 0; _i < 2; ++_i) \
;         __builtin_amdgcn_global_load_lds((const unsigned*)((const char*)(gbase) + (voff)[_i]), (PG8_LAS unsigned*)(lds + (bufoff) + ldsw + _i * 8192), 16, 0, 0); } while (0)
; #define PG8_LDA(dst, b, h) do { _Pragma("unroll") for (int m = 0; m < 4; ++m) _Pragma("unroll") for (int k = 0; k < 2; ++k) dst[m][k] = *(const PG8_LAS bf16x8*)(lds + PG8_SA(b, h) + aoff + m * 2048 + k * 1024); } while (0)
; #define PG8_BAR __builtin_amdgcn_s_barrier()
; template <class Epi, class Sched, bool ALIGN_EPI = false, bool SP2 = false>
; __device__ __forceinline__ void gemm_phase(PG8_LAS unsigned char* lds, const Gemm g, const Sched& S, const Epi& E) {
;     ...
;         const bool has_next = S.next(ui + 1, nxt);
;         const char* nA = has_next ? (const char*)g.A + (size_t)nxt.pm * tstep + (size_t)nxt.ko * 2 : cA; const char* nB = has_next ? (const char*)g.Bt + (size_t)nxt.pn * tstep + (size_t)nxt.ko * 2 : cB;
;         for (int t = 0; t < nt; t += 2) {
;             const bool last = (t == nt - 2);
;             const char* a1 = cA + (size_t)(t + 1) * kstep;
;             const char* a2 = last ? nA : cA + (size_t)(t + 2) * kstep; const char* b2 = last ? nB : cB + (size_t)(t + 2) * kstep;
;             const char* a3 = a2 + kstep; const char* b3 = b2 + kstep;
;             if (last && has_next) S.a_ready(nxt);
;             if constexpr (SP2) {
;             PG8_LDB(B0, 0, 0); PG8_LDB(B1, 0, 1); PG8_SCHED; PG8_LDA(At, 0, 0); PG8_STAGE(PG8_SA(1, 1), a1 + hstep, voffA);
;             PG8_WAIT_V(8); PG8_WAIT_L(0); PG8_BAR; PG8_MMA(0, 0, At, B0); PG8_MMA(0, 1, At, B1); PG8_BAR; PG8_SCHED;
;             PG8_LDA(At, 0, 1); PG8_STAGE(PG8_SB(0, 0), b2, voffB); PG8_STAGE(PG8_SB(0, 1), b2 + hstep, voffB); PG8_STAGE(PG8_SA(0, 0), a2, voffA);
;             PG8_WAIT_V(8); PG8_WAIT_L(0); PG8_BAR; PG8_MMA(1, 0, At, B0); PG8_MMA(1, 1, At, B1); PG8_BAR; PG8_SCHED;
.LBB0_881:
	s_add_u32 s30, s28, 0x100
	s_addc_u32 s31, s29, 0
	s_add_i32 s59, 0, 0x10000
	s_cmp_eq_u32 s57, 28
	s_cselect_b32 s37, s2, s31
	s_cselect_b32 s36, s3, s30
	s_cselect_b32 s35, s21, s56
	s_cselect_b32 s34, s23, s55
	s_add_i32 s60, 0, 0x14000
	v_add_u32_e32 v144, s59, v156
	v_add_u32_e32 v154, s60, v156
	ds_read_b128 v[132:135], v144
	ds_read_b128 v[136:139], v144 offset:1024
	ds_read_b128 v[140:143], v144 offset:2048
	ds_read_b128 v[144:147], v144 offset:3072
	ds_read_b128 v[160:163], v154
	ds_read_b128 v[164:167], v154 offset:1024
	ds_read_b128 v[168:171], v154 offset:2048
	ds_read_b128 v[172:175], v154 offset:3072
	v_lshl_add_u64 v[154:155], s[28:29], 0, v[150:151]
	s_add_i32 m0, s39, 0xc000
	ds_read_b128 v[176:179], v158
	ds_read_b128 v[180:183], v158 offset:1024
	ds_read_b128 v[184:187], v158 offset:2048
	ds_read_b128 v[188:191], v158 offset:3072
	ds_read_b128 v[192:195], v158 offset:4096
	ds_read_b128 v[196:199], v158 offset:5120
	ds_read_b128 v[200:203], v158 offset:6144
	ds_read_b128 v[204:207], v158 offset:7168
	global_load_lds_dwordx4 v[154:155], off
	v_lshl_add_u64 v[154:155], s[28:29], 0, v[152:153]
	s_add_i32 m0, s39, 0xe000
	s_nop 0
	global_load_lds_dwordx4 v[154:155], off
	s_waitcnt vmcnt(8)
	s_waitcnt lgkmcnt(0)
	s_barrier
	v_mfma_f32_16x16x32_bf16 v[128:131], v[132:135], v[176:179], v[128:131]
	v_mfma_f32_16x16x32_bf16 v[124:127], v[140:143], v[176:179], v[124:127]
	v_mfma_f32_16x16x32_bf16 v[120:123], v[132:135], v[184:187], v[120:123]
	v_mfma_f32_16x16x32_bf16 v[112:115], v[140:143], v[184:187], v[112:115]
	v_mfma_f32_16x16x32_bf16 v[104:107], v[132:135], v[192:195], v[104:107]
	v_mfma_f32_16x16x32_bf16 v[96:99], v[140:143], v[192:195], v[96:99]
	v_mfma_f32_16x16x32_bf16 v[88:91], v[132:135], v[200:203], v[88:91]
	v_mfma_f32_16x16x32_bf16 v[76:79], v[140:143], v[200:203], v[76:79]
	v_mfma_f32_16x16x32_bf16 v[128:131], v[136:139], v[180:183], v[128:131]
	v_mfma_f32_16x16x32_bf16 v[124:127], v[144:147], v[180:183], v[124:127]
	v_mfma_f32_16x16x32_bf16 v[120:123], v[136:139], v[188:191], v[120:123]
	v_mfma_f32_16x16x32_bf16 v[112:115], v[144:147], v[188:191], v[112:115]
	v_mfma_f32_16x16x32_bf16 v[104:107], v[136:139], v[196:199], v[104:107]
	v_mfma_f32_16x16x32_bf16 v[96:99], v[144:147], v[196:199], v[96:99]
	v_mfma_f32_16x16x32_bf16 v[88:91], v[136:139], v[204:207], v[88:91]
	v_mfma_f32_16x16x32_bf16 v[76:79], v[144:147], v[204:207], v[76:79]
	v_mfma_f32_16x16x32_bf16 v[116:119], v[160:163], v[176:179], v[116:119]
	v_mfma_f32_16x16x32_bf16 v[108:111], v[168:171], v[176:179], v[108:111]
	v_mfma_f32_16x16x32_bf16 v[100:103], v[160:163], v[184:187], v[100:103]
	v_mfma_f32_16x16x32_bf16 v[92:95], v[168:171], v[184:187], v[92:95]
	v_mfma_f32_16x16x32_bf16 v[84:87], v[160:163], v[192:195], v[84:87]
	v_mfma_f32_16x16x32_bf16 v[80:83], v[168:171], v[192:195], v[80:83]
	v_mfma_f32_16x16x32_bf16 v[72:75], v[160:163], v[200:203], v[72:75]
	v_mfma_f32_16x16x32_bf16 v[68:71], v[168:171], v[200:203], v[68:71]
	v_mfma_f32_16x16x32_bf16 v[116:119], v[164:167], v[180:183], v[116:119]
	v_mfma_f32_16x16x32_bf16 v[108:111], v[172:175], v[180:183], v[108:111]
	v_mfma_f32_16x16x32_bf16 v[100:103], v[164:167], v[188:191], v[100:103]
	v_mfma_f32_16x16x32_bf16 v[92:95], v[172:175], v[188:191], v[92:95]
	v_mfma_f32_16x16x32_bf16 v[84:87], v[164:167], v[196:199], v[84:87]
	v_mfma_f32_16x16x32_bf16 v[80:83], v[172:175], v[196:199], v[80:83]
	v_mfma_f32_16x16x32_bf16 v[72:75], v[164:167], v[204:207], v[72:75]
	v_mfma_f32_16x16x32_bf16 v[68:71], v[172:175], v[204:207], v[68:71]
	s_barrier
	s_add_i32 s28, s59, s38
	v_lshl_add_u64 v[154:155], s[34:35], 0, v[66:67]
	s_mov_b32 m0, s28
	ds_read_b128 v[176:179], v158 offset:16384
	ds_read_b128 v[180:183], v158 offset:17408
	ds_read_b128 v[184:187], v158 offset:18432
	ds_read_b128 v[188:191], v158 offset:19456
	ds_read_b128 v[192:195], v158 offset:20480
	ds_read_b128 v[196:199], v158 offset:21504
	ds_read_b128 v[200:203], v158 offset:22528
	ds_read_b128 v[204:207], v158 offset:23552
	global_load_lds_dwordx4 v[154:155], off
	s_add_i32 m0, s28, 0x2000
	s_add_u32 s28, s34, 0x80000
	v_lshl_add_u64 v[208:209], s[34:35], 0, v[148:149]
	s_addc_u32 s29, s35, 0
	s_add_i32 s59, s60, s38
	global_load_lds_dwordx4 v[208:209], off
	v_lshl_add_u64 v[210:211], s[28:29], 0, v[66:67]
	s_mov_b32 m0, s59
	v_lshl_add_u64 v[220:221], s[36:37], 0, v[148:149]
	global_load_lds_dwordx4 v[210:211], off
	v_lshl_add_u64 v[210:211], s[28:29], 0, v[148:149]
	s_add_i32 m0, s59, 0x2000
	s_nop 0
	global_load_lds_dwordx4 v[210:211], off
	v_lshl_add_u64 v[210:211], s[36:37], 0, v[66:67]
	s_mov_b32 m0, s39
	s_nop 0
	global_load_lds_dwordx4 v[210:211], off
	s_mov_b32 m0, s40
	s_nop 0
	global_load_lds_dwordx4 v[220:221], off
	s_waitcnt vmcnt(8)
	s_waitcnt lgkmcnt(0)
	s_barrier
; #define PG8_STAGE(bufoff, gbase, voff) do { _Pragma("unroll") for (int _i = 0; _i < 2; ++_i) \
;         __builtin_amdgcn_global_load_lds((const unsigned*)((const char*)(gbase) + (voff)[_i]), (PG8_LAS unsigned*)(lds + (bufoff) + ldsw + _i * 8192), 16, 0, 0); } while (0)
; #define PG8_LDA(dst, b, h) do { _Pragma("unroll") for (int m = 0; m < 4; ++m) _Pragma("unroll") for (int k = 0; k < 2; ++k) dst[m][k] = *(const PG8_LAS bf16x8*)(lds + PG8_SA(b, h) + aoff + m * 2048 + k * 1024); } while (0)
; #define PG8_LDB(dst, b, h) do { _Pragma("unroll") for (int n = 0; n < 2; ++n) _Pragma("unroll") for (int k = 0; k < 2; ++k) dst[n][k] = *(const PG8_LAS bf16x8*)(lds + PG8_SB(b, h) + boff + n * 2048 + k * 1024); } while (0)
; #define PG8_MMA(ai, bj, At, Bt) do { __builtin_amdgcn_s_setprio(1); _Pragma("unroll") for (int m = 0; m < 4; ++m) _Pragma("unroll") for (int n = 0; n < 2; ++n) _Pragma("unroll") for (int k = 0; k < 2; ++k) \
;         acc[ai][bj][m][n] = __builtin_amdgcn_mfma_f32_16x16x32_bf16(Bt[n][k], At[m][k], acc[ai][bj][m][n], 0, 0, 0); __builtin_amdgcn_s_setprio(0); } while (0)
; #define PG8_WAIT_V(n) asm volatile("s_waitcnt vmcnt(" #n ")" ::: "memory")
; #define PG8_WAIT_L(n) asm volatile("s_waitcnt lgkmcnt(" #n ")" ::: "memory")
; #define PG8_BAR __builtin_amdgcn_s_barrier()
; #define PG8_SCHED __builtin_amdgcn_sched_barrier(0)
; template <class Epi, class Sched, bool ALIGN_EPI = false, bool SP2 = false>
; __device__ __forceinline__ void gemm_phase(PG8_LAS unsigned char* lds, const Gemm g, const Sched& S, const Epi& E) {
;     ...
;             PG8_WAIT_V(8); PG8_WAIT_L(0); PG8_BAR; PG8_MMA(1, 0, At, B0); PG8_MMA(1, 1, At, B1); PG8_BAR; PG8_SCHED;
;             PG8_LDB(B0, 1, 0); PG8_LDB(B1, 1, 1); PG8_SCHED; PG8_LDA(At, 1, 0); PG8_STAGE(PG8_SA(0, 1), a2 + hstep, voffA);
;             PG8_WAIT_V(8); PG8_WAIT_L(0); PG8_BAR; PG8_MMA(0, 0, At, B0); PG8_MMA(0, 1, At, B1); PG8_BAR; PG8_SCHED;
	v_mfma_f32_16x16x32_bf16 v[62:65], v[132:135], v[176:179], v[62:65]
	v_mfma_f32_16x16x32_bf16 v[58:61], v[140:143], v[176:179], v[58:61]
	v_mfma_f32_16x16x32_bf16 v[54:57], v[132:135], v[184:187], v[54:57]
	v_mfma_f32_16x16x32_bf16 v[46:49], v[140:143], v[184:187], v[46:49]
	v_mfma_f32_16x16x32_bf16 v[38:41], v[132:135], v[192:195], v[38:41]
	v_mfma_f32_16x16x32_bf16 v[30:33], v[140:143], v[192:195], v[30:33]
	v_mfma_f32_16x16x32_bf16 v[22:25], v[132:135], v[200:203], v[22:25]
	v_mfma_f32_16x16x32_bf16 v[10:13], v[140:143], v[200:203], v[10:13]
	v_mfma_f32_16x16x32_bf16 v[62:65], v[136:139], v[180:183], v[62:65]
	v_mfma_f32_16x16x32_bf16 v[58:61], v[144:147], v[180:183], v[58:61]
	v_mfma_f32_16x16x32_bf16 v[54:57], v[136:139], v[188:191], v[54:57]
	v_mfma_f32_16x16x32_bf16 v[46:49], v[144:147], v[188:191], v[46:49]
	v_mfma_f32_16x16x32_bf16 v[38:41], v[136:139], v[196:199], v[38:41]
	v_mfma_f32_16x16x32_bf16 v[30:33], v[144:147], v[196:199], v[30:33]
	v_mfma_f32_16x16x32_bf16 v[22:25], v[136:139], v[204:207], v[22:25]
	v_mfma_f32_16x16x32_bf16 v[10:13], v[144:147], v[204:207], v[10:13]
	v_mfma_f32_16x16x32_bf16 v[50:53], v[160:163], v[176:179], v[50:53]
	v_mfma_f32_16x16x32_bf16 v[42:45], v[168:171], v[176:179], v[42:45]
	v_mfma_f32_16x16x32_bf16 v[34:37], v[160:163], v[184:187], v[34:37]
	v_mfma_f32_16x16x32_bf16 v[26:29], v[168:171], v[184:187], v[26:29]
	v_mfma_f32_16x16x32_bf16 v[18:21], v[160:163], v[192:195], v[18:21]
	v_mfma_f32_16x16x32_bf16 v[14:17], v[168:171], v[192:195], v[14:17]
	v_mfma_f32_16x16x32_bf16 v[6:9], v[160:163], v[200:203], v[6:9]
	v_mfma_f32_16x16x32_bf16 v[2:5], v[168:171], v[200:203], v[2:5]
	v_mfma_f32_16x16x32_bf16 v[50:53], v[164:167], v[180:183], v[50:53]
	v_mfma_f32_16x16x32_bf16 v[42:45], v[172:175], v[180:183], v[42:45]
	v_mfma_f32_16x16x32_bf16 v[34:37], v[164:167], v[188:191], v[34:37]
	v_mfma_f32_16x16x32_bf16 v[26:29], v[172:175], v[188:191], v[26:29]
	v_mfma_f32_16x16x32_bf16 v[18:21], v[164:167], v[196:199], v[18:21]
	v_mfma_f32_16x16x32_bf16 v[14:17], v[172:175], v[196:199], v[14:17]
	v_mfma_f32_16x16x32_bf16 v[6:9], v[164:167], v[204:207], v[6:9]
	v_mfma_f32_16x16x32_bf16 v[2:5], v[172:175], v[204:207], v[2:5]
	s_barrier
	s_add_i32 s59, 0, 0x18000
	s_add_i32 s60, 0, 0x1c000
	v_add_u32_e32 v144, s59, v156
	v_add_u32_e32 v159, s60, v156
	ds_read_b128 v[132:135], v144
	ds_read_b128 v[136:139], v144 offset:1024
	ds_read_b128 v[140:143], v144 offset:2048
	ds_read_b128 v[144:147], v144 offset:3072
	ds_read_b128 v[160:163], v159
	ds_read_b128 v[164:167], v159 offset:1024
	ds_read_b128 v[168:171], v159 offset:2048
	ds_read_b128 v[172:175], v159 offset:3072
	s_add_u32 s28, s36, 0x80000
	s_addc_u32 s29, s37, 0
	s_mov_b32 m0, s41
	v_lshl_add_u64 v[222:223], s[28:29], 0, v[66:67]
	ds_read_b128 v[176:179], v158 offset:32768
	ds_read_b128 v[180:183], v158 offset:33792
	ds_read_b128 v[184:187], v158 offset:34816
	ds_read_b128 v[188:191], v158 offset:35840
	ds_read_b128 v[192:195], v158 offset:36864
	ds_read_b128 v[196:199], v158 offset:37888
	ds_read_b128 v[200:203], v158 offset:38912
	ds_read_b128 v[204:207], v158 offset:39936
	global_load_lds_dwordx4 v[222:223], off
	v_lshl_add_u64 v[222:223], s[28:29], 0, v[148:149]
	s_mov_b32 m0, s44
	s_nop 0
	global_load_lds_dwordx4 v[222:223], off
	s_waitcnt vmcnt(8)
	s_waitcnt lgkmcnt(0)
	s_barrier
	v_mfma_f32_16x16x32_bf16 v[128:131], v[132:135], v[176:179], v[128:131]
	v_mfma_f32_16x16x32_bf16 v[124:127], v[140:143], v[176:179], v[124:127]
	v_mfma_f32_16x16x32_bf16 v[120:123], v[132:135], v[184:187], v[120:123]
	v_mfma_f32_16x16x32_bf16 v[112:115], v[140:143], v[184:187], v[112:115]
	v_mfma_f32_16x16x32_bf16 v[104:107], v[132:135], v[192:195], v[104:107]
	v_mfma_f32_16x16x32_bf16 v[96:99], v[140:143], v[192:195], v[96:99]
	v_mfma_f32_16x16x32_bf16 v[88:91], v[132:135], v[200:203], v[88:91]
	v_mfma_f32_16x16x32_bf16 v[76:79], v[140:143], v[200:203], v[76:79]
	v_mfma_f32_16x16x32_bf16 v[128:131], v[136:139], v[180:183], v[128:131]
	v_mfma_f32_16x16x32_bf16 v[124:127], v[144:147], v[180:183], v[124:127]
	v_mfma_f32_16x16x32_bf16 v[120:123], v[136:139], v[188:191], v[120:123]
	v_mfma_f32_16x16x32_bf16 v[112:115], v[144:147], v[188:191], v[112:115]
	v_mfma_f32_16x16x32_bf16 v[104:107], v[136:139], v[196:199], v[104:107]
	v_mfma_f32_16x16x32_bf16 v[96:99], v[144:147], v[196:199], v[96:99]
	v_mfma_f32_16x16x32_bf16 v[88:91], v[136:139], v[204:207], v[88:91]
	v_mfma_f32_16x16x32_bf16 v[76:79], v[144:147], v[204:207], v[76:79]
	v_mfma_f32_16x16x32_bf16 v[116:119], v[160:163], v[176:179], v[116:119]
	v_mfma_f32_16x16x32_bf16 v[108:111], v[168:171], v[176:179], v[108:111]
	v_mfma_f32_16x16x32_bf16 v[100:103], v[160:163], v[184:187], v[100:103]
	v_mfma_f32_16x16x32_bf16 v[92:95], v[168:171], v[184:187], v[92:95]
	v_mfma_f32_16x16x32_bf16 v[84:87], v[160:163], v[192:195], v[84:87]
	v_mfma_f32_16x16x32_bf16 v[80:83], v[168:171], v[192:195], v[80:83]
	v_mfma_f32_16x16x32_bf16 v[72:75], v[160:163], v[200:203], v[72:75]
	v_mfma_f32_16x16x32_bf16 v[68:71], v[168:171], v[200:203], v[68:71]
	v_mfma_f32_16x16x32_bf16 v[116:119], v[164:167], v[180:183], v[116:119]
	v_mfma_f32_16x16x32_bf16 v[108:111], v[172:175], v[180:183], v[108:111]
	v_mfma_f32_16x16x32_bf16 v[100:103], v[164:167], v[188:191], v[100:103]
	v_mfma_f32_16x16x32_bf16 v[92:95], v[172:175], v[188:191], v[92:95]
	v_mfma_f32_16x16x32_bf16 v[84:87], v[164:167], v[196:199], v[84:87]
	v_mfma_f32_16x16x32_bf16 v[80:83], v[172:175], v[196:199], v[80:83]
	v_mfma_f32_16x16x32_bf16 v[72:75], v[164:167], v[204:207], v[72:75]
	v_mfma_f32_16x16x32_bf16 v[68:71], v[172:175], v[204:207], v[68:71]
	s_barrier
; #define PG8_STAGE(bufoff, gbase, voff) do { _Pragma("unroll") for (int _i = 0; _i < 2; ++_i) \
;         __builtin_amdgcn_global_load_lds((const unsigned*)((const char*)(gbase) + (voff)[_i]), (PG8_LAS unsigned*)(lds + (bufoff) + ldsw + _i * 8192), 16, 0, 0); } while (0)
; #define PG8_LDA(dst, b, h) do { _Pragma("unroll") for (int m = 0; m < 4; ++m) _Pragma("unroll") for (int k = 0; k < 2; ++k) dst[m][k] = *(const PG8_LAS bf16x8*)(lds + PG8_SA(b, h) + aoff + m * 2048 + k * 1024); } while (0)
; #define PG8_MMA(ai, bj, At, Bt) do { __builtin_amdgcn_s_setprio(1); _Pragma("unroll") for (int m = 0; m < 4; ++m) _Pragma("unroll") for (int n = 0; n < 2; ++n) _Pragma("unroll") for (int k = 0; k < 2; ++k) \
;         acc[ai][bj][m][n] = __builtin_amdgcn_mfma_f32_16x16x32_bf16(Bt[n][k], At[m][k], acc[ai][bj][m][n], 0, 0, 0); __builtin_amdgcn_s_setprio(0); } while (0)
; #define PG8_WAIT_V(n) asm volatile("s_waitcnt vmcnt(" #n ")" ::: "memory")
; #define PG8_WAIT_L(n) asm volatile("s_waitcnt lgkmcnt(" #n ")" ::: "memory")
; #define PG8_BAR __builtin_amdgcn_s_barrier()
; #define PG8_SCHED __builtin_amdgcn_sched_barrier(0)
; template <class Epi, class Sched, bool ALIGN_EPI = false, bool SP2 = false>
; __device__ __forceinline__ void gemm_phase(PG8_LAS unsigned char* lds, const Gemm g, const Sched& S, const Epi& E) {
;     ...
;             PG8_LDA(At, 1, 1); PG8_STAGE(PG8_SB(1, 0), b3, voffB); PG8_STAGE(PG8_SB(1, 1), b3 + hstep, voffB); PG8_STAGE(PG8_SA(1, 0), a3, voffA);
;             PG8_WAIT_V(8); PG8_WAIT_L(0); PG8_BAR; PG8_MMA(1, 0, At, B0); PG8_MMA(1, 1, At, B1); PG8_BAR; PG8_SCHED;
	s_add_i32 s28, s59, s38
	v_lshl_add_u64 v[154:155], v[154:155], 0, s[88:89]
	s_mov_b32 m0, s28
	ds_read_b128 v[176:179], v158 offset:49152
	ds_read_b128 v[180:183], v158 offset:50176
	ds_read_b128 v[184:187], v158 offset:51200
	ds_read_b128 v[188:191], v158 offset:52224
	ds_read_b128 v[192:195], v158 offset:53248
	ds_read_b128 v[196:199], v158 offset:54272
	ds_read_b128 v[200:203], v158 offset:55296
	ds_read_b128 v[204:207], v158 offset:56320
	global_load_lds_dwordx4 v[154:155], off
	s_add_i32 m0, s28, 0x2000
	s_add_u32 s28, s34, 0x80080
	v_lshl_add_u64 v[154:155], v[208:209], 0, s[88:89]
	s_addc_u32 s29, s35, 0
	s_add_i32 s34, s60, s38
	global_load_lds_dwordx4 v[154:155], off
	v_lshl_add_u64 v[154:155], s[28:29], 0, v[66:67]
	s_mov_b32 m0, s34
	s_nop 0
	global_load_lds_dwordx4 v[154:155], off
	v_lshl_add_u64 v[154:155], s[28:29], 0, v[148:149]
	s_add_i32 m0, s34, 0x2000
	s_nop 0
	global_load_lds_dwordx4 v[154:155], off
	v_lshl_add_u64 v[154:155], v[210:211], 0, s[88:89]
	s_mov_b32 m0, s47
	s_nop 0
	global_load_lds_dwordx4 v[154:155], off
	v_lshl_add_u64 v[154:155], v[220:221], 0, s[88:89]
	s_mov_b32 m0, s50
	s_nop 0
	global_load_lds_dwordx4 v[154:155], off
	s_waitcnt vmcnt(8)
	s_waitcnt lgkmcnt(0)
	s_barrier
	v_mfma_f32_16x16x32_bf16 v[62:65], v[132:135], v[176:179], v[62:65]
	v_mfma_f32_16x16x32_bf16 v[58:61], v[140:143], v[176:179], v[58:61]
	v_mfma_f32_16x16x32_bf16 v[54:57], v[132:135], v[184:187], v[54:57]
	v_mfma_f32_16x16x32_bf16 v[46:49], v[140:143], v[184:187], v[46:49]
	v_mfma_f32_16x16x32_bf16 v[38:41], v[132:135], v[192:195], v[38:41]
	v_mfma_f32_16x16x32_bf16 v[30:33], v[140:143], v[192:195], v[30:33]
	v_mfma_f32_16x16x32_bf16 v[22:25], v[132:135], v[200:203], v[22:25]
	v_mfma_f32_16x16x32_bf16 v[10:13], v[140:143], v[200:203], v[10:13]
	v_mfma_f32_16x16x32_bf16 v[62:65], v[136:139], v[180:183], v[62:65]
	v_mfma_f32_16x16x32_bf16 v[58:61], v[144:147], v[180:183], v[58:61]
	v_mfma_f32_16x16x32_bf16 v[54:57], v[136:139], v[188:191], v[54:57]
	v_mfma_f32_16x16x32_bf16 v[46:49], v[144:147], v[188:191], v[46:49]
	v_mfma_f32_16x16x32_bf16 v[38:41], v[136:139], v[196:199], v[38:41]
	v_mfma_f32_16x16x32_bf16 v[30:33], v[144:147], v[196:199], v[30:33]
	v_mfma_f32_16x16x32_bf16 v[22:25], v[136:139], v[204:207], v[22:25]
	v_mfma_f32_16x16x32_bf16 v[10:13], v[144:147], v[204:207], v[10:13]
	v_mfma_f32_16x16x32_bf16 v[50:53], v[160:163], v[176:179], v[50:53]
	v_mfma_f32_16x16x32_bf16 v[42:45], v[168:171], v[176:179], v[42:45]
	v_mfma_f32_16x16x32_bf16 v[34:37], v[160:163], v[184:187], v[34:37]
	v_mfma_f32_16x16x32_bf16 v[26:29], v[168:171], v[184:187], v[26:29]
	v_mfma_f32_16x16x32_bf16 v[18:21], v[160:163], v[192:195], v[18:21]
	v_mfma_f32_16x16x32_bf16 v[14:17], v[168:171], v[192:195], v[14:17]
	v_mfma_f32_16x16x32_bf16 v[6:9], v[160:163], v[200:203], v[6:9]
	v_mfma_f32_16x16x32_bf16 v[2:5], v[168:171], v[200:203], v[2:5]
	v_mfma_f32_16x16x32_bf16 v[50:53], v[164:167], v[180:183], v[50:53]
	v_mfma_f32_16x16x32_bf16 v[42:45], v[172:175], v[180:183], v[42:45]
	v_mfma_f32_16x16x32_bf16 v[34:37], v[164:167], v[188:191], v[34:37]
	v_mfma_f32_16x16x32_bf16 v[26:29], v[172:175], v[188:191], v[26:29]
	v_mfma_f32_16x16x32_bf16 v[18:21], v[164:167], v[196:199], v[18:21]
	v_mfma_f32_16x16x32_bf16 v[14:17], v[172:175], v[196:199], v[14:17]
	v_mfma_f32_16x16x32_bf16 v[6:9], v[164:167], v[204:207], v[6:9]
	v_mfma_f32_16x16x32_bf16 v[2:5], v[172:175], v[204:207], v[2:5]
	s_barrier
	s_add_i32 s57, s57, 2
	s_add_u32 s55, s55, 0x100
	s_addc_u32 s56, s56, 0
	s_cmp_gt_u32 s57, 29
	s_mov_b64 s[28:29], s[30:31]
	s_cbranch_scc0 .LBB0_881
	s_nop 0
	s_nop 0
	s_nop 0
	s_nop 0
	s_nop 0
	s_nop 0
	s_nop 0
	s_nop 0
	s_nop 0
	s_nop 0
	s_nop 0
	s_nop 0
	s_nop 0
	s_nop 0
	s_nop 0
	s_nop 0
	s_nop 0
	s_nop 0
	s_nop 0
	s_nop 0
	s_and_b64 vcc, exec, s[12:13]
	s_cbranch_vccz .LBB0_884
	s_barrier

;     __host__ __device__ bool next(int i, Unit& u) const { if (i != 0 || r < 0 || r >= 148) return false; if (r < 116) { u.pm = r % 29; u.pn = 47 + r / 29; } else { u.pm = 32; u.pn = 19 + (r - 116); } u.ko = 0; return true; }
;     __host__ __device__ bool next(int i, Unit& u) const { const int L = i * G + (G - 1 - c); if (L >= nN * S) return false; u.pm = pm; u.pn = L % nN; u.ko = (L / nN) * ksub; return true; }
; #define PG8_STAGE(bufoff, gbase, voff) do { _Pragma("unroll") for (int _i = 0; _i < 2; ++_i) \
;         __builtin_amdgcn_global_load_lds((const unsigned*)((const char*)(gbase) + (voff)[_i]), (PG8_LAS unsigned*)(lds + (bufoff) + ldsw + _i * 8192), 16, 0, 0); } while (0)
; #define PG8_LDA(dst, b, h) do { _Pragma("unroll") for (int m = 0; m < 4; ++m) _Pragma("unroll") for (int k = 0; k < 2; ++k) dst[m][k] = *(const PG8_LAS bf16x8*)(lds + PG8_SA(b, h) + aoff + m * 2048 + k * 1024); } while (0)
; #define PG8_BAR __builtin_amdgcn_s_barrier()
; template <class Epi, class Sched, bool ALIGN_EPI = false, bool SP2 = false>
; __device__ __forceinline__ void gemm_phase(PG8_LAS unsigned char* lds, const Gemm g, const Sched& S, const Epi& E) {
;     ...
;         const bool has_next = S.next(ui + 1, nxt);
;         const char* nA = has_next ? (const char*)g.A + (size_t)nxt.pm * tstep + (size_t)nxt.ko * 2 : cA; const char* nB = has_next ? (const char*)g.Bt + (size_t)nxt.pn * tstep + (size_t)nxt.ko * 2 : cB;
;         for (int t = 0; t < nt; t += 2) {
;             const bool last = (t == nt - 2);
;             const char* a1 = cA + (size_t)(t + 1) * kstep;
;             const char* a2 = last ? nA : cA + (size_t)(t + 2) * kstep; const char* b2 = last ? nB : cB + (size_t)(t + 2) * kstep;
;             const char* a3 = a2 + kstep; const char* b3 = b2 + kstep;
;             if (last && has_next) S.a_ready(nxt);
;             if constexpr (SP2) {
;             PG8_LDB(B0, 0, 0); PG8_LDB(B1, 0, 1); PG8_SCHED; PG8_LDA(At, 0, 0); PG8_STAGE(PG8_SA(1, 1), a1 + hstep, voffA);
;             PG8_WAIT_V(8); PG8_WAIT_L(0); PG8_BAR; PG8_MMA(0, 0, At, B0); PG8_MMA(0, 1, At, B1); PG8_BAR; PG8_SCHED;
;             PG8_LDA(At, 0, 1); PG8_STAGE(PG8_SB(0, 0), b2, voffB); PG8_STAGE(PG8_SB(0, 1), b2 + hstep, voffB); PG8_STAGE(PG8_SA(0, 0), a2, voffA);
;             PG8_WAIT_V(8); PG8_WAIT_L(0); PG8_BAR; PG8_MMA(1, 0, At, B0); PG8_MMA(1, 1, At, B1); PG8_BAR; PG8_SCHED;
.LBB0_905:
	s_add_u32 s38, s22, s36
	s_addc_u32 s39, s23, s37
	s_add_u32 s38, s38, 0x100
	s_addc_u32 s39, s39, 0
	s_add_u32 s63, s3, s36
	s_addc_u32 s64, s59, s37
	s_add_i32 s65, 0, 0x10000
	s_cmpk_eq_i32 s36, 0xf00
	s_cselect_b32 s41, s29, s39
	s_cselect_b32 s40, s60, s38
	s_cselect_b32 s39, s27, s64
	s_cselect_b32 s38, s61, s63
	s_add_i32 s63, 0, 0x14000
	v_add_u32_e32 v156, s65, v142
	v_add_u32_e32 v172, s63, v142
	ds_read_b128 v[144:147], v156
	ds_read_b128 v[148:151], v156 offset:1024
	ds_read_b128 v[152:155], v156 offset:2048
	ds_read_b128 v[156:159], v156 offset:3072
	ds_read_b128 v[160:163], v172
	ds_read_b128 v[164:167], v172 offset:1024
	ds_read_b128 v[168:171], v172 offset:2048
	ds_read_b128 v[172:175], v172 offset:3072
	v_lshl_add_u64 v[188:189], v[134:135], 0, s[36:37]
	s_add_i32 m0, s51, 0xc000
	ds_read_b128 v[176:179], v143
	ds_read_b128 v[180:183], v143 offset:1024
	ds_read_b128 v[184:187], v143 offset:2048
	ds_read_b128 v[192:195], v143 offset:3072
	ds_read_b128 v[196:199], v143 offset:4096
	ds_read_b128 v[200:203], v143 offset:5120
	ds_read_b128 v[204:207], v143 offset:6144
	ds_read_b128 v[208:211], v143 offset:7168
	global_load_lds_dwordx4 v[188:189], off
	v_lshl_add_u64 v[188:189], v[140:141], 0, s[36:37]
	s_add_i32 m0, s51, 0xe000
	s_nop 0
	global_load_lds_dwordx4 v[188:189], off
	s_waitcnt vmcnt(8)
	s_waitcnt lgkmcnt(0)
	s_barrier
	v_mfma_f32_16x16x32_bf16 v[68:71], v[144:147], v[176:179], v[68:71]
	v_mfma_f32_16x16x32_bf16 v[72:75], v[152:155], v[176:179], v[72:75]
	v_mfma_f32_16x16x32_bf16 v[92:95], v[144:147], v[184:187], v[92:95]
	v_mfma_f32_16x16x32_bf16 v[80:83], v[152:155], v[184:187], v[80:83]
	v_mfma_f32_16x16x32_bf16 v[128:131], v[144:147], v[196:199], v[128:131]
	v_mfma_f32_16x16x32_bf16 v[112:115], v[152:155], v[196:199], v[112:115]
	v_mfma_f32_16x16x32_bf16 v[136:139], v[144:147], v[204:207], v[136:139]
	v_mfma_f32_16x16x32_bf16 v[120:123], v[152:155], v[204:207], v[120:123]
	v_mfma_f32_16x16x32_bf16 v[68:71], v[148:151], v[180:183], v[68:71]
	v_mfma_f32_16x16x32_bf16 v[72:75], v[156:159], v[180:183], v[72:75]
	v_mfma_f32_16x16x32_bf16 v[92:95], v[148:151], v[192:195], v[92:95]
	v_mfma_f32_16x16x32_bf16 v[80:83], v[156:159], v[192:195], v[80:83]
	v_mfma_f32_16x16x32_bf16 v[128:131], v[148:151], v[200:203], v[128:131]
	v_mfma_f32_16x16x32_bf16 v[112:115], v[156:159], v[200:203], v[112:115]
	v_mfma_f32_16x16x32_bf16 v[136:139], v[148:151], v[208:211], v[136:139]
	v_mfma_f32_16x16x32_bf16 v[120:123], v[156:159], v[208:211], v[120:123]
	v_mfma_f32_16x16x32_bf16 v[58:61], v[160:163], v[176:179], v[58:61]
	v_mfma_f32_16x16x32_bf16 v[46:49], v[168:171], v[176:179], v[46:49]
	v_mfma_f32_16x16x32_bf16 v[76:79], v[160:163], v[184:187], v[76:79]
	v_mfma_f32_16x16x32_bf16 v[50:53], v[168:171], v[184:187], v[50:53]
	v_mfma_f32_16x16x32_bf16 v[124:127], v[160:163], v[196:199], v[124:127]
	v_mfma_f32_16x16x32_bf16 v[116:119], v[168:171], v[196:199], v[116:119]
	v_mfma_f32_16x16x32_bf16 v[108:111], v[160:163], v[204:207], v[108:111]
	v_mfma_f32_16x16x32_bf16 v[104:107], v[168:171], v[204:207], v[104:107]
	v_mfma_f32_16x16x32_bf16 v[58:61], v[164:167], v[180:183], v[58:61]
	v_mfma_f32_16x16x32_bf16 v[46:49], v[172:175], v[180:183], v[46:49]
	v_mfma_f32_16x16x32_bf16 v[76:79], v[164:167], v[192:195], v[76:79]
	v_mfma_f32_16x16x32_bf16 v[50:53], v[172:175], v[192:195], v[50:53]
	v_mfma_f32_16x16x32_bf16 v[124:127], v[164:167], v[200:203], v[124:127]
	v_mfma_f32_16x16x32_bf16 v[116:119], v[172:175], v[200:203], v[116:119]
	v_mfma_f32_16x16x32_bf16 v[108:111], v[164:167], v[208:211], v[108:111]
	v_mfma_f32_16x16x32_bf16 v[104:107], v[172:175], v[208:211], v[104:107]
	s_barrier
	s_add_i32 s64, s65, s50
	v_lshl_add_u64 v[188:189], s[38:39], 0, v[66:67]
	s_mov_b32 m0, s64
	ds_read_b128 v[176:179], v143 offset:16384
	ds_read_b128 v[180:183], v143 offset:17408
	ds_read_b128 v[184:187], v143 offset:18432
	ds_read_b128 v[192:195], v143 offset:19456
	ds_read_b128 v[196:199], v143 offset:20480
	ds_read_b128 v[200:203], v143 offset:21504
	ds_read_b128 v[204:207], v143 offset:22528
	ds_read_b128 v[208:211], v143 offset:23552
	global_load_lds_dwordx4 v[188:189], off
	s_add_i32 m0, s64, 0x2000
	s_add_u32 s64, s38, 0x80000
	v_lshl_add_u64 v[220:221], s[38:39], 0, v[84:85]
	s_addc_u32 s65, s39, 0
	s_add_i32 s63, s63, s50
	global_load_lds_dwordx4 v[220:221], off
	v_lshl_add_u64 v[222:223], s[64:65], 0, v[66:67]
	s_mov_b32 m0, s63
	v_lshl_add_u64 v[224:225], s[40:41], 0, v[84:85]
	global_load_lds_dwordx4 v[222:223], off
	v_lshl_add_u64 v[222:223], s[64:65], 0, v[84:85]
	s_add_i32 m0, s63, 0x2000
	s_nop 0
	global_load_lds_dwordx4 v[222:223], off
	v_lshl_add_u64 v[222:223], s[40:41], 0, v[66:67]
	s_mov_b32 m0, s51
	s_nop 0
	global_load_lds_dwordx4 v[222:223], off
	s_mov_b32 m0, s52
	s_nop 0
	global_load_lds_dwordx4 v[224:225], off
	s_waitcnt vmcnt(8)
	s_waitcnt lgkmcnt(0)
	s_barrier
; #define PG8_STAGE(bufoff, gbase, voff) do { _Pragma("unroll") for (int _i = 0; _i < 2; ++_i) \
;         __builtin_amdgcn_global_load_lds((const unsigned*)((const char*)(gbase) + (voff)[_i]), (PG8_LAS unsigned*)(lds + (bufoff) + ldsw + _i * 8192), 16, 0, 0); } while (0)
; #define PG8_LDA(dst, b, h) do { _Pragma("unroll") for (int m = 0; m < 4; ++m) _Pragma("unroll") for (int k = 0; k < 2; ++k) dst[m][k] = *(const PG8_LAS bf16x8*)(lds + PG8_SA(b, h) + aoff + m * 2048 + k * 1024); } while (0)
; #define PG8_LDB(dst, b, h) do { _Pragma("unroll") for (int n = 0; n < 2; ++n) _Pragma("unroll") for (int k = 0; k < 2; ++k) dst[n][k] = *(const PG8_LAS bf16x8*)(lds + PG8_SB(b, h) + boff + n * 2048 + k * 1024); } while (0)
; #define PG8_MMA(ai, bj, At, Bt) do { __builtin_amdgcn_s_setprio(1); _Pragma("unroll") for (int m = 0; m < 4; ++m) _Pragma("unroll") for (int n = 0; n < 2; ++n) _Pragma("unroll") for (int k = 0; k < 2; ++k) \
;         acc[ai][bj][m][n] = __builtin_amdgcn_mfma_f32_16x16x32_bf16(Bt[n][k], At[m][k], acc[ai][bj][m][n], 0, 0, 0); __builtin_amdgcn_s_setprio(0); } while (0)
; #define PG8_WAIT_V(n) asm volatile("s_waitcnt vmcnt(" #n ")" ::: "memory")
; #define PG8_WAIT_L(n) asm volatile("s_waitcnt lgkmcnt(" #n ")" ::: "memory")
; #define PG8_BAR __builtin_amdgcn_s_barrier()
; #define PG8_SCHED __builtin_amdgcn_sched_barrier(0)
; template <class Epi, class Sched, bool ALIGN_EPI = false, bool SP2 = false>
; __device__ __forceinline__ void gemm_phase(PG8_LAS unsigned char* lds, const Gemm g, const Sched& S, const Epi& E) {
;     ...
;             PG8_WAIT_V(8); PG8_WAIT_L(0); PG8_BAR; PG8_MMA(1, 0, At, B0); PG8_MMA(1, 1, At, B1); PG8_BAR; PG8_SCHED;
;             PG8_LDB(B0, 1, 0); PG8_LDB(B1, 1, 1); PG8_SCHED; PG8_LDA(At, 1, 0); PG8_STAGE(PG8_SA(0, 1), a2 + hstep, voffA);
;             PG8_WAIT_V(8); PG8_WAIT_L(0); PG8_BAR; PG8_MMA(0, 0, At, B0); PG8_MMA(0, 1, At, B1); PG8_BAR; PG8_SCHED;
	v_mfma_f32_16x16x32_bf16 v[100:103], v[144:147], v[176:179], v[100:103]
	v_mfma_f32_16x16x32_bf16 v[96:99], v[152:155], v[176:179], v[96:99]
	v_mfma_f32_16x16x32_bf16 v[88:91], v[144:147], v[184:187], v[88:91]
	v_mfma_f32_16x16x32_bf16 v[42:45], v[152:155], v[184:187], v[42:45]
	v_mfma_f32_16x16x32_bf16 v[38:41], v[144:147], v[196:199], v[38:41]
	v_mfma_f32_16x16x32_bf16 v[26:29], v[152:155], v[196:199], v[26:29]
	v_mfma_f32_16x16x32_bf16 v[22:25], v[144:147], v[204:207], v[22:25]
	v_mfma_f32_16x16x32_bf16 v[14:17], v[152:155], v[204:207], v[14:17]
	v_mfma_f32_16x16x32_bf16 v[100:103], v[148:151], v[180:183], v[100:103]
	v_mfma_f32_16x16x32_bf16 v[96:99], v[156:159], v[180:183], v[96:99]
	v_mfma_f32_16x16x32_bf16 v[88:91], v[148:151], v[192:195], v[88:91]
	v_mfma_f32_16x16x32_bf16 v[42:45], v[156:159], v[192:195], v[42:45]
	v_mfma_f32_16x16x32_bf16 v[38:41], v[148:151], v[200:203], v[38:41]
	v_mfma_f32_16x16x32_bf16 v[26:29], v[156:159], v[200:203], v[26:29]
	v_mfma_f32_16x16x32_bf16 v[22:25], v[148:151], v[208:211], v[22:25]
	v_mfma_f32_16x16x32_bf16 v[14:17], v[156:159], v[208:211], v[14:17]
	v_mfma_f32_16x16x32_bf16 v[62:65], v[160:163], v[176:179], v[62:65]
	v_mfma_f32_16x16x32_bf16 v[54:57], v[168:171], v[176:179], v[54:57]
	v_mfma_f32_16x16x32_bf16 v[34:37], v[160:163], v[184:187], v[34:37]
	v_mfma_f32_16x16x32_bf16 v[30:33], v[168:171], v[184:187], v[30:33]
	v_mfma_f32_16x16x32_bf16 v[18:21], v[160:163], v[196:199], v[18:21]
	v_mfma_f32_16x16x32_bf16 v[10:13], v[168:171], v[196:199], v[10:13]
	v_mfma_f32_16x16x32_bf16 v[6:9], v[160:163], v[204:207], v[6:9]
	v_mfma_f32_16x16x32_bf16 v[2:5], v[168:171], v[204:207], v[2:5]
	v_mfma_f32_16x16x32_bf16 v[62:65], v[164:167], v[180:183], v[62:65]
	v_mfma_f32_16x16x32_bf16 v[54:57], v[172:175], v[180:183], v[54:57]
	v_mfma_f32_16x16x32_bf16 v[34:37], v[164:167], v[192:195], v[34:37]
	v_mfma_f32_16x16x32_bf16 v[30:33], v[172:175], v[192:195], v[30:33]
	v_mfma_f32_16x16x32_bf16 v[18:21], v[164:167], v[200:203], v[18:21]
	v_mfma_f32_16x16x32_bf16 v[10:13], v[172:175], v[200:203], v[10:13]
	v_mfma_f32_16x16x32_bf16 v[6:9], v[164:167], v[208:211], v[6:9]
	v_mfma_f32_16x16x32_bf16 v[2:5], v[172:175], v[208:211], v[2:5]
	s_barrier
	s_add_i32 s63, 0, 0x18000
	s_add_i32 s64, 0, 0x1c000
	v_add_u32_e32 v156, s63, v142
	v_add_u32_e32 v172, s64, v142
	ds_read_b128 v[144:147], v156
	ds_read_b128 v[148:151], v156 offset:1024
	ds_read_b128 v[152:155], v156 offset:2048
	ds_read_b128 v[156:159], v156 offset:3072
	ds_read_b128 v[160:163], v172
	ds_read_b128 v[164:167], v172 offset:1024
	ds_read_b128 v[168:171], v172 offset:2048
	ds_read_b128 v[172:175], v172 offset:3072
	s_add_u32 s40, s40, 0x80000
	s_addc_u32 s41, s41, 0
	s_mov_b32 m0, s1
	v_lshl_add_u64 v[226:227], s[40:41], 0, v[66:67]
	ds_read_b128 v[176:179], v143 offset:32768
	ds_read_b128 v[180:183], v143 offset:33792
	ds_read_b128 v[184:187], v143 offset:34816
	ds_read_b128 v[192:195], v143 offset:35840
	ds_read_b128 v[196:199], v143 offset:36864
	ds_read_b128 v[200:203], v143 offset:37888
	ds_read_b128 v[204:207], v143 offset:38912
	ds_read_b128 v[208:211], v143 offset:39936
	global_load_lds_dwordx4 v[226:227], off
	v_lshl_add_u64 v[226:227], s[40:41], 0, v[84:85]
	s_mov_b32 m0, s54
	s_nop 0
	global_load_lds_dwordx4 v[226:227], off
	s_waitcnt vmcnt(8)
	s_waitcnt lgkmcnt(0)
	s_barrier
	v_mfma_f32_16x16x32_bf16 v[68:71], v[144:147], v[176:179], v[68:71]
	v_mfma_f32_16x16x32_bf16 v[72:75], v[152:155], v[176:179], v[72:75]
	v_mfma_f32_16x16x32_bf16 v[92:95], v[144:147], v[184:187], v[92:95]
	v_mfma_f32_16x16x32_bf16 v[80:83], v[152:155], v[184:187], v[80:83]
	v_mfma_f32_16x16x32_bf16 v[128:131], v[144:147], v[196:199], v[128:131]
	v_mfma_f32_16x16x32_bf16 v[112:115], v[152:155], v[196:199], v[112:115]
	v_mfma_f32_16x16x32_bf16 v[136:139], v[144:147], v[204:207], v[136:139]
	v_mfma_f32_16x16x32_bf16 v[120:123], v[152:155], v[204:207], v[120:123]
	v_mfma_f32_16x16x32_bf16 v[68:71], v[148:151], v[180:183], v[68:71]
	v_mfma_f32_16x16x32_bf16 v[72:75], v[156:159], v[180:183], v[72:75]
	v_mfma_f32_16x16x32_bf16 v[92:95], v[148:151], v[192:195], v[92:95]
	v_mfma_f32_16x16x32_bf16 v[80:83], v[156:159], v[192:195], v[80:83]
	v_mfma_f32_16x16x32_bf16 v[128:131], v[148:151], v[200:203], v[128:131]
	v_mfma_f32_16x16x32_bf16 v[112:115], v[156:159], v[200:203], v[112:115]
	v_mfma_f32_16x16x32_bf16 v[136:139], v[148:151], v[208:211], v[136:139]
	v_mfma_f32_16x16x32_bf16 v[120:123], v[156:159], v[208:211], v[120:123]
	v_mfma_f32_16x16x32_bf16 v[58:61], v[160:163], v[176:179], v[58:61]
	v_mfma_f32_16x16x32_bf16 v[46:49], v[168:171], v[176:179], v[46:49]
	v_mfma_f32_16x16x32_bf16 v[76:79], v[160:163], v[184:187], v[76:79]
	v_mfma_f32_16x16x32_bf16 v[50:53], v[168:171], v[184:187], v[50:53]
	v_mfma_f32_16x16x32_bf16 v[124:127], v[160:163], v[196:199], v[124:127]
	v_mfma_f32_16x16x32_bf16 v[116:119], v[168:171], v[196:199], v[116:119]
	v_mfma_f32_16x16x32_bf16 v[108:111], v[160:163], v[204:207], v[108:111]
	v_mfma_f32_16x16x32_bf16 v[104:107], v[168:171], v[204:207], v[104:107]
	v_mfma_f32_16x16x32_bf16 v[58:61], v[164:167], v[180:183], v[58:61]
	v_mfma_f32_16x16x32_bf16 v[46:49], v[172:175], v[180:183], v[46:49]
	v_mfma_f32_16x16x32_bf16 v[76:79], v[164:167], v[192:195], v[76:79]
	v_mfma_f32_16x16x32_bf16 v[50:53], v[172:175], v[192:195], v[50:53]
	v_mfma_f32_16x16x32_bf16 v[124:127], v[164:167], v[200:203], v[124:127]
	v_mfma_f32_16x16x32_bf16 v[116:119], v[172:175], v[200:203], v[116:119]
	v_mfma_f32_16x16x32_bf16 v[108:111], v[164:167], v[208:211], v[108:111]
	v_mfma_f32_16x16x32_bf16 v[104:107], v[172:175], v[208:211], v[104:107]
	s_barrier
; #define PG8_STAGE(bufoff, gbase, voff) do { _Pragma("unroll") for (int _i = 0; _i < 2; ++_i) \
;         __builtin_amdgcn_global_load_lds((const unsigned*)((const char*)(gbase) + (voff)[_i]), (PG8_LAS unsigned*)(lds + (bufoff) + ldsw + _i * 8192), 16, 0, 0); } while (0)
; #define PG8_LDA(dst, b, h) do { _Pragma("unroll") for (int m = 0; m < 4; ++m) _Pragma("unroll") for (int k = 0; k < 2; ++k) dst[m][k] = *(const PG8_LAS bf16x8*)(lds + PG8_SA(b, h) + aoff + m * 2048 + k * 1024); } while (0)
; #define PG8_LDB(dst, b, h) do { _Pragma("unroll") for (int n = 0; n < 2; ++n) _Pragma("unroll") for (int k = 0; k < 2; ++k) dst[n][k] = *(const PG8_LAS bf16x8*)(lds + PG8_SB(b, h) + boff + n * 2048 + k * 1024); } while (0)
; #define PG8_WAIT_V(n) asm volatile("s_waitcnt vmcnt(" #n ")" ::: "memory")
; template <class Epi, class Sched, bool ALIGN_EPI = false, bool SP2 = false>
; __device__ __forceinline__ void gemm_phase(PG8_LAS unsigned char* lds, const Gemm g, const Sched& S, const Epi& E) {
;     ...
;             PG8_LDB(B0, 0, 0); PG8_LDB(B1, 0, 1); PG8_SCHED; PG8_LDA(At, 0, 0); PG8_STAGE(PG8_SA(1, 1), a1 + hstep, voffA);
;             PG8_WAIT_V(8); PG8_WAIT_L(0); PG8_BAR; PG8_MMA(0, 0, At, B0); PG8_MMA(0, 1, At, B1); PG8_BAR; PG8_SCHED;
;             PG8_LDA(At, 0, 1); PG8_STAGE(PG8_SB(0, 0), b2, voffB); PG8_STAGE(PG8_SB(0, 1), b2 + hstep, voffB); PG8_STAGE(PG8_SA(0, 0), a2, voffA);
;             PG8_WAIT_V(8); PG8_WAIT_L(0); PG8_BAR; PG8_MMA(1, 0, At, B0); PG8_MMA(1, 1, At, B1); PG8_BAR; PG8_SCHED;
;             PG8_LDB(B0, 1, 0); PG8_LDB(B1, 1, 1); PG8_SCHED; PG8_LDA(At, 1, 0); PG8_STAGE(PG8_SA(0, 1), a2 + hstep, voffA);
;             PG8_WAIT_V(8); PG8_WAIT_L(0); PG8_BAR; PG8_MMA(0, 0, At, B0); PG8_MMA(0, 1, At, B1); PG8_BAR; PG8_SCHED;
;             PG8_LDA(At, 1, 1); PG8_STAGE(PG8_SB(1, 0), b3, voffB); PG8_STAGE(PG8_SB(1, 1), b3 + hstep, voffB); PG8_STAGE(PG8_SA(1, 0), a3, voffA);
;             PG8_WAIT_V(8); PG8_WAIT_L(0); PG8_BAR; PG8_MMA(1, 0, At, B0); PG8_MMA(1, 1, At, B1); PG8_BAR; PG8_SCHED;
;     ...
; #pragma unroll
;         for (int a = 0; a < 2; ++a)
; #pragma unroll
;             for (int b = 0; b < 2; ++b)
; #pragma unroll
;                 for (int m = 0; m < 4; ++m)
; #pragma unroll
;                     for (int n = 0; n < 2; ++n) acc[a][b][m][n] = (f32x4){0.f, 0.f, 0.f, 0.f};
;         cur = nxt; cA = nA; cB = nB; ++ui;
	s_add_i32 s40, s63, s50
	v_lshl_add_u64 v[188:189], v[188:189], 0, s[88:89]
	s_mov_b32 m0, s40
	ds_read_b128 v[176:179], v143 offset:49152
	ds_read_b128 v[180:183], v143 offset:50176
	ds_read_b128 v[184:187], v143 offset:51200
	ds_read_b128 v[192:195], v143 offset:52224
	ds_read_b128 v[196:199], v143 offset:53248
	ds_read_b128 v[200:203], v143 offset:54272
	ds_read_b128 v[204:207], v143 offset:55296
	ds_read_b128 v[208:211], v143 offset:56320
	global_load_lds_dwordx4 v[188:189], off
	s_add_i32 m0, s40, 0x2000
	s_add_u32 s38, s38, 0x80080
	v_lshl_add_u64 v[188:189], v[220:221], 0, s[88:89]
	s_addc_u32 s39, s39, 0
	s_add_i32 s40, s64, s50
	global_load_lds_dwordx4 v[188:189], off
	v_lshl_add_u64 v[188:189], s[38:39], 0, v[66:67]
	s_mov_b32 m0, s40
	s_nop 0
	global_load_lds_dwordx4 v[188:189], off
	v_lshl_add_u64 v[188:189], s[38:39], 0, v[84:85]
	s_add_i32 m0, s40, 0x2000
	s_nop 0
	global_load_lds_dwordx4 v[188:189], off
	v_lshl_add_u64 v[188:189], v[222:223], 0, s[88:89]
	s_mov_b32 m0, s55
	s_nop 0
	global_load_lds_dwordx4 v[188:189], off
	v_lshl_add_u64 v[188:189], v[224:225], 0, s[88:89]
	s_mov_b32 m0, s56
	s_nop 0
	global_load_lds_dwordx4 v[188:189], off
	s_waitcnt vmcnt(8)
	s_waitcnt lgkmcnt(0)
	s_barrier
	v_mfma_f32_16x16x32_bf16 v[100:103], v[144:147], v[176:179], v[100:103]
	v_mfma_f32_16x16x32_bf16 v[96:99], v[152:155], v[176:179], v[96:99]
	v_mfma_f32_16x16x32_bf16 v[88:91], v[144:147], v[184:187], v[88:91]
	v_mfma_f32_16x16x32_bf16 v[42:45], v[152:155], v[184:187], v[42:45]
	v_mfma_f32_16x16x32_bf16 v[38:41], v[144:147], v[196:199], v[38:41]
	v_mfma_f32_16x16x32_bf16 v[26:29], v[152:155], v[196:199], v[26:29]
	v_mfma_f32_16x16x32_bf16 v[22:25], v[144:147], v[204:207], v[22:25]
	v_mfma_f32_16x16x32_bf16 v[14:17], v[152:155], v[204:207], v[14:17]
	v_mfma_f32_16x16x32_bf16 v[100:103], v[148:151], v[180:183], v[100:103]
	v_mfma_f32_16x16x32_bf16 v[96:99], v[156:159], v[180:183], v[96:99]
	v_mfma_f32_16x16x32_bf16 v[88:91], v[148:151], v[192:195], v[88:91]
	v_mfma_f32_16x16x32_bf16 v[42:45], v[156:159], v[192:195], v[42:45]
	v_mfma_f32_16x16x32_bf16 v[38:41], v[148:151], v[200:203], v[38:41]
	v_mfma_f32_16x16x32_bf16 v[26:29], v[156:159], v[200:203], v[26:29]
	v_mfma_f32_16x16x32_bf16 v[22:25], v[148:151], v[208:211], v[22:25]
	v_mfma_f32_16x16x32_bf16 v[14:17], v[156:159], v[208:211], v[14:17]
	v_mfma_f32_16x16x32_bf16 v[62:65], v[160:163], v[176:179], v[62:65]
	v_mfma_f32_16x16x32_bf16 v[54:57], v[168:171], v[176:179], v[54:57]
	v_mfma_f32_16x16x32_bf16 v[34:37], v[160:163], v[184:187], v[34:37]
	v_mfma_f32_16x16x32_bf16 v[30:33], v[168:171], v[184:187], v[30:33]
	v_mfma_f32_16x16x32_bf16 v[18:21], v[160:163], v[196:199], v[18:21]
	v_mfma_f32_16x16x32_bf16 v[10:13], v[168:171], v[196:199], v[10:13]
	v_mfma_f32_16x16x32_bf16 v[6:9], v[160:163], v[204:207], v[6:9]
	v_mfma_f32_16x16x32_bf16 v[2:5], v[168:171], v[204:207], v[2:5]
	v_mfma_f32_16x16x32_bf16 v[62:65], v[164:167], v[180:183], v[62:65]
	v_mfma_f32_16x16x32_bf16 v[54:57], v[172:175], v[180:183], v[54:57]
	v_mfma_f32_16x16x32_bf16 v[34:37], v[164:167], v[192:195], v[34:37]
	v_mfma_f32_16x16x32_bf16 v[30:33], v[172:175], v[192:195], v[30:33]
	v_mfma_f32_16x16x32_bf16 v[18:21], v[164:167], v[200:203], v[18:21]
	v_mfma_f32_16x16x32_bf16 v[10:13], v[172:175], v[200:203], v[10:13]
	v_mfma_f32_16x16x32_bf16 v[6:9], v[164:167], v[208:211], v[6:9]
	v_mfma_f32_16x16x32_bf16 v[2:5], v[172:175], v[208:211], v[2:5]
	s_barrier
	s_add_i32 s62, s62, 2
	s_add_u32 s36, s36, 0x100
	s_addc_u32 s37, s37, 0
	s_cmp_gt_u32 s62, 29
	s_cbranch_scc0 .LBB0_905
	s_nop 0
	s_nop 0
	s_nop 0
	s_nop 0
	s_nop 0
	s_nop 0
	s_nop 0
	s_nop 0
	s_nop 0
	s_nop 0
	s_nop 0
	s_nop 0
	s_nop 0
	s_nop 0
	s_nop 0
	s_nop 0
	s_nop 0
	s_nop 0
	s_nop 0
	s_nop 0
	s_add_u32 s36, s3, 0xffffff00
	s_addc_u32 s37, s59, -1
	s_andn2_b64 vcc, exec, s[10:11]
	s_cbranch_vccnz .LBB0_896
	v_mov_b32_e32 v2, 0
	s_mov_b32 s12, s26
	s_mov_b32 s46, s28
	s_mov_b64 s[22:23], s[34:35]
	s_mov_b32 s57, s2
	v_mov_b32_e32 v3, v2
	v_mov_b32_e32 v4, v2
	v_mov_b32_e32 v5, v2
	v_mov_b32_e32 v6, v2
	v_mov_b32_e32 v7, v2
	v_mov_b32_e32 v8, v2
	v_mov_b32_e32 v9, v2
	v_mov_b32_e32 v10, v2
	v_mov_b32_e32 v11, v2
	v_mov_b32_e32 v12, v2
	v_mov_b32_e32 v13, v2
	v_mov_b32_e32 v18, v2
	v_mov_b32_e32 v19, v2
	v_mov_b32_e32 v20, v2
	v_mov_b32_e32 v21, v2
	v_mov_b32_e32 v30, v2
	v_mov_b32_e32 v31, v2
	v_mov_b32_e32 v32, v2
	v_mov_b32_e32 v33, v2
	v_mov_b32_e32 v34, v2
	v_mov_b32_e32 v35, v2
	v_mov_b32_e32 v36, v2
	v_mov_b32_e32 v37, v2
	v_mov_b32_e32 v54, v2
	v_mov_b32_e32 v55, v2
	v_mov_b32_e32 v56, v2
	v_mov_b32_e32 v57, v2
	v_mov_b32_e32 v62, v2
	v_mov_b32_e32 v63, v2
	v_mov_b32_e32 v64, v2
	v_mov_b32_e32 v65, v2
	v_mov_b32_e32 v14, v2
	v_mov_b32_e32 v15, v2
	v_mov_b32_e32 v16, v2
	v_mov_b32_e32 v17, v2
	v_mov_b32_e32 v22, v2
	v_mov_b32_e32 v23, v2
	v_mov_b32_e32 v24, v2
	v_mov_b32_e32 v25, v2
	v_mov_b32_e32 v26, v2
	v_mov_b32_e32 v27, v2
	v_mov_b32_e32 v28, v2
	v_mov_b32_e32 v29, v2
	v_mov_b32_e32 v38, v2
	v_mov_b32_e32 v39, v2
	v_mov_b32_e32 v40, v2
	v_mov_b32_e32 v41, v2
	v_mov_b32_e32 v42, v2
	v_mov_b32_e32 v43, v2
	v_mov_b32_e32 v44, v2
	v_mov_b32_e32 v45, v2
	v_mov_b32_e32 v88, v2
	v_mov_b32_e32 v89, v2
	v_mov_b32_e32 v90, v2
	v_mov_b32_e32 v91, v2
	v_mov_b32_e32 v96, v2
	v_mov_b32_e32 v97, v2
	v_mov_b32_e32 v98, v2
	v_mov_b32_e32 v99, v2
	v_mov_b32_e32 v100, v2
	v_mov_b32_e32 v101, v2
	v_mov_b32_e32 v102, v2
	v_mov_b32_e32 v103, v2
	v_mov_b32_e32 v104, v2
	v_mov_b32_e32 v105, v2
	v_mov_b32_e32 v106, v2
	v_mov_b32_e32 v107, v2
	v_mov_b32_e32 v108, v2
	v_mov_b32_e32 v109, v2
	v_mov_b32_e32 v110, v2
	v_mov_b32_e32 v111, v2
	v_mov_b32_e32 v116, v2
	v_mov_b32_e32 v117, v2
	v_mov_b32_e32 v118, v2
	v_mov_b32_e32 v119, v2
	v_mov_b32_e32 v124, v2
	v_mov_b32_e32 v125, v2
	v_mov_b32_e32 v126, v2
	v_mov_b32_e32 v127, v2
	v_mov_b32_e32 v50, v2
	v_mov_b32_e32 v51, v2
	v_mov_b32_e32 v52, v2
	v_mov_b32_e32 v53, v2
	v_mov_b32_e32 v76, v2
	v_mov_b32_e32 v77, v2
	v_mov_b32_e32 v78, v2
	v_mov_b32_e32 v79, v2
	v_mov_b32_e32 v46, v2
	v_mov_b32_e32 v47, v2
	v_mov_b32_e32 v48, v2
	v_mov_b32_e32 v49, v2
	v_mov_b32_e32 v58, v2
	v_mov_b32_e32 v59, v2
	v_mov_b32_e32 v60, v2
	v_mov_b32_e32 v61, v2
	v_mov_b32_e32 v120, v2
	v_mov_b32_e32 v121, v2
	v_mov_b32_e32 v122, v2
	v_mov_b32_e32 v123, v2
	v_mov_b32_e32 v136, v2
	v_mov_b32_e32 v137, v2
	v_mov_b32_e32 v138, v2
	v_mov_b32_e32 v139, v2
	v_mov_b32_e32 v112, v2
	v_mov_b32_e32 v113, v2
	v_mov_b32_e32 v114, v2
	v_mov_b32_e32 v115, v2
	v_mov_b32_e32 v128, v2
	v_mov_b32_e32 v129, v2
	v_mov_b32_e32 v130, v2
	v_mov_b32_e32 v131, v2
	v_mov_b32_e32 v80, v2
	v_mov_b32_e32 v81, v2
	v_mov_b32_e32 v82, v2
	v_mov_b32_e32 v83, v2
	v_mov_b32_e32 v92, v2
	v_mov_b32_e32 v93, v2
	v_mov_b32_e32 v94, v2
	v_mov_b32_e32 v95, v2
	v_mov_b32_e32 v72, v2
	v_mov_b32_e32 v73, v2
	v_mov_b32_e32 v74, v2
	v_mov_b32_e32 v75, v2
	v_mov_b32_e32 v68, v2
	v_mov_b32_e32 v69, v2
	v_mov_b32_e32 v70, v2
	v_mov_b32_e32 v71, v2
	s_mov_b64 s[64:65], s[72:73]
	s_andn2_b64 vcc, exec, s[8:9]
	s_mov_b32 s72, s67
	s_cbranch_vccnz .LBB0_897

; #define PG8_STAGE(bufoff, gbase, voff) do { _Pragma("unroll") for (int _i = 0; _i < 2; ++_i) \
;         __builtin_amdgcn_global_load_lds((const unsigned*)((const char*)(gbase) + (voff)[_i]), (PG8_LAS unsigned*)(lds + (bufoff) + ldsw + _i * 8192), 16, 0, 0); } while (0)
; #define PG8_LDA(dst, b, h) do { _Pragma("unroll") for (int m = 0; m < 4; ++m) _Pragma("unroll") for (int k = 0; k < 2; ++k) dst[m][k] = *(const PG8_LAS bf16x8*)(lds + PG8_SA(b, h) + aoff + m * 2048 + k * 1024); } while (0)
; #define PG8_LDB(dst, b, h) do { _Pragma("unroll") for (int n = 0; n < 2; ++n) _Pragma("unroll") for (int k = 0; k < 2; ++k) dst[n][k] = *(const PG8_LAS bf16x8*)(lds + PG8_SB(b, h) + boff + n * 2048 + k * 1024); } while (0)
; #define PG8_MMA(ai, bj, At, Bt) do { __builtin_amdgcn_s_setprio(1); _Pragma("unroll") for (int m = 0; m < 4; ++m) _Pragma("unroll") for (int n = 0; n < 2; ++n) _Pragma("unroll") for (int k = 0; k < 2; ++k) \
;         acc[ai][bj][m][n] = __builtin_amdgcn_mfma_f32_16x16x32_bf16(Bt[n][k], At[m][k], acc[ai][bj][m][n], 0, 0, 0); __builtin_amdgcn_s_setprio(0); } while (0)
; #define PG8_WAIT_V(n) asm volatile("s_waitcnt vmcnt(" #n ")" ::: "memory")
; #define PG8_WAIT_L(n) asm volatile("s_waitcnt lgkmcnt(" #n ")" ::: "memory")
; #define PG8_BAR __builtin_amdgcn_s_barrier()
; template <class Epi, class Sched, bool ALIGN_EPI = false, bool SP2 = false>
; __device__ __forceinline__ void gemm_phase(PG8_LAS unsigned char* lds, const Gemm g, const Sched& S, const Epi& E) {
;     ...
;             const char* a1 = cA + (size_t)(t + 1) * kstep;
;             const char* a2 = last ? nA : cA + (size_t)(t + 2) * kstep; const char* b2 = last ? nB : cB + (size_t)(t + 2) * kstep;
;             const char* a3 = a2 + kstep; const char* b3 = b2 + kstep;
;             if (last && has_next) S.a_ready(nxt);
;             if constexpr (SP2) {
;             PG8_LDB(B0, 0, 0); PG8_LDB(B1, 0, 1); PG8_SCHED; PG8_LDA(At, 0, 0); PG8_STAGE(PG8_SA(1, 1), a1 + hstep, voffA);
;             PG8_WAIT_V(8); PG8_WAIT_L(0); PG8_BAR; PG8_MMA(0, 0, At, B0); PG8_MMA(0, 1, At, B1); PG8_BAR; PG8_SCHED;
;             PG8_LDA(At, 0, 1); PG8_STAGE(PG8_SB(0, 0), b2, voffB); PG8_STAGE(PG8_SB(0, 1), b2 + hstep, voffB); PG8_STAGE(PG8_SA(0, 0), a2, voffA);
;             PG8_WAIT_V(8); PG8_WAIT_L(0); PG8_BAR; PG8_MMA(1, 0, At, B0); PG8_MMA(1, 1, At, B1); PG8_BAR; PG8_SCHED;
.LBB0_979:
	s_xor_b64 s[40:41], s[38:39], -1
	s_add_u32 s27, s12, s2
	s_addc_u32 s29, s13, 0
	s_add_u32 s3, s27, 0x100
	s_addc_u32 s44, s29, 0
	s_and_b64 s[42:43], s[38:39], exec
	s_cselect_b32 s43, s44, s35
	s_cselect_b32 s42, s3, s34
	s_add_u32 s2, s20, s2
	s_addc_u32 s3, s21, 0
	s_add_u32 s44, s2, 0x100
	s_addc_u32 s45, s3, 0
	s_and_b64 s[2:3], s[38:39], exec
	s_cselect_b32 s39, s45, s31
	s_cselect_b32 s38, s44, s30
	s_add_i32 s44, 0, 0x10000
	s_add_i32 s45, 0, 0x14000
	v_add_u32_e32 v164, s44, v0
	v_add_u32_e32 v180, s45, v0
	ds_read_b128 v[152:155], v164
	ds_read_b128 v[156:159], v164 offset:1024
	ds_read_b128 v[160:163], v164 offset:2048
	ds_read_b128 v[164:167], v164 offset:3072
	ds_read_b128 v[168:171], v180
	ds_read_b128 v[172:175], v180 offset:1024
	ds_read_b128 v[176:179], v180 offset:2048
	ds_read_b128 v[180:183], v180 offset:3072
	s_add_u32 s2, s27, 0x80080
	s_addc_u32 s3, s29, 0
	v_lshl_add_u64 v[224:225], s[2:3], 0, v[66:67]
	s_add_i32 m0, s52, 0xc000
	ds_read_b128 v[184:187], v151
	ds_read_b128 v[188:191], v151 offset:1024
	ds_read_b128 v[192:195], v151 offset:2048
	ds_read_b128 v[196:199], v151 offset:3072
	ds_read_b128 v[200:203], v151 offset:4096
	ds_read_b128 v[204:207], v151 offset:5120
	ds_read_b128 v[208:211], v151 offset:6144
	ds_read_b128 v[220:223], v151 offset:7168
	global_load_lds_dwordx4 v[224:225], off
	v_lshl_add_u64 v[224:225], s[2:3], 0, v[132:133]
	s_add_i32 m0, s52, 0xe000
	s_nop 0
	global_load_lds_dwordx4 v[224:225], off
	s_waitcnt vmcnt(8)
	s_waitcnt lgkmcnt(0)
	s_barrier
	v_mfma_f32_16x16x32_bf16 v[128:131], v[152:155], v[184:187], v[128:131]
	v_mfma_f32_16x16x32_bf16 v[124:127], v[160:163], v[184:187], v[124:127]
	v_mfma_f32_16x16x32_bf16 v[120:123], v[152:155], v[192:195], v[120:123]
	v_mfma_f32_16x16x32_bf16 v[116:119], v[160:163], v[192:195], v[116:119]
	v_mfma_f32_16x16x32_bf16 v[112:115], v[152:155], v[200:203], v[112:115]
	v_mfma_f32_16x16x32_bf16 v[108:111], v[160:163], v[200:203], v[108:111]
	v_mfma_f32_16x16x32_bf16 v[100:103], v[152:155], v[208:211], v[100:103]
	v_mfma_f32_16x16x32_bf16 v[92:95], v[160:163], v[208:211], v[92:95]
	v_mfma_f32_16x16x32_bf16 v[128:131], v[156:159], v[188:191], v[128:131]
	v_mfma_f32_16x16x32_bf16 v[124:127], v[164:167], v[188:191], v[124:127]
	v_mfma_f32_16x16x32_bf16 v[120:123], v[156:159], v[196:199], v[120:123]
	v_mfma_f32_16x16x32_bf16 v[116:119], v[164:167], v[196:199], v[116:119]
	v_mfma_f32_16x16x32_bf16 v[112:115], v[156:159], v[204:207], v[112:115]
	v_mfma_f32_16x16x32_bf16 v[108:111], v[164:167], v[204:207], v[108:111]
	v_mfma_f32_16x16x32_bf16 v[100:103], v[156:159], v[220:223], v[100:103]
	v_mfma_f32_16x16x32_bf16 v[92:95], v[164:167], v[220:223], v[92:95]
	v_mfma_f32_16x16x32_bf16 v[104:107], v[168:171], v[184:187], v[104:107]
	v_mfma_f32_16x16x32_bf16 v[96:99], v[176:179], v[184:187], v[96:99]
	v_mfma_f32_16x16x32_bf16 v[88:91], v[168:171], v[192:195], v[88:91]
	v_mfma_f32_16x16x32_bf16 v[84:87], v[176:179], v[192:195], v[84:87]
	v_mfma_f32_16x16x32_bf16 v[80:83], v[168:171], v[200:203], v[80:83]
	v_mfma_f32_16x16x32_bf16 v[76:79], v[176:179], v[200:203], v[76:79]
	v_mfma_f32_16x16x32_bf16 v[72:75], v[168:171], v[208:211], v[72:75]
	v_mfma_f32_16x16x32_bf16 v[68:71], v[176:179], v[208:211], v[68:71]
	v_mfma_f32_16x16x32_bf16 v[104:107], v[172:175], v[188:191], v[104:107]
	v_mfma_f32_16x16x32_bf16 v[96:99], v[180:183], v[188:191], v[96:99]
	v_mfma_f32_16x16x32_bf16 v[88:91], v[172:175], v[196:199], v[88:91]
	v_mfma_f32_16x16x32_bf16 v[84:87], v[180:183], v[196:199], v[84:87]
	v_mfma_f32_16x16x32_bf16 v[80:83], v[172:175], v[204:207], v[80:83]
	v_mfma_f32_16x16x32_bf16 v[76:79], v[180:183], v[204:207], v[76:79]
	v_mfma_f32_16x16x32_bf16 v[72:75], v[172:175], v[220:223], v[72:75]
	v_mfma_f32_16x16x32_bf16 v[68:71], v[180:183], v[220:223], v[68:71]
	s_barrier
	s_add_i32 s2, s44, s51
	v_lshl_add_u64 v[224:225], s[38:39], 0, v[66:67]
	s_mov_b32 m0, s2
	ds_read_b128 v[184:187], v151 offset:16384
	ds_read_b128 v[188:191], v151 offset:17408
	ds_read_b128 v[192:195], v151 offset:18432
	ds_read_b128 v[196:199], v151 offset:19456
	ds_read_b128 v[200:203], v151 offset:20480
	ds_read_b128 v[204:207], v151 offset:21504
	ds_read_b128 v[208:211], v151 offset:22528
	ds_read_b128 v[220:223], v151 offset:23552
	global_load_lds_dwordx4 v[224:225], off
	s_add_i32 m0, s2, 0x2000
	s_add_u32 s2, s38, 0x80000
	v_lshl_add_u64 v[226:227], s[38:39], 0, v[132:133]
	s_addc_u32 s3, s39, 0
	s_add_i32 s27, s45, s51
	global_load_lds_dwordx4 v[226:227], off
	v_lshl_add_u64 v[228:229], s[2:3], 0, v[66:67]
	s_mov_b32 m0, s27
	v_lshl_add_u64 v[230:231], s[42:43], 0, v[132:133]
	global_load_lds_dwordx4 v[228:229], off
	v_lshl_add_u64 v[228:229], s[2:3], 0, v[132:133]
	s_add_i32 m0, s27, 0x2000
	s_nop 0
	global_load_lds_dwordx4 v[228:229], off
	v_lshl_add_u64 v[228:229], s[42:43], 0, v[66:67]
	s_mov_b32 m0, s52
	s_nop 0
	global_load_lds_dwordx4 v[228:229], off
	s_mov_b32 m0, s53
	s_nop 0
	global_load_lds_dwordx4 v[230:231], off
	s_waitcnt vmcnt(8)
	s_waitcnt lgkmcnt(0)
	s_barrier
; #define PG8_STAGE(bufoff, gbase, voff) do { _Pragma("unroll") for (int _i = 0; _i < 2; ++_i) \
;         __builtin_amdgcn_global_load_lds((const unsigned*)((const char*)(gbase) + (voff)[_i]), (PG8_LAS unsigned*)(lds + (bufoff) + ldsw + _i * 8192), 16, 0, 0); } while (0)
; #define PG8_LDA(dst, b, h) do { _Pragma("unroll") for (int m = 0; m < 4; ++m) _Pragma("unroll") for (int k = 0; k < 2; ++k) dst[m][k] = *(const PG8_LAS bf16x8*)(lds + PG8_SA(b, h) + aoff + m * 2048 + k * 1024); } while (0)
; #define PG8_LDB(dst, b, h) do { _Pragma("unroll") for (int n = 0; n < 2; ++n) _Pragma("unroll") for (int k = 0; k < 2; ++k) dst[n][k] = *(const PG8_LAS bf16x8*)(lds + PG8_SB(b, h) + boff + n * 2048 + k * 1024); } while (0)
; #define PG8_MMA(ai, bj, At, Bt) do { __builtin_amdgcn_s_setprio(1); _Pragma("unroll") for (int m = 0; m < 4; ++m) _Pragma("unroll") for (int n = 0; n < 2; ++n) _Pragma("unroll") for (int k = 0; k < 2; ++k) \
;         acc[ai][bj][m][n] = __builtin_amdgcn_mfma_f32_16x16x32_bf16(Bt[n][k], At[m][k], acc[ai][bj][m][n], 0, 0, 0); __builtin_amdgcn_s_setprio(0); } while (0)
; #define PG8_WAIT_V(n) asm volatile("s_waitcnt vmcnt(" #n ")" ::: "memory")
; #define PG8_WAIT_L(n) asm volatile("s_waitcnt lgkmcnt(" #n ")" ::: "memory")
; #define PG8_BAR __builtin_amdgcn_s_barrier()
; #define PG8_SCHED __builtin_amdgcn_sched_barrier(0)
; template <class Epi, class Sched, bool ALIGN_EPI = false, bool SP2 = false>
; __device__ __forceinline__ void gemm_phase(PG8_LAS unsigned char* lds, const Gemm g, const Sched& S, const Epi& E) {
;     ...
;             PG8_WAIT_V(8); PG8_WAIT_L(0); PG8_BAR; PG8_MMA(1, 0, At, B0); PG8_MMA(1, 1, At, B1); PG8_BAR; PG8_SCHED;
;             PG8_LDB(B0, 1, 0); PG8_LDB(B1, 1, 1); PG8_SCHED; PG8_LDA(At, 1, 0); PG8_STAGE(PG8_SA(0, 1), a2 + hstep, voffA);
;             PG8_WAIT_V(8); PG8_WAIT_L(0); PG8_BAR; PG8_MMA(0, 0, At, B0); PG8_MMA(0, 1, At, B1); PG8_BAR; PG8_SCHED;
;             PG8_LDA(At, 1, 1); PG8_STAGE(PG8_SB(1, 0), b3, voffB); PG8_STAGE(PG8_SB(1, 1), b3 + hstep, voffB); PG8_STAGE(PG8_SA(1, 0), a3, voffA);
	v_mfma_f32_16x16x32_bf16 v[62:65], v[152:155], v[184:187], v[62:65]
	v_mfma_f32_16x16x32_bf16 v[58:61], v[160:163], v[184:187], v[58:61]
	v_mfma_f32_16x16x32_bf16 v[54:57], v[152:155], v[192:195], v[54:57]
	v_mfma_f32_16x16x32_bf16 v[50:53], v[160:163], v[192:195], v[50:53]
	v_mfma_f32_16x16x32_bf16 v[46:49], v[152:155], v[200:203], v[46:49]
	v_mfma_f32_16x16x32_bf16 v[42:45], v[160:163], v[200:203], v[42:45]
	v_mfma_f32_16x16x32_bf16 v[34:37], v[152:155], v[208:211], v[34:37]
	v_mfma_f32_16x16x32_bf16 v[26:29], v[160:163], v[208:211], v[26:29]
	v_mfma_f32_16x16x32_bf16 v[62:65], v[156:159], v[188:191], v[62:65]
	v_mfma_f32_16x16x32_bf16 v[58:61], v[164:167], v[188:191], v[58:61]
	v_mfma_f32_16x16x32_bf16 v[54:57], v[156:159], v[196:199], v[54:57]
	v_mfma_f32_16x16x32_bf16 v[50:53], v[164:167], v[196:199], v[50:53]
	v_mfma_f32_16x16x32_bf16 v[46:49], v[156:159], v[204:207], v[46:49]
	v_mfma_f32_16x16x32_bf16 v[42:45], v[164:167], v[204:207], v[42:45]
	v_mfma_f32_16x16x32_bf16 v[34:37], v[156:159], v[220:223], v[34:37]
	v_mfma_f32_16x16x32_bf16 v[26:29], v[164:167], v[220:223], v[26:29]
	v_mfma_f32_16x16x32_bf16 v[38:41], v[168:171], v[184:187], v[38:41]
	v_mfma_f32_16x16x32_bf16 v[30:33], v[176:179], v[184:187], v[30:33]
	v_mfma_f32_16x16x32_bf16 v[22:25], v[168:171], v[192:195], v[22:25]
	v_mfma_f32_16x16x32_bf16 v[18:21], v[176:179], v[192:195], v[18:21]
	v_mfma_f32_16x16x32_bf16 v[14:17], v[168:171], v[200:203], v[14:17]
	v_mfma_f32_16x16x32_bf16 v[10:13], v[176:179], v[200:203], v[10:13]
	v_mfma_f32_16x16x32_bf16 v[6:9], v[168:171], v[208:211], v[6:9]
	v_mfma_f32_16x16x32_bf16 v[2:5], v[176:179], v[208:211], v[2:5]
	v_mfma_f32_16x16x32_bf16 v[38:41], v[172:175], v[188:191], v[38:41]
	v_mfma_f32_16x16x32_bf16 v[30:33], v[180:183], v[188:191], v[30:33]
	v_mfma_f32_16x16x32_bf16 v[22:25], v[172:175], v[196:199], v[22:25]
	v_mfma_f32_16x16x32_bf16 v[18:21], v[180:183], v[196:199], v[18:21]
	v_mfma_f32_16x16x32_bf16 v[14:17], v[172:175], v[204:207], v[14:17]
	v_mfma_f32_16x16x32_bf16 v[10:13], v[180:183], v[204:207], v[10:13]
	v_mfma_f32_16x16x32_bf16 v[6:9], v[172:175], v[220:223], v[6:9]
	v_mfma_f32_16x16x32_bf16 v[2:5], v[180:183], v[220:223], v[2:5]
	s_barrier
	s_add_i32 s27, 0, 0x18000
	s_add_i32 s29, 0, 0x1c000
	v_add_u32_e32 v164, s27, v0
	v_add_u32_e32 v180, s29, v0
	ds_read_b128 v[152:155], v164
	ds_read_b128 v[156:159], v164 offset:1024
	ds_read_b128 v[160:163], v164 offset:2048
	ds_read_b128 v[164:167], v164 offset:3072
	ds_read_b128 v[168:171], v180
	ds_read_b128 v[172:175], v180 offset:1024
	ds_read_b128 v[176:179], v180 offset:2048
	ds_read_b128 v[180:183], v180 offset:3072
	s_add_u32 s2, s42, 0x80000
	s_addc_u32 s3, s43, 0
	s_mov_b32 m0, s54
	v_lshl_add_u64 v[232:233], s[2:3], 0, v[66:67]
	ds_read_b128 v[184:187], v151 offset:32768
	ds_read_b128 v[188:191], v151 offset:33792
	ds_read_b128 v[192:195], v151 offset:34816
	ds_read_b128 v[196:199], v151 offset:35840
	ds_read_b128 v[200:203], v151 offset:36864
	ds_read_b128 v[204:207], v151 offset:37888
	ds_read_b128 v[208:211], v151 offset:38912
	ds_read_b128 v[220:223], v151 offset:39936
	global_load_lds_dwordx4 v[232:233], off
	v_lshl_add_u64 v[232:233], s[2:3], 0, v[132:133]
	s_mov_b32 m0, s55
	s_nop 0
	global_load_lds_dwordx4 v[232:233], off
	s_waitcnt vmcnt(8)
	s_waitcnt lgkmcnt(0)
	s_barrier
	v_mfma_f32_16x16x32_bf16 v[128:131], v[152:155], v[184:187], v[128:131]
	v_mfma_f32_16x16x32_bf16 v[124:127], v[160:163], v[184:187], v[124:127]
	v_mfma_f32_16x16x32_bf16 v[120:123], v[152:155], v[192:195], v[120:123]
	v_mfma_f32_16x16x32_bf16 v[116:119], v[160:163], v[192:195], v[116:119]
	v_mfma_f32_16x16x32_bf16 v[112:115], v[152:155], v[200:203], v[112:115]
	v_mfma_f32_16x16x32_bf16 v[108:111], v[160:163], v[200:203], v[108:111]
	v_mfma_f32_16x16x32_bf16 v[100:103], v[152:155], v[208:211], v[100:103]
	v_mfma_f32_16x16x32_bf16 v[92:95], v[160:163], v[208:211], v[92:95]
	v_mfma_f32_16x16x32_bf16 v[128:131], v[156:159], v[188:191], v[128:131]
	v_mfma_f32_16x16x32_bf16 v[124:127], v[164:167], v[188:191], v[124:127]
	v_mfma_f32_16x16x32_bf16 v[120:123], v[156:159], v[196:199], v[120:123]
	v_mfma_f32_16x16x32_bf16 v[116:119], v[164:167], v[196:199], v[116:119]
	v_mfma_f32_16x16x32_bf16 v[112:115], v[156:159], v[204:207], v[112:115]
	v_mfma_f32_16x16x32_bf16 v[108:111], v[164:167], v[204:207], v[108:111]
	v_mfma_f32_16x16x32_bf16 v[100:103], v[156:159], v[220:223], v[100:103]
	v_mfma_f32_16x16x32_bf16 v[92:95], v[164:167], v[220:223], v[92:95]
	v_mfma_f32_16x16x32_bf16 v[104:107], v[168:171], v[184:187], v[104:107]
	v_mfma_f32_16x16x32_bf16 v[96:99], v[176:179], v[184:187], v[96:99]
	v_mfma_f32_16x16x32_bf16 v[88:91], v[168:171], v[192:195], v[88:91]
	v_mfma_f32_16x16x32_bf16 v[84:87], v[176:179], v[192:195], v[84:87]
	v_mfma_f32_16x16x32_bf16 v[80:83], v[168:171], v[200:203], v[80:83]
	v_mfma_f32_16x16x32_bf16 v[76:79], v[176:179], v[200:203], v[76:79]
	v_mfma_f32_16x16x32_bf16 v[72:75], v[168:171], v[208:211], v[72:75]
	v_mfma_f32_16x16x32_bf16 v[68:71], v[176:179], v[208:211], v[68:71]
	v_mfma_f32_16x16x32_bf16 v[104:107], v[172:175], v[188:191], v[104:107]
	v_mfma_f32_16x16x32_bf16 v[96:99], v[180:183], v[188:191], v[96:99]
	v_mfma_f32_16x16x32_bf16 v[88:91], v[172:175], v[196:199], v[88:91]
	v_mfma_f32_16x16x32_bf16 v[84:87], v[180:183], v[196:199], v[84:87]
	v_mfma_f32_16x16x32_bf16 v[80:83], v[172:175], v[204:207], v[80:83]
	v_mfma_f32_16x16x32_bf16 v[76:79], v[180:183], v[204:207], v[76:79]
	v_mfma_f32_16x16x32_bf16 v[72:75], v[172:175], v[220:223], v[72:75]
	v_mfma_f32_16x16x32_bf16 v[68:71], v[180:183], v[220:223], v[68:71]
	s_barrier
; #define PG8_STAGE(bufoff, gbase, voff) do { _Pragma("unroll") for (int _i = 0; _i < 2; ++_i) \
;         __builtin_amdgcn_global_load_lds((const unsigned*)((const char*)(gbase) + (voff)[_i]), (PG8_LAS unsigned*)(lds + (bufoff) + ldsw + _i * 8192), 16, 0, 0); } while (0)
; #define PG8_LDA(dst, b, h) do { _Pragma("unroll") for (int m = 0; m < 4; ++m) _Pragma("unroll") for (int k = 0; k < 2; ++k) dst[m][k] = *(const PG8_LAS bf16x8*)(lds + PG8_SA(b, h) + aoff + m * 2048 + k * 1024); } while (0)
; #define PG8_MMA(ai, bj, At, Bt) do { __builtin_amdgcn_s_setprio(1); _Pragma("unroll") for (int m = 0; m < 4; ++m) _Pragma("unroll") for (int n = 0; n < 2; ++n) _Pragma("unroll") for (int k = 0; k < 2; ++k) \
;         acc[ai][bj][m][n] = __builtin_amdgcn_mfma_f32_16x16x32_bf16(Bt[n][k], At[m][k], acc[ai][bj][m][n], 0, 0, 0); __builtin_amdgcn_s_setprio(0); } while (0)
; #define PG8_WAIT_V(n) asm volatile("s_waitcnt vmcnt(" #n ")" ::: "memory")
; #define PG8_WAIT_L(n) asm volatile("s_waitcnt lgkmcnt(" #n ")" ::: "memory")
; #define PG8_BAR __builtin_amdgcn_s_barrier()
; #define PG8_SCHED __builtin_amdgcn_sched_barrier(0)
;     __device__ __forceinline__ void a_ready(const Unit&) const {
;         if (need == 0u) return;
;         if (threadIdx.x < 64) {
;             const unsigned long long t0 = __builtin_amdgcn_s_memrealtime();
;             while ((unsigned)__builtin_amdgcn_readfirstlane(__hip_atomic_load(ready, __ATOMIC_RELAXED, __HIP_MEMORY_SCOPE_AGENT)) < need) {
;                 if (__builtin_amdgcn_s_memrealtime() - t0 > 2000000ull) { if (threadIdx.x == 0) __hip_atomic_store(tmo, 1u, __ATOMIC_RELAXED, __HIP_MEMORY_SCOPE_AGENT); break; }
;                 __builtin_amdgcn_s_sleep(2); }
; template <class Epi, class Sched, bool ALIGN_EPI = false, bool SP2 = false>
; __device__ __forceinline__ void gemm_phase(PG8_LAS unsigned char* lds, const Gemm g, const Sched& S, const Epi& E) {
;     ...
;             PG8_LDA(At, 1, 1); PG8_STAGE(PG8_SB(1, 0), b3, voffB); PG8_STAGE(PG8_SB(1, 1), b3 + hstep, voffB); PG8_STAGE(PG8_SA(1, 0), a3, voffA);
;             PG8_WAIT_V(8); PG8_WAIT_L(0); PG8_BAR; PG8_MMA(1, 0, At, B0); PG8_MMA(1, 1, At, B1); PG8_BAR; PG8_SCHED;
	s_add_i32 s2, s27, s51
	v_lshl_add_u64 v[224:225], v[224:225], 0, s[88:89]
	s_mov_b32 m0, s2
	ds_read_b128 v[184:187], v151 offset:49152
	ds_read_b128 v[188:191], v151 offset:50176
	ds_read_b128 v[192:195], v151 offset:51200
	ds_read_b128 v[196:199], v151 offset:52224
	ds_read_b128 v[200:203], v151 offset:53248
	ds_read_b128 v[204:207], v151 offset:54272
	ds_read_b128 v[208:211], v151 offset:55296
	ds_read_b128 v[220:223], v151 offset:56320
	global_load_lds_dwordx4 v[224:225], off
	s_add_i32 m0, s2, 0x2000
	s_add_u32 s2, s38, 0x80080
	v_lshl_add_u64 v[224:225], v[226:227], 0, s[88:89]
	s_addc_u32 s3, s39, 0
	s_add_i32 s27, s29, s51
	global_load_lds_dwordx4 v[224:225], off
	v_lshl_add_u64 v[224:225], s[2:3], 0, v[66:67]
	s_mov_b32 m0, s27
	s_nop 0
	global_load_lds_dwordx4 v[224:225], off
	v_lshl_add_u64 v[224:225], s[2:3], 0, v[132:133]
	s_add_i32 m0, s27, 0x2000
	s_nop 0
	global_load_lds_dwordx4 v[224:225], off
	v_lshl_add_u64 v[224:225], v[228:229], 0, s[88:89]
	s_mov_b32 m0, s59
	s_nop 0
	global_load_lds_dwordx4 v[224:225], off
	v_lshl_add_u64 v[224:225], v[230:231], 0, s[88:89]
	s_mov_b32 m0, s60
	s_nop 0
	global_load_lds_dwordx4 v[224:225], off
	s_waitcnt vmcnt(8)
	s_waitcnt lgkmcnt(0)
	s_barrier
	v_mfma_f32_16x16x32_bf16 v[62:65], v[152:155], v[184:187], v[62:65]
	v_mfma_f32_16x16x32_bf16 v[58:61], v[160:163], v[184:187], v[58:61]
	v_mfma_f32_16x16x32_bf16 v[54:57], v[152:155], v[192:195], v[54:57]
	v_mfma_f32_16x16x32_bf16 v[50:53], v[160:163], v[192:195], v[50:53]
	v_mfma_f32_16x16x32_bf16 v[46:49], v[152:155], v[200:203], v[46:49]
	v_mfma_f32_16x16x32_bf16 v[42:45], v[160:163], v[200:203], v[42:45]
	v_mfma_f32_16x16x32_bf16 v[34:37], v[152:155], v[208:211], v[34:37]
	v_mfma_f32_16x16x32_bf16 v[26:29], v[160:163], v[208:211], v[26:29]
	v_mfma_f32_16x16x32_bf16 v[62:65], v[156:159], v[188:191], v[62:65]
	v_mfma_f32_16x16x32_bf16 v[58:61], v[164:167], v[188:191], v[58:61]
	v_mfma_f32_16x16x32_bf16 v[54:57], v[156:159], v[196:199], v[54:57]
	v_mfma_f32_16x16x32_bf16 v[50:53], v[164:167], v[196:199], v[50:53]
	v_mfma_f32_16x16x32_bf16 v[46:49], v[156:159], v[204:207], v[46:49]
	v_mfma_f32_16x16x32_bf16 v[42:45], v[164:167], v[204:207], v[42:45]
	v_mfma_f32_16x16x32_bf16 v[34:37], v[156:159], v[220:223], v[34:37]
	v_mfma_f32_16x16x32_bf16 v[26:29], v[164:167], v[220:223], v[26:29]
	v_mfma_f32_16x16x32_bf16 v[38:41], v[168:171], v[184:187], v[38:41]
	v_mfma_f32_16x16x32_bf16 v[30:33], v[176:179], v[184:187], v[30:33]
	v_mfma_f32_16x16x32_bf16 v[22:25], v[168:171], v[192:195], v[22:25]
	v_mfma_f32_16x16x32_bf16 v[18:21], v[176:179], v[192:195], v[18:21]
	v_mfma_f32_16x16x32_bf16 v[14:17], v[168:171], v[200:203], v[14:17]
	v_mfma_f32_16x16x32_bf16 v[10:13], v[176:179], v[200:203], v[10:13]
	v_mfma_f32_16x16x32_bf16 v[6:9], v[168:171], v[208:211], v[6:9]
	v_mfma_f32_16x16x32_bf16 v[2:5], v[176:179], v[208:211], v[2:5]
	v_mfma_f32_16x16x32_bf16 v[38:41], v[172:175], v[188:191], v[38:41]
	v_mfma_f32_16x16x32_bf16 v[30:33], v[180:183], v[188:191], v[30:33]
	v_mfma_f32_16x16x32_bf16 v[22:25], v[172:175], v[196:199], v[22:25]
	v_mfma_f32_16x16x32_bf16 v[18:21], v[180:183], v[196:199], v[18:21]
	v_mfma_f32_16x16x32_bf16 v[14:17], v[172:175], v[204:207], v[14:17]
	v_mfma_f32_16x16x32_bf16 v[10:13], v[180:183], v[204:207], v[10:13]
	v_mfma_f32_16x16x32_bf16 v[6:9], v[172:175], v[220:223], v[6:9]
	v_mfma_f32_16x16x32_bf16 v[2:5], v[180:183], v[220:223], v[2:5]
	s_barrier
	s_movk_i32 s2, 0x100
	s_mov_b64 s[38:39], 0
	s_and_b64 vcc, exec, s[40:41]
	s_cbranch_vccnz .LBB0_991
.LBB0_980:
	s_or_b64 s[40:41], s[36:37], s[38:39]
	s_or_b64 s[40:41], s[40:41], s[76:77]
	s_and_b64 vcc, exec, s[40:41]
	s_cbranch_vccnz .LBB0_979
	s_nop 0
	s_nop 0
	s_nop 0
	s_nop 0
	s_nop 0
	s_nop 0
	s_nop 0
	s_nop 0
	s_nop 0
	s_nop 0
	s_nop 0
	s_nop 0
	s_nop 0
	s_nop 0
	s_nop 0
	s_nop 0
	s_nop 0
	s_nop 0
	s_nop 0
	s_nop 0
	v_readlane_b32 s4, v253, 20
	v_readlane_b32 s5, v253, 21
	s_and_saveexec_b64 s[40:41], s[4:5]
	s_cbranch_execz .LBB0_978
	s_memrealtime s[42:43]
	s_branch .LBB0_985

; #define PG8_STAGE(bufoff, gbase, voff) do { _Pragma("unroll") for (int _i = 0; _i < 2; ++_i) \
;         __builtin_amdgcn_global_load_lds((const unsigned*)((const char*)(gbase) + (voff)[_i]), (PG8_LAS unsigned*)(lds + (bufoff) + ldsw + _i * 8192), 16, 0, 0); } while (0)
; #define PG8_LDA(dst, b, h) do { _Pragma("unroll") for (int m = 0; m < 4; ++m) _Pragma("unroll") for (int k = 0; k < 2; ++k) dst[m][k] = *(const PG8_LAS bf16x8*)(lds + PG8_SA(b, h) + aoff + m * 2048 + k * 1024); } while (0)
; #define PG8_LDB(dst, b, h) do { _Pragma("unroll") for (int n = 0; n < 2; ++n) _Pragma("unroll") for (int k = 0; k < 2; ++k) dst[n][k] = *(const PG8_LAS bf16x8*)(lds + PG8_SB(b, h) + boff + n * 2048 + k * 1024); } while (0)
; #define PG8_MMA(ai, bj, At, Bt) do { __builtin_amdgcn_s_setprio(1); _Pragma("unroll") for (int m = 0; m < 4; ++m) _Pragma("unroll") for (int n = 0; n < 2; ++n) _Pragma("unroll") for (int k = 0; k < 2; ++k) \
;         acc[ai][bj][m][n] = __builtin_amdgcn_mfma_f32_16x16x32_bf16(Bt[n][k], At[m][k], acc[ai][bj][m][n], 0, 0, 0); __builtin_amdgcn_s_setprio(0); } while (0)
; #define PG8_WAIT_V(n) asm volatile("s_waitcnt vmcnt(" #n ")" ::: "memory")
; #define PG8_BAR __builtin_amdgcn_s_barrier()
; template <class Epi, class Sched, bool ALIGN_EPI = false, bool SP2 = false>
; __device__ __forceinline__ void gemm_phase(PG8_LAS unsigned char* lds, const Gemm g, const Sched& S, const Epi& E) {
;     ...
;         for (int t = 0; t < nt; t += 2) {
;             const bool last = (t == nt - 2);
;             const char* a1 = cA + (size_t)(t + 1) * kstep;
;             const char* a2 = last ? nA : cA + (size_t)(t + 2) * kstep; const char* b2 = last ? nB : cB + (size_t)(t + 2) * kstep;
;             const char* a3 = a2 + kstep; const char* b3 = b2 + kstep;
;             if (last && has_next) S.a_ready(nxt);
;             if constexpr (SP2) {
;             PG8_LDB(B0, 0, 0); PG8_LDB(B1, 0, 1); PG8_SCHED; PG8_LDA(At, 0, 0); PG8_STAGE(PG8_SA(1, 1), a1 + hstep, voffA);
;             PG8_WAIT_V(8); PG8_WAIT_L(0); PG8_BAR; PG8_MMA(0, 0, At, B0); PG8_MMA(0, 1, At, B1); PG8_BAR; PG8_SCHED;
;             PG8_LDA(At, 0, 1); PG8_STAGE(PG8_SB(0, 0), b2, voffB); PG8_STAGE(PG8_SB(0, 1), b2 + hstep, voffB); PG8_STAGE(PG8_SA(0, 0), a2, voffA);
;             PG8_WAIT_V(8); PG8_WAIT_L(0); PG8_BAR; PG8_MMA(1, 0, At, B0); PG8_MMA(1, 1, At, B1); PG8_BAR; PG8_SCHED;
.LBB0_1205:
	s_lshl_b32 s52, s31, 7
	s_add_u32 s53, s42, s52
	s_addc_u32 s54, s43, 0
	s_add_u32 s55, s53, 0x100
	s_addc_u32 s56, s54, 0
	s_and_b64 s[50:51], s[48:49], exec
	s_cselect_b32 s51, s56, s1
	s_cselect_b32 s50, s55, s2
	s_add_u32 s52, s44, s52
	s_addc_u32 s55, s45, 0
	s_add_u32 s52, s52, 0x100
	s_addc_u32 s55, s55, 0
	s_and_b64 s[48:49], s[48:49], exec
	s_cselect_b32 s49, s55, s3
	s_cselect_b32 s48, s52, s29
	s_add_i32 s55, 0, 0x10000
	v_add_u32_e32 v138, s55, v140
	s_add_i32 s56, 0, 0x14000
	ds_read_b128 v[144:147], v138
	ds_read_b128 v[148:151], v138 offset:1024
	ds_read_b128 v[152:155], v138 offset:2048
	ds_read_b128 v[156:159], v138 offset:3072
	v_add_u32_e32 v138, s56, v140
	ds_read_b128 v[160:163], v138
	ds_read_b128 v[164:167], v138 offset:1024
	ds_read_b128 v[168:171], v138 offset:2048
	ds_read_b128 v[172:175], v138 offset:3072
	s_add_u32 s52, s53, 0x80080
	s_addc_u32 s53, s54, 0
	v_lshl_add_u64 v[138:139], s[52:53], 0, v[132:133]
	s_add_i32 m0, s41, 0xc000
	ds_read_b128 v[176:179], v142
	ds_read_b128 v[180:183], v142 offset:1024
	ds_read_b128 v[184:187], v142 offset:2048
	ds_read_b128 v[188:191], v142 offset:3072
	ds_read_b128 v[192:195], v142 offset:4096
	ds_read_b128 v[196:199], v142 offset:5120
	ds_read_b128 v[200:203], v142 offset:6144
	ds_read_b128 v[204:207], v142 offset:7168
	global_load_lds_dwordx4 v[138:139], off
	v_lshl_add_u64 v[138:139], s[52:53], 0, v[134:135]
	s_add_i32 m0, s41, 0xe000
	s_nop 0
	global_load_lds_dwordx4 v[138:139], off
	s_waitcnt vmcnt(8)
	s_waitcnt lgkmcnt(0)
	s_barrier
	v_mfma_f32_16x16x32_bf16 v[128:131], v[144:147], v[176:179], v[128:131]
	v_mfma_f32_16x16x32_bf16 v[124:127], v[152:155], v[176:179], v[124:127]
	v_mfma_f32_16x16x32_bf16 v[112:115], v[144:147], v[184:187], v[112:115]
	v_mfma_f32_16x16x32_bf16 v[108:111], v[152:155], v[184:187], v[108:111]
	v_mfma_f32_16x16x32_bf16 v[96:99], v[144:147], v[192:195], v[96:99]
	v_mfma_f32_16x16x32_bf16 v[92:95], v[152:155], v[192:195], v[92:95]
	v_mfma_f32_16x16x32_bf16 v[80:83], v[144:147], v[200:203], v[80:83]
	v_mfma_f32_16x16x32_bf16 v[76:79], v[152:155], v[200:203], v[76:79]
	v_mfma_f32_16x16x32_bf16 v[128:131], v[148:151], v[180:183], v[128:131]
	v_mfma_f32_16x16x32_bf16 v[124:127], v[156:159], v[180:183], v[124:127]
	v_mfma_f32_16x16x32_bf16 v[112:115], v[148:151], v[188:191], v[112:115]
	v_mfma_f32_16x16x32_bf16 v[108:111], v[156:159], v[188:191], v[108:111]
	v_mfma_f32_16x16x32_bf16 v[96:99], v[148:151], v[196:199], v[96:99]
	v_mfma_f32_16x16x32_bf16 v[92:95], v[156:159], v[196:199], v[92:95]
	v_mfma_f32_16x16x32_bf16 v[80:83], v[148:151], v[204:207], v[80:83]
	v_mfma_f32_16x16x32_bf16 v[76:79], v[156:159], v[204:207], v[76:79]
	v_mfma_f32_16x16x32_bf16 v[120:123], v[160:163], v[176:179], v[120:123]
	v_mfma_f32_16x16x32_bf16 v[116:119], v[168:171], v[176:179], v[116:119]
	v_mfma_f32_16x16x32_bf16 v[104:107], v[160:163], v[184:187], v[104:107]
	v_mfma_f32_16x16x32_bf16 v[100:103], v[168:171], v[184:187], v[100:103]
	v_mfma_f32_16x16x32_bf16 v[88:91], v[160:163], v[192:195], v[88:91]
	v_mfma_f32_16x16x32_bf16 v[84:87], v[168:171], v[192:195], v[84:87]
	v_mfma_f32_16x16x32_bf16 v[72:75], v[160:163], v[200:203], v[72:75]
	v_mfma_f32_16x16x32_bf16 v[68:71], v[168:171], v[200:203], v[68:71]
	v_mfma_f32_16x16x32_bf16 v[120:123], v[164:167], v[180:183], v[120:123]
	v_mfma_f32_16x16x32_bf16 v[116:119], v[172:175], v[180:183], v[116:119]
	v_mfma_f32_16x16x32_bf16 v[104:107], v[164:167], v[188:191], v[104:107]
	v_mfma_f32_16x16x32_bf16 v[100:103], v[172:175], v[188:191], v[100:103]
	v_mfma_f32_16x16x32_bf16 v[88:91], v[164:167], v[196:199], v[88:91]
	v_mfma_f32_16x16x32_bf16 v[84:87], v[172:175], v[196:199], v[84:87]
	v_mfma_f32_16x16x32_bf16 v[72:75], v[164:167], v[204:207], v[72:75]
	v_mfma_f32_16x16x32_bf16 v[68:71], v[172:175], v[204:207], v[68:71]
	s_barrier
	s_add_i32 s52, s55, s39
	v_lshl_add_u64 v[138:139], s[48:49], 0, v[66:67]
	s_mov_b32 m0, s52
	ds_read_b128 v[176:179], v142 offset:16384
	ds_read_b128 v[180:183], v142 offset:17408
	ds_read_b128 v[184:187], v142 offset:18432
	ds_read_b128 v[188:191], v142 offset:19456
	ds_read_b128 v[192:195], v142 offset:20480
	ds_read_b128 v[196:199], v142 offset:21504
	ds_read_b128 v[200:203], v142 offset:22528
	ds_read_b128 v[204:207], v142 offset:23552
	global_load_lds_dwordx4 v[138:139], off
	s_add_i32 m0, s52, 0x2000
	s_add_u32 s52, s48, 0x80000
	v_lshl_add_u64 v[208:209], s[48:49], 0, v[136:137]
	s_addc_u32 s53, s49, 0
	s_add_i32 s54, s56, s39
	global_load_lds_dwordx4 v[208:209], off
	v_lshl_add_u64 v[210:211], s[52:53], 0, v[66:67]
	s_mov_b32 m0, s54
	v_lshl_add_u64 v[220:221], s[50:51], 0, v[134:135]
	global_load_lds_dwordx4 v[210:211], off
	v_lshl_add_u64 v[210:211], s[52:53], 0, v[136:137]
	s_add_i32 m0, s54, 0x2000
	s_nop 0
	global_load_lds_dwordx4 v[210:211], off
	v_lshl_add_u64 v[210:211], s[50:51], 0, v[132:133]
	s_mov_b32 m0, s41
	s_nop 0
	global_load_lds_dwordx4 v[210:211], off
	s_mov_b32 m0, s68
	s_nop 0
	global_load_lds_dwordx4 v[220:221], off
	s_waitcnt vmcnt(8)
	s_waitcnt lgkmcnt(0)
	s_barrier
; #define PG8_STAGE(bufoff, gbase, voff) do { _Pragma("unroll") for (int _i = 0; _i < 2; ++_i) \
;         __builtin_amdgcn_global_load_lds((const unsigned*)((const char*)(gbase) + (voff)[_i]), (PG8_LAS unsigned*)(lds + (bufoff) + ldsw + _i * 8192), 16, 0, 0); } while (0)
; #define PG8_LDA(dst, b, h) do { _Pragma("unroll") for (int m = 0; m < 4; ++m) _Pragma("unroll") for (int k = 0; k < 2; ++k) dst[m][k] = *(const PG8_LAS bf16x8*)(lds + PG8_SA(b, h) + aoff + m * 2048 + k * 1024); } while (0)
; #define PG8_LDB(dst, b, h) do { _Pragma("unroll") for (int n = 0; n < 2; ++n) _Pragma("unroll") for (int k = 0; k < 2; ++k) dst[n][k] = *(const PG8_LAS bf16x8*)(lds + PG8_SB(b, h) + boff + n * 2048 + k * 1024); } while (0)
; #define PG8_MMA(ai, bj, At, Bt) do { __builtin_amdgcn_s_setprio(1); _Pragma("unroll") for (int m = 0; m < 4; ++m) _Pragma("unroll") for (int n = 0; n < 2; ++n) _Pragma("unroll") for (int k = 0; k < 2; ++k) \
;         acc[ai][bj][m][n] = __builtin_amdgcn_mfma_f32_16x16x32_bf16(Bt[n][k], At[m][k], acc[ai][bj][m][n], 0, 0, 0); __builtin_amdgcn_s_setprio(0); } while (0)
; #define PG8_WAIT_V(n) asm volatile("s_waitcnt vmcnt(" #n ")" ::: "memory")
; #define PG8_WAIT_L(n) asm volatile("s_waitcnt lgkmcnt(" #n ")" ::: "memory")
; #define PG8_BAR __builtin_amdgcn_s_barrier()
; #define PG8_SCHED __builtin_amdgcn_sched_barrier(0)
; template <class Epi, class Sched, bool ALIGN_EPI = false, bool SP2 = false>
; __device__ __forceinline__ void gemm_phase(PG8_LAS unsigned char* lds, const Gemm g, const Sched& S, const Epi& E) {
;     ...
;             PG8_WAIT_V(8); PG8_WAIT_L(0); PG8_BAR; PG8_MMA(1, 0, At, B0); PG8_MMA(1, 1, At, B1); PG8_BAR; PG8_SCHED;
;             PG8_LDB(B0, 1, 0); PG8_LDB(B1, 1, 1); PG8_SCHED; PG8_LDA(At, 1, 0); PG8_STAGE(PG8_SA(0, 1), a2 + hstep, voffA);
;             PG8_WAIT_V(8); PG8_WAIT_L(0); PG8_BAR; PG8_MMA(0, 0, At, B0); PG8_MMA(0, 1, At, B1); PG8_BAR; PG8_SCHED;
;             PG8_LDA(At, 1, 1); PG8_STAGE(PG8_SB(1, 0), b3, voffB); PG8_STAGE(PG8_SB(1, 1), b3 + hstep, voffB); PG8_STAGE(PG8_SA(1, 0), a3, voffA);
	v_mfma_f32_16x16x32_bf16 v[62:65], v[144:147], v[176:179], v[62:65]
	v_mfma_f32_16x16x32_bf16 v[58:61], v[152:155], v[176:179], v[58:61]
	v_mfma_f32_16x16x32_bf16 v[46:49], v[144:147], v[184:187], v[46:49]
	v_mfma_f32_16x16x32_bf16 v[42:45], v[152:155], v[184:187], v[42:45]
	v_mfma_f32_16x16x32_bf16 v[30:33], v[144:147], v[192:195], v[30:33]
	v_mfma_f32_16x16x32_bf16 v[26:29], v[152:155], v[192:195], v[26:29]
	v_mfma_f32_16x16x32_bf16 v[14:17], v[144:147], v[200:203], v[14:17]
	v_mfma_f32_16x16x32_bf16 v[10:13], v[152:155], v[200:203], v[10:13]
	v_mfma_f32_16x16x32_bf16 v[62:65], v[148:151], v[180:183], v[62:65]
	v_mfma_f32_16x16x32_bf16 v[58:61], v[156:159], v[180:183], v[58:61]
	v_mfma_f32_16x16x32_bf16 v[46:49], v[148:151], v[188:191], v[46:49]
	v_mfma_f32_16x16x32_bf16 v[42:45], v[156:159], v[188:191], v[42:45]
	v_mfma_f32_16x16x32_bf16 v[30:33], v[148:151], v[196:199], v[30:33]
	v_mfma_f32_16x16x32_bf16 v[26:29], v[156:159], v[196:199], v[26:29]
	v_mfma_f32_16x16x32_bf16 v[14:17], v[148:151], v[204:207], v[14:17]
	v_mfma_f32_16x16x32_bf16 v[10:13], v[156:159], v[204:207], v[10:13]
	v_mfma_f32_16x16x32_bf16 v[54:57], v[160:163], v[176:179], v[54:57]
	v_mfma_f32_16x16x32_bf16 v[50:53], v[168:171], v[176:179], v[50:53]
	v_mfma_f32_16x16x32_bf16 v[38:41], v[160:163], v[184:187], v[38:41]
	v_mfma_f32_16x16x32_bf16 v[34:37], v[168:171], v[184:187], v[34:37]
	v_mfma_f32_16x16x32_bf16 v[22:25], v[160:163], v[192:195], v[22:25]
	v_mfma_f32_16x16x32_bf16 v[18:21], v[168:171], v[192:195], v[18:21]
	v_mfma_f32_16x16x32_bf16 v[6:9], v[160:163], v[200:203], v[6:9]
	v_mfma_f32_16x16x32_bf16 v[2:5], v[168:171], v[200:203], v[2:5]
	v_mfma_f32_16x16x32_bf16 v[54:57], v[164:167], v[180:183], v[54:57]
	v_mfma_f32_16x16x32_bf16 v[50:53], v[172:175], v[180:183], v[50:53]
	v_mfma_f32_16x16x32_bf16 v[38:41], v[164:167], v[188:191], v[38:41]
	v_mfma_f32_16x16x32_bf16 v[34:37], v[172:175], v[188:191], v[34:37]
	v_mfma_f32_16x16x32_bf16 v[22:25], v[164:167], v[196:199], v[22:25]
	v_mfma_f32_16x16x32_bf16 v[18:21], v[172:175], v[196:199], v[18:21]
	v_mfma_f32_16x16x32_bf16 v[6:9], v[164:167], v[204:207], v[6:9]
	v_mfma_f32_16x16x32_bf16 v[2:5], v[172:175], v[204:207], v[2:5]
	s_barrier
	s_add_i32 s52, 0, 0x18000
	v_add_u32_e32 v143, s52, v140
	s_add_i32 s53, 0, 0x1c000
	ds_read_b128 v[144:147], v143
	ds_read_b128 v[148:151], v143 offset:1024
	ds_read_b128 v[152:155], v143 offset:2048
	ds_read_b128 v[156:159], v143 offset:3072
	v_add_u32_e32 v143, s53, v140
	ds_read_b128 v[160:163], v143
	ds_read_b128 v[164:167], v143 offset:1024
	ds_read_b128 v[168:171], v143 offset:2048
	ds_read_b128 v[172:175], v143 offset:3072
	s_add_u32 s50, s50, 0x80000
	s_addc_u32 s51, s51, 0
	s_mov_b32 m0, s69
	v_lshl_add_u64 v[222:223], s[50:51], 0, v[132:133]
	ds_read_b128 v[176:179], v142 offset:32768
	ds_read_b128 v[180:183], v142 offset:33792
	ds_read_b128 v[184:187], v142 offset:34816
	ds_read_b128 v[188:191], v142 offset:35840
	ds_read_b128 v[192:195], v142 offset:36864
	ds_read_b128 v[196:199], v142 offset:37888
	ds_read_b128 v[200:203], v142 offset:38912
	ds_read_b128 v[204:207], v142 offset:39936
	global_load_lds_dwordx4 v[222:223], off
	v_lshl_add_u64 v[222:223], s[50:51], 0, v[134:135]
	s_mov_b32 m0, s70
	s_nop 0
	global_load_lds_dwordx4 v[222:223], off
	s_waitcnt vmcnt(8)
	s_waitcnt lgkmcnt(0)
	s_barrier
	v_mfma_f32_16x16x32_bf16 v[128:131], v[144:147], v[176:179], v[128:131]
	v_mfma_f32_16x16x32_bf16 v[124:127], v[152:155], v[176:179], v[124:127]
	v_mfma_f32_16x16x32_bf16 v[112:115], v[144:147], v[184:187], v[112:115]
	v_mfma_f32_16x16x32_bf16 v[108:111], v[152:155], v[184:187], v[108:111]
	v_mfma_f32_16x16x32_bf16 v[96:99], v[144:147], v[192:195], v[96:99]
	v_mfma_f32_16x16x32_bf16 v[92:95], v[152:155], v[192:195], v[92:95]
	v_mfma_f32_16x16x32_bf16 v[80:83], v[144:147], v[200:203], v[80:83]
	v_mfma_f32_16x16x32_bf16 v[76:79], v[152:155], v[200:203], v[76:79]
	v_mfma_f32_16x16x32_bf16 v[128:131], v[148:151], v[180:183], v[128:131]
	v_mfma_f32_16x16x32_bf16 v[124:127], v[156:159], v[180:183], v[124:127]
	v_mfma_f32_16x16x32_bf16 v[112:115], v[148:151], v[188:191], v[112:115]
	v_mfma_f32_16x16x32_bf16 v[108:111], v[156:159], v[188:191], v[108:111]
	v_mfma_f32_16x16x32_bf16 v[96:99], v[148:151], v[196:199], v[96:99]
	v_mfma_f32_16x16x32_bf16 v[92:95], v[156:159], v[196:199], v[92:95]
	v_mfma_f32_16x16x32_bf16 v[80:83], v[148:151], v[204:207], v[80:83]
	v_mfma_f32_16x16x32_bf16 v[76:79], v[156:159], v[204:207], v[76:79]
	v_mfma_f32_16x16x32_bf16 v[120:123], v[160:163], v[176:179], v[120:123]
	v_mfma_f32_16x16x32_bf16 v[116:119], v[168:171], v[176:179], v[116:119]
	v_mfma_f32_16x16x32_bf16 v[104:107], v[160:163], v[184:187], v[104:107]
	v_mfma_f32_16x16x32_bf16 v[100:103], v[168:171], v[184:187], v[100:103]
	v_mfma_f32_16x16x32_bf16 v[88:91], v[160:163], v[192:195], v[88:91]
	v_mfma_f32_16x16x32_bf16 v[84:87], v[168:171], v[192:195], v[84:87]
	v_mfma_f32_16x16x32_bf16 v[72:75], v[160:163], v[200:203], v[72:75]
	v_mfma_f32_16x16x32_bf16 v[68:71], v[168:171], v[200:203], v[68:71]
	v_mfma_f32_16x16x32_bf16 v[120:123], v[164:167], v[180:183], v[120:123]
	v_mfma_f32_16x16x32_bf16 v[116:119], v[172:175], v[180:183], v[116:119]
	v_mfma_f32_16x16x32_bf16 v[104:107], v[164:167], v[188:191], v[104:107]
	v_mfma_f32_16x16x32_bf16 v[100:103], v[172:175], v[188:191], v[100:103]
	v_mfma_f32_16x16x32_bf16 v[88:91], v[164:167], v[196:199], v[88:91]
	v_mfma_f32_16x16x32_bf16 v[84:87], v[172:175], v[196:199], v[84:87]
	v_mfma_f32_16x16x32_bf16 v[72:75], v[164:167], v[204:207], v[72:75]
	v_mfma_f32_16x16x32_bf16 v[68:71], v[172:175], v[204:207], v[68:71]
	s_barrier
; #define PG8_STAGE(bufoff, gbase, voff) do { _Pragma("unroll") for (int _i = 0; _i < 2; ++_i) \
;         __builtin_amdgcn_global_load_lds((const unsigned*)((const char*)(gbase) + (voff)[_i]), (PG8_LAS unsigned*)(lds + (bufoff) + ldsw + _i * 8192), 16, 0, 0); } while (0)
; #define PG8_LDA(dst, b, h) do { _Pragma("unroll") for (int m = 0; m < 4; ++m) _Pragma("unroll") for (int k = 0; k < 2; ++k) dst[m][k] = *(const PG8_LAS bf16x8*)(lds + PG8_SA(b, h) + aoff + m * 2048 + k * 1024); } while (0)
; #define PG8_MMA(ai, bj, At, Bt) do { __builtin_amdgcn_s_setprio(1); _Pragma("unroll") for (int m = 0; m < 4; ++m) _Pragma("unroll") for (int n = 0; n < 2; ++n) _Pragma("unroll") for (int k = 0; k < 2; ++k) \
;         acc[ai][bj][m][n] = __builtin_amdgcn_mfma_f32_16x16x32_bf16(Bt[n][k], At[m][k], acc[ai][bj][m][n], 0, 0, 0); __builtin_amdgcn_s_setprio(0); } while (0)
; #define PG8_WAIT_V(n) asm volatile("s_waitcnt vmcnt(" #n ")" ::: "memory")
; #define PG8_WAIT_L(n) asm volatile("s_waitcnt lgkmcnt(" #n ")" ::: "memory")
; #define PG8_BAR __builtin_amdgcn_s_barrier()
; #define PG8_SCHED __builtin_amdgcn_sched_barrier(0)
;     __device__ __forceinline__ void a_ready(const Unit& u) const {
;         if (u.pm != 32 || need == 0u) return;
;         if (threadIdx.x < 64) {
;             const unsigned long long t0 = __builtin_amdgcn_s_memrealtime();
;             while ((unsigned)__builtin_amdgcn_readfirstlane(__hip_atomic_load(ready, __ATOMIC_RELAXED, __HIP_MEMORY_SCOPE_AGENT)) < need) {
;                 if (__builtin_amdgcn_s_memrealtime() - t0 > 2000000ull) { if (threadIdx.x == 0) __hip_atomic_store(tmo, 1u, __ATOMIC_RELAXED, __HIP_MEMORY_SCOPE_AGENT); break; }
;                 __builtin_amdgcn_s_sleep(2); }
; template <class Epi, class Sched, bool ALIGN_EPI = false, bool SP2 = false>
; __device__ __forceinline__ void gemm_phase(PG8_LAS unsigned char* lds, const Gemm g, const Sched& S, const Epi& E) {
;     ...
;             PG8_LDA(At, 1, 1); PG8_STAGE(PG8_SB(1, 0), b3, voffB); PG8_STAGE(PG8_SB(1, 1), b3 + hstep, voffB); PG8_STAGE(PG8_SA(1, 0), a3, voffA);
;             PG8_WAIT_V(8); PG8_WAIT_L(0); PG8_BAR; PG8_MMA(1, 0, At, B0); PG8_MMA(1, 1, At, B1); PG8_BAR; PG8_SCHED;
	s_add_i32 s50, s52, s39
	v_lshl_add_u64 v[138:139], v[138:139], 0, s[88:89]
	s_mov_b32 m0, s50
	ds_read_b128 v[176:179], v142 offset:49152
	ds_read_b128 v[180:183], v142 offset:50176
	ds_read_b128 v[184:187], v142 offset:51200
	ds_read_b128 v[188:191], v142 offset:52224
	ds_read_b128 v[192:195], v142 offset:53248
	ds_read_b128 v[196:199], v142 offset:54272
	ds_read_b128 v[200:203], v142 offset:55296
	ds_read_b128 v[204:207], v142 offset:56320
	global_load_lds_dwordx4 v[138:139], off
	s_add_i32 m0, s50, 0x2000
	s_add_u32 s48, s48, 0x80080
	v_lshl_add_u64 v[138:139], v[208:209], 0, s[88:89]
	s_addc_u32 s49, s49, 0
	s_add_i32 s50, s53, s39
	global_load_lds_dwordx4 v[138:139], off
	v_lshl_add_u64 v[138:139], s[48:49], 0, v[66:67]
	s_mov_b32 m0, s50
	s_nop 0
	global_load_lds_dwordx4 v[138:139], off
	v_lshl_add_u64 v[138:139], s[48:49], 0, v[136:137]
	s_add_i32 m0, s50, 0x2000
	s_nop 0
	global_load_lds_dwordx4 v[138:139], off
	v_lshl_add_u64 v[138:139], v[210:211], 0, s[88:89]
	s_mov_b32 m0, s71
	s_nop 0
	global_load_lds_dwordx4 v[138:139], off
	v_lshl_add_u64 v[138:139], v[220:221], 0, s[88:89]
	s_mov_b32 m0, s72
	s_nop 0
	global_load_lds_dwordx4 v[138:139], off
	s_waitcnt vmcnt(8)
	s_waitcnt lgkmcnt(0)
	s_barrier
	v_mfma_f32_16x16x32_bf16 v[62:65], v[144:147], v[176:179], v[62:65]
	v_mfma_f32_16x16x32_bf16 v[58:61], v[152:155], v[176:179], v[58:61]
	v_mfma_f32_16x16x32_bf16 v[46:49], v[144:147], v[184:187], v[46:49]
	v_mfma_f32_16x16x32_bf16 v[42:45], v[152:155], v[184:187], v[42:45]
	v_mfma_f32_16x16x32_bf16 v[30:33], v[144:147], v[192:195], v[30:33]
	v_mfma_f32_16x16x32_bf16 v[26:29], v[152:155], v[192:195], v[26:29]
	v_mfma_f32_16x16x32_bf16 v[14:17], v[144:147], v[200:203], v[14:17]
	v_mfma_f32_16x16x32_bf16 v[10:13], v[152:155], v[200:203], v[10:13]
	v_mfma_f32_16x16x32_bf16 v[62:65], v[148:151], v[180:183], v[62:65]
	v_mfma_f32_16x16x32_bf16 v[58:61], v[156:159], v[180:183], v[58:61]
	v_mfma_f32_16x16x32_bf16 v[46:49], v[148:151], v[188:191], v[46:49]
	v_mfma_f32_16x16x32_bf16 v[42:45], v[156:159], v[188:191], v[42:45]
	v_mfma_f32_16x16x32_bf16 v[30:33], v[148:151], v[196:199], v[30:33]
	v_mfma_f32_16x16x32_bf16 v[26:29], v[156:159], v[196:199], v[26:29]
	v_mfma_f32_16x16x32_bf16 v[14:17], v[148:151], v[204:207], v[14:17]
	v_mfma_f32_16x16x32_bf16 v[10:13], v[156:159], v[204:207], v[10:13]
	v_mfma_f32_16x16x32_bf16 v[54:57], v[160:163], v[176:179], v[54:57]
	v_mfma_f32_16x16x32_bf16 v[50:53], v[168:171], v[176:179], v[50:53]
	v_mfma_f32_16x16x32_bf16 v[38:41], v[160:163], v[184:187], v[38:41]
	v_mfma_f32_16x16x32_bf16 v[34:37], v[168:171], v[184:187], v[34:37]
	v_mfma_f32_16x16x32_bf16 v[22:25], v[160:163], v[192:195], v[22:25]
	v_mfma_f32_16x16x32_bf16 v[18:21], v[168:171], v[192:195], v[18:21]
	v_mfma_f32_16x16x32_bf16 v[6:9], v[160:163], v[200:203], v[6:9]
	v_mfma_f32_16x16x32_bf16 v[2:5], v[168:171], v[200:203], v[2:5]
	v_mfma_f32_16x16x32_bf16 v[54:57], v[164:167], v[180:183], v[54:57]
	v_mfma_f32_16x16x32_bf16 v[50:53], v[172:175], v[180:183], v[50:53]
	v_mfma_f32_16x16x32_bf16 v[38:41], v[164:167], v[188:191], v[38:41]
	v_mfma_f32_16x16x32_bf16 v[34:37], v[172:175], v[188:191], v[34:37]
	v_mfma_f32_16x16x32_bf16 v[22:25], v[164:167], v[196:199], v[22:25]
	v_mfma_f32_16x16x32_bf16 v[18:21], v[172:175], v[196:199], v[18:21]
	v_mfma_f32_16x16x32_bf16 v[6:9], v[164:167], v[204:207], v[6:9]
	v_mfma_f32_16x16x32_bf16 v[2:5], v[172:175], v[204:207], v[2:5]
	s_barrier
	s_add_i32 s48, s31, 2
	s_cmp_gt_u32 s31, 29
	s_mov_b32 s31, s48
	s_cbranch_scc1 .LBB0_1217
.LBB0_1206:
	s_cmp_lg_u32 s31, 30
	s_cselect_b64 s[48:49], -1, 0
	s_or_b64 s[50:51], s[12:13], s[48:49]
	s_or_b64 s[50:51], s[50:51], s[46:47]
	s_or_b64 s[50:51], s[50:51], s[20:21]
	s_and_b64 vcc, exec, s[50:51]
	s_cbranch_vccnz .LBB0_1205
	s_nop 0
	s_nop 0
	s_nop 0
	s_nop 0
	s_nop 0
	s_nop 0
	s_nop 0
	s_nop 0
	s_nop 0
	s_nop 0
	s_nop 0
	s_nop 0
	s_nop 0
	s_nop 0
	s_nop 0
	s_nop 0
	s_nop 0
	s_nop 0
	s_nop 0
	s_nop 0
	v_readlane_b32 s4, v253, 20
	v_readlane_b32 s5, v253, 21
	s_and_saveexec_b64 s[50:51], s[4:5]
	s_cbranch_execz .LBB0_1204
	s_memrealtime s[52:53]
	s_branch .LBB0_1211

; #define PG8_STAGE(bufoff, gbase, voff) do { _Pragma("unroll") for (int _i = 0; _i < 2; ++_i) \
;         __builtin_amdgcn_global_load_lds((const unsigned*)((const char*)(gbase) + (voff)[_i]), (PG8_LAS unsigned*)(lds + (bufoff) + ldsw + _i * 8192), 16, 0, 0); } while (0)
; #define PG8_LDA(dst, b, h) do { _Pragma("unroll") for (int m = 0; m < 4; ++m) _Pragma("unroll") for (int k = 0; k < 2; ++k) dst[m][k] = *(const PG8_LAS bf16x8*)(lds + PG8_SA(b, h) + aoff + m * 2048 + k * 1024); } while (0)
; #define PG8_LDB(dst, b, h) do { _Pragma("unroll") for (int n = 0; n < 2; ++n) _Pragma("unroll") for (int k = 0; k < 2; ++k) dst[n][k] = *(const PG8_LAS bf16x8*)(lds + PG8_SB(b, h) + boff + n * 2048 + k * 1024); } while (0)
; #define PG8_MMA(ai, bj, At, Bt) do { __builtin_amdgcn_s_setprio(1); _Pragma("unroll") for (int m = 0; m < 4; ++m) _Pragma("unroll") for (int n = 0; n < 2; ++n) _Pragma("unroll") for (int k = 0; k < 2; ++k) \
;         acc[ai][bj][m][n] = __builtin_amdgcn_mfma_f32_16x16x32_bf16(Bt[n][k], At[m][k], acc[ai][bj][m][n], 0, 0, 0); __builtin_amdgcn_s_setprio(0); } while (0)
; #define PG8_WAIT_V(n) asm volatile("s_waitcnt vmcnt(" #n ")" ::: "memory")
; #define PG8_BAR __builtin_amdgcn_s_barrier()
; template <class Epi, class Sched, bool ALIGN_EPI = false, bool SP2 = false>
; __device__ __forceinline__ void gemm_phase(PG8_LAS unsigned char* lds, const Gemm g, const Sched& S, const Epi& E) {
;     ...
;         for (int t = 0; t < nt; t += 2) {
;             const bool last = (t == nt - 2);
;             const char* a1 = cA + (size_t)(t + 1) * kstep;
;             const char* a2 = last ? nA : cA + (size_t)(t + 2) * kstep; const char* b2 = last ? nB : cB + (size_t)(t + 2) * kstep;
;             const char* a3 = a2 + kstep; const char* b3 = b2 + kstep;
;             if (last && has_next) S.a_ready(nxt);
;             if constexpr (SP2) {
;             PG8_LDB(B0, 0, 0); PG8_LDB(B1, 0, 1); PG8_SCHED; PG8_LDA(At, 0, 0); PG8_STAGE(PG8_SA(1, 1), a1 + hstep, voffA);
;             PG8_WAIT_V(8); PG8_WAIT_L(0); PG8_BAR; PG8_MMA(0, 0, At, B0); PG8_MMA(0, 1, At, B1); PG8_BAR; PG8_SCHED;
;             PG8_LDA(At, 0, 1); PG8_STAGE(PG8_SB(0, 0), b2, voffB); PG8_STAGE(PG8_SB(0, 1), b2 + hstep, voffB); PG8_STAGE(PG8_SA(0, 0), a2, voffA);
;             PG8_WAIT_V(8); PG8_WAIT_L(0); PG8_BAR; PG8_MMA(1, 0, At, B0); PG8_MMA(1, 1, At, B1); PG8_BAR; PG8_SCHED;
.LBB0_1294:
	s_add_u32 s26, s24, 0x100
	s_addc_u32 s27, s25, 0
	s_add_i32 s54, 0, 0x10000
	s_cmpk_eq_i32 s53, 0x54
	s_cselect_b32 s31, s13, s27
	s_cselect_b32 s30, s12, s26
	s_cselect_b32 s29, s23, s3
	s_cselect_b32 s28, s22, s2
	s_add_i32 s55, 0, 0x14000
	v_add_u32_e32 v144, s54, v156
	v_add_u32_e32 v154, s55, v156
	ds_read_b128 v[132:135], v144
	ds_read_b128 v[136:139], v144 offset:1024
	ds_read_b128 v[140:143], v144 offset:2048
	ds_read_b128 v[144:147], v144 offset:3072
	ds_read_b128 v[160:163], v154
	ds_read_b128 v[164:167], v154 offset:1024
	ds_read_b128 v[168:171], v154 offset:2048
	ds_read_b128 v[172:175], v154 offset:3072
	v_lshl_add_u64 v[154:155], s[24:25], 0, v[150:151]
	s_add_i32 m0, s39, 0xc000
	ds_read_b128 v[176:179], v158
	ds_read_b128 v[180:183], v158 offset:1024
	ds_read_b128 v[184:187], v158 offset:2048
	ds_read_b128 v[188:191], v158 offset:3072
	ds_read_b128 v[192:195], v158 offset:4096
	ds_read_b128 v[196:199], v158 offset:5120
	ds_read_b128 v[200:203], v158 offset:6144
	ds_read_b128 v[204:207], v158 offset:7168
	global_load_lds_dwordx4 v[154:155], off
	v_lshl_add_u64 v[154:155], s[24:25], 0, v[152:153]
	s_add_i32 m0, s39, 0xe000
	s_nop 0
	global_load_lds_dwordx4 v[154:155], off
	s_waitcnt vmcnt(8)
	s_waitcnt lgkmcnt(0)
	s_barrier
	v_mfma_f32_16x16x32_bf16 v[128:131], v[132:135], v[176:179], v[128:131]
	v_mfma_f32_16x16x32_bf16 v[124:127], v[140:143], v[176:179], v[124:127]
	v_mfma_f32_16x16x32_bf16 v[120:123], v[132:135], v[184:187], v[120:123]
	v_mfma_f32_16x16x32_bf16 v[112:115], v[140:143], v[184:187], v[112:115]
	v_mfma_f32_16x16x32_bf16 v[104:107], v[132:135], v[192:195], v[104:107]
	v_mfma_f32_16x16x32_bf16 v[96:99], v[140:143], v[192:195], v[96:99]
	v_mfma_f32_16x16x32_bf16 v[88:91], v[132:135], v[200:203], v[88:91]
	v_mfma_f32_16x16x32_bf16 v[76:79], v[140:143], v[200:203], v[76:79]
	v_mfma_f32_16x16x32_bf16 v[128:131], v[136:139], v[180:183], v[128:131]
	v_mfma_f32_16x16x32_bf16 v[124:127], v[144:147], v[180:183], v[124:127]
	v_mfma_f32_16x16x32_bf16 v[120:123], v[136:139], v[188:191], v[120:123]
	v_mfma_f32_16x16x32_bf16 v[112:115], v[144:147], v[188:191], v[112:115]
	v_mfma_f32_16x16x32_bf16 v[104:107], v[136:139], v[196:199], v[104:107]
	v_mfma_f32_16x16x32_bf16 v[96:99], v[144:147], v[196:199], v[96:99]
	v_mfma_f32_16x16x32_bf16 v[88:91], v[136:139], v[204:207], v[88:91]
	v_mfma_f32_16x16x32_bf16 v[76:79], v[144:147], v[204:207], v[76:79]
	v_mfma_f32_16x16x32_bf16 v[116:119], v[160:163], v[176:179], v[116:119]
	v_mfma_f32_16x16x32_bf16 v[108:111], v[168:171], v[176:179], v[108:111]
	v_mfma_f32_16x16x32_bf16 v[100:103], v[160:163], v[184:187], v[100:103]
	v_mfma_f32_16x16x32_bf16 v[92:95], v[168:171], v[184:187], v[92:95]
	v_mfma_f32_16x16x32_bf16 v[84:87], v[160:163], v[192:195], v[84:87]
	v_mfma_f32_16x16x32_bf16 v[80:83], v[168:171], v[192:195], v[80:83]
	v_mfma_f32_16x16x32_bf16 v[72:75], v[160:163], v[200:203], v[72:75]
	v_mfma_f32_16x16x32_bf16 v[68:71], v[168:171], v[200:203], v[68:71]
	v_mfma_f32_16x16x32_bf16 v[116:119], v[164:167], v[180:183], v[116:119]
	v_mfma_f32_16x16x32_bf16 v[108:111], v[172:175], v[180:183], v[108:111]
	v_mfma_f32_16x16x32_bf16 v[100:103], v[164:167], v[188:191], v[100:103]
	v_mfma_f32_16x16x32_bf16 v[92:95], v[172:175], v[188:191], v[92:95]
	v_mfma_f32_16x16x32_bf16 v[84:87], v[164:167], v[196:199], v[84:87]
	v_mfma_f32_16x16x32_bf16 v[80:83], v[172:175], v[196:199], v[80:83]
	v_mfma_f32_16x16x32_bf16 v[72:75], v[164:167], v[204:207], v[72:75]
	v_mfma_f32_16x16x32_bf16 v[68:71], v[172:175], v[204:207], v[68:71]
	s_barrier
	s_add_i32 s24, s54, s38
	v_lshl_add_u64 v[154:155], s[28:29], 0, v[66:67]
	s_mov_b32 m0, s24
	ds_read_b128 v[176:179], v158 offset:16384
	ds_read_b128 v[180:183], v158 offset:17408
	ds_read_b128 v[184:187], v158 offset:18432
	ds_read_b128 v[188:191], v158 offset:19456
	ds_read_b128 v[192:195], v158 offset:20480
	ds_read_b128 v[196:199], v158 offset:21504
	ds_read_b128 v[200:203], v158 offset:22528
	ds_read_b128 v[204:207], v158 offset:23552
	global_load_lds_dwordx4 v[154:155], off
	s_add_i32 m0, s24, 0x2000
	s_add_u32 s24, s28, 0x160000
	v_lshl_add_u64 v[208:209], s[28:29], 0, v[148:149]
	s_addc_u32 s25, s29, 0
	s_add_i32 s54, s55, s38
	global_load_lds_dwordx4 v[208:209], off
	v_lshl_add_u64 v[210:211], s[24:25], 0, v[66:67]
	s_mov_b32 m0, s54
	v_lshl_add_u64 v[220:221], s[30:31], 0, v[148:149]
	global_load_lds_dwordx4 v[210:211], off
	v_lshl_add_u64 v[210:211], s[24:25], 0, v[148:149]
	s_add_i32 m0, s54, 0x2000
	s_nop 0
	global_load_lds_dwordx4 v[210:211], off
	v_lshl_add_u64 v[210:211], s[30:31], 0, v[66:67]
	s_mov_b32 m0, s39
	s_nop 0
	global_load_lds_dwordx4 v[210:211], off
	s_mov_b32 m0, s40
	s_nop 0
	global_load_lds_dwordx4 v[220:221], off
	s_waitcnt vmcnt(8)
	s_waitcnt lgkmcnt(0)
	s_barrier
; #define PG8_STAGE(bufoff, gbase, voff) do { _Pragma("unroll") for (int _i = 0; _i < 2; ++_i) \
;         __builtin_amdgcn_global_load_lds((const unsigned*)((const char*)(gbase) + (voff)[_i]), (PG8_LAS unsigned*)(lds + (bufoff) + ldsw + _i * 8192), 16, 0, 0); } while (0)
; #define PG8_LDA(dst, b, h) do { _Pragma("unroll") for (int m = 0; m < 4; ++m) _Pragma("unroll") for (int k = 0; k < 2; ++k) dst[m][k] = *(const PG8_LAS bf16x8*)(lds + PG8_SA(b, h) + aoff + m * 2048 + k * 1024); } while (0)
; #define PG8_LDB(dst, b, h) do { _Pragma("unroll") for (int n = 0; n < 2; ++n) _Pragma("unroll") for (int k = 0; k < 2; ++k) dst[n][k] = *(const PG8_LAS bf16x8*)(lds + PG8_SB(b, h) + boff + n * 2048 + k * 1024); } while (0)
; #define PG8_MMA(ai, bj, At, Bt) do { __builtin_amdgcn_s_setprio(1); _Pragma("unroll") for (int m = 0; m < 4; ++m) _Pragma("unroll") for (int n = 0; n < 2; ++n) _Pragma("unroll") for (int k = 0; k < 2; ++k) \
;         acc[ai][bj][m][n] = __builtin_amdgcn_mfma_f32_16x16x32_bf16(Bt[n][k], At[m][k], acc[ai][bj][m][n], 0, 0, 0); __builtin_amdgcn_s_setprio(0); } while (0)
; #define PG8_WAIT_V(n) asm volatile("s_waitcnt vmcnt(" #n ")" ::: "memory")
; #define PG8_WAIT_L(n) asm volatile("s_waitcnt lgkmcnt(" #n ")" ::: "memory")
; #define PG8_BAR __builtin_amdgcn_s_barrier()
; #define PG8_SCHED __builtin_amdgcn_sched_barrier(0)
; template <class Epi, class Sched, bool ALIGN_EPI = false, bool SP2 = false>
; __device__ __forceinline__ void gemm_phase(PG8_LAS unsigned char* lds, const Gemm g, const Sched& S, const Epi& E) {
;     ...
;             PG8_WAIT_V(8); PG8_WAIT_L(0); PG8_BAR; PG8_MMA(1, 0, At, B0); PG8_MMA(1, 1, At, B1); PG8_BAR; PG8_SCHED;
;             PG8_LDB(B0, 1, 0); PG8_LDB(B1, 1, 1); PG8_SCHED; PG8_LDA(At, 1, 0); PG8_STAGE(PG8_SA(0, 1), a2 + hstep, voffA);
;             PG8_WAIT_V(8); PG8_WAIT_L(0); PG8_BAR; PG8_MMA(0, 0, At, B0); PG8_MMA(0, 1, At, B1); PG8_BAR; PG8_SCHED;
;             PG8_LDA(At, 1, 1); PG8_STAGE(PG8_SB(1, 0), b3, voffB); PG8_STAGE(PG8_SB(1, 1), b3 + hstep, voffB); PG8_STAGE(PG8_SA(1, 0), a3, voffA);
	v_mfma_f32_16x16x32_bf16 v[62:65], v[132:135], v[176:179], v[62:65]
	v_mfma_f32_16x16x32_bf16 v[58:61], v[140:143], v[176:179], v[58:61]
	v_mfma_f32_16x16x32_bf16 v[54:57], v[132:135], v[184:187], v[54:57]
	v_mfma_f32_16x16x32_bf16 v[46:49], v[140:143], v[184:187], v[46:49]
	v_mfma_f32_16x16x32_bf16 v[38:41], v[132:135], v[192:195], v[38:41]
	v_mfma_f32_16x16x32_bf16 v[30:33], v[140:143], v[192:195], v[30:33]
	v_mfma_f32_16x16x32_bf16 v[22:25], v[132:135], v[200:203], v[22:25]
	v_mfma_f32_16x16x32_bf16 v[10:13], v[140:143], v[200:203], v[10:13]
	v_mfma_f32_16x16x32_bf16 v[62:65], v[136:139], v[180:183], v[62:65]
	v_mfma_f32_16x16x32_bf16 v[58:61], v[144:147], v[180:183], v[58:61]
	v_mfma_f32_16x16x32_bf16 v[54:57], v[136:139], v[188:191], v[54:57]
	v_mfma_f32_16x16x32_bf16 v[46:49], v[144:147], v[188:191], v[46:49]
	v_mfma_f32_16x16x32_bf16 v[38:41], v[136:139], v[196:199], v[38:41]
	v_mfma_f32_16x16x32_bf16 v[30:33], v[144:147], v[196:199], v[30:33]
	v_mfma_f32_16x16x32_bf16 v[22:25], v[136:139], v[204:207], v[22:25]
	v_mfma_f32_16x16x32_bf16 v[10:13], v[144:147], v[204:207], v[10:13]
	v_mfma_f32_16x16x32_bf16 v[50:53], v[160:163], v[176:179], v[50:53]
	v_mfma_f32_16x16x32_bf16 v[42:45], v[168:171], v[176:179], v[42:45]
	v_mfma_f32_16x16x32_bf16 v[34:37], v[160:163], v[184:187], v[34:37]
	v_mfma_f32_16x16x32_bf16 v[26:29], v[168:171], v[184:187], v[26:29]
	v_mfma_f32_16x16x32_bf16 v[18:21], v[160:163], v[192:195], v[18:21]
	v_mfma_f32_16x16x32_bf16 v[14:17], v[168:171], v[192:195], v[14:17]
	v_mfma_f32_16x16x32_bf16 v[6:9], v[160:163], v[200:203], v[6:9]
	v_mfma_f32_16x16x32_bf16 v[2:5], v[168:171], v[200:203], v[2:5]
	v_mfma_f32_16x16x32_bf16 v[50:53], v[164:167], v[180:183], v[50:53]
	v_mfma_f32_16x16x32_bf16 v[42:45], v[172:175], v[180:183], v[42:45]
	v_mfma_f32_16x16x32_bf16 v[34:37], v[164:167], v[188:191], v[34:37]
	v_mfma_f32_16x16x32_bf16 v[26:29], v[172:175], v[188:191], v[26:29]
	v_mfma_f32_16x16x32_bf16 v[18:21], v[164:167], v[196:199], v[18:21]
	v_mfma_f32_16x16x32_bf16 v[14:17], v[172:175], v[196:199], v[14:17]
	v_mfma_f32_16x16x32_bf16 v[6:9], v[164:167], v[204:207], v[6:9]
	v_mfma_f32_16x16x32_bf16 v[2:5], v[172:175], v[204:207], v[2:5]
	s_barrier
	s_add_i32 s54, 0, 0x18000
	s_add_i32 s55, 0, 0x1c000
	v_add_u32_e32 v144, s54, v156
	v_add_u32_e32 v159, s55, v156
	ds_read_b128 v[132:135], v144
	ds_read_b128 v[136:139], v144 offset:1024
	ds_read_b128 v[140:143], v144 offset:2048
	ds_read_b128 v[144:147], v144 offset:3072
	ds_read_b128 v[160:163], v159
	ds_read_b128 v[164:167], v159 offset:1024
	ds_read_b128 v[168:171], v159 offset:2048
	ds_read_b128 v[172:175], v159 offset:3072
	s_add_u32 s24, s30, 0x160000
	s_addc_u32 s25, s31, 0
	s_mov_b32 m0, s41
	v_lshl_add_u64 v[222:223], s[24:25], 0, v[66:67]
	ds_read_b128 v[176:179], v158 offset:32768
	ds_read_b128 v[180:183], v158 offset:33792
	ds_read_b128 v[184:187], v158 offset:34816
	ds_read_b128 v[188:191], v158 offset:35840
	ds_read_b128 v[192:195], v158 offset:36864
	ds_read_b128 v[196:199], v158 offset:37888
	ds_read_b128 v[200:203], v158 offset:38912
	ds_read_b128 v[204:207], v158 offset:39936
	global_load_lds_dwordx4 v[222:223], off
	v_lshl_add_u64 v[222:223], s[24:25], 0, v[148:149]
	s_mov_b32 m0, s42
	s_nop 0
	global_load_lds_dwordx4 v[222:223], off
	s_waitcnt vmcnt(8)
	s_waitcnt lgkmcnt(0)
	s_barrier
	v_mfma_f32_16x16x32_bf16 v[128:131], v[132:135], v[176:179], v[128:131]
	v_mfma_f32_16x16x32_bf16 v[124:127], v[140:143], v[176:179], v[124:127]
	v_mfma_f32_16x16x32_bf16 v[120:123], v[132:135], v[184:187], v[120:123]
	v_mfma_f32_16x16x32_bf16 v[112:115], v[140:143], v[184:187], v[112:115]
	v_mfma_f32_16x16x32_bf16 v[104:107], v[132:135], v[192:195], v[104:107]
	v_mfma_f32_16x16x32_bf16 v[96:99], v[140:143], v[192:195], v[96:99]
	v_mfma_f32_16x16x32_bf16 v[88:91], v[132:135], v[200:203], v[88:91]
	v_mfma_f32_16x16x32_bf16 v[76:79], v[140:143], v[200:203], v[76:79]
	v_mfma_f32_16x16x32_bf16 v[128:131], v[136:139], v[180:183], v[128:131]
	v_mfma_f32_16x16x32_bf16 v[124:127], v[144:147], v[180:183], v[124:127]
	v_mfma_f32_16x16x32_bf16 v[120:123], v[136:139], v[188:191], v[120:123]
	v_mfma_f32_16x16x32_bf16 v[112:115], v[144:147], v[188:191], v[112:115]
	v_mfma_f32_16x16x32_bf16 v[104:107], v[136:139], v[196:199], v[104:107]
	v_mfma_f32_16x16x32_bf16 v[96:99], v[144:147], v[196:199], v[96:99]
	v_mfma_f32_16x16x32_bf16 v[88:91], v[136:139], v[204:207], v[88:91]
	v_mfma_f32_16x16x32_bf16 v[76:79], v[144:147], v[204:207], v[76:79]
	v_mfma_f32_16x16x32_bf16 v[116:119], v[160:163], v[176:179], v[116:119]
	v_mfma_f32_16x16x32_bf16 v[108:111], v[168:171], v[176:179], v[108:111]
	v_mfma_f32_16x16x32_bf16 v[100:103], v[160:163], v[184:187], v[100:103]
	v_mfma_f32_16x16x32_bf16 v[92:95], v[168:171], v[184:187], v[92:95]
	v_mfma_f32_16x16x32_bf16 v[84:87], v[160:163], v[192:195], v[84:87]
	v_mfma_f32_16x16x32_bf16 v[80:83], v[168:171], v[192:195], v[80:83]
	v_mfma_f32_16x16x32_bf16 v[72:75], v[160:163], v[200:203], v[72:75]
	v_mfma_f32_16x16x32_bf16 v[68:71], v[168:171], v[200:203], v[68:71]
	v_mfma_f32_16x16x32_bf16 v[116:119], v[164:167], v[180:183], v[116:119]
	v_mfma_f32_16x16x32_bf16 v[108:111], v[172:175], v[180:183], v[108:111]
	v_mfma_f32_16x16x32_bf16 v[100:103], v[164:167], v[188:191], v[100:103]
	v_mfma_f32_16x16x32_bf16 v[92:95], v[172:175], v[188:191], v[92:95]
	v_mfma_f32_16x16x32_bf16 v[84:87], v[164:167], v[196:199], v[84:87]
	v_mfma_f32_16x16x32_bf16 v[80:83], v[172:175], v[196:199], v[80:83]
	v_mfma_f32_16x16x32_bf16 v[72:75], v[164:167], v[204:207], v[72:75]
	v_mfma_f32_16x16x32_bf16 v[68:71], v[172:175], v[204:207], v[68:71]
	s_barrier
; #define PG8_STAGE(bufoff, gbase, voff) do { _Pragma("unroll") for (int _i = 0; _i < 2; ++_i) \
;         __builtin_amdgcn_global_load_lds((const unsigned*)((const char*)(gbase) + (voff)[_i]), (PG8_LAS unsigned*)(lds + (bufoff) + ldsw + _i * 8192), 16, 0, 0); } while (0)
; #define PG8_LDA(dst, b, h) do { _Pragma("unroll") for (int m = 0; m < 4; ++m) _Pragma("unroll") for (int k = 0; k < 2; ++k) dst[m][k] = *(const PG8_LAS bf16x8*)(lds + PG8_SA(b, h) + aoff + m * 2048 + k * 1024); } while (0)
; #define PG8_MMA(ai, bj, At, Bt) do { __builtin_amdgcn_s_setprio(1); _Pragma("unroll") for (int m = 0; m < 4; ++m) _Pragma("unroll") for (int n = 0; n < 2; ++n) _Pragma("unroll") for (int k = 0; k < 2; ++k) \
;         acc[ai][bj][m][n] = __builtin_amdgcn_mfma_f32_16x16x32_bf16(Bt[n][k], At[m][k], acc[ai][bj][m][n], 0, 0, 0); __builtin_amdgcn_s_setprio(0); } while (0)
; #define PG8_WAIT_V(n) asm volatile("s_waitcnt vmcnt(" #n ")" ::: "memory")
; #define PG8_WAIT_L(n) asm volatile("s_waitcnt lgkmcnt(" #n ")" ::: "memory")
; #define PG8_BAR __builtin_amdgcn_s_barrier()
; #define PG8_SCHED __builtin_amdgcn_sched_barrier(0)
; template <class Epi, class Sched, bool ALIGN_EPI = false, bool SP2 = false>
; __device__ __forceinline__ void gemm_phase(PG8_LAS unsigned char* lds, const Gemm g, const Sched& S, const Epi& E) {
;     ...
;             PG8_LDA(At, 1, 1); PG8_STAGE(PG8_SB(1, 0), b3, voffB); PG8_STAGE(PG8_SB(1, 1), b3 + hstep, voffB); PG8_STAGE(PG8_SA(1, 0), a3, voffA);
;             PG8_WAIT_V(8); PG8_WAIT_L(0); PG8_BAR; PG8_MMA(1, 0, At, B0); PG8_MMA(1, 1, At, B1); PG8_BAR; PG8_SCHED;
;     ...
;     PG8_WAIT_V(0);
;     if constexpr (!ALIGN_EPI) { if (wr == 0) PG8_BAR; }
;     PG8_BAR;
	s_add_i32 s24, s54, s38
	v_lshl_add_u64 v[154:155], v[154:155], 0, s[88:89]
	s_mov_b32 m0, s24
	ds_read_b128 v[176:179], v158 offset:49152
	ds_read_b128 v[180:183], v158 offset:50176
	ds_read_b128 v[184:187], v158 offset:51200
	ds_read_b128 v[188:191], v158 offset:52224
	ds_read_b128 v[192:195], v158 offset:53248
	ds_read_b128 v[196:199], v158 offset:54272
	ds_read_b128 v[200:203], v158 offset:55296
	ds_read_b128 v[204:207], v158 offset:56320
	global_load_lds_dwordx4 v[154:155], off
	s_add_i32 m0, s24, 0x2000
	s_add_u32 s24, s28, 0x160080
	v_lshl_add_u64 v[154:155], v[208:209], 0, s[88:89]
	s_addc_u32 s25, s29, 0
	s_add_i32 s28, s55, s38
	global_load_lds_dwordx4 v[154:155], off
	v_lshl_add_u64 v[154:155], s[24:25], 0, v[66:67]
	s_mov_b32 m0, s28
	s_nop 0
	global_load_lds_dwordx4 v[154:155], off
	v_lshl_add_u64 v[154:155], s[24:25], 0, v[148:149]
	s_add_i32 m0, s28, 0x2000
	s_nop 0
	global_load_lds_dwordx4 v[154:155], off
	v_lshl_add_u64 v[154:155], v[210:211], 0, s[88:89]
	s_mov_b32 m0, s45
	s_nop 0
	global_load_lds_dwordx4 v[154:155], off
	v_lshl_add_u64 v[154:155], v[220:221], 0, s[88:89]
	s_mov_b32 m0, s46
	s_nop 0
	global_load_lds_dwordx4 v[154:155], off
	s_waitcnt vmcnt(8)
	s_waitcnt lgkmcnt(0)
	s_barrier
	v_mfma_f32_16x16x32_bf16 v[62:65], v[132:135], v[176:179], v[62:65]
	v_mfma_f32_16x16x32_bf16 v[58:61], v[140:143], v[176:179], v[58:61]
	v_mfma_f32_16x16x32_bf16 v[54:57], v[132:135], v[184:187], v[54:57]
	v_mfma_f32_16x16x32_bf16 v[46:49], v[140:143], v[184:187], v[46:49]
	v_mfma_f32_16x16x32_bf16 v[38:41], v[132:135], v[192:195], v[38:41]
	v_mfma_f32_16x16x32_bf16 v[30:33], v[140:143], v[192:195], v[30:33]
	v_mfma_f32_16x16x32_bf16 v[22:25], v[132:135], v[200:203], v[22:25]
	v_mfma_f32_16x16x32_bf16 v[10:13], v[140:143], v[200:203], v[10:13]
	v_mfma_f32_16x16x32_bf16 v[62:65], v[136:139], v[180:183], v[62:65]
	v_mfma_f32_16x16x32_bf16 v[58:61], v[144:147], v[180:183], v[58:61]
	v_mfma_f32_16x16x32_bf16 v[54:57], v[136:139], v[188:191], v[54:57]
	v_mfma_f32_16x16x32_bf16 v[46:49], v[144:147], v[188:191], v[46:49]
	v_mfma_f32_16x16x32_bf16 v[38:41], v[136:139], v[196:199], v[38:41]
	v_mfma_f32_16x16x32_bf16 v[30:33], v[144:147], v[196:199], v[30:33]
	v_mfma_f32_16x16x32_bf16 v[22:25], v[136:139], v[204:207], v[22:25]
	v_mfma_f32_16x16x32_bf16 v[10:13], v[144:147], v[204:207], v[10:13]
	v_mfma_f32_16x16x32_bf16 v[50:53], v[160:163], v[176:179], v[50:53]
	v_mfma_f32_16x16x32_bf16 v[42:45], v[168:171], v[176:179], v[42:45]
	v_mfma_f32_16x16x32_bf16 v[34:37], v[160:163], v[184:187], v[34:37]
	v_mfma_f32_16x16x32_bf16 v[26:29], v[168:171], v[184:187], v[26:29]
	v_mfma_f32_16x16x32_bf16 v[18:21], v[160:163], v[192:195], v[18:21]
	v_mfma_f32_16x16x32_bf16 v[14:17], v[168:171], v[192:195], v[14:17]
	v_mfma_f32_16x16x32_bf16 v[6:9], v[160:163], v[200:203], v[6:9]
	v_mfma_f32_16x16x32_bf16 v[2:5], v[168:171], v[200:203], v[2:5]
	v_mfma_f32_16x16x32_bf16 v[50:53], v[164:167], v[180:183], v[50:53]
	v_mfma_f32_16x16x32_bf16 v[42:45], v[172:175], v[180:183], v[42:45]
	v_mfma_f32_16x16x32_bf16 v[34:37], v[164:167], v[188:191], v[34:37]
	v_mfma_f32_16x16x32_bf16 v[26:29], v[172:175], v[188:191], v[26:29]
	v_mfma_f32_16x16x32_bf16 v[18:21], v[164:167], v[196:199], v[18:21]
	v_mfma_f32_16x16x32_bf16 v[14:17], v[172:175], v[196:199], v[14:17]
	v_mfma_f32_16x16x32_bf16 v[6:9], v[164:167], v[204:207], v[6:9]
	v_mfma_f32_16x16x32_bf16 v[2:5], v[172:175], v[204:207], v[2:5]
	s_barrier
	s_add_i32 s53, s53, 2
	s_add_u32 s2, s2, 0x100
	s_addc_u32 s3, s3, 0
	s_cmpk_gt_u32 s53, 0x55
	s_mov_b64 s[24:25], s[26:27]
	s_cbranch_scc0 .LBB0_1294
	s_nop 0
	s_nop 0
	s_nop 0
	s_nop 0
	s_nop 0
	s_nop 0
	s_nop 0
	s_nop 0
	s_nop 0
	s_nop 0
	s_nop 0
	s_nop 0
	s_nop 0
	s_nop 0
	s_nop 0
	s_nop 0
	s_nop 0
	s_nop 0
	s_nop 0
	s_nop 0
	s_and_b64 vcc, exec, s[20:21]
	s_cbranch_vccz .LBB0_1297
	s_barrier

; #define PG8_STAGE(bufoff, gbase, voff) do { _Pragma("unroll") for (int _i = 0; _i < 2; ++_i) \
;         __builtin_amdgcn_global_load_lds((const unsigned*)((const char*)(gbase) + (voff)[_i]), (PG8_LAS unsigned*)(lds + (bufoff) + ldsw + _i * 8192), 16, 0, 0); } while (0)
; #define PG8_LDA(dst, b, h) do { _Pragma("unroll") for (int m = 0; m < 4; ++m) _Pragma("unroll") for (int k = 0; k < 2; ++k) dst[m][k] = *(const PG8_LAS bf16x8*)(lds + PG8_SA(b, h) + aoff + m * 2048 + k * 1024); } while (0)
; #define PG8_LDB(dst, b, h) do { _Pragma("unroll") for (int n = 0; n < 2; ++n) _Pragma("unroll") for (int k = 0; k < 2; ++k) dst[n][k] = *(const PG8_LAS bf16x8*)(lds + PG8_SB(b, h) + boff + n * 2048 + k * 1024); } while (0)
; #define PG8_MMA(ai, bj, At, Bt) do { __builtin_amdgcn_s_setprio(1); _Pragma("unroll") for (int m = 0; m < 4; ++m) _Pragma("unroll") for (int n = 0; n < 2; ++n) _Pragma("unroll") for (int k = 0; k < 2; ++k) \
;         acc[ai][bj][m][n] = __builtin_amdgcn_mfma_f32_16x16x32_bf16(Bt[n][k], At[m][k], acc[ai][bj][m][n], 0, 0, 0); __builtin_amdgcn_s_setprio(0); } while (0)
; #define PG8_WAIT_V(n) asm volatile("s_waitcnt vmcnt(" #n ")" ::: "memory")
; #define PG8_BAR __builtin_amdgcn_s_barrier()
; template <class Epi, class Sched, bool ALIGN_EPI = false, bool SP2 = false>
; __device__ __forceinline__ void gemm_phase(PG8_LAS unsigned char* lds, const Gemm g, const Sched& S, const Epi& E) {
;     ...
;         for (int t = 0; t < nt; t += 2) {
;             const bool last = (t == nt - 2);
;             const char* a1 = cA + (size_t)(t + 1) * kstep;
;             const char* a2 = last ? nA : cA + (size_t)(t + 2) * kstep; const char* b2 = last ? nB : cB + (size_t)(t + 2) * kstep;
;             const char* a3 = a2 + kstep; const char* b3 = b2 + kstep;
;             if (last && has_next) S.a_ready(nxt);
;             if constexpr (SP2) {
;             PG8_LDB(B0, 0, 0); PG8_LDB(B1, 0, 1); PG8_SCHED; PG8_LDA(At, 0, 0); PG8_STAGE(PG8_SA(1, 1), a1 + hstep, voffA);
;             PG8_WAIT_V(8); PG8_WAIT_L(0); PG8_BAR; PG8_MMA(0, 0, At, B0); PG8_MMA(0, 1, At, B1); PG8_BAR; PG8_SCHED;
;             PG8_LDA(At, 0, 1); PG8_STAGE(PG8_SB(0, 0), b2, voffB); PG8_STAGE(PG8_SB(0, 1), b2 + hstep, voffB); PG8_STAGE(PG8_SA(0, 0), a2, voffA);
;             PG8_WAIT_V(8); PG8_WAIT_L(0); PG8_BAR; PG8_MMA(1, 0, At, B0); PG8_MMA(1, 1, At, B1); PG8_BAR; PG8_SCHED;
.LBB0_1324:
	s_add_u32 s28, s22, s26
	s_addc_u32 s29, s23, s27
	s_add_u32 s28, s28, 0x100
	s_addc_u32 s29, s29, 0
	s_add_u32 s54, s3, s26
	s_addc_u32 s55, s52, s27
	s_add_i32 s56, 0, 0x10000
	s_cmpk_eq_i32 s26, 0x2b00
	s_cselect_b32 s31, s25, s29
	s_cselect_b32 s30, s24, s28
	s_cselect_b32 s29, s13, s55
	s_cselect_b32 s28, s12, s54
	s_add_i32 s57, 0, 0x14000
	v_add_u32_e32 v156, s56, v142
	v_add_u32_e32 v172, s57, v142
	ds_read_b128 v[144:147], v156
	ds_read_b128 v[148:151], v156 offset:1024
	ds_read_b128 v[152:155], v156 offset:2048
	ds_read_b128 v[156:159], v156 offset:3072
	ds_read_b128 v[160:163], v172
	ds_read_b128 v[164:167], v172 offset:1024
	ds_read_b128 v[168:171], v172 offset:2048
	ds_read_b128 v[172:175], v172 offset:3072
	v_lshl_add_u64 v[208:209], v[138:139], 0, s[26:27]
	s_add_i32 m0, s43, 0xc000
	ds_read_b128 v[176:179], v143
	ds_read_b128 v[180:183], v143 offset:1024
	ds_read_b128 v[184:187], v143 offset:2048
	ds_read_b128 v[188:191], v143 offset:3072
	ds_read_b128 v[192:195], v143 offset:4096
	ds_read_b128 v[196:199], v143 offset:5120
	ds_read_b128 v[200:203], v143 offset:6144
	ds_read_b128 v[204:207], v143 offset:7168
	global_load_lds_dwordx4 v[208:209], off
	v_lshl_add_u64 v[208:209], v[140:141], 0, s[26:27]
	s_add_i32 m0, s43, 0xe000
	s_nop 0
	global_load_lds_dwordx4 v[208:209], off
	s_waitcnt vmcnt(8)
	s_waitcnt lgkmcnt(0)
	s_barrier
	v_mfma_f32_16x16x32_bf16 v[128:131], v[144:147], v[176:179], v[128:131]
	v_mfma_f32_16x16x32_bf16 v[124:127], v[152:155], v[176:179], v[124:127]
	v_mfma_f32_16x16x32_bf16 v[112:115], v[144:147], v[184:187], v[112:115]
	v_mfma_f32_16x16x32_bf16 v[104:107], v[152:155], v[184:187], v[104:107]
	v_mfma_f32_16x16x32_bf16 v[96:99], v[144:147], v[192:195], v[96:99]
	v_mfma_f32_16x16x32_bf16 v[88:91], v[152:155], v[192:195], v[88:91]
	v_mfma_f32_16x16x32_bf16 v[80:83], v[144:147], v[200:203], v[80:83]
	v_mfma_f32_16x16x32_bf16 v[72:75], v[152:155], v[200:203], v[72:75]
	v_mfma_f32_16x16x32_bf16 v[128:131], v[148:151], v[180:183], v[128:131]
	v_mfma_f32_16x16x32_bf16 v[124:127], v[156:159], v[180:183], v[124:127]
	v_mfma_f32_16x16x32_bf16 v[112:115], v[148:151], v[188:191], v[112:115]
	v_mfma_f32_16x16x32_bf16 v[104:107], v[156:159], v[188:191], v[104:107]
	v_mfma_f32_16x16x32_bf16 v[96:99], v[148:151], v[196:199], v[96:99]
	v_mfma_f32_16x16x32_bf16 v[88:91], v[156:159], v[196:199], v[88:91]
	v_mfma_f32_16x16x32_bf16 v[80:83], v[148:151], v[204:207], v[80:83]
	v_mfma_f32_16x16x32_bf16 v[72:75], v[156:159], v[204:207], v[72:75]
	v_mfma_f32_16x16x32_bf16 v[116:119], v[160:163], v[176:179], v[116:119]
	v_mfma_f32_16x16x32_bf16 v[108:111], v[168:171], v[176:179], v[108:111]
	v_mfma_f32_16x16x32_bf16 v[100:103], v[160:163], v[184:187], v[100:103]
	v_mfma_f32_16x16x32_bf16 v[92:95], v[168:171], v[184:187], v[92:95]
	v_mfma_f32_16x16x32_bf16 v[84:87], v[160:163], v[192:195], v[84:87]
	v_mfma_f32_16x16x32_bf16 v[76:79], v[168:171], v[192:195], v[76:79]
	v_mfma_f32_16x16x32_bf16 v[68:71], v[160:163], v[200:203], v[68:71]
	v_mfma_f32_16x16x32_bf16 v[62:65], v[168:171], v[200:203], v[62:65]
	v_mfma_f32_16x16x32_bf16 v[116:119], v[164:167], v[180:183], v[116:119]
	v_mfma_f32_16x16x32_bf16 v[108:111], v[172:175], v[180:183], v[108:111]
	v_mfma_f32_16x16x32_bf16 v[100:103], v[164:167], v[188:191], v[100:103]
	v_mfma_f32_16x16x32_bf16 v[92:95], v[172:175], v[188:191], v[92:95]
	v_mfma_f32_16x16x32_bf16 v[84:87], v[164:167], v[196:199], v[84:87]
	v_mfma_f32_16x16x32_bf16 v[76:79], v[172:175], v[196:199], v[76:79]
	v_mfma_f32_16x16x32_bf16 v[68:71], v[164:167], v[204:207], v[68:71]
	v_mfma_f32_16x16x32_bf16 v[62:65], v[172:175], v[204:207], v[62:65]
	s_barrier
	s_add_i32 s54, s56, s42
	v_lshl_add_u64 v[208:209], s[28:29], 0, v[66:67]
	s_mov_b32 m0, s54
	ds_read_b128 v[176:179], v143 offset:16384
	ds_read_b128 v[180:183], v143 offset:17408
	ds_read_b128 v[184:187], v143 offset:18432
	ds_read_b128 v[188:191], v143 offset:19456
	ds_read_b128 v[192:195], v143 offset:20480
	ds_read_b128 v[196:199], v143 offset:21504
	ds_read_b128 v[200:203], v143 offset:22528
	ds_read_b128 v[204:207], v143 offset:23552
	global_load_lds_dwordx4 v[208:209], off
	s_add_i32 m0, s54, 0x2000
	s_add_u32 s54, s28, 0x160000
	v_lshl_add_u64 v[210:211], s[28:29], 0, v[132:133]
	s_addc_u32 s55, s29, 0
	s_add_i32 s56, s57, s42
	global_load_lds_dwordx4 v[210:211], off
	v_lshl_add_u64 v[220:221], s[54:55], 0, v[66:67]
	s_mov_b32 m0, s56
	v_lshl_add_u64 v[222:223], s[30:31], 0, v[132:133]
	global_load_lds_dwordx4 v[220:221], off
	v_lshl_add_u64 v[220:221], s[54:55], 0, v[132:133]
	s_add_i32 m0, s56, 0x2000
	s_nop 0
	global_load_lds_dwordx4 v[220:221], off
	v_lshl_add_u64 v[220:221], s[30:31], 0, v[66:67]
	s_mov_b32 m0, s43
	s_nop 0
	global_load_lds_dwordx4 v[220:221], off
	s_mov_b32 m0, s44
	s_nop 0
	global_load_lds_dwordx4 v[222:223], off
	s_waitcnt vmcnt(8)
	s_waitcnt lgkmcnt(0)
	s_barrier
; #define PG8_STAGE(bufoff, gbase, voff) do { _Pragma("unroll") for (int _i = 0; _i < 2; ++_i) \
;         __builtin_amdgcn_global_load_lds((const unsigned*)((const char*)(gbase) + (voff)[_i]), (PG8_LAS unsigned*)(lds + (bufoff) + ldsw + _i * 8192), 16, 0, 0); } while (0)
; #define PG8_LDA(dst, b, h) do { _Pragma("unroll") for (int m = 0; m < 4; ++m) _Pragma("unroll") for (int k = 0; k < 2; ++k) dst[m][k] = *(const PG8_LAS bf16x8*)(lds + PG8_SA(b, h) + aoff + m * 2048 + k * 1024); } while (0)
; #define PG8_LDB(dst, b, h) do { _Pragma("unroll") for (int n = 0; n < 2; ++n) _Pragma("unroll") for (int k = 0; k < 2; ++k) dst[n][k] = *(const PG8_LAS bf16x8*)(lds + PG8_SB(b, h) + boff + n * 2048 + k * 1024); } while (0)
; #define PG8_MMA(ai, bj, At, Bt) do { __builtin_amdgcn_s_setprio(1); _Pragma("unroll") for (int m = 0; m < 4; ++m) _Pragma("unroll") for (int n = 0; n < 2; ++n) _Pragma("unroll") for (int k = 0; k < 2; ++k) \
;         acc[ai][bj][m][n] = __builtin_amdgcn_mfma_f32_16x16x32_bf16(Bt[n][k], At[m][k], acc[ai][bj][m][n], 0, 0, 0); __builtin_amdgcn_s_setprio(0); } while (0)
; #define PG8_WAIT_V(n) asm volatile("s_waitcnt vmcnt(" #n ")" ::: "memory")
; #define PG8_WAIT_L(n) asm volatile("s_waitcnt lgkmcnt(" #n ")" ::: "memory")
; #define PG8_BAR __builtin_amdgcn_s_barrier()
; #define PG8_SCHED __builtin_amdgcn_sched_barrier(0)
; template <class Epi, class Sched, bool ALIGN_EPI = false, bool SP2 = false>
; __device__ __forceinline__ void gemm_phase(PG8_LAS unsigned char* lds, const Gemm g, const Sched& S, const Epi& E) {
;     ...
;             PG8_WAIT_V(8); PG8_WAIT_L(0); PG8_BAR; PG8_MMA(1, 0, At, B0); PG8_MMA(1, 1, At, B1); PG8_BAR; PG8_SCHED;
;             PG8_LDB(B0, 1, 0); PG8_LDB(B1, 1, 1); PG8_SCHED; PG8_LDA(At, 1, 0); PG8_STAGE(PG8_SA(0, 1), a2 + hstep, voffA);
;             PG8_WAIT_V(8); PG8_WAIT_L(0); PG8_BAR; PG8_MMA(0, 0, At, B0); PG8_MMA(0, 1, At, B1); PG8_BAR; PG8_SCHED;
;             PG8_LDA(At, 1, 1); PG8_STAGE(PG8_SB(1, 0), b3, voffB); PG8_STAGE(PG8_SB(1, 1), b3 + hstep, voffB); PG8_STAGE(PG8_SA(1, 0), a3, voffA);
	v_mfma_f32_16x16x32_bf16 v[58:61], v[144:147], v[176:179], v[58:61]
	v_mfma_f32_16x16x32_bf16 v[54:57], v[152:155], v[176:179], v[54:57]
	v_mfma_f32_16x16x32_bf16 v[46:49], v[144:147], v[184:187], v[46:49]
	v_mfma_f32_16x16x32_bf16 v[38:41], v[152:155], v[184:187], v[38:41]
	v_mfma_f32_16x16x32_bf16 v[30:33], v[144:147], v[192:195], v[30:33]
	v_mfma_f32_16x16x32_bf16 v[22:25], v[152:155], v[192:195], v[22:25]
	v_mfma_f32_16x16x32_bf16 v[120:123], v[144:147], v[200:203], v[120:123]
	v_mfma_f32_16x16x32_bf16 v[10:13], v[152:155], v[200:203], v[10:13]
	v_mfma_f32_16x16x32_bf16 v[58:61], v[148:151], v[180:183], v[58:61]
	v_mfma_f32_16x16x32_bf16 v[54:57], v[156:159], v[180:183], v[54:57]
	v_mfma_f32_16x16x32_bf16 v[46:49], v[148:151], v[188:191], v[46:49]
	v_mfma_f32_16x16x32_bf16 v[38:41], v[156:159], v[188:191], v[38:41]
	v_mfma_f32_16x16x32_bf16 v[30:33], v[148:151], v[196:199], v[30:33]
	v_mfma_f32_16x16x32_bf16 v[22:25], v[156:159], v[196:199], v[22:25]
	v_mfma_f32_16x16x32_bf16 v[120:123], v[148:151], v[204:207], v[120:123]
	v_mfma_f32_16x16x32_bf16 v[10:13], v[156:159], v[204:207], v[10:13]
	v_mfma_f32_16x16x32_bf16 v[50:53], v[160:163], v[176:179], v[50:53]
	v_mfma_f32_16x16x32_bf16 v[42:45], v[168:171], v[176:179], v[42:45]
	v_mfma_f32_16x16x32_bf16 v[34:37], v[160:163], v[184:187], v[34:37]
	v_mfma_f32_16x16x32_bf16 v[26:29], v[168:171], v[184:187], v[26:29]
	v_mfma_f32_16x16x32_bf16 v[18:21], v[160:163], v[192:195], v[18:21]
	v_mfma_f32_16x16x32_bf16 v[14:17], v[168:171], v[192:195], v[14:17]
	v_mfma_f32_16x16x32_bf16 v[6:9], v[160:163], v[200:203], v[6:9]
	v_mfma_f32_16x16x32_bf16 v[2:5], v[168:171], v[200:203], v[2:5]
	v_mfma_f32_16x16x32_bf16 v[50:53], v[164:167], v[180:183], v[50:53]
	v_mfma_f32_16x16x32_bf16 v[42:45], v[172:175], v[180:183], v[42:45]
	v_mfma_f32_16x16x32_bf16 v[34:37], v[164:167], v[188:191], v[34:37]
	v_mfma_f32_16x16x32_bf16 v[26:29], v[172:175], v[188:191], v[26:29]
	v_mfma_f32_16x16x32_bf16 v[18:21], v[164:167], v[196:199], v[18:21]
	v_mfma_f32_16x16x32_bf16 v[14:17], v[172:175], v[196:199], v[14:17]
	v_mfma_f32_16x16x32_bf16 v[6:9], v[164:167], v[204:207], v[6:9]
	v_mfma_f32_16x16x32_bf16 v[2:5], v[172:175], v[204:207], v[2:5]
	s_barrier
	s_add_i32 s54, 0, 0x18000
	s_add_i32 s55, 0, 0x1c000
	v_add_u32_e32 v156, s54, v142
	v_add_u32_e32 v172, s55, v142
	ds_read_b128 v[144:147], v156
	ds_read_b128 v[148:151], v156 offset:1024
	ds_read_b128 v[152:155], v156 offset:2048
	ds_read_b128 v[156:159], v156 offset:3072
	ds_read_b128 v[160:163], v172
	ds_read_b128 v[164:167], v172 offset:1024
	ds_read_b128 v[168:171], v172 offset:2048
	ds_read_b128 v[172:175], v172 offset:3072
	s_add_u32 s30, s30, 0x160000
	s_addc_u32 s31, s31, 0
	s_mov_b32 m0, s45
	v_lshl_add_u64 v[224:225], s[30:31], 0, v[66:67]
	ds_read_b128 v[176:179], v143 offset:32768
	ds_read_b128 v[180:183], v143 offset:33792
	ds_read_b128 v[184:187], v143 offset:34816
	ds_read_b128 v[188:191], v143 offset:35840
	ds_read_b128 v[192:195], v143 offset:36864
	ds_read_b128 v[196:199], v143 offset:37888
	ds_read_b128 v[200:203], v143 offset:38912
	ds_read_b128 v[204:207], v143 offset:39936
	global_load_lds_dwordx4 v[224:225], off
	v_lshl_add_u64 v[224:225], s[30:31], 0, v[132:133]
	s_mov_b32 m0, s1
	s_nop 0
	global_load_lds_dwordx4 v[224:225], off
	s_waitcnt vmcnt(8)
	s_waitcnt lgkmcnt(0)
	s_barrier
	v_mfma_f32_16x16x32_bf16 v[128:131], v[144:147], v[176:179], v[128:131]
	v_mfma_f32_16x16x32_bf16 v[124:127], v[152:155], v[176:179], v[124:127]
	v_mfma_f32_16x16x32_bf16 v[112:115], v[144:147], v[184:187], v[112:115]
	v_mfma_f32_16x16x32_bf16 v[104:107], v[152:155], v[184:187], v[104:107]
	v_mfma_f32_16x16x32_bf16 v[96:99], v[144:147], v[192:195], v[96:99]
	v_mfma_f32_16x16x32_bf16 v[88:91], v[152:155], v[192:195], v[88:91]
	v_mfma_f32_16x16x32_bf16 v[80:83], v[144:147], v[200:203], v[80:83]
	v_mfma_f32_16x16x32_bf16 v[72:75], v[152:155], v[200:203], v[72:75]
	v_mfma_f32_16x16x32_bf16 v[128:131], v[148:151], v[180:183], v[128:131]
	v_mfma_f32_16x16x32_bf16 v[124:127], v[156:159], v[180:183], v[124:127]
	v_mfma_f32_16x16x32_bf16 v[112:115], v[148:151], v[188:191], v[112:115]
	v_mfma_f32_16x16x32_bf16 v[104:107], v[156:159], v[188:191], v[104:107]
	v_mfma_f32_16x16x32_bf16 v[96:99], v[148:151], v[196:199], v[96:99]
	v_mfma_f32_16x16x32_bf16 v[88:91], v[156:159], v[196:199], v[88:91]
	v_mfma_f32_16x16x32_bf16 v[80:83], v[148:151], v[204:207], v[80:83]
	v_mfma_f32_16x16x32_bf16 v[72:75], v[156:159], v[204:207], v[72:75]
	v_mfma_f32_16x16x32_bf16 v[116:119], v[160:163], v[176:179], v[116:119]
	v_mfma_f32_16x16x32_bf16 v[108:111], v[168:171], v[176:179], v[108:111]
	v_mfma_f32_16x16x32_bf16 v[100:103], v[160:163], v[184:187], v[100:103]
	v_mfma_f32_16x16x32_bf16 v[92:95], v[168:171], v[184:187], v[92:95]
	v_mfma_f32_16x16x32_bf16 v[84:87], v[160:163], v[192:195], v[84:87]
	v_mfma_f32_16x16x32_bf16 v[76:79], v[168:171], v[192:195], v[76:79]
	v_mfma_f32_16x16x32_bf16 v[68:71], v[160:163], v[200:203], v[68:71]
	v_mfma_f32_16x16x32_bf16 v[62:65], v[168:171], v[200:203], v[62:65]
	v_mfma_f32_16x16x32_bf16 v[116:119], v[164:167], v[180:183], v[116:119]
	v_mfma_f32_16x16x32_bf16 v[108:111], v[172:175], v[180:183], v[108:111]
	v_mfma_f32_16x16x32_bf16 v[100:103], v[164:167], v[188:191], v[100:103]
	v_mfma_f32_16x16x32_bf16 v[92:95], v[172:175], v[188:191], v[92:95]
	v_mfma_f32_16x16x32_bf16 v[84:87], v[164:167], v[196:199], v[84:87]
	v_mfma_f32_16x16x32_bf16 v[76:79], v[172:175], v[196:199], v[76:79]
	v_mfma_f32_16x16x32_bf16 v[68:71], v[164:167], v[204:207], v[68:71]
	v_mfma_f32_16x16x32_bf16 v[62:65], v[172:175], v[204:207], v[62:65]
	s_barrier
; #define PG8_STAGE(bufoff, gbase, voff) do { _Pragma("unroll") for (int _i = 0; _i < 2; ++_i) \
;         __builtin_amdgcn_global_load_lds((const unsigned*)((const char*)(gbase) + (voff)[_i]), (PG8_LAS unsigned*)(lds + (bufoff) + ldsw + _i * 8192), 16, 0, 0); } while (0)
; #define PG8_LDA(dst, b, h) do { _Pragma("unroll") for (int m = 0; m < 4; ++m) _Pragma("unroll") for (int k = 0; k < 2; ++k) dst[m][k] = *(const PG8_LAS bf16x8*)(lds + PG8_SA(b, h) + aoff + m * 2048 + k * 1024); } while (0)
; #define PG8_MMA(ai, bj, At, Bt) do { __builtin_amdgcn_s_setprio(1); _Pragma("unroll") for (int m = 0; m < 4; ++m) _Pragma("unroll") for (int n = 0; n < 2; ++n) _Pragma("unroll") for (int k = 0; k < 2; ++k) \
;         acc[ai][bj][m][n] = __builtin_amdgcn_mfma_f32_16x16x32_bf16(Bt[n][k], At[m][k], acc[ai][bj][m][n], 0, 0, 0); __builtin_amdgcn_s_setprio(0); } while (0)
; #define PG8_WAIT_V(n) asm volatile("s_waitcnt vmcnt(" #n ")" ::: "memory")
; #define PG8_WAIT_L(n) asm volatile("s_waitcnt lgkmcnt(" #n ")" ::: "memory")
; #define PG8_BAR __builtin_amdgcn_s_barrier()
; #define PG8_SCHED __builtin_amdgcn_sched_barrier(0)
; template <class Epi, class Sched, bool ALIGN_EPI = false, bool SP2 = false>
; __device__ __forceinline__ void gemm_phase(PG8_LAS unsigned char* lds, const Gemm g, const Sched& S, const Epi& E) {
;     ...
;             PG8_LDA(At, 1, 1); PG8_STAGE(PG8_SB(1, 0), b3, voffB); PG8_STAGE(PG8_SB(1, 1), b3 + hstep, voffB); PG8_STAGE(PG8_SA(1, 0), a3, voffA);
;             PG8_WAIT_V(8); PG8_WAIT_L(0); PG8_BAR; PG8_MMA(1, 0, At, B0); PG8_MMA(1, 1, At, B1); PG8_BAR; PG8_SCHED;
;     ...
; #pragma unroll
;         for (int a = 0; a < 2; ++a)
; #pragma unroll
;             for (int b = 0; b < 2; ++b)
; #pragma unroll
;                 for (int m = 0; m < 4; ++m)
; #pragma unroll
;                     for (int n = 0; n < 2; ++n) acc[a][b][m][n] = (f32x4){0.f, 0.f, 0.f, 0.f};
;         cur = nxt; cA = nA; cB = nB; ++ui;
	s_add_i32 s30, s54, s42
	v_lshl_add_u64 v[208:209], v[208:209], 0, s[88:89]
	s_mov_b32 m0, s30
	ds_read_b128 v[176:179], v143 offset:49152
	ds_read_b128 v[180:183], v143 offset:50176
	ds_read_b128 v[184:187], v143 offset:51200
	ds_read_b128 v[188:191], v143 offset:52224
	ds_read_b128 v[192:195], v143 offset:53248
	ds_read_b128 v[196:199], v143 offset:54272
	ds_read_b128 v[200:203], v143 offset:55296
	ds_read_b128 v[204:207], v143 offset:56320
	global_load_lds_dwordx4 v[208:209], off
	s_add_i32 m0, s30, 0x2000
	s_add_u32 s28, s28, 0x160080
	v_lshl_add_u64 v[208:209], v[210:211], 0, s[88:89]
	s_addc_u32 s29, s29, 0
	s_add_i32 s30, s55, s42
	global_load_lds_dwordx4 v[208:209], off
	v_lshl_add_u64 v[208:209], s[28:29], 0, v[66:67]
	s_mov_b32 m0, s30
	s_nop 0
	global_load_lds_dwordx4 v[208:209], off
	v_lshl_add_u64 v[208:209], s[28:29], 0, v[132:133]
	s_add_i32 m0, s30, 0x2000
	s_nop 0
	global_load_lds_dwordx4 v[208:209], off
	v_lshl_add_u64 v[208:209], v[220:221], 0, s[88:89]
	s_mov_b32 m0, s47
	s_nop 0
	global_load_lds_dwordx4 v[208:209], off
	v_lshl_add_u64 v[208:209], v[222:223], 0, s[88:89]
	s_mov_b32 m0, s48
	s_nop 0
	global_load_lds_dwordx4 v[208:209], off
	s_waitcnt vmcnt(8)
	s_waitcnt lgkmcnt(0)
	s_barrier
	v_mfma_f32_16x16x32_bf16 v[58:61], v[144:147], v[176:179], v[58:61]
	v_mfma_f32_16x16x32_bf16 v[54:57], v[152:155], v[176:179], v[54:57]
	v_mfma_f32_16x16x32_bf16 v[46:49], v[144:147], v[184:187], v[46:49]
	v_mfma_f32_16x16x32_bf16 v[38:41], v[152:155], v[184:187], v[38:41]
	v_mfma_f32_16x16x32_bf16 v[30:33], v[144:147], v[192:195], v[30:33]
	v_mfma_f32_16x16x32_bf16 v[22:25], v[152:155], v[192:195], v[22:25]
	v_mfma_f32_16x16x32_bf16 v[120:123], v[144:147], v[200:203], v[120:123]
	v_mfma_f32_16x16x32_bf16 v[10:13], v[152:155], v[200:203], v[10:13]
	v_mfma_f32_16x16x32_bf16 v[58:61], v[148:151], v[180:183], v[58:61]
	v_mfma_f32_16x16x32_bf16 v[54:57], v[156:159], v[180:183], v[54:57]
	v_mfma_f32_16x16x32_bf16 v[46:49], v[148:151], v[188:191], v[46:49]
	v_mfma_f32_16x16x32_bf16 v[38:41], v[156:159], v[188:191], v[38:41]
	v_mfma_f32_16x16x32_bf16 v[30:33], v[148:151], v[196:199], v[30:33]
	v_mfma_f32_16x16x32_bf16 v[22:25], v[156:159], v[196:199], v[22:25]
	v_mfma_f32_16x16x32_bf16 v[120:123], v[148:151], v[204:207], v[120:123]
	v_mfma_f32_16x16x32_bf16 v[10:13], v[156:159], v[204:207], v[10:13]
	v_mfma_f32_16x16x32_bf16 v[50:53], v[160:163], v[176:179], v[50:53]
	v_mfma_f32_16x16x32_bf16 v[42:45], v[168:171], v[176:179], v[42:45]
	v_mfma_f32_16x16x32_bf16 v[34:37], v[160:163], v[184:187], v[34:37]
	v_mfma_f32_16x16x32_bf16 v[26:29], v[168:171], v[184:187], v[26:29]
	v_mfma_f32_16x16x32_bf16 v[18:21], v[160:163], v[192:195], v[18:21]
	v_mfma_f32_16x16x32_bf16 v[14:17], v[168:171], v[192:195], v[14:17]
	v_mfma_f32_16x16x32_bf16 v[6:9], v[160:163], v[200:203], v[6:9]
	v_mfma_f32_16x16x32_bf16 v[2:5], v[168:171], v[200:203], v[2:5]
	v_mfma_f32_16x16x32_bf16 v[50:53], v[164:167], v[180:183], v[50:53]
	v_mfma_f32_16x16x32_bf16 v[42:45], v[172:175], v[180:183], v[42:45]
	v_mfma_f32_16x16x32_bf16 v[34:37], v[164:167], v[188:191], v[34:37]
	v_mfma_f32_16x16x32_bf16 v[26:29], v[172:175], v[188:191], v[26:29]
	v_mfma_f32_16x16x32_bf16 v[18:21], v[164:167], v[196:199], v[18:21]
	v_mfma_f32_16x16x32_bf16 v[14:17], v[172:175], v[196:199], v[14:17]
	v_mfma_f32_16x16x32_bf16 v[6:9], v[164:167], v[204:207], v[6:9]
	v_mfma_f32_16x16x32_bf16 v[2:5], v[172:175], v[204:207], v[2:5]
	s_barrier
	s_add_i32 s53, s53, 2
	s_add_u32 s26, s26, 0x100
	s_addc_u32 s27, s27, 0
	s_cmpk_gt_u32 s53, 0x55
	s_cbranch_scc0 .LBB0_1324
	s_nop 0
	s_nop 0
	s_nop 0
	s_nop 0
	s_nop 0
	s_nop 0
	s_nop 0
	s_nop 0
	s_nop 0
	s_nop 0
	s_nop 0
	s_nop 0
	s_nop 0
	s_nop 0
	s_nop 0
	s_nop 0
	s_nop 0
	s_nop 0
	s_nop 0
	s_nop 0
	s_add_u32 s26, s3, 0xffffff00
	s_addc_u32 s27, s52, -1
	s_and_b64 vcc, exec, s[10:11]
	s_cbranch_vccnz .LBB0_1311
	v_mov_b32_e32 v2, 0
	s_mov_b32 s20, s50
	s_mov_b32 s40, s51
	s_mov_b64 s[22:23], s[24:25]
	s_mov_b32 s49, s2
	v_mov_b32_e32 v3, v2
	v_mov_b32_e32 v4, v2
	v_mov_b32_e32 v5, v2
	v_mov_b32_e32 v6, v2
	v_mov_b32_e32 v7, v2
	v_mov_b32_e32 v8, v2
	v_mov_b32_e32 v9, v2
	v_mov_b32_e32 v14, v2
	v_mov_b32_e32 v15, v2
	v_mov_b32_e32 v16, v2
	v_mov_b32_e32 v17, v2
	v_mov_b32_e32 v18, v2
	v_mov_b32_e32 v19, v2
	v_mov_b32_e32 v20, v2
	v_mov_b32_e32 v21, v2
	v_mov_b32_e32 v26, v2
	v_mov_b32_e32 v27, v2
	v_mov_b32_e32 v28, v2
	v_mov_b32_e32 v29, v2
	v_mov_b32_e32 v34, v2
	v_mov_b32_e32 v35, v2
	v_mov_b32_e32 v36, v2
	v_mov_b32_e32 v37, v2
	v_mov_b32_e32 v42, v2
	v_mov_b32_e32 v43, v2
	v_mov_b32_e32 v44, v2
	v_mov_b32_e32 v45, v2
	v_mov_b32_e32 v50, v2
	v_mov_b32_e32 v51, v2
	v_mov_b32_e32 v52, v2
	v_mov_b32_e32 v53, v2
	v_mov_b32_e32 v10, v2
	v_mov_b32_e32 v11, v2
	v_mov_b32_e32 v12, v2
	v_mov_b32_e32 v13, v2
	v_mov_b32_e32 v120, v2
	v_mov_b32_e32 v121, v2
	v_mov_b32_e32 v122, v2
	v_mov_b32_e32 v123, v2
	v_mov_b32_e32 v22, v2
	v_mov_b32_e32 v23, v2
	v_mov_b32_e32 v24, v2
	v_mov_b32_e32 v25, v2
	v_mov_b32_e32 v30, v2
	v_mov_b32_e32 v31, v2
	v_mov_b32_e32 v32, v2
	v_mov_b32_e32 v33, v2
	v_mov_b32_e32 v38, v2
	v_mov_b32_e32 v39, v2
	v_mov_b32_e32 v40, v2
	v_mov_b32_e32 v41, v2
	v_mov_b32_e32 v46, v2
	v_mov_b32_e32 v47, v2
	v_mov_b32_e32 v48, v2
	v_mov_b32_e32 v49, v2
	v_mov_b32_e32 v54, v2
	v_mov_b32_e32 v55, v2
	v_mov_b32_e32 v56, v2
	v_mov_b32_e32 v57, v2
	v_mov_b32_e32 v58, v2
	v_mov_b32_e32 v59, v2
	v_mov_b32_e32 v60, v2
	v_mov_b32_e32 v61, v2
	v_mov_b32_e32 v62, v2
	v_mov_b32_e32 v63, v2
	v_mov_b32_e32 v64, v2
	v_mov_b32_e32 v65, v2
	v_mov_b32_e32 v68, v2
	v_mov_b32_e32 v69, v2
	v_mov_b32_e32 v70, v2
	v_mov_b32_e32 v71, v2
	v_mov_b32_e32 v76, v2
	v_mov_b32_e32 v77, v2
	v_mov_b32_e32 v78, v2
	v_mov_b32_e32 v79, v2
	v_mov_b32_e32 v84, v2
	v_mov_b32_e32 v85, v2
	v_mov_b32_e32 v86, v2
	v_mov_b32_e32 v87, v2
	v_mov_b32_e32 v92, v2
	v_mov_b32_e32 v93, v2
	v_mov_b32_e32 v94, v2
	v_mov_b32_e32 v95, v2
	v_mov_b32_e32 v100, v2
	v_mov_b32_e32 v101, v2
	v_mov_b32_e32 v102, v2
	v_mov_b32_e32 v103, v2
	v_mov_b32_e32 v108, v2
	v_mov_b32_e32 v109, v2
	v_mov_b32_e32 v110, v2
	v_mov_b32_e32 v111, v2
	v_mov_b32_e32 v116, v2
	v_mov_b32_e32 v117, v2
	v_mov_b32_e32 v118, v2
	v_mov_b32_e32 v119, v2
	v_mov_b32_e32 v72, v2
	v_mov_b32_e32 v73, v2
	v_mov_b32_e32 v74, v2
	v_mov_b32_e32 v75, v2
	v_mov_b32_e32 v80, v2
	v_mov_b32_e32 v81, v2
	v_mov_b32_e32 v82, v2
	v_mov_b32_e32 v83, v2
	v_mov_b32_e32 v88, v2
	v_mov_b32_e32 v89, v2
	v_mov_b32_e32 v90, v2
	v_mov_b32_e32 v91, v2
	v_mov_b32_e32 v96, v2
	v_mov_b32_e32 v97, v2
	v_mov_b32_e32 v98, v2
	v_mov_b32_e32 v99, v2
	v_mov_b32_e32 v104, v2
	v_mov_b32_e32 v105, v2
	v_mov_b32_e32 v106, v2
	v_mov_b32_e32 v107, v2
	v_mov_b32_e32 v112, v2
	v_mov_b32_e32 v113, v2
	v_mov_b32_e32 v114, v2
	v_mov_b32_e32 v115, v2
	v_mov_b32_e32 v124, v2
	v_mov_b32_e32 v125, v2
	v_mov_b32_e32 v126, v2
	v_mov_b32_e32 v127, v2
	v_mov_b32_e32 v128, v2
	v_mov_b32_e32 v129, v2
	v_mov_b32_e32 v130, v2
	v_mov_b32_e32 v131, v2
	s_andn2_b64 vcc, exec, s[6:7]
	s_cbranch_vccnz .LBB0_1312

; #define PG8_STAGE(bufoff, gbase, voff) do { _Pragma("unroll") for (int _i = 0; _i < 2; ++_i) \
;         __builtin_amdgcn_global_load_lds((const unsigned*)((const char*)(gbase) + (voff)[_i]), (PG8_LAS unsigned*)(lds + (bufoff) + ldsw + _i * 8192), 16, 0, 0); } while (0)
; #define PG8_LDA(dst, b, h) do { _Pragma("unroll") for (int m = 0; m < 4; ++m) _Pragma("unroll") for (int k = 0; k < 2; ++k) dst[m][k] = *(const PG8_LAS bf16x8*)(lds + PG8_SA(b, h) + aoff + m * 2048 + k * 1024); } while (0)
; #define PG8_LDB(dst, b, h) do { _Pragma("unroll") for (int n = 0; n < 2; ++n) _Pragma("unroll") for (int k = 0; k < 2; ++k) dst[n][k] = *(const PG8_LAS bf16x8*)(lds + PG8_SB(b, h) + boff + n * 2048 + k * 1024); } while (0)
; #define PG8_MMA(ai, bj, At, Bt) do { __builtin_amdgcn_s_setprio(1); _Pragma("unroll") for (int m = 0; m < 4; ++m) _Pragma("unroll") for (int n = 0; n < 2; ++n) _Pragma("unroll") for (int k = 0; k < 2; ++k) \
;         acc[ai][bj][m][n] = __builtin_amdgcn_mfma_f32_16x16x32_bf16(Bt[n][k], At[m][k], acc[ai][bj][m][n], 0, 0, 0); __builtin_amdgcn_s_setprio(0); } while (0)
; #define PG8_WAIT_V(n) asm volatile("s_waitcnt vmcnt(" #n ")" ::: "memory")
; #define PG8_BAR __builtin_amdgcn_s_barrier()
; template <class Epi, class Sched, bool ALIGN_EPI = false, bool SP2 = false>
; __device__ __forceinline__ void gemm_phase(PG8_LAS unsigned char* lds, const Gemm g, const Sched& S, const Epi& E) {
;     ...
;         for (int t = 0; t < nt; t += 2) {
;             const bool last = (t == nt - 2);
;             const char* a1 = cA + (size_t)(t + 1) * kstep;
;             const char* a2 = last ? nA : cA + (size_t)(t + 2) * kstep; const char* b2 = last ? nB : cB + (size_t)(t + 2) * kstep;
;             const char* a3 = a2 + kstep; const char* b3 = b2 + kstep;
;             if (last && has_next) S.a_ready(nxt);
;             if constexpr (SP2) {
;             PG8_LDB(B0, 0, 0); PG8_LDB(B1, 0, 1); PG8_SCHED; PG8_LDA(At, 0, 0); PG8_STAGE(PG8_SA(1, 1), a1 + hstep, voffA);
;             PG8_WAIT_V(8); PG8_WAIT_L(0); PG8_BAR; PG8_MMA(0, 0, At, B0); PG8_MMA(0, 1, At, B1); PG8_BAR; PG8_SCHED;
;             PG8_LDA(At, 0, 1); PG8_STAGE(PG8_SB(0, 0), b2, voffB); PG8_STAGE(PG8_SB(0, 1), b2 + hstep, voffB); PG8_STAGE(PG8_SA(0, 0), a2, voffA);
;             PG8_WAIT_V(8); PG8_WAIT_L(0); PG8_BAR; PG8_MMA(1, 0, At, B0); PG8_MMA(1, 1, At, B1); PG8_BAR; PG8_SCHED;
.LBB0_1583:
	s_add_u32 s20, s18, 0x100
	s_addc_u32 s21, s19, 0
	s_cmp_eq_u32 s43, 4
	s_cselect_b32 s25, s17, s21
	s_cselect_b32 s24, s16, s20
	s_cselect_b32 s23, s15, s42
	s_cselect_b32 s22, s14, s13
	s_add_i32 s44, 0, 0x10000
	s_add_i32 s45, 0, 0x14000
	v_add_u32_e32 v168, s44, v0
	v_add_u32_e32 v184, s45, v0
	ds_read_b128 v[156:159], v168
	ds_read_b128 v[160:163], v168 offset:1024
	ds_read_b128 v[164:167], v168 offset:2048
	ds_read_b128 v[168:171], v168 offset:3072
	ds_read_b128 v[172:175], v184
	ds_read_b128 v[176:179], v184 offset:1024
	ds_read_b128 v[180:183], v184 offset:2048
	ds_read_b128 v[184:187], v184 offset:3072
	v_lshl_add_u64 v[228:229], s[18:19], 0, v[150:151]
	s_add_i32 m0, s28, 0xc000
	ds_read_b128 v[188:191], v155
	ds_read_b128 v[192:195], v155 offset:1024
	ds_read_b128 v[196:199], v155 offset:2048
	ds_read_b128 v[200:203], v155 offset:3072
	ds_read_b128 v[204:207], v155 offset:4096
	ds_read_b128 v[208:211], v155 offset:5120
	ds_read_b128 v[220:223], v155 offset:6144
	ds_read_b128 v[224:227], v155 offset:7168
	global_load_lds_dwordx4 v[228:229], off
	v_lshl_add_u64 v[228:229], s[18:19], 0, v[152:153]
	s_add_i32 m0, s28, 0xe000
	s_nop 0
	global_load_lds_dwordx4 v[228:229], off
	s_waitcnt vmcnt(8)
	s_waitcnt lgkmcnt(0)
	s_barrier
	v_mfma_f32_16x16x32_bf16 v[128:131], v[156:159], v[188:191], v[128:131]
	v_mfma_f32_16x16x32_bf16 v[124:127], v[164:167], v[188:191], v[124:127]
	v_mfma_f32_16x16x32_bf16 v[120:123], v[156:159], v[196:199], v[120:123]
	v_mfma_f32_16x16x32_bf16 v[116:119], v[164:167], v[196:199], v[116:119]
	v_mfma_f32_16x16x32_bf16 v[112:115], v[156:159], v[204:207], v[112:115]
	v_mfma_f32_16x16x32_bf16 v[108:111], v[164:167], v[204:207], v[108:111]
	v_mfma_f32_16x16x32_bf16 v[100:103], v[156:159], v[220:223], v[100:103]
	v_mfma_f32_16x16x32_bf16 v[92:95], v[164:167], v[220:223], v[92:95]
	v_mfma_f32_16x16x32_bf16 v[128:131], v[160:163], v[192:195], v[128:131]
	v_mfma_f32_16x16x32_bf16 v[124:127], v[168:171], v[192:195], v[124:127]
	v_mfma_f32_16x16x32_bf16 v[120:123], v[160:163], v[200:203], v[120:123]
	v_mfma_f32_16x16x32_bf16 v[116:119], v[168:171], v[200:203], v[116:119]
	v_mfma_f32_16x16x32_bf16 v[112:115], v[160:163], v[208:211], v[112:115]
	v_mfma_f32_16x16x32_bf16 v[108:111], v[168:171], v[208:211], v[108:111]
	v_mfma_f32_16x16x32_bf16 v[100:103], v[160:163], v[224:227], v[100:103]
	v_mfma_f32_16x16x32_bf16 v[92:95], v[168:171], v[224:227], v[92:95]
	v_mfma_f32_16x16x32_bf16 v[104:107], v[172:175], v[188:191], v[104:107]
	v_mfma_f32_16x16x32_bf16 v[96:99], v[180:183], v[188:191], v[96:99]
	v_mfma_f32_16x16x32_bf16 v[88:91], v[172:175], v[196:199], v[88:91]
	v_mfma_f32_16x16x32_bf16 v[84:87], v[180:183], v[196:199], v[84:87]
	v_mfma_f32_16x16x32_bf16 v[80:83], v[172:175], v[204:207], v[80:83]
	v_mfma_f32_16x16x32_bf16 v[76:79], v[180:183], v[204:207], v[76:79]
	v_mfma_f32_16x16x32_bf16 v[72:75], v[172:175], v[220:223], v[72:75]
	v_mfma_f32_16x16x32_bf16 v[68:71], v[180:183], v[220:223], v[68:71]
	v_mfma_f32_16x16x32_bf16 v[104:107], v[176:179], v[192:195], v[104:107]
	v_mfma_f32_16x16x32_bf16 v[96:99], v[184:187], v[192:195], v[96:99]
	v_mfma_f32_16x16x32_bf16 v[88:91], v[176:179], v[200:203], v[88:91]
	v_mfma_f32_16x16x32_bf16 v[84:87], v[184:187], v[200:203], v[84:87]
	v_mfma_f32_16x16x32_bf16 v[80:83], v[176:179], v[208:211], v[80:83]
	v_mfma_f32_16x16x32_bf16 v[76:79], v[184:187], v[208:211], v[76:79]
	v_mfma_f32_16x16x32_bf16 v[72:75], v[176:179], v[224:227], v[72:75]
	v_mfma_f32_16x16x32_bf16 v[68:71], v[184:187], v[224:227], v[68:71]
	s_barrier
	s_add_i32 s18, s44, s1
	v_lshl_add_u64 v[228:229], s[22:23], 0, v[66:67]
	s_mov_b32 m0, s18
	ds_read_b128 v[188:191], v155 offset:16384
	ds_read_b128 v[192:195], v155 offset:17408
	ds_read_b128 v[196:199], v155 offset:18432
	ds_read_b128 v[200:203], v155 offset:19456
	ds_read_b128 v[204:207], v155 offset:20480
	ds_read_b128 v[208:211], v155 offset:21504
	ds_read_b128 v[220:223], v155 offset:22528
	ds_read_b128 v[224:227], v155 offset:23552
	global_load_lds_dwordx4 v[228:229], off
	s_add_i32 m0, s18, 0x2000
	s_add_u32 s18, s22, 0x160000
	v_lshl_add_u64 v[230:231], s[22:23], 0, v[132:133]
	s_addc_u32 s19, s23, 0
	s_add_i32 s44, s45, s1
	global_load_lds_dwordx4 v[230:231], off
	v_lshl_add_u64 v[232:233], s[18:19], 0, v[66:67]
	s_mov_b32 m0, s44
	v_lshl_add_u64 v[234:235], s[24:25], 0, v[132:133]
	global_load_lds_dwordx4 v[232:233], off
	v_lshl_add_u64 v[232:233], s[18:19], 0, v[132:133]
	s_add_i32 m0, s44, 0x2000
	s_nop 0
	global_load_lds_dwordx4 v[232:233], off
	v_lshl_add_u64 v[232:233], s[24:25], 0, v[66:67]
	s_mov_b32 m0, s28
	s_nop 0
	global_load_lds_dwordx4 v[232:233], off
	s_mov_b32 m0, s29
	s_nop 0
	global_load_lds_dwordx4 v[234:235], off
	s_waitcnt vmcnt(8)
	s_waitcnt lgkmcnt(0)
	s_barrier
; #define PG8_STAGE(bufoff, gbase, voff) do { _Pragma("unroll") for (int _i = 0; _i < 2; ++_i) \
;         __builtin_amdgcn_global_load_lds((const unsigned*)((const char*)(gbase) + (voff)[_i]), (PG8_LAS unsigned*)(lds + (bufoff) + ldsw + _i * 8192), 16, 0, 0); } while (0)
; #define PG8_LDA(dst, b, h) do { _Pragma("unroll") for (int m = 0; m < 4; ++m) _Pragma("unroll") for (int k = 0; k < 2; ++k) dst[m][k] = *(const PG8_LAS bf16x8*)(lds + PG8_SA(b, h) + aoff + m * 2048 + k * 1024); } while (0)
; #define PG8_LDB(dst, b, h) do { _Pragma("unroll") for (int n = 0; n < 2; ++n) _Pragma("unroll") for (int k = 0; k < 2; ++k) dst[n][k] = *(const PG8_LAS bf16x8*)(lds + PG8_SB(b, h) + boff + n * 2048 + k * 1024); } while (0)
; #define PG8_MMA(ai, bj, At, Bt) do { __builtin_amdgcn_s_setprio(1); _Pragma("unroll") for (int m = 0; m < 4; ++m) _Pragma("unroll") for (int n = 0; n < 2; ++n) _Pragma("unroll") for (int k = 0; k < 2; ++k) \
;         acc[ai][bj][m][n] = __builtin_amdgcn_mfma_f32_16x16x32_bf16(Bt[n][k], At[m][k], acc[ai][bj][m][n], 0, 0, 0); __builtin_amdgcn_s_setprio(0); } while (0)
; #define PG8_WAIT_V(n) asm volatile("s_waitcnt vmcnt(" #n ")" ::: "memory")
; #define PG8_WAIT_L(n) asm volatile("s_waitcnt lgkmcnt(" #n ")" ::: "memory")
; #define PG8_BAR __builtin_amdgcn_s_barrier()
; #define PG8_SCHED __builtin_amdgcn_sched_barrier(0)
; template <class Epi, class Sched, bool ALIGN_EPI = false, bool SP2 = false>
; __device__ __forceinline__ void gemm_phase(PG8_LAS unsigned char* lds, const Gemm g, const Sched& S, const Epi& E) {
;     ...
;             PG8_WAIT_V(8); PG8_WAIT_L(0); PG8_BAR; PG8_MMA(1, 0, At, B0); PG8_MMA(1, 1, At, B1); PG8_BAR; PG8_SCHED;
;             PG8_LDB(B0, 1, 0); PG8_LDB(B1, 1, 1); PG8_SCHED; PG8_LDA(At, 1, 0); PG8_STAGE(PG8_SA(0, 1), a2 + hstep, voffA);
;             PG8_WAIT_V(8); PG8_WAIT_L(0); PG8_BAR; PG8_MMA(0, 0, At, B0); PG8_MMA(0, 1, At, B1); PG8_BAR; PG8_SCHED;
;             PG8_LDA(At, 1, 1); PG8_STAGE(PG8_SB(1, 0), b3, voffB); PG8_STAGE(PG8_SB(1, 1), b3 + hstep, voffB); PG8_STAGE(PG8_SA(1, 0), a3, voffA);
	v_mfma_f32_16x16x32_bf16 v[62:65], v[156:159], v[188:191], v[62:65]
	v_mfma_f32_16x16x32_bf16 v[58:61], v[164:167], v[188:191], v[58:61]
	v_mfma_f32_16x16x32_bf16 v[54:57], v[156:159], v[196:199], v[54:57]
	v_mfma_f32_16x16x32_bf16 v[50:53], v[164:167], v[196:199], v[50:53]
	v_mfma_f32_16x16x32_bf16 v[46:49], v[156:159], v[204:207], v[46:49]
	v_mfma_f32_16x16x32_bf16 v[42:45], v[164:167], v[204:207], v[42:45]
	v_mfma_f32_16x16x32_bf16 v[34:37], v[156:159], v[220:223], v[34:37]
	v_mfma_f32_16x16x32_bf16 v[26:29], v[164:167], v[220:223], v[26:29]
	v_mfma_f32_16x16x32_bf16 v[62:65], v[160:163], v[192:195], v[62:65]
	v_mfma_f32_16x16x32_bf16 v[58:61], v[168:171], v[192:195], v[58:61]
	v_mfma_f32_16x16x32_bf16 v[54:57], v[160:163], v[200:203], v[54:57]
	v_mfma_f32_16x16x32_bf16 v[50:53], v[168:171], v[200:203], v[50:53]
	v_mfma_f32_16x16x32_bf16 v[46:49], v[160:163], v[208:211], v[46:49]
	v_mfma_f32_16x16x32_bf16 v[42:45], v[168:171], v[208:211], v[42:45]
	v_mfma_f32_16x16x32_bf16 v[34:37], v[160:163], v[224:227], v[34:37]
	v_mfma_f32_16x16x32_bf16 v[26:29], v[168:171], v[224:227], v[26:29]
	v_mfma_f32_16x16x32_bf16 v[38:41], v[172:175], v[188:191], v[38:41]
	v_mfma_f32_16x16x32_bf16 v[30:33], v[180:183], v[188:191], v[30:33]
	v_mfma_f32_16x16x32_bf16 v[22:25], v[172:175], v[196:199], v[22:25]
	v_mfma_f32_16x16x32_bf16 v[18:21], v[180:183], v[196:199], v[18:21]
	v_mfma_f32_16x16x32_bf16 v[14:17], v[172:175], v[204:207], v[14:17]
	v_mfma_f32_16x16x32_bf16 v[10:13], v[180:183], v[204:207], v[10:13]
	v_mfma_f32_16x16x32_bf16 v[6:9], v[172:175], v[220:223], v[6:9]
	v_mfma_f32_16x16x32_bf16 v[2:5], v[180:183], v[220:223], v[2:5]
	v_mfma_f32_16x16x32_bf16 v[38:41], v[176:179], v[192:195], v[38:41]
	v_mfma_f32_16x16x32_bf16 v[30:33], v[184:187], v[192:195], v[30:33]
	v_mfma_f32_16x16x32_bf16 v[22:25], v[176:179], v[200:203], v[22:25]
	v_mfma_f32_16x16x32_bf16 v[18:21], v[184:187], v[200:203], v[18:21]
	v_mfma_f32_16x16x32_bf16 v[14:17], v[176:179], v[208:211], v[14:17]
	v_mfma_f32_16x16x32_bf16 v[10:13], v[184:187], v[208:211], v[10:13]
	v_mfma_f32_16x16x32_bf16 v[6:9], v[176:179], v[224:227], v[6:9]
	v_mfma_f32_16x16x32_bf16 v[2:5], v[184:187], v[224:227], v[2:5]
	s_barrier
	s_add_i32 s44, 0, 0x18000
	s_add_i32 s45, 0, 0x1c000
	v_add_u32_e32 v168, s44, v0
	v_add_u32_e32 v184, s45, v0
	ds_read_b128 v[156:159], v168
	ds_read_b128 v[160:163], v168 offset:1024
	ds_read_b128 v[164:167], v168 offset:2048
	ds_read_b128 v[168:171], v168 offset:3072
	ds_read_b128 v[172:175], v184
	ds_read_b128 v[176:179], v184 offset:1024
	ds_read_b128 v[180:183], v184 offset:2048
	ds_read_b128 v[184:187], v184 offset:3072
	s_add_u32 s18, s24, 0x160000
	s_addc_u32 s19, s25, 0
	s_mov_b32 m0, s30
	v_lshl_add_u64 v[246:247], s[18:19], 0, v[66:67]
	ds_read_b128 v[188:191], v155 offset:32768
	ds_read_b128 v[192:195], v155 offset:33792
	ds_read_b128 v[196:199], v155 offset:34816
	ds_read_b128 v[200:203], v155 offset:35840
	ds_read_b128 v[204:207], v155 offset:36864
	ds_read_b128 v[208:211], v155 offset:37888
	ds_read_b128 v[220:223], v155 offset:38912
	ds_read_b128 v[224:227], v155 offset:39936
	global_load_lds_dwordx4 v[246:247], off
	v_lshl_add_u64 v[246:247], s[18:19], 0, v[132:133]
	s_mov_b32 m0, s31
	s_nop 0
	global_load_lds_dwordx4 v[246:247], off
	s_waitcnt vmcnt(8)
	s_waitcnt lgkmcnt(0)
	s_barrier
	v_mfma_f32_16x16x32_bf16 v[128:131], v[156:159], v[188:191], v[128:131]
	v_mfma_f32_16x16x32_bf16 v[124:127], v[164:167], v[188:191], v[124:127]
	v_mfma_f32_16x16x32_bf16 v[120:123], v[156:159], v[196:199], v[120:123]
	v_mfma_f32_16x16x32_bf16 v[116:119], v[164:167], v[196:199], v[116:119]
	v_mfma_f32_16x16x32_bf16 v[112:115], v[156:159], v[204:207], v[112:115]
	v_mfma_f32_16x16x32_bf16 v[108:111], v[164:167], v[204:207], v[108:111]
	v_mfma_f32_16x16x32_bf16 v[100:103], v[156:159], v[220:223], v[100:103]
	v_mfma_f32_16x16x32_bf16 v[92:95], v[164:167], v[220:223], v[92:95]
	v_mfma_f32_16x16x32_bf16 v[128:131], v[160:163], v[192:195], v[128:131]
	v_mfma_f32_16x16x32_bf16 v[124:127], v[168:171], v[192:195], v[124:127]
	v_mfma_f32_16x16x32_bf16 v[120:123], v[160:163], v[200:203], v[120:123]
	v_mfma_f32_16x16x32_bf16 v[116:119], v[168:171], v[200:203], v[116:119]
	v_mfma_f32_16x16x32_bf16 v[112:115], v[160:163], v[208:211], v[112:115]
	v_mfma_f32_16x16x32_bf16 v[108:111], v[168:171], v[208:211], v[108:111]
	v_mfma_f32_16x16x32_bf16 v[100:103], v[160:163], v[224:227], v[100:103]
	v_mfma_f32_16x16x32_bf16 v[92:95], v[168:171], v[224:227], v[92:95]
	v_mfma_f32_16x16x32_bf16 v[104:107], v[172:175], v[188:191], v[104:107]
	v_mfma_f32_16x16x32_bf16 v[96:99], v[180:183], v[188:191], v[96:99]
	v_mfma_f32_16x16x32_bf16 v[88:91], v[172:175], v[196:199], v[88:91]
	v_mfma_f32_16x16x32_bf16 v[84:87], v[180:183], v[196:199], v[84:87]
	v_mfma_f32_16x16x32_bf16 v[80:83], v[172:175], v[204:207], v[80:83]
	v_mfma_f32_16x16x32_bf16 v[76:79], v[180:183], v[204:207], v[76:79]
	v_mfma_f32_16x16x32_bf16 v[72:75], v[172:175], v[220:223], v[72:75]
	v_mfma_f32_16x16x32_bf16 v[68:71], v[180:183], v[220:223], v[68:71]
	v_mfma_f32_16x16x32_bf16 v[104:107], v[176:179], v[192:195], v[104:107]
	v_mfma_f32_16x16x32_bf16 v[96:99], v[184:187], v[192:195], v[96:99]
	v_mfma_f32_16x16x32_bf16 v[88:91], v[176:179], v[200:203], v[88:91]
	v_mfma_f32_16x16x32_bf16 v[84:87], v[184:187], v[200:203], v[84:87]
	v_mfma_f32_16x16x32_bf16 v[80:83], v[176:179], v[208:211], v[80:83]
	v_mfma_f32_16x16x32_bf16 v[76:79], v[184:187], v[208:211], v[76:79]
	v_mfma_f32_16x16x32_bf16 v[72:75], v[176:179], v[224:227], v[72:75]
	v_mfma_f32_16x16x32_bf16 v[68:71], v[184:187], v[224:227], v[68:71]
	s_barrier
; #define PG8_STAGE(bufoff, gbase, voff) do { _Pragma("unroll") for (int _i = 0; _i < 2; ++_i) \
;         __builtin_amdgcn_global_load_lds((const unsigned*)((const char*)(gbase) + (voff)[_i]), (PG8_LAS unsigned*)(lds + (bufoff) + ldsw + _i * 8192), 16, 0, 0); } while (0)
; #define PG8_LDA(dst, b, h) do { _Pragma("unroll") for (int m = 0; m < 4; ++m) _Pragma("unroll") for (int k = 0; k < 2; ++k) dst[m][k] = *(const PG8_LAS bf16x8*)(lds + PG8_SA(b, h) + aoff + m * 2048 + k * 1024); } while (0)
; #define PG8_MMA(ai, bj, At, Bt) do { __builtin_amdgcn_s_setprio(1); _Pragma("unroll") for (int m = 0; m < 4; ++m) _Pragma("unroll") for (int n = 0; n < 2; ++n) _Pragma("unroll") for (int k = 0; k < 2; ++k) \
;         acc[ai][bj][m][n] = __builtin_amdgcn_mfma_f32_16x16x32_bf16(Bt[n][k], At[m][k], acc[ai][bj][m][n], 0, 0, 0); __builtin_amdgcn_s_setprio(0); } while (0)
; #define PG8_WAIT_V(n) asm volatile("s_waitcnt vmcnt(" #n ")" ::: "memory")
; #define PG8_WAIT_L(n) asm volatile("s_waitcnt lgkmcnt(" #n ")" ::: "memory")
; #define PG8_BAR __builtin_amdgcn_s_barrier()
; #define PG8_SCHED __builtin_amdgcn_sched_barrier(0)
; template <class Epi, class Sched, bool ALIGN_EPI = false, bool SP2 = false>
; __device__ __forceinline__ void gemm_phase(PG8_LAS unsigned char* lds, const Gemm g, const Sched& S, const Epi& E) {
;     ...
;             PG8_LDA(At, 1, 1); PG8_STAGE(PG8_SB(1, 0), b3, voffB); PG8_STAGE(PG8_SB(1, 1), b3 + hstep, voffB); PG8_STAGE(PG8_SA(1, 0), a3, voffA);
;             PG8_WAIT_V(8); PG8_WAIT_L(0); PG8_BAR; PG8_MMA(1, 0, At, B0); PG8_MMA(1, 1, At, B1); PG8_BAR; PG8_SCHED;
;     ...
;         if constexpr (ALIGN_EPI) { if (wr == 0) PG8_BAR; }
	s_add_i32 s18, s44, s1
	v_lshl_add_u64 v[228:229], v[228:229], 0, s[88:89]
	s_mov_b32 m0, s18
	ds_read_b128 v[188:191], v155 offset:49152
	ds_read_b128 v[192:195], v155 offset:50176
	ds_read_b128 v[196:199], v155 offset:51200
	ds_read_b128 v[200:203], v155 offset:52224
	ds_read_b128 v[204:207], v155 offset:53248
	ds_read_b128 v[208:211], v155 offset:54272
	ds_read_b128 v[220:223], v155 offset:55296
	ds_read_b128 v[224:227], v155 offset:56320
	global_load_lds_dwordx4 v[228:229], off
	s_add_i32 m0, s18, 0x2000
	s_add_u32 s18, s22, 0x160080
	v_lshl_add_u64 v[228:229], v[230:231], 0, s[88:89]
	s_addc_u32 s19, s23, 0
	s_add_i32 s22, s45, s1
	global_load_lds_dwordx4 v[228:229], off
	v_lshl_add_u64 v[228:229], s[18:19], 0, v[66:67]
	s_mov_b32 m0, s22
	s_nop 0
	global_load_lds_dwordx4 v[228:229], off
	v_lshl_add_u64 v[228:229], s[18:19], 0, v[132:133]
	s_add_i32 m0, s22, 0x2000
	s_nop 0
	global_load_lds_dwordx4 v[228:229], off
	v_lshl_add_u64 v[228:229], v[232:233], 0, s[88:89]
	s_mov_b32 m0, s38
	s_nop 0
	global_load_lds_dwordx4 v[228:229], off
	v_lshl_add_u64 v[228:229], v[234:235], 0, s[88:89]
	s_mov_b32 m0, s39
	s_nop 0
	global_load_lds_dwordx4 v[228:229], off
	s_waitcnt vmcnt(8)
	s_waitcnt lgkmcnt(0)
	s_barrier
	v_mfma_f32_16x16x32_bf16 v[62:65], v[156:159], v[188:191], v[62:65]
	v_mfma_f32_16x16x32_bf16 v[58:61], v[164:167], v[188:191], v[58:61]
	v_mfma_f32_16x16x32_bf16 v[54:57], v[156:159], v[196:199], v[54:57]
	v_mfma_f32_16x16x32_bf16 v[50:53], v[164:167], v[196:199], v[50:53]
	v_mfma_f32_16x16x32_bf16 v[46:49], v[156:159], v[204:207], v[46:49]
	v_mfma_f32_16x16x32_bf16 v[42:45], v[164:167], v[204:207], v[42:45]
	v_mfma_f32_16x16x32_bf16 v[34:37], v[156:159], v[220:223], v[34:37]
	v_mfma_f32_16x16x32_bf16 v[26:29], v[164:167], v[220:223], v[26:29]
	v_mfma_f32_16x16x32_bf16 v[62:65], v[160:163], v[192:195], v[62:65]
	v_mfma_f32_16x16x32_bf16 v[58:61], v[168:171], v[192:195], v[58:61]
	v_mfma_f32_16x16x32_bf16 v[54:57], v[160:163], v[200:203], v[54:57]
	v_mfma_f32_16x16x32_bf16 v[50:53], v[168:171], v[200:203], v[50:53]
	v_mfma_f32_16x16x32_bf16 v[46:49], v[160:163], v[208:211], v[46:49]
	v_mfma_f32_16x16x32_bf16 v[42:45], v[168:171], v[208:211], v[42:45]
	v_mfma_f32_16x16x32_bf16 v[34:37], v[160:163], v[224:227], v[34:37]
	v_mfma_f32_16x16x32_bf16 v[26:29], v[168:171], v[224:227], v[26:29]
	v_mfma_f32_16x16x32_bf16 v[38:41], v[172:175], v[188:191], v[38:41]
	v_mfma_f32_16x16x32_bf16 v[30:33], v[180:183], v[188:191], v[30:33]
	v_mfma_f32_16x16x32_bf16 v[22:25], v[172:175], v[196:199], v[22:25]
	v_mfma_f32_16x16x32_bf16 v[18:21], v[180:183], v[196:199], v[18:21]
	v_mfma_f32_16x16x32_bf16 v[14:17], v[172:175], v[204:207], v[14:17]
	v_mfma_f32_16x16x32_bf16 v[10:13], v[180:183], v[204:207], v[10:13]
	v_mfma_f32_16x16x32_bf16 v[6:9], v[172:175], v[220:223], v[6:9]
	v_mfma_f32_16x16x32_bf16 v[2:5], v[180:183], v[220:223], v[2:5]
	v_mfma_f32_16x16x32_bf16 v[38:41], v[176:179], v[192:195], v[38:41]
	v_mfma_f32_16x16x32_bf16 v[30:33], v[184:187], v[192:195], v[30:33]
	v_mfma_f32_16x16x32_bf16 v[22:25], v[176:179], v[200:203], v[22:25]
	v_mfma_f32_16x16x32_bf16 v[18:21], v[184:187], v[200:203], v[18:21]
	v_mfma_f32_16x16x32_bf16 v[14:17], v[176:179], v[208:211], v[14:17]
	v_mfma_f32_16x16x32_bf16 v[10:13], v[184:187], v[208:211], v[10:13]
	v_mfma_f32_16x16x32_bf16 v[6:9], v[176:179], v[224:227], v[6:9]
	v_mfma_f32_16x16x32_bf16 v[2:5], v[184:187], v[224:227], v[2:5]
	s_barrier
	s_add_i32 s43, s43, 2
	s_add_u32 s13, s13, 0x100
	s_addc_u32 s42, s42, 0
	s_cmp_gt_u32 s43, 5
	s_mov_b64 s[18:19], s[20:21]
	s_cbranch_scc0 .LBB0_1583
	s_nop 0
	s_nop 0
	s_nop 0
	s_nop 0
	s_nop 0
	s_nop 0
	s_nop 0
	s_nop 0
	s_nop 0
	s_nop 0
	s_nop 0
	s_nop 0
	s_nop 0
	s_nop 0
	s_nop 0
	s_nop 0
	s_nop 0
	s_nop 0
	s_nop 0
	s_nop 0
	s_and_b64 vcc, exec, s[10:11]
	s_cbranch_vccz .LBB0_1586
	s_barrier
